# GEMM K-loops: last LDS-DMA stage of the 6-piece load segment moved to the next 2-piece segment (4/4), wait vmcnt(6); plus nosync+cvt4
# speedup vs baseline: 1.0068x; 1.0023x over previous
; #define PG8_STAGE(bufoff, gbase, voff) do { _Pragma("unroll") for (int _i = 0; _i < 2; ++_i) \
;         __builtin_amdgcn_global_load_lds((const unsigned*)((const char*)(gbase) + (voff)[_i]), (PG8_LAS unsigned*)(lds + (bufoff) + ldsw + _i * 8192), 16, 0, 0); } while (0)
; #define PG8_LDA(dst, b, h) do { _Pragma("unroll") for (int m = 0; m < 4; ++m) _Pragma("unroll") for (int k = 0; k < 2; ++k) dst[m][k] = *(const PG8_LAS bf16x8*)(lds + PG8_SA(b, h) + aoff + m * 2048 + k * 1024); } while (0)
; #define PG8_LDB(dst, b, h) do { _Pragma("unroll") for (int n = 0; n < 2; ++n) _Pragma("unroll") for (int k = 0; k < 2; ++k) dst[n][k] = *(const PG8_LAS bf16x8*)(lds + PG8_SB(b, h) + boff + n * 2048 + k * 1024); } while (0)
; #define PG8_MMA(ai, bj, At, Bt) do { __builtin_amdgcn_s_setprio(1); _Pragma("unroll") for (int m = 0; m < 4; ++m) _Pragma("unroll") for (int n = 0; n < 2; ++n) _Pragma("unroll") for (int k = 0; k < 2; ++k) \
;         acc[ai][bj][m][n] = __builtin_amdgcn_mfma_f32_16x16x32_bf16(Bt[n][k], At[m][k], acc[ai][bj][m][n], 0, 0, 0); __builtin_amdgcn_s_setprio(0); } while (0)
; #define PG8_WAIT_V(n) asm volatile("s_waitcnt vmcnt(" #n ")" ::: "memory")
; #define PG8_WAIT_L(n) asm volatile("s_waitcnt lgkmcnt(" #n ")" ::: "memory")
; template <class Epi, class Sched, bool ALIGN_EPI = false, bool SP2 = false>
; __device__ __forceinline__ void gemm_phase(PG8_LAS unsigned char* lds, const Gemm g, const Sched& S, const Epi& E) {
;     ...
;             const bool last = (t == nt - 2);
;             const char* a1 = cA + PG8_AK(t + 1);
;             const char* a2 = last ? nA : cA + PG8_AK(t + 2); const char* b2 = last ? nB : cB + (size_t)(t + 2) * kstep;
;             const char* a3 = last ? nA + PG8_AK(1) : cA + PG8_AK(t + 3); const char* b3 = b2 + kstep;
;             if (last && has_next) S.a_ready(nxt);
;             if constexpr (SP2) {
;             PG8_LDB(B0, 0, 0); PG8_LDB(B1, 0, 1); PG8_SCHED; PG8_LDA(At, 0, 0); PG8_STAGE(PG8_SA(1, 1), a1 + hstepA, voffA);
;             PG8_WAIT_V(8); PG8_WAIT_L(0); PG8_BAR; PG8_MMA(0, 0, At, B0); PG8_MMA(0, 1, At, B1); PG8_BAR; PG8_SCHED;
;             PG8_LDA(At, 0, 1); PG8_STAGE(PG8_SB(0, 0), b2, voffB); PG8_STAGE(PG8_SB(0, 1), b2 + hstepB, voffB); PG8_STAGE(PG8_SA(0, 0), a2, voffA);
;             PG8_WAIT_V(8); PG8_WAIT_L(0); PG8_BAR; PG8_MMA(1, 0, At, B0); PG8_MMA(1, 1, At, B1); PG8_BAR; PG8_SCHED;
.LBB0_129:
	ds_read_b128 v[132:135], v172
	ds_read_b128 v[158:161], v172 offset:1024
	ds_read_b128 v[176:179], v172 offset:2048
	ds_read_b128 v[180:183], v172 offset:3072
	ds_read_b128 v[184:187], v173
	ds_read_b128 v[188:191], v173 offset:1024
	ds_read_b128 v[192:195], v173 offset:2048
	ds_read_b128 v[196:199], v173 offset:3072
	s_add_u32 s38, s28, s34
	s_addc_u32 s39, s29, s35
	s_add_u32 s42, s38, 0x100
	s_addc_u32 s43, s39, 0
	s_add_u32 s40, s62, s34
	s_addc_u32 s41, s63, s35
	s_add_u32 s38, s38, 0x180
	s_addc_u32 s39, s39, 0
	s_cmpk_eq_i32 s34, 0x700
	s_cselect_b32 s39, s37, s39
	s_cselect_b32 s38, s31, s38
	s_cselect_b32 s41, s21, s41
	s_cselect_b32 s40, s23, s40
	s_cselect_b32 s43, s3, s43
	s_cselect_b32 s42, s10, s42
	v_lshl_add_u64 v[204:205], v[130:131], 0, s[34:35]
	s_add_i32 m0, s49, 0xc000
	ds_read_b128 v[200:203], v174
	ds_read_b128 v[208:211], v174 offset:1024
	ds_read_b128 v[212:215], v174 offset:2048
	ds_read_b128 v[216:219], v174 offset:3072
	ds_read_b128 v[220:223], v174 offset:4096
	ds_read_b128 v[224:227], v174 offset:5120
	ds_read_b128 v[228:231], v174 offset:6144
	ds_read_b128 v[232:235], v174 offset:7168
	global_load_lds_dwordx4 v[204:205], off
	v_lshl_add_u64 v[204:205], v[128:129], 0, s[34:35]
	s_add_i32 m0, s49, 0xe000
	s_nop 0
	global_load_lds_dwordx4 v[204:205], off
	s_waitcnt vmcnt(8)
	s_waitcnt lgkmcnt(0)
	s_barrier
	s_setprio 1
	s_waitcnt lgkmcnt(0)
	v_mfma_f32_16x16x32_bf16 v[124:127], v[132:135], v[200:203], v[124:127]
	v_mfma_f32_16x16x32_bf16 v[120:123], v[176:179], v[200:203], v[120:123]
	v_mfma_f32_16x16x32_bf16 v[108:111], v[132:135], v[212:215], v[108:111]
	v_mfma_f32_16x16x32_bf16 v[104:107], v[176:179], v[212:215], v[104:107]
	v_mfma_f32_16x16x32_bf16 v[92:95], v[132:135], v[220:223], v[92:95]
	v_mfma_f32_16x16x32_bf16 v[88:91], v[176:179], v[220:223], v[88:91]
	v_mfma_f32_16x16x32_bf16 v[76:79], v[132:135], v[228:231], v[76:79]
	v_mfma_f32_16x16x32_bf16 v[72:75], v[176:179], v[228:231], v[72:75]
	v_mfma_f32_16x16x32_bf16 v[124:127], v[158:161], v[208:211], v[124:127]
	v_mfma_f32_16x16x32_bf16 v[120:123], v[180:183], v[208:211], v[120:123]
	v_mfma_f32_16x16x32_bf16 v[108:111], v[158:161], v[216:219], v[108:111]
	v_mfma_f32_16x16x32_bf16 v[104:107], v[180:183], v[216:219], v[104:107]
	v_mfma_f32_16x16x32_bf16 v[92:95], v[158:161], v[224:227], v[92:95]
	v_mfma_f32_16x16x32_bf16 v[88:91], v[180:183], v[224:227], v[88:91]
	v_mfma_f32_16x16x32_bf16 v[76:79], v[158:161], v[232:235], v[76:79]
	v_mfma_f32_16x16x32_bf16 v[72:75], v[180:183], v[232:235], v[72:75]
	s_setprio 0
	s_setprio 1
	v_mfma_f32_16x16x32_bf16 v[116:119], v[184:187], v[200:203], v[116:119]
	v_mfma_f32_16x16x32_bf16 v[112:115], v[192:195], v[200:203], v[112:115]
	v_mfma_f32_16x16x32_bf16 v[100:103], v[184:187], v[212:215], v[100:103]
	v_mfma_f32_16x16x32_bf16 v[96:99], v[192:195], v[212:215], v[96:99]
	v_mfma_f32_16x16x32_bf16 v[84:87], v[184:187], v[220:223], v[84:87]
	v_mfma_f32_16x16x32_bf16 v[80:83], v[192:195], v[220:223], v[80:83]
	v_mfma_f32_16x16x32_bf16 v[68:71], v[184:187], v[228:231], v[68:71]
	v_mfma_f32_16x16x32_bf16 v[64:67], v[192:195], v[228:231], v[64:67]
	v_mfma_f32_16x16x32_bf16 v[116:119], v[188:191], v[208:211], v[116:119]
	v_mfma_f32_16x16x32_bf16 v[112:115], v[196:199], v[208:211], v[112:115]
	v_mfma_f32_16x16x32_bf16 v[100:103], v[188:191], v[216:219], v[100:103]
	v_mfma_f32_16x16x32_bf16 v[96:99], v[196:199], v[216:219], v[96:99]
	v_mfma_f32_16x16x32_bf16 v[84:87], v[188:191], v[224:227], v[84:87]
	v_mfma_f32_16x16x32_bf16 v[80:83], v[196:199], v[224:227], v[80:83]
	v_mfma_f32_16x16x32_bf16 v[68:71], v[188:191], v[232:235], v[68:71]
	v_mfma_f32_16x16x32_bf16 v[64:67], v[196:199], v[232:235], v[64:67]
	s_setprio 0
	s_barrier
	s_add_i32 s65, s58, s48
	v_lshl_add_u64 v[204:205], s[40:41], 0, v[138:139]
	s_mov_b32 m0, s65
	ds_read_b128 v[200:203], v174 offset:16384
	ds_read_b128 v[208:211], v174 offset:17408
	ds_read_b128 v[212:215], v174 offset:18432
	ds_read_b128 v[216:219], v174 offset:19456
	ds_read_b128 v[220:223], v174 offset:20480
	ds_read_b128 v[224:227], v174 offset:21504
	ds_read_b128 v[228:231], v174 offset:22528
	ds_read_b128 v[232:235], v174 offset:23552
	global_load_lds_dwordx4 v[204:205], off
	s_add_i32 m0, s65, 0x2000
	s_add_u32 s66, s40, 0x40000
	v_lshl_add_u64 v[206:207], s[40:41], 0, v[142:143]
	s_addc_u32 s67, s41, 0
	s_add_i32 s65, s59, s48
	global_load_lds_dwordx4 v[206:207], off
	v_lshl_add_u64 v[236:237], s[66:67], 0, v[138:139]
	s_mov_b32 m0, s65
	s_nop 0
	global_load_lds_dwordx4 v[236:237], off
	v_lshl_add_u64 v[236:237], s[66:67], 0, v[142:143]
	s_add_i32 m0, s65, 0x2000
	s_nop 0
	global_load_lds_dwordx4 v[236:237], off
	s_waitcnt vmcnt(6)
	s_waitcnt lgkmcnt(0)
	s_barrier
; #define PG8_STAGE(bufoff, gbase, voff) do { _Pragma("unroll") for (int _i = 0; _i < 2; ++_i) \
;         __builtin_amdgcn_global_load_lds((const unsigned*)((const char*)(gbase) + (voff)[_i]), (PG8_LAS unsigned*)(lds + (bufoff) + ldsw + _i * 8192), 16, 0, 0); } while (0)
; #define PG8_LDA(dst, b, h) do { _Pragma("unroll") for (int m = 0; m < 4; ++m) _Pragma("unroll") for (int k = 0; k < 2; ++k) dst[m][k] = *(const PG8_LAS bf16x8*)(lds + PG8_SA(b, h) + aoff + m * 2048 + k * 1024); } while (0)
; #define PG8_LDB(dst, b, h) do { _Pragma("unroll") for (int n = 0; n < 2; ++n) _Pragma("unroll") for (int k = 0; k < 2; ++k) dst[n][k] = *(const PG8_LAS bf16x8*)(lds + PG8_SB(b, h) + boff + n * 2048 + k * 1024); } while (0)
; #define PG8_MMA(ai, bj, At, Bt) do { __builtin_amdgcn_s_setprio(1); _Pragma("unroll") for (int m = 0; m < 4; ++m) _Pragma("unroll") for (int n = 0; n < 2; ++n) _Pragma("unroll") for (int k = 0; k < 2; ++k) \
;         acc[ai][bj][m][n] = __builtin_amdgcn_mfma_f32_16x16x32_bf16(Bt[n][k], At[m][k], acc[ai][bj][m][n], 0, 0, 0); __builtin_amdgcn_s_setprio(0); } while (0)
; #define PG8_WAIT_V(n) asm volatile("s_waitcnt vmcnt(" #n ")" ::: "memory")
; #define PG8_WAIT_L(n) asm volatile("s_waitcnt lgkmcnt(" #n ")" ::: "memory")
; #define PG8_BAR __builtin_amdgcn_s_barrier()
; #define PG8_SCHED __builtin_amdgcn_sched_barrier(0)
; template <class Epi, class Sched, bool ALIGN_EPI = false, bool SP2 = false>
; __device__ __forceinline__ void gemm_phase(PG8_LAS unsigned char* lds, const Gemm g, const Sched& S, const Epi& E) {
;     ...
;             PG8_WAIT_V(8); PG8_WAIT_L(0); PG8_BAR; PG8_MMA(1, 0, At, B0); PG8_MMA(1, 1, At, B1); PG8_BAR; PG8_SCHED;
;             PG8_LDB(B0, 1, 0); PG8_LDB(B1, 1, 1); PG8_SCHED; PG8_LDA(At, 1, 0); PG8_STAGE(PG8_SA(0, 1), a2 + hstepA, voffA);
;             PG8_WAIT_V(8); PG8_WAIT_L(0); PG8_BAR; PG8_MMA(0, 0, At, B0); PG8_MMA(0, 1, At, B1); PG8_BAR; PG8_SCHED;
	s_setprio 1
	s_waitcnt lgkmcnt(0)
	v_mfma_f32_16x16x32_bf16 v[60:63], v[132:135], v[200:203], v[60:63]
	v_mfma_f32_16x16x32_bf16 v[56:59], v[176:179], v[200:203], v[56:59]
	v_mfma_f32_16x16x32_bf16 v[44:47], v[132:135], v[212:215], v[44:47]
	v_mfma_f32_16x16x32_bf16 v[40:43], v[176:179], v[212:215], v[40:43]
	v_mfma_f32_16x16x32_bf16 v[28:31], v[132:135], v[220:223], v[28:31]
	v_mfma_f32_16x16x32_bf16 v[24:27], v[176:179], v[220:223], v[24:27]
	v_mfma_f32_16x16x32_bf16 v[12:15], v[132:135], v[228:231], v[12:15]
	v_mfma_f32_16x16x32_bf16 v[8:11], v[176:179], v[228:231], v[8:11]
	v_mfma_f32_16x16x32_bf16 v[60:63], v[158:161], v[208:211], v[60:63]
	v_mfma_f32_16x16x32_bf16 v[56:59], v[180:183], v[208:211], v[56:59]
	v_mfma_f32_16x16x32_bf16 v[44:47], v[158:161], v[216:219], v[44:47]
	v_mfma_f32_16x16x32_bf16 v[40:43], v[180:183], v[216:219], v[40:43]
	v_mfma_f32_16x16x32_bf16 v[28:31], v[158:161], v[224:227], v[28:31]
	v_mfma_f32_16x16x32_bf16 v[24:27], v[180:183], v[224:227], v[24:27]
	v_mfma_f32_16x16x32_bf16 v[12:15], v[158:161], v[232:235], v[12:15]
	v_mfma_f32_16x16x32_bf16 v[8:11], v[180:183], v[232:235], v[8:11]
	s_setprio 0
	s_setprio 1
	v_mfma_f32_16x16x32_bf16 v[52:55], v[184:187], v[200:203], v[52:55]
	v_mfma_f32_16x16x32_bf16 v[48:51], v[192:195], v[200:203], v[48:51]
	v_mfma_f32_16x16x32_bf16 v[36:39], v[184:187], v[212:215], v[36:39]
	v_mfma_f32_16x16x32_bf16 v[32:35], v[192:195], v[212:215], v[32:35]
	v_mfma_f32_16x16x32_bf16 v[20:23], v[184:187], v[220:223], v[20:23]
	v_mfma_f32_16x16x32_bf16 v[16:19], v[192:195], v[220:223], v[16:19]
	v_mfma_f32_16x16x32_bf16 v[4:7], v[184:187], v[228:231], v[4:7]
	v_mfma_f32_16x16x32_bf16 v[0:3], v[192:195], v[228:231], v[0:3]
	v_mfma_f32_16x16x32_bf16 v[52:55], v[188:191], v[208:211], v[52:55]
	v_mfma_f32_16x16x32_bf16 v[48:51], v[196:199], v[208:211], v[48:51]
	v_mfma_f32_16x16x32_bf16 v[36:39], v[188:191], v[216:219], v[36:39]
	v_mfma_f32_16x16x32_bf16 v[32:35], v[196:199], v[216:219], v[32:35]
	v_mfma_f32_16x16x32_bf16 v[20:23], v[188:191], v[224:227], v[20:23]
	v_mfma_f32_16x16x32_bf16 v[16:19], v[196:199], v[224:227], v[16:19]
	v_mfma_f32_16x16x32_bf16 v[4:7], v[188:191], v[232:235], v[4:7]
	v_mfma_f32_16x16x32_bf16 v[0:3], v[196:199], v[232:235], v[0:3]
	s_setprio 0
	s_barrier
	s_add_i32 s65, 0, 0x18000
	v_add_u32_e32 v144, s65, v163
	s_add_i32 s66, 0, 0x1c000
	ds_read_b128 v[132:135], v144
	ds_read_b128 v[158:161], v144 offset:1024
	ds_read_b128 v[176:179], v144 offset:2048
	ds_read_b128 v[180:183], v144 offset:3072
	v_add_u32_e32 v144, s66, v163
	ds_read_b128 v[184:187], v144
	ds_read_b128 v[188:191], v144 offset:1024
	ds_read_b128 v[192:195], v144 offset:2048
	ds_read_b128 v[196:199], v144 offset:3072
	v_lshl_add_u64 v[236:237], s[42:43], 0, v[136:137]
	s_mov_b32 m0, s49
	s_nop 0
	global_load_lds_dwordx4 v[236:237], off
	v_lshl_add_u64 v[236:237], s[42:43], 0, v[140:141]
	s_mov_b32 m0, s50
	s_nop 0
	global_load_lds_dwordx4 v[236:237], off
	s_add_u32 s42, s42, 0x40000
	s_addc_u32 s43, s43, 0
	s_mov_b32 m0, s51
	v_lshl_add_u64 v[236:237], s[42:43], 0, v[136:137]
	ds_read_b128 v[200:203], v174 offset:32768
	ds_read_b128 v[208:211], v174 offset:33792
	ds_read_b128 v[212:215], v174 offset:34816
	ds_read_b128 v[216:219], v174 offset:35840
	ds_read_b128 v[220:223], v174 offset:36864
	ds_read_b128 v[224:227], v174 offset:37888
	ds_read_b128 v[228:231], v174 offset:38912
	ds_read_b128 v[232:235], v174 offset:39936
	global_load_lds_dwordx4 v[236:237], off
	v_lshl_add_u64 v[236:237], s[42:43], 0, v[140:141]
	s_mov_b32 m0, s52
	s_nop 0
	global_load_lds_dwordx4 v[236:237], off
	s_waitcnt vmcnt(8)
	s_waitcnt lgkmcnt(0)
	s_barrier
	s_setprio 1
	s_waitcnt lgkmcnt(0)
	v_mfma_f32_16x16x32_bf16 v[124:127], v[132:135], v[200:203], v[124:127]
	v_mfma_f32_16x16x32_bf16 v[120:123], v[176:179], v[200:203], v[120:123]
	v_mfma_f32_16x16x32_bf16 v[108:111], v[132:135], v[212:215], v[108:111]
	v_mfma_f32_16x16x32_bf16 v[104:107], v[176:179], v[212:215], v[104:107]
	v_mfma_f32_16x16x32_bf16 v[92:95], v[132:135], v[220:223], v[92:95]
	v_mfma_f32_16x16x32_bf16 v[88:91], v[176:179], v[220:223], v[88:91]
	v_mfma_f32_16x16x32_bf16 v[76:79], v[132:135], v[228:231], v[76:79]
	v_mfma_f32_16x16x32_bf16 v[72:75], v[176:179], v[228:231], v[72:75]
	v_mfma_f32_16x16x32_bf16 v[124:127], v[158:161], v[208:211], v[124:127]
	v_mfma_f32_16x16x32_bf16 v[120:123], v[180:183], v[208:211], v[120:123]
	v_mfma_f32_16x16x32_bf16 v[108:111], v[158:161], v[216:219], v[108:111]
	v_mfma_f32_16x16x32_bf16 v[104:107], v[180:183], v[216:219], v[104:107]
	v_mfma_f32_16x16x32_bf16 v[92:95], v[158:161], v[224:227], v[92:95]
	v_mfma_f32_16x16x32_bf16 v[88:91], v[180:183], v[224:227], v[88:91]
	v_mfma_f32_16x16x32_bf16 v[76:79], v[158:161], v[232:235], v[76:79]
	v_mfma_f32_16x16x32_bf16 v[72:75], v[180:183], v[232:235], v[72:75]
	s_setprio 0
	s_setprio 1
	v_mfma_f32_16x16x32_bf16 v[116:119], v[184:187], v[200:203], v[116:119]
	v_mfma_f32_16x16x32_bf16 v[112:115], v[192:195], v[200:203], v[112:115]
	v_mfma_f32_16x16x32_bf16 v[100:103], v[184:187], v[212:215], v[100:103]
	v_mfma_f32_16x16x32_bf16 v[96:99], v[192:195], v[212:215], v[96:99]
	v_mfma_f32_16x16x32_bf16 v[84:87], v[184:187], v[220:223], v[84:87]
	v_mfma_f32_16x16x32_bf16 v[80:83], v[192:195], v[220:223], v[80:83]
	v_mfma_f32_16x16x32_bf16 v[68:71], v[184:187], v[228:231], v[68:71]
	v_mfma_f32_16x16x32_bf16 v[64:67], v[192:195], v[228:231], v[64:67]
	v_mfma_f32_16x16x32_bf16 v[116:119], v[188:191], v[208:211], v[116:119]
	v_mfma_f32_16x16x32_bf16 v[112:115], v[196:199], v[208:211], v[112:115]
	v_mfma_f32_16x16x32_bf16 v[100:103], v[188:191], v[216:219], v[100:103]
	v_mfma_f32_16x16x32_bf16 v[96:99], v[196:199], v[216:219], v[96:99]
	v_mfma_f32_16x16x32_bf16 v[84:87], v[188:191], v[224:227], v[84:87]
	v_mfma_f32_16x16x32_bf16 v[80:83], v[196:199], v[224:227], v[80:83]
	v_mfma_f32_16x16x32_bf16 v[68:71], v[188:191], v[232:235], v[68:71]
	v_mfma_f32_16x16x32_bf16 v[64:67], v[196:199], v[232:235], v[64:67]
	s_setprio 0
	s_barrier
; #define PG8_STAGE(bufoff, gbase, voff) do { _Pragma("unroll") for (int _i = 0; _i < 2; ++_i) \
;         __builtin_amdgcn_global_load_lds((const unsigned*)((const char*)(gbase) + (voff)[_i]), (PG8_LAS unsigned*)(lds + (bufoff) + ldsw + _i * 8192), 16, 0, 0); } while (0)
; #define PG8_LDA(dst, b, h) do { _Pragma("unroll") for (int m = 0; m < 4; ++m) _Pragma("unroll") for (int k = 0; k < 2; ++k) dst[m][k] = *(const PG8_LAS bf16x8*)(lds + PG8_SA(b, h) + aoff + m * 2048 + k * 1024); } while (0)
; #define PG8_MMA(ai, bj, At, Bt) do { __builtin_amdgcn_s_setprio(1); _Pragma("unroll") for (int m = 0; m < 4; ++m) _Pragma("unroll") for (int n = 0; n < 2; ++n) _Pragma("unroll") for (int k = 0; k < 2; ++k) \
;         acc[ai][bj][m][n] = __builtin_amdgcn_mfma_f32_16x16x32_bf16(Bt[n][k], At[m][k], acc[ai][bj][m][n], 0, 0, 0); __builtin_amdgcn_s_setprio(0); } while (0)
; #define PG8_WAIT_V(n) asm volatile("s_waitcnt vmcnt(" #n ")" ::: "memory")
; #define PG8_WAIT_L(n) asm volatile("s_waitcnt lgkmcnt(" #n ")" ::: "memory")
; #define PG8_BAR __builtin_amdgcn_s_barrier()
; #define PG8_SCHED __builtin_amdgcn_sched_barrier(0)
; template <class Epi, class Sched, bool ALIGN_EPI = false, bool SP2 = false>
; __device__ __forceinline__ void gemm_phase(PG8_LAS unsigned char* lds, const Gemm g, const Sched& S, const Epi& E) {
;     ...
;             PG8_LDA(At, 1, 1); PG8_STAGE(PG8_SB(1, 0), b3, voffB); PG8_STAGE(PG8_SB(1, 1), b3 + hstepB, voffB); PG8_STAGE(PG8_SA(1, 0), a3, voffA);
;             PG8_WAIT_V(8); PG8_WAIT_L(0); PG8_BAR; PG8_MMA(1, 0, At, B0); PG8_MMA(1, 1, At, B1); PG8_BAR; PG8_SCHED;
	s_add_i32 s42, s65, s48
	v_lshl_add_u64 v[204:205], v[204:205], 0, s[14:15]
	s_mov_b32 m0, s42
	ds_read_b128 v[200:203], v174 offset:49152
	ds_read_b128 v[208:211], v174 offset:50176
	ds_read_b128 v[212:215], v174 offset:51200
	ds_read_b128 v[216:219], v174 offset:52224
	ds_read_b128 v[220:223], v174 offset:53248
	ds_read_b128 v[224:227], v174 offset:54272
	ds_read_b128 v[228:231], v174 offset:55296
	ds_read_b128 v[232:235], v174 offset:56320
	global_load_lds_dwordx4 v[204:205], off
	s_add_i32 m0, s42, 0x2000
	s_add_u32 s40, s40, 0x40080
	v_lshl_add_u64 v[204:205], v[206:207], 0, s[14:15]
	s_addc_u32 s41, s41, 0
	s_add_i32 s42, s66, s48
	global_load_lds_dwordx4 v[204:205], off
	v_lshl_add_u64 v[204:205], s[40:41], 0, v[138:139]
	s_mov_b32 m0, s42
	s_nop 0
	global_load_lds_dwordx4 v[204:205], off
	v_lshl_add_u64 v[204:205], s[40:41], 0, v[142:143]
	s_add_i32 m0, s42, 0x2000
	s_nop 0
	global_load_lds_dwordx4 v[204:205], off
	v_lshl_add_u64 v[204:205], s[38:39], 0, v[136:137]
	s_mov_b32 m0, s53
	s_nop 0
	global_load_lds_dwordx4 v[204:205], off
	v_lshl_add_u64 v[204:205], s[38:39], 0, v[140:141]
	s_mov_b32 m0, s54
	s_nop 0
	global_load_lds_dwordx4 v[204:205], off
	s_waitcnt vmcnt(8)
	s_waitcnt lgkmcnt(0)
	s_barrier
	s_setprio 1
	s_waitcnt lgkmcnt(0)
	v_mfma_f32_16x16x32_bf16 v[60:63], v[132:135], v[200:203], v[60:63]
	v_mfma_f32_16x16x32_bf16 v[56:59], v[176:179], v[200:203], v[56:59]
	v_mfma_f32_16x16x32_bf16 v[44:47], v[132:135], v[212:215], v[44:47]
	v_mfma_f32_16x16x32_bf16 v[40:43], v[176:179], v[212:215], v[40:43]
	v_mfma_f32_16x16x32_bf16 v[28:31], v[132:135], v[220:223], v[28:31]
	v_mfma_f32_16x16x32_bf16 v[24:27], v[176:179], v[220:223], v[24:27]
	v_mfma_f32_16x16x32_bf16 v[12:15], v[132:135], v[228:231], v[12:15]
	v_mfma_f32_16x16x32_bf16 v[8:11], v[176:179], v[228:231], v[8:11]
	v_mfma_f32_16x16x32_bf16 v[60:63], v[158:161], v[208:211], v[60:63]
	v_mfma_f32_16x16x32_bf16 v[56:59], v[180:183], v[208:211], v[56:59]
	v_mfma_f32_16x16x32_bf16 v[44:47], v[158:161], v[216:219], v[44:47]
	v_mfma_f32_16x16x32_bf16 v[40:43], v[180:183], v[216:219], v[40:43]
	v_mfma_f32_16x16x32_bf16 v[28:31], v[158:161], v[224:227], v[28:31]
	v_mfma_f32_16x16x32_bf16 v[24:27], v[180:183], v[224:227], v[24:27]
	v_mfma_f32_16x16x32_bf16 v[12:15], v[158:161], v[232:235], v[12:15]
	v_mfma_f32_16x16x32_bf16 v[8:11], v[180:183], v[232:235], v[8:11]
	s_setprio 0
	s_setprio 1
	v_mfma_f32_16x16x32_bf16 v[52:55], v[184:187], v[200:203], v[52:55]
	v_mfma_f32_16x16x32_bf16 v[48:51], v[192:195], v[200:203], v[48:51]
	v_mfma_f32_16x16x32_bf16 v[36:39], v[184:187], v[212:215], v[36:39]
	v_mfma_f32_16x16x32_bf16 v[32:35], v[192:195], v[212:215], v[32:35]
	v_mfma_f32_16x16x32_bf16 v[20:23], v[184:187], v[220:223], v[20:23]
	v_mfma_f32_16x16x32_bf16 v[16:19], v[192:195], v[220:223], v[16:19]
	v_mfma_f32_16x16x32_bf16 v[4:7], v[184:187], v[228:231], v[4:7]
	v_mfma_f32_16x16x32_bf16 v[0:3], v[192:195], v[228:231], v[0:3]
	v_mfma_f32_16x16x32_bf16 v[52:55], v[188:191], v[208:211], v[52:55]
	v_mfma_f32_16x16x32_bf16 v[48:51], v[196:199], v[208:211], v[48:51]
	v_mfma_f32_16x16x32_bf16 v[36:39], v[188:191], v[216:219], v[36:39]
	v_mfma_f32_16x16x32_bf16 v[32:35], v[196:199], v[216:219], v[32:35]
	v_mfma_f32_16x16x32_bf16 v[20:23], v[188:191], v[224:227], v[20:23]
	v_mfma_f32_16x16x32_bf16 v[16:19], v[196:199], v[224:227], v[16:19]
	v_mfma_f32_16x16x32_bf16 v[4:7], v[188:191], v[232:235], v[4:7]
	v_mfma_f32_16x16x32_bf16 v[0:3], v[196:199], v[232:235], v[0:3]
	s_setprio 0
	s_barrier
	s_add_i32 s64, s64, 2
	s_add_u32 s34, s34, 0x100
	s_addc_u32 s35, s35, 0
	s_cmp_gt_u32 s64, 13
	s_cbranch_scc0 .LBB0_129
	s_and_b64 vcc, exec, s[16:17]
	s_cbranch_vccz .LBB0_134
	s_barrier
	s_cmp_gt_i32 s30, 3
	s_mov_b64 s[28:29], -1
	s_cbranch_scc1 .LBB0_135

; #define PG8_STAGE(bufoff, gbase, voff) do { _Pragma("unroll") for (int _i = 0; _i < 2; ++_i) \
;         __builtin_amdgcn_global_load_lds((const unsigned*)((const char*)(gbase) + (voff)[_i]), (PG8_LAS unsigned*)(lds + (bufoff) + ldsw + _i * 8192), 16, 0, 0); } while (0)
; #define PG8_LDA(dst, b, h) do { _Pragma("unroll") for (int m = 0; m < 4; ++m) _Pragma("unroll") for (int k = 0; k < 2; ++k) dst[m][k] = *(const PG8_LAS bf16x8*)(lds + PG8_SA(b, h) + aoff + m * 2048 + k * 1024); } while (0)
; #define PG8_LDB(dst, b, h) do { _Pragma("unroll") for (int n = 0; n < 2; ++n) _Pragma("unroll") for (int k = 0; k < 2; ++k) dst[n][k] = *(const PG8_LAS bf16x8*)(lds + PG8_SB(b, h) + boff + n * 2048 + k * 1024); } while (0)
; #define PG8_MMA(ai, bj, At, Bt) do { __builtin_amdgcn_s_setprio(1); _Pragma("unroll") for (int m = 0; m < 4; ++m) _Pragma("unroll") for (int n = 0; n < 2; ++n) _Pragma("unroll") for (int k = 0; k < 2; ++k) \
;         acc[ai][bj][m][n] = __builtin_amdgcn_mfma_f32_16x16x32_bf16(Bt[n][k], At[m][k], acc[ai][bj][m][n], 0, 0, 0); __builtin_amdgcn_s_setprio(0); } while (0)
; #define PG8_WAIT_V(n) asm volatile("s_waitcnt vmcnt(" #n ")" ::: "memory")
; #define PG8_WAIT_L(n) asm volatile("s_waitcnt lgkmcnt(" #n ")" ::: "memory")
; template <class Epi, class Sched, bool ALIGN_EPI = false, bool SP2 = false>
; __device__ __forceinline__ void gemm_phase(PG8_LAS unsigned char* lds, const Gemm g, const Sched& S, const Epi& E) {
;     ...
;             const bool last = (t == nt - 2);
;             const char* a1 = cA + PG8_AK(t + 1);
;             const char* a2 = last ? nA : cA + PG8_AK(t + 2); const char* b2 = last ? nB : cB + (size_t)(t + 2) * kstep;
;             const char* a3 = last ? nA + PG8_AK(1) : cA + PG8_AK(t + 3); const char* b3 = b2 + kstep;
;             if (last && has_next) S.a_ready(nxt);
;             if constexpr (SP2) {
;             PG8_LDB(B0, 0, 0); PG8_LDB(B1, 0, 1); PG8_SCHED; PG8_LDA(At, 0, 0); PG8_STAGE(PG8_SA(1, 1), a1 + hstepA, voffA);
;             PG8_WAIT_V(8); PG8_WAIT_L(0); PG8_BAR; PG8_MMA(0, 0, At, B0); PG8_MMA(0, 1, At, B1); PG8_BAR; PG8_SCHED;
;             PG8_LDA(At, 0, 1); PG8_STAGE(PG8_SB(0, 0), b2, voffB); PG8_STAGE(PG8_SB(0, 1), b2 + hstepB, voffB); PG8_STAGE(PG8_SA(0, 0), a2, voffA);
;             PG8_WAIT_V(8); PG8_WAIT_L(0); PG8_BAR; PG8_MMA(1, 0, At, B0); PG8_MMA(1, 1, At, B1); PG8_BAR; PG8_SCHED;
.LBB0_332:
	ds_read_b128 v[180:183], v147
	ds_read_b128 v[184:187], v147 offset:1024
	ds_read_b128 v[188:191], v147 offset:2048
	ds_read_b128 v[192:195], v147 offset:3072
	ds_read_b128 v[196:199], v149
	ds_read_b128 v[200:203], v149 offset:1024
	ds_read_b128 v[208:211], v149 offset:2048
	ds_read_b128 v[212:215], v149 offset:3072
	s_add_u32 s42, s38, s40
	s_addc_u32 s43, s39, s41
	s_add_u32 s46, s42, 0x100
	s_addc_u32 s47, s43, 0
	s_add_u32 s44, s79, s40
	s_addc_u32 s45, s80, s41
	s_add_u32 s42, s42, 0x180
	s_addc_u32 s43, s43, 0
	s_cmpk_eq_i32 s40, 0x700
	s_cselect_b32 s43, s78, s43
	s_cselect_b32 s42, s69, s42
	s_cselect_b32 s45, s27, s45
	s_cselect_b32 s44, s37, s44
	s_cselect_b32 s47, s3, s47
	s_cselect_b32 s46, s29, s46
	v_lshl_add_u64 v[204:205], v[178:179], 0, s[40:41]
	s_add_i32 m0, s54, 0xc000
	ds_read_b128 v[216:219], v143
	ds_read_b128 v[220:223], v143 offset:1024
	ds_read_b128 v[224:227], v143 offset:2048
	ds_read_b128 v[228:231], v143 offset:3072
	ds_read_b128 v[232:235], v143 offset:4096
	ds_read_b128 v[236:239], v143 offset:5120
	ds_read_b128 v[240:243], v143 offset:6144
	ds_read_b128 v[244:247], v143 offset:7168
	global_load_lds_dwordx4 v[204:205], off
	v_lshl_add_u64 v[204:205], v[176:177], 0, s[40:41]
	s_add_i32 m0, s54, 0xe000
	s_nop 0
	global_load_lds_dwordx4 v[204:205], off
	s_waitcnt vmcnt(8)
	s_waitcnt lgkmcnt(0)
	s_barrier
	s_setprio 1
	s_waitcnt lgkmcnt(0)
	v_mfma_f32_16x16x32_bf16 v[124:127], v[180:183], v[216:219], v[124:127]
	v_mfma_f32_16x16x32_bf16 v[120:123], v[188:191], v[216:219], v[120:123]
	v_mfma_f32_16x16x32_bf16 v[116:119], v[180:183], v[224:227], v[116:119]
	v_mfma_f32_16x16x32_bf16 v[112:115], v[188:191], v[224:227], v[112:115]
	v_mfma_f32_16x16x32_bf16 v[108:111], v[180:183], v[232:235], v[108:111]
	v_mfma_f32_16x16x32_bf16 v[104:107], v[188:191], v[232:235], v[104:107]
	v_mfma_f32_16x16x32_bf16 v[100:103], v[180:183], v[240:243], v[100:103]
	v_mfma_f32_16x16x32_bf16 v[96:99], v[188:191], v[240:243], v[96:99]
	v_mfma_f32_16x16x32_bf16 v[124:127], v[184:187], v[220:223], v[124:127]
	v_mfma_f32_16x16x32_bf16 v[120:123], v[192:195], v[220:223], v[120:123]
	v_mfma_f32_16x16x32_bf16 v[116:119], v[184:187], v[228:231], v[116:119]
	v_mfma_f32_16x16x32_bf16 v[112:115], v[192:195], v[228:231], v[112:115]
	v_mfma_f32_16x16x32_bf16 v[108:111], v[184:187], v[236:239], v[108:111]
	v_mfma_f32_16x16x32_bf16 v[104:107], v[192:195], v[236:239], v[104:107]
	v_mfma_f32_16x16x32_bf16 v[100:103], v[184:187], v[244:247], v[100:103]
	v_mfma_f32_16x16x32_bf16 v[96:99], v[192:195], v[244:247], v[96:99]
	s_setprio 0
	s_setprio 1
	v_mfma_f32_16x16x32_bf16 v[64:67], v[196:199], v[216:219], v[64:67]
	v_mfma_f32_16x16x32_bf16 v[56:59], v[208:211], v[216:219], v[56:59]
	v_mfma_f32_16x16x32_bf16 v[52:55], v[196:199], v[224:227], v[52:55]
	v_mfma_f32_16x16x32_bf16 v[48:51], v[208:211], v[224:227], v[48:51]
	v_mfma_f32_16x16x32_bf16 v[44:47], v[196:199], v[232:235], v[44:47]
	v_mfma_f32_16x16x32_bf16 v[40:43], v[208:211], v[232:235], v[40:43]
	v_mfma_f32_16x16x32_bf16 v[36:39], v[196:199], v[240:243], v[36:39]
	v_mfma_f32_16x16x32_bf16 v[32:35], v[208:211], v[240:243], v[32:35]
	v_mfma_f32_16x16x32_bf16 v[64:67], v[200:203], v[220:223], v[64:67]
	v_mfma_f32_16x16x32_bf16 v[56:59], v[212:215], v[220:223], v[56:59]
	v_mfma_f32_16x16x32_bf16 v[52:55], v[200:203], v[228:231], v[52:55]
	v_mfma_f32_16x16x32_bf16 v[48:51], v[212:215], v[228:231], v[48:51]
	v_mfma_f32_16x16x32_bf16 v[44:47], v[200:203], v[236:239], v[44:47]
	v_mfma_f32_16x16x32_bf16 v[40:43], v[212:215], v[236:239], v[40:43]
	v_mfma_f32_16x16x32_bf16 v[36:39], v[200:203], v[244:247], v[36:39]
	v_mfma_f32_16x16x32_bf16 v[32:35], v[212:215], v[244:247], v[32:35]
	s_setprio 0
	s_barrier
	s_add_i32 s70, s66, s53
	v_lshl_add_u64 v[204:205], s[44:45], 0, v[130:131]
	s_mov_b32 m0, s70
	ds_read_b128 v[216:219], v143 offset:16384
	ds_read_b128 v[220:223], v143 offset:17408
	ds_read_b128 v[224:227], v143 offset:18432
	ds_read_b128 v[228:231], v143 offset:19456
	ds_read_b128 v[232:235], v143 offset:20480
	ds_read_b128 v[236:239], v143 offset:21504
	ds_read_b128 v[240:243], v143 offset:22528
	ds_read_b128 v[244:247], v143 offset:23552
	global_load_lds_dwordx4 v[204:205], off
	s_add_i32 m0, s70, 0x2000
	s_add_u32 s70, s44, 0x40000
	v_lshl_add_u64 v[206:207], s[44:45], 0, v[134:135]
	s_addc_u32 s71, s45, 0
	s_add_i32 s82, s67, s53
	global_load_lds_dwordx4 v[206:207], off
	v_lshl_add_u64 v[248:249], s[70:71], 0, v[130:131]
	s_mov_b32 m0, s82
	s_nop 0
	global_load_lds_dwordx4 v[248:249], off
	v_lshl_add_u64 v[248:249], s[70:71], 0, v[134:135]
	s_add_i32 m0, s82, 0x2000
	s_nop 0
	global_load_lds_dwordx4 v[248:249], off
	s_waitcnt vmcnt(6)
	s_waitcnt lgkmcnt(0)
	s_barrier
; #define PG8_STAGE(bufoff, gbase, voff) do { _Pragma("unroll") for (int _i = 0; _i < 2; ++_i) \
;         __builtin_amdgcn_global_load_lds((const unsigned*)((const char*)(gbase) + (voff)[_i]), (PG8_LAS unsigned*)(lds + (bufoff) + ldsw + _i * 8192), 16, 0, 0); } while (0)
; #define PG8_LDA(dst, b, h) do { _Pragma("unroll") for (int m = 0; m < 4; ++m) _Pragma("unroll") for (int k = 0; k < 2; ++k) dst[m][k] = *(const PG8_LAS bf16x8*)(lds + PG8_SA(b, h) + aoff + m * 2048 + k * 1024); } while (0)
; #define PG8_LDB(dst, b, h) do { _Pragma("unroll") for (int n = 0; n < 2; ++n) _Pragma("unroll") for (int k = 0; k < 2; ++k) dst[n][k] = *(const PG8_LAS bf16x8*)(lds + PG8_SB(b, h) + boff + n * 2048 + k * 1024); } while (0)
; #define PG8_MMA(ai, bj, At, Bt) do { __builtin_amdgcn_s_setprio(1); _Pragma("unroll") for (int m = 0; m < 4; ++m) _Pragma("unroll") for (int n = 0; n < 2; ++n) _Pragma("unroll") for (int k = 0; k < 2; ++k) \
;         acc[ai][bj][m][n] = __builtin_amdgcn_mfma_f32_16x16x32_bf16(Bt[n][k], At[m][k], acc[ai][bj][m][n], 0, 0, 0); __builtin_amdgcn_s_setprio(0); } while (0)
; #define PG8_WAIT_V(n) asm volatile("s_waitcnt vmcnt(" #n ")" ::: "memory")
; #define PG8_WAIT_L(n) asm volatile("s_waitcnt lgkmcnt(" #n ")" ::: "memory")
; #define PG8_BAR __builtin_amdgcn_s_barrier()
; #define PG8_SCHED __builtin_amdgcn_sched_barrier(0)
; template <class Epi, class Sched, bool ALIGN_EPI = false, bool SP2 = false>
; __device__ __forceinline__ void gemm_phase(PG8_LAS unsigned char* lds, const Gemm g, const Sched& S, const Epi& E) {
;     ...
;             PG8_WAIT_V(8); PG8_WAIT_L(0); PG8_BAR; PG8_MMA(1, 0, At, B0); PG8_MMA(1, 1, At, B1); PG8_BAR; PG8_SCHED;
;             PG8_LDB(B0, 1, 0); PG8_LDB(B1, 1, 1); PG8_SCHED; PG8_LDA(At, 1, 0); PG8_STAGE(PG8_SA(0, 1), a2 + hstepA, voffA);
;             PG8_WAIT_V(8); PG8_WAIT_L(0); PG8_BAR; PG8_MMA(0, 0, At, B0); PG8_MMA(0, 1, At, B1); PG8_BAR; PG8_SCHED;
	s_setprio 1
	s_waitcnt lgkmcnt(0)
	v_mfma_f32_16x16x32_bf16 v[92:95], v[180:183], v[216:219], v[92:95]
	v_mfma_f32_16x16x32_bf16 v[88:91], v[188:191], v[216:219], v[88:91]
	v_mfma_f32_16x16x32_bf16 v[84:87], v[180:183], v[224:227], v[84:87]
	v_mfma_f32_16x16x32_bf16 v[80:83], v[188:191], v[224:227], v[80:83]
	v_mfma_f32_16x16x32_bf16 v[76:79], v[180:183], v[232:235], v[76:79]
	v_mfma_f32_16x16x32_bf16 v[72:75], v[188:191], v[232:235], v[72:75]
	v_mfma_f32_16x16x32_bf16 v[68:71], v[180:183], v[240:243], v[68:71]
	v_mfma_f32_16x16x32_bf16 v[60:63], v[188:191], v[240:243], v[60:63]
	v_mfma_f32_16x16x32_bf16 v[92:95], v[184:187], v[220:223], v[92:95]
	v_mfma_f32_16x16x32_bf16 v[88:91], v[192:195], v[220:223], v[88:91]
	v_mfma_f32_16x16x32_bf16 v[84:87], v[184:187], v[228:231], v[84:87]
	v_mfma_f32_16x16x32_bf16 v[80:83], v[192:195], v[228:231], v[80:83]
	v_mfma_f32_16x16x32_bf16 v[76:79], v[184:187], v[236:239], v[76:79]
	v_mfma_f32_16x16x32_bf16 v[72:75], v[192:195], v[236:239], v[72:75]
	v_mfma_f32_16x16x32_bf16 v[68:71], v[184:187], v[244:247], v[68:71]
	v_mfma_f32_16x16x32_bf16 v[60:63], v[192:195], v[244:247], v[60:63]
	s_setprio 0
	s_setprio 1
	v_mfma_f32_16x16x32_bf16 v[28:31], v[196:199], v[216:219], v[28:31]
	v_mfma_f32_16x16x32_bf16 v[24:27], v[208:211], v[216:219], v[24:27]
	v_mfma_f32_16x16x32_bf16 v[20:23], v[196:199], v[224:227], v[20:23]
	v_mfma_f32_16x16x32_bf16 v[16:19], v[208:211], v[224:227], v[16:19]
	v_mfma_f32_16x16x32_bf16 v[12:15], v[196:199], v[232:235], v[12:15]
	v_mfma_f32_16x16x32_bf16 v[8:11], v[208:211], v[232:235], v[8:11]
	v_mfma_f32_16x16x32_bf16 v[4:7], v[196:199], v[240:243], v[4:7]
	v_mfma_f32_16x16x32_bf16 v[0:3], v[208:211], v[240:243], v[0:3]
	v_mfma_f32_16x16x32_bf16 v[28:31], v[200:203], v[220:223], v[28:31]
	v_mfma_f32_16x16x32_bf16 v[24:27], v[212:215], v[220:223], v[24:27]
	v_mfma_f32_16x16x32_bf16 v[20:23], v[200:203], v[228:231], v[20:23]
	v_mfma_f32_16x16x32_bf16 v[16:19], v[212:215], v[228:231], v[16:19]
	v_mfma_f32_16x16x32_bf16 v[12:15], v[200:203], v[236:239], v[12:15]
	v_mfma_f32_16x16x32_bf16 v[8:11], v[212:215], v[236:239], v[8:11]
	v_mfma_f32_16x16x32_bf16 v[4:7], v[200:203], v[244:247], v[4:7]
	v_mfma_f32_16x16x32_bf16 v[0:3], v[212:215], v[244:247], v[0:3]
	s_setprio 0
	s_barrier
	s_add_i32 s70, 0, 0x18000
	v_add_u32_e32 v137, s70, v141
	s_add_i32 s71, 0, 0x1c000
	ds_read_b128 v[180:183], v137
	ds_read_b128 v[184:187], v137 offset:1024
	ds_read_b128 v[188:191], v137 offset:2048
	ds_read_b128 v[192:195], v137 offset:3072
	v_add_u32_e32 v137, s71, v141
	ds_read_b128 v[196:199], v137
	ds_read_b128 v[200:203], v137 offset:1024
	ds_read_b128 v[208:211], v137 offset:2048
	ds_read_b128 v[212:215], v137 offset:3072
	v_lshl_add_u64 v[248:249], s[46:47], 0, v[128:129]
	s_mov_b32 m0, s54
	s_nop 0
	global_load_lds_dwordx4 v[248:249], off
	v_lshl_add_u64 v[248:249], s[46:47], 0, v[132:133]
	s_mov_b32 m0, s55
	s_nop 0
	global_load_lds_dwordx4 v[248:249], off
	s_add_u32 s46, s46, 0x40000
	s_addc_u32 s47, s47, 0
	s_mov_b32 m0, s56
	v_lshl_add_u64 v[248:249], s[46:47], 0, v[128:129]
	ds_read_b128 v[216:219], v143 offset:32768
	ds_read_b128 v[220:223], v143 offset:33792
	ds_read_b128 v[224:227], v143 offset:34816
	ds_read_b128 v[228:231], v143 offset:35840
	ds_read_b128 v[232:235], v143 offset:36864
	ds_read_b128 v[236:239], v143 offset:37888
	ds_read_b128 v[240:243], v143 offset:38912
	ds_read_b128 v[244:247], v143 offset:39936
	global_load_lds_dwordx4 v[248:249], off
	v_lshl_add_u64 v[248:249], s[46:47], 0, v[132:133]
	s_mov_b32 m0, s57
	s_nop 0
	global_load_lds_dwordx4 v[248:249], off
	s_waitcnt vmcnt(8)
	s_waitcnt lgkmcnt(0)
	s_barrier
	s_setprio 1
	s_waitcnt lgkmcnt(0)
	v_mfma_f32_16x16x32_bf16 v[124:127], v[180:183], v[216:219], v[124:127]
	v_mfma_f32_16x16x32_bf16 v[120:123], v[188:191], v[216:219], v[120:123]
	v_mfma_f32_16x16x32_bf16 v[116:119], v[180:183], v[224:227], v[116:119]
	v_mfma_f32_16x16x32_bf16 v[112:115], v[188:191], v[224:227], v[112:115]
	v_mfma_f32_16x16x32_bf16 v[108:111], v[180:183], v[232:235], v[108:111]
	v_mfma_f32_16x16x32_bf16 v[104:107], v[188:191], v[232:235], v[104:107]
	v_mfma_f32_16x16x32_bf16 v[100:103], v[180:183], v[240:243], v[100:103]
	v_mfma_f32_16x16x32_bf16 v[96:99], v[188:191], v[240:243], v[96:99]
	v_mfma_f32_16x16x32_bf16 v[124:127], v[184:187], v[220:223], v[124:127]
	v_mfma_f32_16x16x32_bf16 v[120:123], v[192:195], v[220:223], v[120:123]
	v_mfma_f32_16x16x32_bf16 v[116:119], v[184:187], v[228:231], v[116:119]
	v_mfma_f32_16x16x32_bf16 v[112:115], v[192:195], v[228:231], v[112:115]
	v_mfma_f32_16x16x32_bf16 v[108:111], v[184:187], v[236:239], v[108:111]
	v_mfma_f32_16x16x32_bf16 v[104:107], v[192:195], v[236:239], v[104:107]
	v_mfma_f32_16x16x32_bf16 v[100:103], v[184:187], v[244:247], v[100:103]
	v_mfma_f32_16x16x32_bf16 v[96:99], v[192:195], v[244:247], v[96:99]
	s_setprio 0
	s_setprio 1
	v_mfma_f32_16x16x32_bf16 v[64:67], v[196:199], v[216:219], v[64:67]
	v_mfma_f32_16x16x32_bf16 v[56:59], v[208:211], v[216:219], v[56:59]
	v_mfma_f32_16x16x32_bf16 v[52:55], v[196:199], v[224:227], v[52:55]
	v_mfma_f32_16x16x32_bf16 v[48:51], v[208:211], v[224:227], v[48:51]
	v_mfma_f32_16x16x32_bf16 v[44:47], v[196:199], v[232:235], v[44:47]
	v_mfma_f32_16x16x32_bf16 v[40:43], v[208:211], v[232:235], v[40:43]
	v_mfma_f32_16x16x32_bf16 v[36:39], v[196:199], v[240:243], v[36:39]
	v_mfma_f32_16x16x32_bf16 v[32:35], v[208:211], v[240:243], v[32:35]
	v_mfma_f32_16x16x32_bf16 v[64:67], v[200:203], v[220:223], v[64:67]
	v_mfma_f32_16x16x32_bf16 v[56:59], v[212:215], v[220:223], v[56:59]
	v_mfma_f32_16x16x32_bf16 v[52:55], v[200:203], v[228:231], v[52:55]
	v_mfma_f32_16x16x32_bf16 v[48:51], v[212:215], v[228:231], v[48:51]
	v_mfma_f32_16x16x32_bf16 v[44:47], v[200:203], v[236:239], v[44:47]
	v_mfma_f32_16x16x32_bf16 v[40:43], v[212:215], v[236:239], v[40:43]
	v_mfma_f32_16x16x32_bf16 v[36:39], v[200:203], v[244:247], v[36:39]
	v_mfma_f32_16x16x32_bf16 v[32:35], v[212:215], v[244:247], v[32:35]
	s_setprio 0
	s_barrier
; #define PG8_STAGE(bufoff, gbase, voff) do { _Pragma("unroll") for (int _i = 0; _i < 2; ++_i) \
;         __builtin_amdgcn_global_load_lds((const unsigned*)((const char*)(gbase) + (voff)[_i]), (PG8_LAS unsigned*)(lds + (bufoff) + ldsw + _i * 8192), 16, 0, 0); } while (0)
; #define PG8_LDA(dst, b, h) do { _Pragma("unroll") for (int m = 0; m < 4; ++m) _Pragma("unroll") for (int k = 0; k < 2; ++k) dst[m][k] = *(const PG8_LAS bf16x8*)(lds + PG8_SA(b, h) + aoff + m * 2048 + k * 1024); } while (0)
; #define PG8_MMA(ai, bj, At, Bt) do { __builtin_amdgcn_s_setprio(1); _Pragma("unroll") for (int m = 0; m < 4; ++m) _Pragma("unroll") for (int n = 0; n < 2; ++n) _Pragma("unroll") for (int k = 0; k < 2; ++k) \
;         acc[ai][bj][m][n] = __builtin_amdgcn_mfma_f32_16x16x32_bf16(Bt[n][k], At[m][k], acc[ai][bj][m][n], 0, 0, 0); __builtin_amdgcn_s_setprio(0); } while (0)
; #define PG8_WAIT_V(n) asm volatile("s_waitcnt vmcnt(" #n ")" ::: "memory")
; #define PG8_WAIT_L(n) asm volatile("s_waitcnt lgkmcnt(" #n ")" ::: "memory")
; #define PG8_BAR __builtin_amdgcn_s_barrier()
; #define PG8_SCHED __builtin_amdgcn_sched_barrier(0)
; template <class Epi, class Sched, bool ALIGN_EPI = false, bool SP2 = false>
; __device__ __forceinline__ void gemm_phase(PG8_LAS unsigned char* lds, const Gemm g, const Sched& S, const Epi& E) {
;     ...
;             PG8_LDA(At, 1, 1); PG8_STAGE(PG8_SB(1, 0), b3, voffB); PG8_STAGE(PG8_SB(1, 1), b3 + hstepB, voffB); PG8_STAGE(PG8_SA(1, 0), a3, voffA);
;             PG8_WAIT_V(8); PG8_WAIT_L(0); PG8_BAR; PG8_MMA(1, 0, At, B0); PG8_MMA(1, 1, At, B1); PG8_BAR; PG8_SCHED;
	s_add_i32 s46, s70, s53
	v_lshl_add_u64 v[204:205], v[204:205], 0, s[20:21]
	s_mov_b32 m0, s46
	ds_read_b128 v[216:219], v143 offset:49152
	ds_read_b128 v[220:223], v143 offset:50176
	ds_read_b128 v[224:227], v143 offset:51200
	ds_read_b128 v[228:231], v143 offset:52224
	ds_read_b128 v[232:235], v143 offset:53248
	ds_read_b128 v[236:239], v143 offset:54272
	ds_read_b128 v[240:243], v143 offset:55296
	ds_read_b128 v[244:247], v143 offset:56320
	global_load_lds_dwordx4 v[204:205], off
	s_add_i32 m0, s46, 0x2000
	s_add_u32 s44, s44, 0x40080
	v_lshl_add_u64 v[204:205], v[206:207], 0, s[20:21]
	s_addc_u32 s45, s45, 0
	s_add_i32 s46, s71, s53
	global_load_lds_dwordx4 v[204:205], off
	v_lshl_add_u64 v[204:205], s[44:45], 0, v[130:131]
	s_mov_b32 m0, s46
	s_nop 0
	global_load_lds_dwordx4 v[204:205], off
	v_lshl_add_u64 v[204:205], s[44:45], 0, v[134:135]
	s_add_i32 m0, s46, 0x2000
	s_nop 0
	global_load_lds_dwordx4 v[204:205], off
	v_lshl_add_u64 v[204:205], s[42:43], 0, v[128:129]
	s_mov_b32 m0, s62
	s_nop 0
	global_load_lds_dwordx4 v[204:205], off
	v_lshl_add_u64 v[204:205], s[42:43], 0, v[132:133]
	s_mov_b32 m0, s63
	s_nop 0
	global_load_lds_dwordx4 v[204:205], off
	s_waitcnt vmcnt(8)
	s_waitcnt lgkmcnt(0)
	s_barrier
	s_setprio 1
	s_waitcnt lgkmcnt(0)
	v_mfma_f32_16x16x32_bf16 v[92:95], v[180:183], v[216:219], v[92:95]
	v_mfma_f32_16x16x32_bf16 v[88:91], v[188:191], v[216:219], v[88:91]
	v_mfma_f32_16x16x32_bf16 v[84:87], v[180:183], v[224:227], v[84:87]
	v_mfma_f32_16x16x32_bf16 v[80:83], v[188:191], v[224:227], v[80:83]
	v_mfma_f32_16x16x32_bf16 v[76:79], v[180:183], v[232:235], v[76:79]
	v_mfma_f32_16x16x32_bf16 v[72:75], v[188:191], v[232:235], v[72:75]
	v_mfma_f32_16x16x32_bf16 v[68:71], v[180:183], v[240:243], v[68:71]
	v_mfma_f32_16x16x32_bf16 v[60:63], v[188:191], v[240:243], v[60:63]
	v_mfma_f32_16x16x32_bf16 v[92:95], v[184:187], v[220:223], v[92:95]
	v_mfma_f32_16x16x32_bf16 v[88:91], v[192:195], v[220:223], v[88:91]
	v_mfma_f32_16x16x32_bf16 v[84:87], v[184:187], v[228:231], v[84:87]
	v_mfma_f32_16x16x32_bf16 v[80:83], v[192:195], v[228:231], v[80:83]
	v_mfma_f32_16x16x32_bf16 v[76:79], v[184:187], v[236:239], v[76:79]
	v_mfma_f32_16x16x32_bf16 v[72:75], v[192:195], v[236:239], v[72:75]
	v_mfma_f32_16x16x32_bf16 v[68:71], v[184:187], v[244:247], v[68:71]
	v_mfma_f32_16x16x32_bf16 v[60:63], v[192:195], v[244:247], v[60:63]
	s_setprio 0
	s_setprio 1
	v_mfma_f32_16x16x32_bf16 v[28:31], v[196:199], v[216:219], v[28:31]
	v_mfma_f32_16x16x32_bf16 v[24:27], v[208:211], v[216:219], v[24:27]
	v_mfma_f32_16x16x32_bf16 v[20:23], v[196:199], v[224:227], v[20:23]
	v_mfma_f32_16x16x32_bf16 v[16:19], v[208:211], v[224:227], v[16:19]
	v_mfma_f32_16x16x32_bf16 v[12:15], v[196:199], v[232:235], v[12:15]
	v_mfma_f32_16x16x32_bf16 v[8:11], v[208:211], v[232:235], v[8:11]
	v_mfma_f32_16x16x32_bf16 v[4:7], v[196:199], v[240:243], v[4:7]
	v_mfma_f32_16x16x32_bf16 v[0:3], v[208:211], v[240:243], v[0:3]
	v_mfma_f32_16x16x32_bf16 v[28:31], v[200:203], v[220:223], v[28:31]
	v_mfma_f32_16x16x32_bf16 v[24:27], v[212:215], v[220:223], v[24:27]
	v_mfma_f32_16x16x32_bf16 v[20:23], v[200:203], v[228:231], v[20:23]
	v_mfma_f32_16x16x32_bf16 v[16:19], v[212:215], v[228:231], v[16:19]
	v_mfma_f32_16x16x32_bf16 v[12:15], v[200:203], v[236:239], v[12:15]
	v_mfma_f32_16x16x32_bf16 v[8:11], v[212:215], v[236:239], v[8:11]
	v_mfma_f32_16x16x32_bf16 v[4:7], v[200:203], v[244:247], v[4:7]
	v_mfma_f32_16x16x32_bf16 v[0:3], v[212:215], v[244:247], v[0:3]
	s_setprio 0
	s_barrier
	s_add_i32 s81, s81, 2
	s_add_u32 s40, s40, 0x100
	s_addc_u32 s41, s41, 0
	s_cmp_gt_u32 s81, 13
	s_cbranch_scc0 .LBB0_332
	s_and_b64 vcc, exec, s[22:23]
	s_cbranch_vccz .LBB0_335
	s_barrier

; #define PG8_STAGE(bufoff, gbase, voff) do { _Pragma("unroll") for (int _i = 0; _i < 2; ++_i) \
;         __builtin_amdgcn_global_load_lds((const unsigned*)((const char*)(gbase) + (voff)[_i]), (PG8_LAS unsigned*)(lds + (bufoff) + ldsw + _i * 8192), 16, 0, 0); } while (0)
; #define PG8_LDA(dst, b, h) do { _Pragma("unroll") for (int m = 0; m < 4; ++m) _Pragma("unroll") for (int k = 0; k < 2; ++k) dst[m][k] = *(const PG8_LAS bf16x8*)(lds + PG8_SA(b, h) + aoff + m * 2048 + k * 1024); } while (0)
; #define PG8_LDB(dst, b, h) do { _Pragma("unroll") for (int n = 0; n < 2; ++n) _Pragma("unroll") for (int k = 0; k < 2; ++k) dst[n][k] = *(const PG8_LAS bf16x8*)(lds + PG8_SB(b, h) + boff + n * 2048 + k * 1024); } while (0)
; #define PG8_MMA(ai, bj, At, Bt) do { __builtin_amdgcn_s_setprio(1); _Pragma("unroll") for (int m = 0; m < 4; ++m) _Pragma("unroll") for (int n = 0; n < 2; ++n) _Pragma("unroll") for (int k = 0; k < 2; ++k) \
;         acc[ai][bj][m][n] = __builtin_amdgcn_mfma_f32_16x16x32_bf16(Bt[n][k], At[m][k], acc[ai][bj][m][n], 0, 0, 0); __builtin_amdgcn_s_setprio(0); } while (0)
; #define PG8_WAIT_V(n) asm volatile("s_waitcnt vmcnt(" #n ")" ::: "memory")
; #define PG8_WAIT_L(n) asm volatile("s_waitcnt lgkmcnt(" #n ")" ::: "memory")
; template <class Epi, class Sched, bool ALIGN_EPI = false, bool SP2 = false>
; __device__ __forceinline__ void gemm_phase(PG8_LAS unsigned char* lds, const Gemm g, const Sched& S, const Epi& E) {
;     ...
;             const bool last = (t == nt - 2);
;             const char* a1 = cA + PG8_AK(t + 1);
;             const char* a2 = last ? nA : cA + PG8_AK(t + 2); const char* b2 = last ? nB : cB + (size_t)(t + 2) * kstep;
;             const char* a3 = last ? nA + PG8_AK(1) : cA + PG8_AK(t + 3); const char* b3 = b2 + kstep;
;             if (last && has_next) S.a_ready(nxt);
;             if constexpr (SP2) {
;             PG8_LDB(B0, 0, 0); PG8_LDB(B1, 0, 1); PG8_SCHED; PG8_LDA(At, 0, 0); PG8_STAGE(PG8_SA(1, 1), a1 + hstepA, voffA);
;             PG8_WAIT_V(8); PG8_WAIT_L(0); PG8_BAR; PG8_MMA(0, 0, At, B0); PG8_MMA(0, 1, At, B1); PG8_BAR; PG8_SCHED;
;             PG8_LDA(At, 0, 1); PG8_STAGE(PG8_SB(0, 0), b2, voffB); PG8_STAGE(PG8_SB(0, 1), b2 + hstepB, voffB); PG8_STAGE(PG8_SA(0, 0), a2, voffA);
;             PG8_WAIT_V(8); PG8_WAIT_L(0); PG8_BAR; PG8_MMA(1, 0, At, B0); PG8_MMA(1, 1, At, B1); PG8_BAR; PG8_SCHED;
.LBB0_416:
	ds_read_b128 v[132:135], v171
	ds_read_b128 v[136:139], v171 offset:1024
	ds_read_b128 v[140:143], v171 offset:2048
	ds_read_b128 v[178:181], v171 offset:3072
	ds_read_b128 v[182:185], v173
	ds_read_b128 v[186:189], v173 offset:1024
	ds_read_b128 v[190:193], v173 offset:2048
	ds_read_b128 v[194:197], v173 offset:3072
	s_add_u32 s38, s34, s36
	s_addc_u32 s39, s35, s37
	s_add_u32 s42, s38, 0x100
	s_addc_u32 s43, s39, 0
	s_add_u32 s40, s66, s36
	s_addc_u32 s41, s67, s37
	s_add_u32 s38, s38, 0x180
	s_addc_u32 s39, s39, 0
	s_cmpk_eq_i32 s36, 0x700
	s_cselect_b32 s39, s65, s39
	s_cselect_b32 s38, s64, s38
	s_cselect_b32 s41, s23, s41
	s_cselect_b32 s40, s63, s40
	s_cselect_b32 s43, s3, s43
	s_cselect_b32 s42, s25, s42
	v_lshl_add_u64 v[206:207], v[130:131], 0, s[36:37]
	s_add_i32 m0, s31, 0xc000
	ds_read_b128 v[198:201], v175
	ds_read_b128 v[202:205], v175 offset:1024
	ds_read_b128 v[208:211], v175 offset:2048
	ds_read_b128 v[212:215], v175 offset:3072
	ds_read_b128 v[216:219], v175 offset:4096
	ds_read_b128 v[220:223], v175 offset:5120
	ds_read_b128 v[224:227], v175 offset:6144
	ds_read_b128 v[228:231], v175 offset:7168
	global_load_lds_dwordx4 v[206:207], off
	v_lshl_add_u64 v[206:207], v[128:129], 0, s[36:37]
	s_add_i32 m0, s31, 0xe000
	s_nop 0
	global_load_lds_dwordx4 v[206:207], off
	s_waitcnt vmcnt(8)
	s_waitcnt lgkmcnt(0)
	s_barrier
	s_setprio 1
	s_waitcnt lgkmcnt(0)
	v_mfma_f32_16x16x32_bf16 v[124:127], v[132:135], v[198:201], v[124:127]
	v_mfma_f32_16x16x32_bf16 v[120:123], v[140:143], v[198:201], v[120:123]
	v_mfma_f32_16x16x32_bf16 v[116:119], v[132:135], v[208:211], v[116:119]
	v_mfma_f32_16x16x32_bf16 v[112:115], v[140:143], v[208:211], v[112:115]
	v_mfma_f32_16x16x32_bf16 v[108:111], v[132:135], v[216:219], v[108:111]
	v_mfma_f32_16x16x32_bf16 v[104:107], v[140:143], v[216:219], v[104:107]
	v_mfma_f32_16x16x32_bf16 v[100:103], v[132:135], v[224:227], v[100:103]
	v_mfma_f32_16x16x32_bf16 v[96:99], v[140:143], v[224:227], v[96:99]
	v_mfma_f32_16x16x32_bf16 v[124:127], v[136:139], v[202:205], v[124:127]
	v_mfma_f32_16x16x32_bf16 v[120:123], v[178:181], v[202:205], v[120:123]
	v_mfma_f32_16x16x32_bf16 v[116:119], v[136:139], v[212:215], v[116:119]
	v_mfma_f32_16x16x32_bf16 v[112:115], v[178:181], v[212:215], v[112:115]
	v_mfma_f32_16x16x32_bf16 v[108:111], v[136:139], v[220:223], v[108:111]
	v_mfma_f32_16x16x32_bf16 v[104:107], v[178:181], v[220:223], v[104:107]
	v_mfma_f32_16x16x32_bf16 v[100:103], v[136:139], v[228:231], v[100:103]
	v_mfma_f32_16x16x32_bf16 v[96:99], v[178:181], v[228:231], v[96:99]
	s_setprio 0
	s_setprio 1
	v_mfma_f32_16x16x32_bf16 v[64:67], v[182:185], v[198:201], v[64:67]
	v_mfma_f32_16x16x32_bf16 v[56:59], v[190:193], v[198:201], v[56:59]
	v_mfma_f32_16x16x32_bf16 v[52:55], v[182:185], v[208:211], v[52:55]
	v_mfma_f32_16x16x32_bf16 v[48:51], v[190:193], v[208:211], v[48:51]
	v_mfma_f32_16x16x32_bf16 v[44:47], v[182:185], v[216:219], v[44:47]
	v_mfma_f32_16x16x32_bf16 v[40:43], v[190:193], v[216:219], v[40:43]
	v_mfma_f32_16x16x32_bf16 v[36:39], v[182:185], v[224:227], v[36:39]
	v_mfma_f32_16x16x32_bf16 v[32:35], v[190:193], v[224:227], v[32:35]
	v_mfma_f32_16x16x32_bf16 v[64:67], v[186:189], v[202:205], v[64:67]
	v_mfma_f32_16x16x32_bf16 v[56:59], v[194:197], v[202:205], v[56:59]
	v_mfma_f32_16x16x32_bf16 v[52:55], v[186:189], v[212:215], v[52:55]
	v_mfma_f32_16x16x32_bf16 v[48:51], v[194:197], v[212:215], v[48:51]
	v_mfma_f32_16x16x32_bf16 v[44:47], v[186:189], v[220:223], v[44:47]
	v_mfma_f32_16x16x32_bf16 v[40:43], v[194:197], v[220:223], v[40:43]
	v_mfma_f32_16x16x32_bf16 v[36:39], v[186:189], v[228:231], v[36:39]
	v_mfma_f32_16x16x32_bf16 v[32:35], v[194:197], v[228:231], v[32:35]
	s_setprio 0
	s_barrier
	s_add_i32 s69, s59, s49
	v_lshl_add_u64 v[206:207], s[40:41], 0, v[148:149]
	s_mov_b32 m0, s69
	ds_read_b128 v[198:201], v175 offset:16384
	ds_read_b128 v[202:205], v175 offset:17408
	ds_read_b128 v[208:211], v175 offset:18432
	ds_read_b128 v[212:215], v175 offset:19456
	ds_read_b128 v[216:219], v175 offset:20480
	ds_read_b128 v[220:223], v175 offset:21504
	ds_read_b128 v[224:227], v175 offset:22528
	ds_read_b128 v[228:231], v175 offset:23552
	global_load_lds_dwordx4 v[206:207], off
	s_add_i32 m0, s69, 0x2000
	s_add_u32 s70, s40, 0x40000
	v_lshl_add_u64 v[232:233], s[40:41], 0, v[144:145]
	s_addc_u32 s71, s41, 0
	s_add_i32 s69, s60, s49
	global_load_lds_dwordx4 v[232:233], off
	v_lshl_add_u64 v[234:235], s[70:71], 0, v[148:149]
	s_mov_b32 m0, s69
	s_nop 0
	global_load_lds_dwordx4 v[234:235], off
	v_lshl_add_u64 v[234:235], s[70:71], 0, v[144:145]
	s_add_i32 m0, s69, 0x2000
	s_nop 0
	global_load_lds_dwordx4 v[234:235], off
	s_waitcnt vmcnt(6)
	s_waitcnt lgkmcnt(0)
	s_barrier
; #define PG8_STAGE(bufoff, gbase, voff) do { _Pragma("unroll") for (int _i = 0; _i < 2; ++_i) \
;         __builtin_amdgcn_global_load_lds((const unsigned*)((const char*)(gbase) + (voff)[_i]), (PG8_LAS unsigned*)(lds + (bufoff) + ldsw + _i * 8192), 16, 0, 0); } while (0)
; #define PG8_LDA(dst, b, h) do { _Pragma("unroll") for (int m = 0; m < 4; ++m) _Pragma("unroll") for (int k = 0; k < 2; ++k) dst[m][k] = *(const PG8_LAS bf16x8*)(lds + PG8_SA(b, h) + aoff + m * 2048 + k * 1024); } while (0)
; #define PG8_LDB(dst, b, h) do { _Pragma("unroll") for (int n = 0; n < 2; ++n) _Pragma("unroll") for (int k = 0; k < 2; ++k) dst[n][k] = *(const PG8_LAS bf16x8*)(lds + PG8_SB(b, h) + boff + n * 2048 + k * 1024); } while (0)
; #define PG8_MMA(ai, bj, At, Bt) do { __builtin_amdgcn_s_setprio(1); _Pragma("unroll") for (int m = 0; m < 4; ++m) _Pragma("unroll") for (int n = 0; n < 2; ++n) _Pragma("unroll") for (int k = 0; k < 2; ++k) \
;         acc[ai][bj][m][n] = __builtin_amdgcn_mfma_f32_16x16x32_bf16(Bt[n][k], At[m][k], acc[ai][bj][m][n], 0, 0, 0); __builtin_amdgcn_s_setprio(0); } while (0)
; #define PG8_WAIT_V(n) asm volatile("s_waitcnt vmcnt(" #n ")" ::: "memory")
; #define PG8_WAIT_L(n) asm volatile("s_waitcnt lgkmcnt(" #n ")" ::: "memory")
; #define PG8_BAR __builtin_amdgcn_s_barrier()
; #define PG8_SCHED __builtin_amdgcn_sched_barrier(0)
; template <class Epi, class Sched, bool ALIGN_EPI = false, bool SP2 = false>
; __device__ __forceinline__ void gemm_phase(PG8_LAS unsigned char* lds, const Gemm g, const Sched& S, const Epi& E) {
;     ...
;             PG8_WAIT_V(8); PG8_WAIT_L(0); PG8_BAR; PG8_MMA(1, 0, At, B0); PG8_MMA(1, 1, At, B1); PG8_BAR; PG8_SCHED;
;             PG8_LDB(B0, 1, 0); PG8_LDB(B1, 1, 1); PG8_SCHED; PG8_LDA(At, 1, 0); PG8_STAGE(PG8_SA(0, 1), a2 + hstepA, voffA);
;             PG8_WAIT_V(8); PG8_WAIT_L(0); PG8_BAR; PG8_MMA(0, 0, At, B0); PG8_MMA(0, 1, At, B1); PG8_BAR; PG8_SCHED;
	s_setprio 1
	s_waitcnt lgkmcnt(0)
	v_mfma_f32_16x16x32_bf16 v[92:95], v[132:135], v[198:201], v[92:95]
	v_mfma_f32_16x16x32_bf16 v[88:91], v[140:143], v[198:201], v[88:91]
	v_mfma_f32_16x16x32_bf16 v[84:87], v[132:135], v[208:211], v[84:87]
	v_mfma_f32_16x16x32_bf16 v[80:83], v[140:143], v[208:211], v[80:83]
	v_mfma_f32_16x16x32_bf16 v[76:79], v[132:135], v[216:219], v[76:79]
	v_mfma_f32_16x16x32_bf16 v[72:75], v[140:143], v[216:219], v[72:75]
	v_mfma_f32_16x16x32_bf16 v[68:71], v[132:135], v[224:227], v[68:71]
	v_mfma_f32_16x16x32_bf16 v[60:63], v[140:143], v[224:227], v[60:63]
	v_mfma_f32_16x16x32_bf16 v[92:95], v[136:139], v[202:205], v[92:95]
	v_mfma_f32_16x16x32_bf16 v[88:91], v[178:181], v[202:205], v[88:91]
	v_mfma_f32_16x16x32_bf16 v[84:87], v[136:139], v[212:215], v[84:87]
	v_mfma_f32_16x16x32_bf16 v[80:83], v[178:181], v[212:215], v[80:83]
	v_mfma_f32_16x16x32_bf16 v[76:79], v[136:139], v[220:223], v[76:79]
	v_mfma_f32_16x16x32_bf16 v[72:75], v[178:181], v[220:223], v[72:75]
	v_mfma_f32_16x16x32_bf16 v[68:71], v[136:139], v[228:231], v[68:71]
	v_mfma_f32_16x16x32_bf16 v[60:63], v[178:181], v[228:231], v[60:63]
	s_setprio 0
	s_setprio 1
	v_mfma_f32_16x16x32_bf16 v[28:31], v[182:185], v[198:201], v[28:31]
	v_mfma_f32_16x16x32_bf16 v[24:27], v[190:193], v[198:201], v[24:27]
	v_mfma_f32_16x16x32_bf16 v[20:23], v[182:185], v[208:211], v[20:23]
	v_mfma_f32_16x16x32_bf16 v[16:19], v[190:193], v[208:211], v[16:19]
	v_mfma_f32_16x16x32_bf16 v[12:15], v[182:185], v[216:219], v[12:15]
	v_mfma_f32_16x16x32_bf16 v[8:11], v[190:193], v[216:219], v[8:11]
	v_mfma_f32_16x16x32_bf16 v[4:7], v[182:185], v[224:227], v[4:7]
	v_mfma_f32_16x16x32_bf16 v[0:3], v[190:193], v[224:227], v[0:3]
	v_mfma_f32_16x16x32_bf16 v[28:31], v[186:189], v[202:205], v[28:31]
	v_mfma_f32_16x16x32_bf16 v[24:27], v[194:197], v[202:205], v[24:27]
	v_mfma_f32_16x16x32_bf16 v[20:23], v[186:189], v[212:215], v[20:23]
	v_mfma_f32_16x16x32_bf16 v[16:19], v[194:197], v[212:215], v[16:19]
	v_mfma_f32_16x16x32_bf16 v[12:15], v[186:189], v[220:223], v[12:15]
	v_mfma_f32_16x16x32_bf16 v[8:11], v[194:197], v[220:223], v[8:11]
	v_mfma_f32_16x16x32_bf16 v[4:7], v[186:189], v[228:231], v[4:7]
	v_mfma_f32_16x16x32_bf16 v[0:3], v[194:197], v[228:231], v[0:3]
	s_setprio 0
	s_barrier
	s_add_i32 s69, 0, 0x18000
	v_add_u32_e32 v160, s69, v163
	s_add_i32 s70, 0, 0x1c000
	ds_read_b128 v[132:135], v160
	ds_read_b128 v[136:139], v160 offset:1024
	ds_read_b128 v[140:143], v160 offset:2048
	ds_read_b128 v[178:181], v160 offset:3072
	v_add_u32_e32 v160, s70, v163
	ds_read_b128 v[182:185], v160
	ds_read_b128 v[186:189], v160 offset:1024
	ds_read_b128 v[190:193], v160 offset:2048
	ds_read_b128 v[194:197], v160 offset:3072
	v_lshl_add_u64 v[234:235], s[42:43], 0, v[150:151]
	s_mov_b32 m0, s31
	s_nop 0
	global_load_lds_dwordx4 v[234:235], off
	v_lshl_add_u64 v[234:235], s[42:43], 0, v[146:147]
	s_mov_b32 m0, s52
	s_nop 0
	global_load_lds_dwordx4 v[234:235], off
	s_add_u32 s42, s42, 0x40000
	s_addc_u32 s43, s43, 0
	s_mov_b32 m0, s53
	v_lshl_add_u64 v[234:235], s[42:43], 0, v[150:151]
	ds_read_b128 v[198:201], v175 offset:32768
	ds_read_b128 v[202:205], v175 offset:33792
	ds_read_b128 v[208:211], v175 offset:34816
	ds_read_b128 v[212:215], v175 offset:35840
	ds_read_b128 v[216:219], v175 offset:36864
	ds_read_b128 v[220:223], v175 offset:37888
	ds_read_b128 v[224:227], v175 offset:38912
	ds_read_b128 v[228:231], v175 offset:39936
	global_load_lds_dwordx4 v[234:235], off
	v_lshl_add_u64 v[234:235], s[42:43], 0, v[146:147]
	s_mov_b32 m0, s54
	s_nop 0
	global_load_lds_dwordx4 v[234:235], off
	s_waitcnt vmcnt(8)
	s_waitcnt lgkmcnt(0)
	s_barrier
	s_setprio 1
	s_waitcnt lgkmcnt(0)
	v_mfma_f32_16x16x32_bf16 v[124:127], v[132:135], v[198:201], v[124:127]
	v_mfma_f32_16x16x32_bf16 v[120:123], v[140:143], v[198:201], v[120:123]
	v_mfma_f32_16x16x32_bf16 v[116:119], v[132:135], v[208:211], v[116:119]
	v_mfma_f32_16x16x32_bf16 v[112:115], v[140:143], v[208:211], v[112:115]
	v_mfma_f32_16x16x32_bf16 v[108:111], v[132:135], v[216:219], v[108:111]
	v_mfma_f32_16x16x32_bf16 v[104:107], v[140:143], v[216:219], v[104:107]
	v_mfma_f32_16x16x32_bf16 v[100:103], v[132:135], v[224:227], v[100:103]
	v_mfma_f32_16x16x32_bf16 v[96:99], v[140:143], v[224:227], v[96:99]
	v_mfma_f32_16x16x32_bf16 v[124:127], v[136:139], v[202:205], v[124:127]
	v_mfma_f32_16x16x32_bf16 v[120:123], v[178:181], v[202:205], v[120:123]
	v_mfma_f32_16x16x32_bf16 v[116:119], v[136:139], v[212:215], v[116:119]
	v_mfma_f32_16x16x32_bf16 v[112:115], v[178:181], v[212:215], v[112:115]
	v_mfma_f32_16x16x32_bf16 v[108:111], v[136:139], v[220:223], v[108:111]
	v_mfma_f32_16x16x32_bf16 v[104:107], v[178:181], v[220:223], v[104:107]
	v_mfma_f32_16x16x32_bf16 v[100:103], v[136:139], v[228:231], v[100:103]
	v_mfma_f32_16x16x32_bf16 v[96:99], v[178:181], v[228:231], v[96:99]
	s_setprio 0
	s_setprio 1
	v_mfma_f32_16x16x32_bf16 v[64:67], v[182:185], v[198:201], v[64:67]
	v_mfma_f32_16x16x32_bf16 v[56:59], v[190:193], v[198:201], v[56:59]
	v_mfma_f32_16x16x32_bf16 v[52:55], v[182:185], v[208:211], v[52:55]
	v_mfma_f32_16x16x32_bf16 v[48:51], v[190:193], v[208:211], v[48:51]
	v_mfma_f32_16x16x32_bf16 v[44:47], v[182:185], v[216:219], v[44:47]
	v_mfma_f32_16x16x32_bf16 v[40:43], v[190:193], v[216:219], v[40:43]
	v_mfma_f32_16x16x32_bf16 v[36:39], v[182:185], v[224:227], v[36:39]
	v_mfma_f32_16x16x32_bf16 v[32:35], v[190:193], v[224:227], v[32:35]
	v_mfma_f32_16x16x32_bf16 v[64:67], v[186:189], v[202:205], v[64:67]
	v_mfma_f32_16x16x32_bf16 v[56:59], v[194:197], v[202:205], v[56:59]
	v_mfma_f32_16x16x32_bf16 v[52:55], v[186:189], v[212:215], v[52:55]
	v_mfma_f32_16x16x32_bf16 v[48:51], v[194:197], v[212:215], v[48:51]
	v_mfma_f32_16x16x32_bf16 v[44:47], v[186:189], v[220:223], v[44:47]
	v_mfma_f32_16x16x32_bf16 v[40:43], v[194:197], v[220:223], v[40:43]
	v_mfma_f32_16x16x32_bf16 v[36:39], v[186:189], v[228:231], v[36:39]
	v_mfma_f32_16x16x32_bf16 v[32:35], v[194:197], v[228:231], v[32:35]
	s_setprio 0
	s_barrier
; #define PG8_STAGE(bufoff, gbase, voff) do { _Pragma("unroll") for (int _i = 0; _i < 2; ++_i) \
;         __builtin_amdgcn_global_load_lds((const unsigned*)((const char*)(gbase) + (voff)[_i]), (PG8_LAS unsigned*)(lds + (bufoff) + ldsw + _i * 8192), 16, 0, 0); } while (0)
; #define PG8_LDA(dst, b, h) do { _Pragma("unroll") for (int m = 0; m < 4; ++m) _Pragma("unroll") for (int k = 0; k < 2; ++k) dst[m][k] = *(const PG8_LAS bf16x8*)(lds + PG8_SA(b, h) + aoff + m * 2048 + k * 1024); } while (0)
; #define PG8_MMA(ai, bj, At, Bt) do { __builtin_amdgcn_s_setprio(1); _Pragma("unroll") for (int m = 0; m < 4; ++m) _Pragma("unroll") for (int n = 0; n < 2; ++n) _Pragma("unroll") for (int k = 0; k < 2; ++k) \
;         acc[ai][bj][m][n] = __builtin_amdgcn_mfma_f32_16x16x32_bf16(Bt[n][k], At[m][k], acc[ai][bj][m][n], 0, 0, 0); __builtin_amdgcn_s_setprio(0); } while (0)
; #define PG8_WAIT_V(n) asm volatile("s_waitcnt vmcnt(" #n ")" ::: "memory")
; #define PG8_WAIT_L(n) asm volatile("s_waitcnt lgkmcnt(" #n ")" ::: "memory")
; #define PG8_BAR __builtin_amdgcn_s_barrier()
; #define PG8_SCHED __builtin_amdgcn_sched_barrier(0)
; template <class Epi, class Sched, bool ALIGN_EPI = false, bool SP2 = false>
; __device__ __forceinline__ void gemm_phase(PG8_LAS unsigned char* lds, const Gemm g, const Sched& S, const Epi& E) {
;     ...
;             PG8_LDA(At, 1, 1); PG8_STAGE(PG8_SB(1, 0), b3, voffB); PG8_STAGE(PG8_SB(1, 1), b3 + hstepB, voffB); PG8_STAGE(PG8_SA(1, 0), a3, voffA);
;             PG8_WAIT_V(8); PG8_WAIT_L(0); PG8_BAR; PG8_MMA(1, 0, At, B0); PG8_MMA(1, 1, At, B1); PG8_BAR; PG8_SCHED;
	s_add_i32 s42, s69, s49
	v_lshl_add_u64 v[206:207], v[206:207], 0, s[16:17]
	s_mov_b32 m0, s42
	ds_read_b128 v[198:201], v175 offset:49152
	ds_read_b128 v[202:205], v175 offset:50176
	ds_read_b128 v[208:211], v175 offset:51200
	ds_read_b128 v[212:215], v175 offset:52224
	ds_read_b128 v[216:219], v175 offset:53248
	ds_read_b128 v[220:223], v175 offset:54272
	ds_read_b128 v[224:227], v175 offset:55296
	ds_read_b128 v[228:231], v175 offset:56320
	global_load_lds_dwordx4 v[206:207], off
	s_add_i32 m0, s42, 0x2000
	s_add_u32 s40, s40, 0x40080
	v_lshl_add_u64 v[206:207], v[232:233], 0, s[16:17]
	s_addc_u32 s41, s41, 0
	s_add_i32 s42, s70, s49
	global_load_lds_dwordx4 v[206:207], off
	v_lshl_add_u64 v[206:207], s[40:41], 0, v[148:149]
	s_mov_b32 m0, s42
	s_nop 0
	global_load_lds_dwordx4 v[206:207], off
	v_lshl_add_u64 v[206:207], s[40:41], 0, v[144:145]
	s_add_i32 m0, s42, 0x2000
	s_nop 0
	global_load_lds_dwordx4 v[206:207], off
	v_lshl_add_u64 v[206:207], s[38:39], 0, v[150:151]
	s_mov_b32 m0, s56
	s_nop 0
	global_load_lds_dwordx4 v[206:207], off
	v_lshl_add_u64 v[206:207], s[38:39], 0, v[146:147]
	s_mov_b32 m0, s57
	s_nop 0
	global_load_lds_dwordx4 v[206:207], off
	s_waitcnt vmcnt(8)
	s_waitcnt lgkmcnt(0)
	s_barrier
	s_setprio 1
	s_waitcnt lgkmcnt(0)
	v_mfma_f32_16x16x32_bf16 v[92:95], v[132:135], v[198:201], v[92:95]
	v_mfma_f32_16x16x32_bf16 v[88:91], v[140:143], v[198:201], v[88:91]
	v_mfma_f32_16x16x32_bf16 v[84:87], v[132:135], v[208:211], v[84:87]
	v_mfma_f32_16x16x32_bf16 v[80:83], v[140:143], v[208:211], v[80:83]
	v_mfma_f32_16x16x32_bf16 v[76:79], v[132:135], v[216:219], v[76:79]
	v_mfma_f32_16x16x32_bf16 v[72:75], v[140:143], v[216:219], v[72:75]
	v_mfma_f32_16x16x32_bf16 v[68:71], v[132:135], v[224:227], v[68:71]
	v_mfma_f32_16x16x32_bf16 v[60:63], v[140:143], v[224:227], v[60:63]
	v_mfma_f32_16x16x32_bf16 v[92:95], v[136:139], v[202:205], v[92:95]
	v_mfma_f32_16x16x32_bf16 v[88:91], v[178:181], v[202:205], v[88:91]
	v_mfma_f32_16x16x32_bf16 v[84:87], v[136:139], v[212:215], v[84:87]
	v_mfma_f32_16x16x32_bf16 v[80:83], v[178:181], v[212:215], v[80:83]
	v_mfma_f32_16x16x32_bf16 v[76:79], v[136:139], v[220:223], v[76:79]
	v_mfma_f32_16x16x32_bf16 v[72:75], v[178:181], v[220:223], v[72:75]
	v_mfma_f32_16x16x32_bf16 v[68:71], v[136:139], v[228:231], v[68:71]
	v_mfma_f32_16x16x32_bf16 v[60:63], v[178:181], v[228:231], v[60:63]
	s_setprio 0
	s_setprio 1
	v_mfma_f32_16x16x32_bf16 v[28:31], v[182:185], v[198:201], v[28:31]
	v_mfma_f32_16x16x32_bf16 v[24:27], v[190:193], v[198:201], v[24:27]
	v_mfma_f32_16x16x32_bf16 v[20:23], v[182:185], v[208:211], v[20:23]
	v_mfma_f32_16x16x32_bf16 v[16:19], v[190:193], v[208:211], v[16:19]
	v_mfma_f32_16x16x32_bf16 v[12:15], v[182:185], v[216:219], v[12:15]
	v_mfma_f32_16x16x32_bf16 v[8:11], v[190:193], v[216:219], v[8:11]
	v_mfma_f32_16x16x32_bf16 v[4:7], v[182:185], v[224:227], v[4:7]
	v_mfma_f32_16x16x32_bf16 v[0:3], v[190:193], v[224:227], v[0:3]
	v_mfma_f32_16x16x32_bf16 v[28:31], v[186:189], v[202:205], v[28:31]
	v_mfma_f32_16x16x32_bf16 v[24:27], v[194:197], v[202:205], v[24:27]
	v_mfma_f32_16x16x32_bf16 v[20:23], v[186:189], v[212:215], v[20:23]
	v_mfma_f32_16x16x32_bf16 v[16:19], v[194:197], v[212:215], v[16:19]
	v_mfma_f32_16x16x32_bf16 v[12:15], v[186:189], v[220:223], v[12:15]
	v_mfma_f32_16x16x32_bf16 v[8:11], v[194:197], v[220:223], v[8:11]
	v_mfma_f32_16x16x32_bf16 v[4:7], v[186:189], v[228:231], v[4:7]
	v_mfma_f32_16x16x32_bf16 v[0:3], v[194:197], v[228:231], v[0:3]
	s_setprio 0
	s_barrier
	s_add_i32 s68, s68, 2
	s_add_u32 s36, s36, 0x100
	s_addc_u32 s37, s37, 0
	s_cmp_gt_u32 s68, 13
	s_cbranch_scc0 .LBB0_416
	s_and_b64 vcc, exec, s[18:19]
	s_cbranch_vccz .LBB0_419
	s_barrier

; #define PG8_STAGE(bufoff, gbase, voff) do { _Pragma("unroll") for (int _i = 0; _i < 2; ++_i) \
;         __builtin_amdgcn_global_load_lds((const unsigned*)((const char*)(gbase) + (voff)[_i]), (PG8_LAS unsigned*)(lds + (bufoff) + ldsw + _i * 8192), 16, 0, 0); } while (0)
; #define PG8_LDA(dst, b, h) do { _Pragma("unroll") for (int m = 0; m < 4; ++m) _Pragma("unroll") for (int k = 0; k < 2; ++k) dst[m][k] = *(const PG8_LAS bf16x8*)(lds + PG8_SA(b, h) + aoff + m * 2048 + k * 1024); } while (0)
; #define PG8_LDB(dst, b, h) do { _Pragma("unroll") for (int n = 0; n < 2; ++n) _Pragma("unroll") for (int k = 0; k < 2; ++k) dst[n][k] = *(const PG8_LAS bf16x8*)(lds + PG8_SB(b, h) + boff + n * 2048 + k * 1024); } while (0)
; #define PG8_MMA(ai, bj, At, Bt) do { __builtin_amdgcn_s_setprio(1); _Pragma("unroll") for (int m = 0; m < 4; ++m) _Pragma("unroll") for (int n = 0; n < 2; ++n) _Pragma("unroll") for (int k = 0; k < 2; ++k) \
;         acc[ai][bj][m][n] = __builtin_amdgcn_mfma_f32_16x16x32_bf16(Bt[n][k], At[m][k], acc[ai][bj][m][n], 0, 0, 0); __builtin_amdgcn_s_setprio(0); } while (0)
; #define PG8_WAIT_V(n) asm volatile("s_waitcnt vmcnt(" #n ")" ::: "memory")
; #define PG8_WAIT_L(n) asm volatile("s_waitcnt lgkmcnt(" #n ")" ::: "memory")
; template <class Epi, class Sched, bool ALIGN_EPI = false, bool SP2 = false>
; __device__ __forceinline__ void gemm_phase(PG8_LAS unsigned char* lds, const Gemm g, const Sched& S, const Epi& E) {
;     ...
;             const bool last = (t == nt - 2);
;             const char* a1 = cA + PG8_AK(t + 1);
;             const char* a2 = last ? nA : cA + PG8_AK(t + 2); const char* b2 = last ? nB : cB + (size_t)(t + 2) * kstep;
;             const char* a3 = last ? nA + PG8_AK(1) : cA + PG8_AK(t + 3); const char* b3 = b2 + kstep;
;             if (last && has_next) S.a_ready(nxt);
;             if constexpr (SP2) {
;             PG8_LDB(B0, 0, 0); PG8_LDB(B1, 0, 1); PG8_SCHED; PG8_LDA(At, 0, 0); PG8_STAGE(PG8_SA(1, 1), a1 + hstepA, voffA);
;             PG8_WAIT_V(8); PG8_WAIT_L(0); PG8_BAR; PG8_MMA(0, 0, At, B0); PG8_MMA(0, 1, At, B1); PG8_BAR; PG8_SCHED;
;             PG8_LDA(At, 0, 1); PG8_STAGE(PG8_SB(0, 0), b2, voffB); PG8_STAGE(PG8_SB(0, 1), b2 + hstepB, voffB); PG8_STAGE(PG8_SA(0, 0), a2, voffA);
;             PG8_WAIT_V(8); PG8_WAIT_L(0); PG8_BAR; PG8_MMA(1, 0, At, B0); PG8_MMA(1, 1, At, B1); PG8_BAR; PG8_SCHED;
.LBB0_520:
	ds_read_b128 v[124:127], v210
	ds_read_b128 v[128:131], v210 offset:1024
	ds_read_b128 v[132:135], v210 offset:2048
	ds_read_b128 v[144:147], v210 offset:3072
	ds_read_b128 v[148:151], v211
	ds_read_b128 v[170:173], v211 offset:1024
	ds_read_b128 v[174:177], v211 offset:2048
	ds_read_b128 v[178:181], v211 offset:3072
	s_add_u32 s42, s38, s40
	s_addc_u32 s43, s39, s41
	s_add_u32 s46, s42, 0x100
	s_addc_u32 s47, s43, 0
	s_add_u32 s44, s79, s40
	s_addc_u32 s45, s83, s41
	s_add_u32 s42, s42, 0x180
	s_addc_u32 s43, s43, 0
	s_cmpk_eq_i32 s40, 0x1500
	s_cselect_b32 s43, s78, s43
	s_cselect_b32 s42, s3, s42
	s_cselect_b32 s45, s37, s45
	s_cselect_b32 s44, s36, s44
	s_cselect_b32 s47, s9, s47
	s_cselect_b32 s46, s8, s46
	v_lshl_add_u64 v[206:207], v[122:123], 0, s[40:41]
	s_add_i32 m0, s53, 0xc000
	ds_read_b128 v[212:215], v191
	ds_read_b128 v[216:219], v191 offset:1024
	ds_read_b128 v[220:223], v191 offset:2048
	ds_read_b128 v[224:227], v191 offset:3072
	ds_read_b128 v[228:231], v191 offset:4096
	ds_read_b128 v[232:235], v191 offset:5120
	ds_read_b128 v[236:239], v191 offset:6144
	ds_read_b128 v[240:243], v191 offset:7168
	global_load_lds_dwordx4 v[206:207], off
	v_lshl_add_u64 v[206:207], v[120:121], 0, s[40:41]
	s_add_i32 m0, s53, 0xe000
	s_nop 0
	global_load_lds_dwordx4 v[206:207], off
	s_waitcnt vmcnt(8)
	s_waitcnt lgkmcnt(0)
	s_barrier
	s_setprio 1
	s_waitcnt lgkmcnt(0)
	v_mfma_f32_16x16x32_bf16 v[140:143], v[124:127], v[212:215], v[140:143]
	v_mfma_f32_16x16x32_bf16 v[136:139], v[132:135], v[212:215], v[136:139]
	v_mfma_f32_16x16x32_bf16 v[116:119], v[124:127], v[220:223], v[116:119]
	v_mfma_f32_16x16x32_bf16 v[112:115], v[132:135], v[220:223], v[112:115]
	v_mfma_f32_16x16x32_bf16 v[108:111], v[124:127], v[228:231], v[108:111]
	v_mfma_f32_16x16x32_bf16 v[104:107], v[132:135], v[228:231], v[104:107]
	v_mfma_f32_16x16x32_bf16 v[100:103], v[124:127], v[236:239], v[100:103]
	v_mfma_f32_16x16x32_bf16 v[96:99], v[132:135], v[236:239], v[96:99]
	v_mfma_f32_16x16x32_bf16 v[140:143], v[128:131], v[216:219], v[140:143]
	v_mfma_f32_16x16x32_bf16 v[136:139], v[144:147], v[216:219], v[136:139]
	v_mfma_f32_16x16x32_bf16 v[116:119], v[128:131], v[224:227], v[116:119]
	v_mfma_f32_16x16x32_bf16 v[112:115], v[144:147], v[224:227], v[112:115]
	v_mfma_f32_16x16x32_bf16 v[108:111], v[128:131], v[232:235], v[108:111]
	v_mfma_f32_16x16x32_bf16 v[104:107], v[144:147], v[232:235], v[104:107]
	v_mfma_f32_16x16x32_bf16 v[100:103], v[128:131], v[240:243], v[100:103]
	v_mfma_f32_16x16x32_bf16 v[96:99], v[144:147], v[240:243], v[96:99]
	s_setprio 0
	s_setprio 1
	v_mfma_f32_16x16x32_bf16 v[60:63], v[148:151], v[212:215], v[60:63]
	v_mfma_f32_16x16x32_bf16 v[56:59], v[174:177], v[212:215], v[56:59]
	v_mfma_f32_16x16x32_bf16 v[52:55], v[148:151], v[220:223], v[52:55]
	v_mfma_f32_16x16x32_bf16 v[48:51], v[174:177], v[220:223], v[48:51]
	v_mfma_f32_16x16x32_bf16 v[44:47], v[148:151], v[228:231], v[44:47]
	v_mfma_f32_16x16x32_bf16 v[40:43], v[174:177], v[228:231], v[40:43]
	v_mfma_f32_16x16x32_bf16 v[36:39], v[148:151], v[236:239], v[36:39]
	v_mfma_f32_16x16x32_bf16 v[32:35], v[174:177], v[236:239], v[32:35]
	v_mfma_f32_16x16x32_bf16 v[60:63], v[170:173], v[216:219], v[60:63]
	v_mfma_f32_16x16x32_bf16 v[56:59], v[178:181], v[216:219], v[56:59]
	v_mfma_f32_16x16x32_bf16 v[52:55], v[170:173], v[224:227], v[52:55]
	v_mfma_f32_16x16x32_bf16 v[48:51], v[178:181], v[224:227], v[48:51]
	v_mfma_f32_16x16x32_bf16 v[44:47], v[170:173], v[232:235], v[44:47]
	v_mfma_f32_16x16x32_bf16 v[40:43], v[178:181], v[232:235], v[40:43]
	v_mfma_f32_16x16x32_bf16 v[36:39], v[170:173], v[240:243], v[36:39]
	v_mfma_f32_16x16x32_bf16 v[32:35], v[178:181], v[240:243], v[32:35]
	s_setprio 0
	s_barrier
	s_add_i32 s70, s67, s52
	v_lshl_add_u64 v[206:207], s[44:45], 0, v[154:155]
	s_mov_b32 m0, s70
	ds_read_b128 v[212:215], v191 offset:16384
	ds_read_b128 v[216:219], v191 offset:17408
	ds_read_b128 v[220:223], v191 offset:18432
	ds_read_b128 v[224:227], v191 offset:19456
	ds_read_b128 v[228:231], v191 offset:20480
	ds_read_b128 v[232:235], v191 offset:21504
	ds_read_b128 v[236:239], v191 offset:22528
	ds_read_b128 v[240:243], v191 offset:23552
	global_load_lds_dwordx4 v[206:207], off
	s_add_i32 m0, s70, 0x2000
	s_add_u32 s70, s44, 0xb0000
	v_lshl_add_u64 v[244:245], s[44:45], 0, v[158:159]
	s_addc_u32 s71, s45, 0
	s_add_i32 s85, s68, s52
	global_load_lds_dwordx4 v[244:245], off
	v_lshl_add_u64 v[246:247], s[70:71], 0, v[154:155]
	s_mov_b32 m0, s85
	s_nop 0
	global_load_lds_dwordx4 v[246:247], off
	v_lshl_add_u64 v[246:247], s[70:71], 0, v[158:159]
	s_add_i32 m0, s85, 0x2000
	s_nop 0
	global_load_lds_dwordx4 v[246:247], off
	s_waitcnt vmcnt(6)
	s_waitcnt lgkmcnt(0)
	s_barrier
; #define PG8_STAGE(bufoff, gbase, voff) do { _Pragma("unroll") for (int _i = 0; _i < 2; ++_i) \
;         __builtin_amdgcn_global_load_lds((const unsigned*)((const char*)(gbase) + (voff)[_i]), (PG8_LAS unsigned*)(lds + (bufoff) + ldsw + _i * 8192), 16, 0, 0); } while (0)
; #define PG8_LDA(dst, b, h) do { _Pragma("unroll") for (int m = 0; m < 4; ++m) _Pragma("unroll") for (int k = 0; k < 2; ++k) dst[m][k] = *(const PG8_LAS bf16x8*)(lds + PG8_SA(b, h) + aoff + m * 2048 + k * 1024); } while (0)
; #define PG8_LDB(dst, b, h) do { _Pragma("unroll") for (int n = 0; n < 2; ++n) _Pragma("unroll") for (int k = 0; k < 2; ++k) dst[n][k] = *(const PG8_LAS bf16x8*)(lds + PG8_SB(b, h) + boff + n * 2048 + k * 1024); } while (0)
; #define PG8_MMA(ai, bj, At, Bt) do { __builtin_amdgcn_s_setprio(1); _Pragma("unroll") for (int m = 0; m < 4; ++m) _Pragma("unroll") for (int n = 0; n < 2; ++n) _Pragma("unroll") for (int k = 0; k < 2; ++k) \
;         acc[ai][bj][m][n] = __builtin_amdgcn_mfma_f32_16x16x32_bf16(Bt[n][k], At[m][k], acc[ai][bj][m][n], 0, 0, 0); __builtin_amdgcn_s_setprio(0); } while (0)
; #define PG8_WAIT_V(n) asm volatile("s_waitcnt vmcnt(" #n ")" ::: "memory")
; #define PG8_WAIT_L(n) asm volatile("s_waitcnt lgkmcnt(" #n ")" ::: "memory")
; #define PG8_BAR __builtin_amdgcn_s_barrier()
; #define PG8_SCHED __builtin_amdgcn_sched_barrier(0)
; template <class Epi, class Sched, bool ALIGN_EPI = false, bool SP2 = false>
; __device__ __forceinline__ void gemm_phase(PG8_LAS unsigned char* lds, const Gemm g, const Sched& S, const Epi& E) {
;     ...
;             PG8_WAIT_V(8); PG8_WAIT_L(0); PG8_BAR; PG8_MMA(1, 0, At, B0); PG8_MMA(1, 1, At, B1); PG8_BAR; PG8_SCHED;
;             PG8_LDB(B0, 1, 0); PG8_LDB(B1, 1, 1); PG8_SCHED; PG8_LDA(At, 1, 0); PG8_STAGE(PG8_SA(0, 1), a2 + hstepA, voffA);
;             PG8_WAIT_V(8); PG8_WAIT_L(0); PG8_BAR; PG8_MMA(0, 0, At, B0); PG8_MMA(0, 1, At, B1); PG8_BAR; PG8_SCHED;
	s_setprio 1
	s_waitcnt lgkmcnt(0)
	v_mfma_f32_16x16x32_bf16 v[92:95], v[124:127], v[212:215], v[92:95]
	v_mfma_f32_16x16x32_bf16 v[88:91], v[132:135], v[212:215], v[88:91]
	v_mfma_f32_16x16x32_bf16 v[84:87], v[124:127], v[220:223], v[84:87]
	v_mfma_f32_16x16x32_bf16 v[80:83], v[132:135], v[220:223], v[80:83]
	v_mfma_f32_16x16x32_bf16 v[76:79], v[124:127], v[228:231], v[76:79]
	v_mfma_f32_16x16x32_bf16 v[72:75], v[132:135], v[228:231], v[72:75]
	v_mfma_f32_16x16x32_bf16 v[68:71], v[124:127], v[236:239], v[68:71]
	v_mfma_f32_16x16x32_bf16 v[64:67], v[132:135], v[236:239], v[64:67]
	v_mfma_f32_16x16x32_bf16 v[92:95], v[128:131], v[216:219], v[92:95]
	v_mfma_f32_16x16x32_bf16 v[88:91], v[144:147], v[216:219], v[88:91]
	v_mfma_f32_16x16x32_bf16 v[84:87], v[128:131], v[224:227], v[84:87]
	v_mfma_f32_16x16x32_bf16 v[80:83], v[144:147], v[224:227], v[80:83]
	v_mfma_f32_16x16x32_bf16 v[76:79], v[128:131], v[232:235], v[76:79]
	v_mfma_f32_16x16x32_bf16 v[72:75], v[144:147], v[232:235], v[72:75]
	v_mfma_f32_16x16x32_bf16 v[68:71], v[128:131], v[240:243], v[68:71]
	v_mfma_f32_16x16x32_bf16 v[64:67], v[144:147], v[240:243], v[64:67]
	s_setprio 0
	s_setprio 1
	v_mfma_f32_16x16x32_bf16 v[28:31], v[148:151], v[212:215], v[28:31]
	v_mfma_f32_16x16x32_bf16 v[24:27], v[174:177], v[212:215], v[24:27]
	v_mfma_f32_16x16x32_bf16 v[20:23], v[148:151], v[220:223], v[20:23]
	v_mfma_f32_16x16x32_bf16 v[16:19], v[174:177], v[220:223], v[16:19]
	v_mfma_f32_16x16x32_bf16 v[12:15], v[148:151], v[228:231], v[12:15]
	v_mfma_f32_16x16x32_bf16 v[8:11], v[174:177], v[228:231], v[8:11]
	v_mfma_f32_16x16x32_bf16 v[4:7], v[148:151], v[236:239], v[4:7]
	v_mfma_f32_16x16x32_bf16 v[0:3], v[174:177], v[236:239], v[0:3]
	v_mfma_f32_16x16x32_bf16 v[28:31], v[170:173], v[216:219], v[28:31]
	v_mfma_f32_16x16x32_bf16 v[24:27], v[178:181], v[216:219], v[24:27]
	v_mfma_f32_16x16x32_bf16 v[20:23], v[170:173], v[224:227], v[20:23]
	v_mfma_f32_16x16x32_bf16 v[16:19], v[178:181], v[224:227], v[16:19]
	v_mfma_f32_16x16x32_bf16 v[12:15], v[170:173], v[232:235], v[12:15]
	v_mfma_f32_16x16x32_bf16 v[8:11], v[178:181], v[232:235], v[8:11]
	v_mfma_f32_16x16x32_bf16 v[4:7], v[170:173], v[240:243], v[4:7]
	v_mfma_f32_16x16x32_bf16 v[0:3], v[178:181], v[240:243], v[0:3]
	s_setprio 0
	s_barrier
	s_add_i32 s70, 0, 0x18000
	s_add_i32 s71, 0, 0x1c000
	v_add_u32_e32 v144, s70, v185
	v_add_u32_e32 v161, s71, v185
	ds_read_b128 v[124:127], v144
	ds_read_b128 v[128:131], v144 offset:1024
	ds_read_b128 v[132:135], v144 offset:2048
	ds_read_b128 v[144:147], v144 offset:3072
	ds_read_b128 v[148:151], v161
	ds_read_b128 v[170:173], v161 offset:1024
	ds_read_b128 v[174:177], v161 offset:2048
	ds_read_b128 v[178:181], v161 offset:3072
	v_lshl_add_u64 v[246:247], s[46:47], 0, v[152:153]
	s_mov_b32 m0, s53
	s_nop 0
	global_load_lds_dwordx4 v[246:247], off
	v_lshl_add_u64 v[246:247], s[46:47], 0, v[156:157]
	s_mov_b32 m0, s54
	s_nop 0
	global_load_lds_dwordx4 v[246:247], off
	s_add_u32 s46, s46, 0xb0000
	s_addc_u32 s47, s47, 0
	s_mov_b32 m0, s55
	v_lshl_add_u64 v[246:247], s[46:47], 0, v[152:153]
	ds_read_b128 v[212:215], v191 offset:32768
	ds_read_b128 v[216:219], v191 offset:33792
	ds_read_b128 v[220:223], v191 offset:34816
	ds_read_b128 v[224:227], v191 offset:35840
	ds_read_b128 v[228:231], v191 offset:36864
	ds_read_b128 v[232:235], v191 offset:37888
	ds_read_b128 v[236:239], v191 offset:38912
	ds_read_b128 v[240:243], v191 offset:39936
	global_load_lds_dwordx4 v[246:247], off
	v_lshl_add_u64 v[246:247], s[46:47], 0, v[156:157]
	s_mov_b32 m0, s56
	s_nop 0
	global_load_lds_dwordx4 v[246:247], off
	s_waitcnt vmcnt(8)
	s_waitcnt lgkmcnt(0)
	s_barrier
	s_setprio 1
	s_waitcnt lgkmcnt(0)
	v_mfma_f32_16x16x32_bf16 v[140:143], v[124:127], v[212:215], v[140:143]
	v_mfma_f32_16x16x32_bf16 v[136:139], v[132:135], v[212:215], v[136:139]
	v_mfma_f32_16x16x32_bf16 v[116:119], v[124:127], v[220:223], v[116:119]
	v_mfma_f32_16x16x32_bf16 v[112:115], v[132:135], v[220:223], v[112:115]
	v_mfma_f32_16x16x32_bf16 v[108:111], v[124:127], v[228:231], v[108:111]
	v_mfma_f32_16x16x32_bf16 v[104:107], v[132:135], v[228:231], v[104:107]
	v_mfma_f32_16x16x32_bf16 v[100:103], v[124:127], v[236:239], v[100:103]
	v_mfma_f32_16x16x32_bf16 v[96:99], v[132:135], v[236:239], v[96:99]
	v_mfma_f32_16x16x32_bf16 v[140:143], v[128:131], v[216:219], v[140:143]
	v_mfma_f32_16x16x32_bf16 v[136:139], v[144:147], v[216:219], v[136:139]
	v_mfma_f32_16x16x32_bf16 v[116:119], v[128:131], v[224:227], v[116:119]
	v_mfma_f32_16x16x32_bf16 v[112:115], v[144:147], v[224:227], v[112:115]
	v_mfma_f32_16x16x32_bf16 v[108:111], v[128:131], v[232:235], v[108:111]
	v_mfma_f32_16x16x32_bf16 v[104:107], v[144:147], v[232:235], v[104:107]
	v_mfma_f32_16x16x32_bf16 v[100:103], v[128:131], v[240:243], v[100:103]
	v_mfma_f32_16x16x32_bf16 v[96:99], v[144:147], v[240:243], v[96:99]
	s_setprio 0
	s_setprio 1
	v_mfma_f32_16x16x32_bf16 v[60:63], v[148:151], v[212:215], v[60:63]
	v_mfma_f32_16x16x32_bf16 v[56:59], v[174:177], v[212:215], v[56:59]
	v_mfma_f32_16x16x32_bf16 v[52:55], v[148:151], v[220:223], v[52:55]
	v_mfma_f32_16x16x32_bf16 v[48:51], v[174:177], v[220:223], v[48:51]
	v_mfma_f32_16x16x32_bf16 v[44:47], v[148:151], v[228:231], v[44:47]
	v_mfma_f32_16x16x32_bf16 v[40:43], v[174:177], v[228:231], v[40:43]
	v_mfma_f32_16x16x32_bf16 v[36:39], v[148:151], v[236:239], v[36:39]
	v_mfma_f32_16x16x32_bf16 v[32:35], v[174:177], v[236:239], v[32:35]
	v_mfma_f32_16x16x32_bf16 v[60:63], v[170:173], v[216:219], v[60:63]
	v_mfma_f32_16x16x32_bf16 v[56:59], v[178:181], v[216:219], v[56:59]
	v_mfma_f32_16x16x32_bf16 v[52:55], v[170:173], v[224:227], v[52:55]
	v_mfma_f32_16x16x32_bf16 v[48:51], v[178:181], v[224:227], v[48:51]
	v_mfma_f32_16x16x32_bf16 v[44:47], v[170:173], v[232:235], v[44:47]
	v_mfma_f32_16x16x32_bf16 v[40:43], v[178:181], v[232:235], v[40:43]
	v_mfma_f32_16x16x32_bf16 v[36:39], v[170:173], v[240:243], v[36:39]
	v_mfma_f32_16x16x32_bf16 v[32:35], v[178:181], v[240:243], v[32:35]
	s_setprio 0
	s_barrier
; #define PG8_STAGE(bufoff, gbase, voff) do { _Pragma("unroll") for (int _i = 0; _i < 2; ++_i) \
;         __builtin_amdgcn_global_load_lds((const unsigned*)((const char*)(gbase) + (voff)[_i]), (PG8_LAS unsigned*)(lds + (bufoff) + ldsw + _i * 8192), 16, 0, 0); } while (0)
; #define PG8_LDA(dst, b, h) do { _Pragma("unroll") for (int m = 0; m < 4; ++m) _Pragma("unroll") for (int k = 0; k < 2; ++k) dst[m][k] = *(const PG8_LAS bf16x8*)(lds + PG8_SA(b, h) + aoff + m * 2048 + k * 1024); } while (0)
; #define PG8_MMA(ai, bj, At, Bt) do { __builtin_amdgcn_s_setprio(1); _Pragma("unroll") for (int m = 0; m < 4; ++m) _Pragma("unroll") for (int n = 0; n < 2; ++n) _Pragma("unroll") for (int k = 0; k < 2; ++k) \
;         acc[ai][bj][m][n] = __builtin_amdgcn_mfma_f32_16x16x32_bf16(Bt[n][k], At[m][k], acc[ai][bj][m][n], 0, 0, 0); __builtin_amdgcn_s_setprio(0); } while (0)
; #define PG8_WAIT_V(n) asm volatile("s_waitcnt vmcnt(" #n ")" ::: "memory")
; #define PG8_WAIT_L(n) asm volatile("s_waitcnt lgkmcnt(" #n ")" ::: "memory")
; #define PG8_BAR __builtin_amdgcn_s_barrier()
; #define PG8_SCHED __builtin_amdgcn_sched_barrier(0)
; template <class Epi, class Sched, bool ALIGN_EPI = false, bool SP2 = false>
; __device__ __forceinline__ void gemm_phase(PG8_LAS unsigned char* lds, const Gemm g, const Sched& S, const Epi& E) {
;     ...
;             PG8_LDA(At, 1, 1); PG8_STAGE(PG8_SB(1, 0), b3, voffB); PG8_STAGE(PG8_SB(1, 1), b3 + hstepB, voffB); PG8_STAGE(PG8_SA(1, 0), a3, voffA);
;             PG8_WAIT_V(8); PG8_WAIT_L(0); PG8_BAR; PG8_MMA(1, 0, At, B0); PG8_MMA(1, 1, At, B1); PG8_BAR; PG8_SCHED;
	s_add_i32 s46, s70, s52
	v_lshl_add_u64 v[206:207], v[206:207], 0, s[26:27]
	s_mov_b32 m0, s46
	ds_read_b128 v[212:215], v191 offset:49152
	ds_read_b128 v[216:219], v191 offset:50176
	ds_read_b128 v[220:223], v191 offset:51200
	ds_read_b128 v[224:227], v191 offset:52224
	ds_read_b128 v[228:231], v191 offset:53248
	ds_read_b128 v[232:235], v191 offset:54272
	ds_read_b128 v[236:239], v191 offset:55296
	ds_read_b128 v[240:243], v191 offset:56320
	global_load_lds_dwordx4 v[206:207], off
	s_add_i32 m0, s46, 0x2000
	s_add_u32 s44, s44, 0xb0080
	v_lshl_add_u64 v[206:207], v[244:245], 0, s[26:27]
	s_addc_u32 s45, s45, 0
	s_add_i32 s46, s71, s52
	global_load_lds_dwordx4 v[206:207], off
	v_lshl_add_u64 v[206:207], s[44:45], 0, v[154:155]
	s_mov_b32 m0, s46
	s_nop 0
	global_load_lds_dwordx4 v[206:207], off
	v_lshl_add_u64 v[206:207], s[44:45], 0, v[158:159]
	s_add_i32 m0, s46, 0x2000
	s_nop 0
	global_load_lds_dwordx4 v[206:207], off
	v_lshl_add_u64 v[206:207], s[42:43], 0, v[152:153]
	s_mov_b32 m0, s63
	s_nop 0
	global_load_lds_dwordx4 v[206:207], off
	v_lshl_add_u64 v[206:207], s[42:43], 0, v[156:157]
	s_mov_b32 m0, s64
	s_nop 0
	global_load_lds_dwordx4 v[206:207], off
	s_waitcnt vmcnt(8)
	s_waitcnt lgkmcnt(0)
	s_barrier
	s_setprio 1
	s_waitcnt lgkmcnt(0)
	v_mfma_f32_16x16x32_bf16 v[92:95], v[124:127], v[212:215], v[92:95]
	v_mfma_f32_16x16x32_bf16 v[88:91], v[132:135], v[212:215], v[88:91]
	v_mfma_f32_16x16x32_bf16 v[84:87], v[124:127], v[220:223], v[84:87]
	v_mfma_f32_16x16x32_bf16 v[80:83], v[132:135], v[220:223], v[80:83]
	v_mfma_f32_16x16x32_bf16 v[76:79], v[124:127], v[228:231], v[76:79]
	v_mfma_f32_16x16x32_bf16 v[72:75], v[132:135], v[228:231], v[72:75]
	v_mfma_f32_16x16x32_bf16 v[68:71], v[124:127], v[236:239], v[68:71]
	v_mfma_f32_16x16x32_bf16 v[64:67], v[132:135], v[236:239], v[64:67]
	v_mfma_f32_16x16x32_bf16 v[92:95], v[128:131], v[216:219], v[92:95]
	v_mfma_f32_16x16x32_bf16 v[88:91], v[144:147], v[216:219], v[88:91]
	v_mfma_f32_16x16x32_bf16 v[84:87], v[128:131], v[224:227], v[84:87]
	v_mfma_f32_16x16x32_bf16 v[80:83], v[144:147], v[224:227], v[80:83]
	v_mfma_f32_16x16x32_bf16 v[76:79], v[128:131], v[232:235], v[76:79]
	v_mfma_f32_16x16x32_bf16 v[72:75], v[144:147], v[232:235], v[72:75]
	v_mfma_f32_16x16x32_bf16 v[68:71], v[128:131], v[240:243], v[68:71]
	v_mfma_f32_16x16x32_bf16 v[64:67], v[144:147], v[240:243], v[64:67]
	s_setprio 0
	s_setprio 1
	v_mfma_f32_16x16x32_bf16 v[28:31], v[148:151], v[212:215], v[28:31]
	v_mfma_f32_16x16x32_bf16 v[24:27], v[174:177], v[212:215], v[24:27]
	v_mfma_f32_16x16x32_bf16 v[20:23], v[148:151], v[220:223], v[20:23]
	v_mfma_f32_16x16x32_bf16 v[16:19], v[174:177], v[220:223], v[16:19]
	v_mfma_f32_16x16x32_bf16 v[12:15], v[148:151], v[228:231], v[12:15]
	v_mfma_f32_16x16x32_bf16 v[8:11], v[174:177], v[228:231], v[8:11]
	v_mfma_f32_16x16x32_bf16 v[4:7], v[148:151], v[236:239], v[4:7]
	v_mfma_f32_16x16x32_bf16 v[0:3], v[174:177], v[236:239], v[0:3]
	v_mfma_f32_16x16x32_bf16 v[28:31], v[170:173], v[216:219], v[28:31]
	v_mfma_f32_16x16x32_bf16 v[24:27], v[178:181], v[216:219], v[24:27]
	v_mfma_f32_16x16x32_bf16 v[20:23], v[170:173], v[224:227], v[20:23]
	v_mfma_f32_16x16x32_bf16 v[16:19], v[178:181], v[224:227], v[16:19]
	v_mfma_f32_16x16x32_bf16 v[12:15], v[170:173], v[232:235], v[12:15]
	v_mfma_f32_16x16x32_bf16 v[8:11], v[178:181], v[232:235], v[8:11]
	v_mfma_f32_16x16x32_bf16 v[4:7], v[170:173], v[240:243], v[4:7]
	v_mfma_f32_16x16x32_bf16 v[0:3], v[178:181], v[240:243], v[0:3]
	s_setprio 0
	s_barrier
	s_add_i32 s84, s84, 2
	s_add_u32 s40, s40, 0x100
	s_addc_u32 s41, s41, 0
	s_cmp_gt_u32 s84, 41
	s_cbranch_scc0 .LBB0_520
	s_and_b64 vcc, exec, s[28:29]
	s_cbranch_vccz .LBB0_523
	s_barrier

; #define PG8_STAGE(bufoff, gbase, voff) do { _Pragma("unroll") for (int _i = 0; _i < 2; ++_i) \
;         __builtin_amdgcn_global_load_lds((const unsigned*)((const char*)(gbase) + (voff)[_i]), (PG8_LAS unsigned*)(lds + (bufoff) + ldsw + _i * 8192), 16, 0, 0); } while (0)
; #define PG8_LDA(dst, b, h) do { _Pragma("unroll") for (int m = 0; m < 4; ++m) _Pragma("unroll") for (int k = 0; k < 2; ++k) dst[m][k] = *(const PG8_LAS bf16x8*)(lds + PG8_SA(b, h) + aoff + m * 2048 + k * 1024); } while (0)
; #define PG8_LDB(dst, b, h) do { _Pragma("unroll") for (int n = 0; n < 2; ++n) _Pragma("unroll") for (int k = 0; k < 2; ++k) dst[n][k] = *(const PG8_LAS bf16x8*)(lds + PG8_SB(b, h) + boff + n * 2048 + k * 1024); } while (0)
; #define PG8_MMA(ai, bj, At, Bt) do { __builtin_amdgcn_s_setprio(1); _Pragma("unroll") for (int m = 0; m < 4; ++m) _Pragma("unroll") for (int n = 0; n < 2; ++n) _Pragma("unroll") for (int k = 0; k < 2; ++k) \
;         acc[ai][bj][m][n] = __builtin_amdgcn_mfma_f32_16x16x32_bf16(Bt[n][k], At[m][k], acc[ai][bj][m][n], 0, 0, 0); __builtin_amdgcn_s_setprio(0); } while (0)
; #define PG8_WAIT_V(n) asm volatile("s_waitcnt vmcnt(" #n ")" ::: "memory")
; #define PG8_WAIT_L(n) asm volatile("s_waitcnt lgkmcnt(" #n ")" ::: "memory")
; template <class Epi, class Sched, bool ALIGN_EPI = false, bool SP2 = false>
; __device__ __forceinline__ void gemm_phase(PG8_LAS unsigned char* lds, const Gemm g, const Sched& S, const Epi& E) {
;     ...
;             const bool last = (t == nt - 2);
;             const char* a1 = cA + PG8_AK(t + 1);
;             const char* a2 = last ? nA : cA + PG8_AK(t + 2); const char* b2 = last ? nB : cB + (size_t)(t + 2) * kstep;
;             const char* a3 = last ? nA + PG8_AK(1) : cA + PG8_AK(t + 3); const char* b3 = b2 + kstep;
;             if (last && has_next) S.a_ready(nxt);
;             if constexpr (SP2) {
;             PG8_LDB(B0, 0, 0); PG8_LDB(B1, 0, 1); PG8_SCHED; PG8_LDA(At, 0, 0); PG8_STAGE(PG8_SA(1, 1), a1 + hstepA, voffA);
;             PG8_WAIT_V(8); PG8_WAIT_L(0); PG8_BAR; PG8_MMA(0, 0, At, B0); PG8_MMA(0, 1, At, B1); PG8_BAR; PG8_SCHED;
;             PG8_LDA(At, 0, 1); PG8_STAGE(PG8_SB(0, 0), b2, voffB); PG8_STAGE(PG8_SB(0, 1), b2 + hstepB, voffB); PG8_STAGE(PG8_SA(0, 0), a2, voffA);
;             PG8_WAIT_V(8); PG8_WAIT_L(0); PG8_BAR; PG8_MMA(1, 0, At, B0); PG8_MMA(1, 1, At, B1); PG8_BAR; PG8_SCHED;
.LBB0_612:
	ds_read_b128 v[100:103], v226
	ds_read_b128 v[104:107], v226 offset:1024
	ds_read_b128 v[108:111], v226 offset:2048
	ds_read_b128 v[120:123], v226 offset:3072
	ds_read_b128 v[124:127], v227
	ds_read_b128 v[128:131], v227 offset:1024
	ds_read_b128 v[132:135], v227 offset:2048
	ds_read_b128 v[160:163], v227 offset:3072
	s_add_u32 s44, s40, s42
	s_addc_u32 s45, s41, s43
	s_add_u32 s48, s44, 0x100
	s_addc_u32 s49, s45, 0
	s_add_u32 s46, s83, s42
	s_addc_u32 s47, s84, s43
	s_add_u32 s44, s44, 0x180
	s_addc_u32 s45, s45, 0
	s_cmpk_eq_i32 s42, 0x700
	s_cselect_b32 s45, s82, s45
	s_cselect_b32 s44, s79, s44
	s_cselect_b32 s47, s29, s47
	s_cselect_b32 s46, s78, s46
	s_cselect_b32 s49, s3, s49
	s_cselect_b32 s48, s31, s48
	v_lshl_add_u64 v[236:237], v[98:99], 0, s[42:43]
	s_add_i32 m0, s57, 0xc000
	ds_read_b128 v[164:167], v209
	ds_read_b128 v[168:171], v209 offset:1024
	ds_read_b128 v[192:195], v209 offset:2048
	ds_read_b128 v[196:199], v209 offset:3072
	ds_read_b128 v[200:203], v209 offset:4096
	ds_read_b128 v[204:207], v209 offset:5120
	ds_read_b128 v[228:231], v209 offset:6144
	ds_read_b128 v[232:235], v209 offset:7168
	global_load_lds_dwordx4 v[236:237], off
	v_lshl_add_u64 v[236:237], v[96:97], 0, s[42:43]
	s_add_i32 m0, s57, 0xe000
	s_nop 0
	global_load_lds_dwordx4 v[236:237], off
	s_waitcnt vmcnt(8)
	s_waitcnt lgkmcnt(0)
	s_barrier
	s_setprio 1
	s_waitcnt lgkmcnt(0)
	v_mfma_f32_16x16x32_bf16 v[156:159], v[100:103], v[164:167], v[156:159]
	v_mfma_f32_16x16x32_bf16 v[152:155], v[108:111], v[164:167], v[152:155]
	v_mfma_f32_16x16x32_bf16 v[148:151], v[100:103], v[192:195], v[148:151]
	v_mfma_f32_16x16x32_bf16 v[144:147], v[108:111], v[192:195], v[144:147]
	v_mfma_f32_16x16x32_bf16 v[140:143], v[100:103], v[200:203], v[140:143]
	v_mfma_f32_16x16x32_bf16 v[136:139], v[108:111], v[200:203], v[136:139]
	v_mfma_f32_16x16x32_bf16 v[116:119], v[100:103], v[228:231], v[116:119]
	v_mfma_f32_16x16x32_bf16 v[112:115], v[108:111], v[228:231], v[112:115]
	v_mfma_f32_16x16x32_bf16 v[156:159], v[104:107], v[168:171], v[156:159]
	v_mfma_f32_16x16x32_bf16 v[152:155], v[120:123], v[168:171], v[152:155]
	v_mfma_f32_16x16x32_bf16 v[148:151], v[104:107], v[196:199], v[148:151]
	v_mfma_f32_16x16x32_bf16 v[144:147], v[120:123], v[196:199], v[144:147]
	v_mfma_f32_16x16x32_bf16 v[140:143], v[104:107], v[204:207], v[140:143]
	v_mfma_f32_16x16x32_bf16 v[136:139], v[120:123], v[204:207], v[136:139]
	v_mfma_f32_16x16x32_bf16 v[116:119], v[104:107], v[232:235], v[116:119]
	v_mfma_f32_16x16x32_bf16 v[112:115], v[120:123], v[232:235], v[112:115]
	s_setprio 0
	s_setprio 1
	v_mfma_f32_16x16x32_bf16 v[60:63], v[124:127], v[164:167], v[60:63]
	v_mfma_f32_16x16x32_bf16 v[56:59], v[132:135], v[164:167], v[56:59]
	v_mfma_f32_16x16x32_bf16 v[52:55], v[124:127], v[192:195], v[52:55]
	v_mfma_f32_16x16x32_bf16 v[48:51], v[132:135], v[192:195], v[48:51]
	v_mfma_f32_16x16x32_bf16 v[44:47], v[124:127], v[200:203], v[44:47]
	v_mfma_f32_16x16x32_bf16 v[40:43], v[132:135], v[200:203], v[40:43]
	v_mfma_f32_16x16x32_bf16 v[36:39], v[124:127], v[228:231], v[36:39]
	v_mfma_f32_16x16x32_bf16 v[32:35], v[132:135], v[228:231], v[32:35]
	v_mfma_f32_16x16x32_bf16 v[60:63], v[128:131], v[168:171], v[60:63]
	v_mfma_f32_16x16x32_bf16 v[56:59], v[160:163], v[168:171], v[56:59]
	v_mfma_f32_16x16x32_bf16 v[52:55], v[128:131], v[196:199], v[52:55]
	v_mfma_f32_16x16x32_bf16 v[48:51], v[160:163], v[196:199], v[48:51]
	v_mfma_f32_16x16x32_bf16 v[44:47], v[128:131], v[204:207], v[44:47]
	v_mfma_f32_16x16x32_bf16 v[40:43], v[160:163], v[204:207], v[40:43]
	v_mfma_f32_16x16x32_bf16 v[36:39], v[128:131], v[232:235], v[36:39]
	v_mfma_f32_16x16x32_bf16 v[32:35], v[160:163], v[232:235], v[32:35]
	s_setprio 0
	s_barrier
	s_add_i32 s70, s69, s56
	v_lshl_add_u64 v[236:237], s[46:47], 0, v[174:175]
	s_mov_b32 m0, s70
	ds_read_b128 v[164:167], v209 offset:16384
	ds_read_b128 v[168:171], v209 offset:17408
	ds_read_b128 v[192:195], v209 offset:18432
	ds_read_b128 v[196:199], v209 offset:19456
	ds_read_b128 v[200:203], v209 offset:20480
	ds_read_b128 v[204:207], v209 offset:21504
	ds_read_b128 v[228:231], v209 offset:22528
	ds_read_b128 v[232:235], v209 offset:23552
	global_load_lds_dwordx4 v[236:237], off
	s_add_i32 m0, s70, 0x2000
	s_add_u32 s70, s46, 0x40000
	v_lshl_add_u64 v[238:239], s[46:47], 0, v[178:179]
	s_addc_u32 s71, s47, 0
	s_add_i32 s86, s80, s56
	global_load_lds_dwordx4 v[238:239], off
	v_lshl_add_u64 v[240:241], s[70:71], 0, v[174:175]
	s_mov_b32 m0, s86
	s_nop 0
	global_load_lds_dwordx4 v[240:241], off
	v_lshl_add_u64 v[240:241], s[70:71], 0, v[178:179]
	s_add_i32 m0, s86, 0x2000
	s_nop 0
	global_load_lds_dwordx4 v[240:241], off
	s_waitcnt vmcnt(6)
	s_waitcnt lgkmcnt(0)
	s_barrier
; #define PG8_STAGE(bufoff, gbase, voff) do { _Pragma("unroll") for (int _i = 0; _i < 2; ++_i) \
;         __builtin_amdgcn_global_load_lds((const unsigned*)((const char*)(gbase) + (voff)[_i]), (PG8_LAS unsigned*)(lds + (bufoff) + ldsw + _i * 8192), 16, 0, 0); } while (0)
; #define PG8_LDA(dst, b, h) do { _Pragma("unroll") for (int m = 0; m < 4; ++m) _Pragma("unroll") for (int k = 0; k < 2; ++k) dst[m][k] = *(const PG8_LAS bf16x8*)(lds + PG8_SA(b, h) + aoff + m * 2048 + k * 1024); } while (0)
; #define PG8_LDB(dst, b, h) do { _Pragma("unroll") for (int n = 0; n < 2; ++n) _Pragma("unroll") for (int k = 0; k < 2; ++k) dst[n][k] = *(const PG8_LAS bf16x8*)(lds + PG8_SB(b, h) + boff + n * 2048 + k * 1024); } while (0)
; #define PG8_MMA(ai, bj, At, Bt) do { __builtin_amdgcn_s_setprio(1); _Pragma("unroll") for (int m = 0; m < 4; ++m) _Pragma("unroll") for (int n = 0; n < 2; ++n) _Pragma("unroll") for (int k = 0; k < 2; ++k) \
;         acc[ai][bj][m][n] = __builtin_amdgcn_mfma_f32_16x16x32_bf16(Bt[n][k], At[m][k], acc[ai][bj][m][n], 0, 0, 0); __builtin_amdgcn_s_setprio(0); } while (0)
; #define PG8_WAIT_V(n) asm volatile("s_waitcnt vmcnt(" #n ")" ::: "memory")
; #define PG8_WAIT_L(n) asm volatile("s_waitcnt lgkmcnt(" #n ")" ::: "memory")
; #define PG8_BAR __builtin_amdgcn_s_barrier()
; #define PG8_SCHED __builtin_amdgcn_sched_barrier(0)
; template <class Epi, class Sched, bool ALIGN_EPI = false, bool SP2 = false>
; __device__ __forceinline__ void gemm_phase(PG8_LAS unsigned char* lds, const Gemm g, const Sched& S, const Epi& E) {
;     ...
;             PG8_WAIT_V(8); PG8_WAIT_L(0); PG8_BAR; PG8_MMA(1, 0, At, B0); PG8_MMA(1, 1, At, B1); PG8_BAR; PG8_SCHED;
;             PG8_LDB(B0, 1, 0); PG8_LDB(B1, 1, 1); PG8_SCHED; PG8_LDA(At, 1, 0); PG8_STAGE(PG8_SA(0, 1), a2 + hstepA, voffA);
;             PG8_WAIT_V(8); PG8_WAIT_L(0); PG8_BAR; PG8_MMA(0, 0, At, B0); PG8_MMA(0, 1, At, B1); PG8_BAR; PG8_SCHED;
	s_setprio 1
	s_waitcnt lgkmcnt(0)
	v_mfma_f32_16x16x32_bf16 v[92:95], v[100:103], v[164:167], v[92:95]
	v_mfma_f32_16x16x32_bf16 v[88:91], v[108:111], v[164:167], v[88:91]
	v_mfma_f32_16x16x32_bf16 v[84:87], v[100:103], v[192:195], v[84:87]
	v_mfma_f32_16x16x32_bf16 v[80:83], v[108:111], v[192:195], v[80:83]
	v_mfma_f32_16x16x32_bf16 v[76:79], v[100:103], v[200:203], v[76:79]
	v_mfma_f32_16x16x32_bf16 v[72:75], v[108:111], v[200:203], v[72:75]
	v_mfma_f32_16x16x32_bf16 v[68:71], v[100:103], v[228:231], v[68:71]
	v_mfma_f32_16x16x32_bf16 v[64:67], v[108:111], v[228:231], v[64:67]
	v_mfma_f32_16x16x32_bf16 v[92:95], v[104:107], v[168:171], v[92:95]
	v_mfma_f32_16x16x32_bf16 v[88:91], v[120:123], v[168:171], v[88:91]
	v_mfma_f32_16x16x32_bf16 v[84:87], v[104:107], v[196:199], v[84:87]
	v_mfma_f32_16x16x32_bf16 v[80:83], v[120:123], v[196:199], v[80:83]
	v_mfma_f32_16x16x32_bf16 v[76:79], v[104:107], v[204:207], v[76:79]
	v_mfma_f32_16x16x32_bf16 v[72:75], v[120:123], v[204:207], v[72:75]
	v_mfma_f32_16x16x32_bf16 v[68:71], v[104:107], v[232:235], v[68:71]
	v_mfma_f32_16x16x32_bf16 v[64:67], v[120:123], v[232:235], v[64:67]
	s_setprio 0
	s_setprio 1
	v_mfma_f32_16x16x32_bf16 v[28:31], v[124:127], v[164:167], v[28:31]
	v_mfma_f32_16x16x32_bf16 v[24:27], v[132:135], v[164:167], v[24:27]
	v_mfma_f32_16x16x32_bf16 v[20:23], v[124:127], v[192:195], v[20:23]
	v_mfma_f32_16x16x32_bf16 v[16:19], v[132:135], v[192:195], v[16:19]
	v_mfma_f32_16x16x32_bf16 v[12:15], v[124:127], v[200:203], v[12:15]
	v_mfma_f32_16x16x32_bf16 v[8:11], v[132:135], v[200:203], v[8:11]
	v_mfma_f32_16x16x32_bf16 v[4:7], v[124:127], v[228:231], v[4:7]
	v_mfma_f32_16x16x32_bf16 v[0:3], v[132:135], v[228:231], v[0:3]
	v_mfma_f32_16x16x32_bf16 v[28:31], v[128:131], v[168:171], v[28:31]
	v_mfma_f32_16x16x32_bf16 v[24:27], v[160:163], v[168:171], v[24:27]
	v_mfma_f32_16x16x32_bf16 v[20:23], v[128:131], v[196:199], v[20:23]
	v_mfma_f32_16x16x32_bf16 v[16:19], v[160:163], v[196:199], v[16:19]
	v_mfma_f32_16x16x32_bf16 v[12:15], v[128:131], v[204:207], v[12:15]
	v_mfma_f32_16x16x32_bf16 v[8:11], v[160:163], v[204:207], v[8:11]
	v_mfma_f32_16x16x32_bf16 v[4:7], v[128:131], v[232:235], v[4:7]
	v_mfma_f32_16x16x32_bf16 v[0:3], v[160:163], v[232:235], v[0:3]
	s_setprio 0
	s_barrier
	s_add_i32 s70, 0, 0x18000
	s_add_i32 s71, 0, 0x1c000
	v_add_u32_e32 v120, s70, v189
	v_add_u32_e32 v160, s71, v189
	ds_read_b128 v[100:103], v120
	ds_read_b128 v[104:107], v120 offset:1024
	ds_read_b128 v[108:111], v120 offset:2048
	ds_read_b128 v[120:123], v120 offset:3072
	ds_read_b128 v[124:127], v160
	ds_read_b128 v[128:131], v160 offset:1024
	ds_read_b128 v[132:135], v160 offset:2048
	ds_read_b128 v[160:163], v160 offset:3072
	v_lshl_add_u64 v[240:241], s[48:49], 0, v[172:173]
	s_mov_b32 m0, s57
	s_nop 0
	global_load_lds_dwordx4 v[240:241], off
	v_lshl_add_u64 v[240:241], s[48:49], 0, v[176:177]
	s_mov_b32 m0, s58
	s_nop 0
	global_load_lds_dwordx4 v[240:241], off
	s_add_u32 s48, s48, 0x40000
	s_addc_u32 s49, s49, 0
	s_mov_b32 m0, s59
	v_lshl_add_u64 v[240:241], s[48:49], 0, v[172:173]
	ds_read_b128 v[164:167], v209 offset:32768
	ds_read_b128 v[168:171], v209 offset:33792
	ds_read_b128 v[192:195], v209 offset:34816
	ds_read_b128 v[196:199], v209 offset:35840
	ds_read_b128 v[200:203], v209 offset:36864
	ds_read_b128 v[204:207], v209 offset:37888
	ds_read_b128 v[228:231], v209 offset:38912
	ds_read_b128 v[232:235], v209 offset:39936
	global_load_lds_dwordx4 v[240:241], off
	v_lshl_add_u64 v[240:241], s[48:49], 0, v[176:177]
	s_mov_b32 m0, s60
	s_nop 0
	global_load_lds_dwordx4 v[240:241], off
	s_waitcnt vmcnt(8)
	s_waitcnt lgkmcnt(0)
	s_barrier
	s_setprio 1
	s_waitcnt lgkmcnt(0)
	v_mfma_f32_16x16x32_bf16 v[156:159], v[100:103], v[164:167], v[156:159]
	v_mfma_f32_16x16x32_bf16 v[152:155], v[108:111], v[164:167], v[152:155]
	v_mfma_f32_16x16x32_bf16 v[148:151], v[100:103], v[192:195], v[148:151]
	v_mfma_f32_16x16x32_bf16 v[144:147], v[108:111], v[192:195], v[144:147]
	v_mfma_f32_16x16x32_bf16 v[140:143], v[100:103], v[200:203], v[140:143]
	v_mfma_f32_16x16x32_bf16 v[136:139], v[108:111], v[200:203], v[136:139]
	v_mfma_f32_16x16x32_bf16 v[116:119], v[100:103], v[228:231], v[116:119]
	v_mfma_f32_16x16x32_bf16 v[112:115], v[108:111], v[228:231], v[112:115]
	v_mfma_f32_16x16x32_bf16 v[156:159], v[104:107], v[168:171], v[156:159]
	v_mfma_f32_16x16x32_bf16 v[152:155], v[120:123], v[168:171], v[152:155]
	v_mfma_f32_16x16x32_bf16 v[148:151], v[104:107], v[196:199], v[148:151]
	v_mfma_f32_16x16x32_bf16 v[144:147], v[120:123], v[196:199], v[144:147]
	v_mfma_f32_16x16x32_bf16 v[140:143], v[104:107], v[204:207], v[140:143]
	v_mfma_f32_16x16x32_bf16 v[136:139], v[120:123], v[204:207], v[136:139]
	v_mfma_f32_16x16x32_bf16 v[116:119], v[104:107], v[232:235], v[116:119]
	v_mfma_f32_16x16x32_bf16 v[112:115], v[120:123], v[232:235], v[112:115]
	s_setprio 0
	s_setprio 1
	v_mfma_f32_16x16x32_bf16 v[60:63], v[124:127], v[164:167], v[60:63]
	v_mfma_f32_16x16x32_bf16 v[56:59], v[132:135], v[164:167], v[56:59]
	v_mfma_f32_16x16x32_bf16 v[52:55], v[124:127], v[192:195], v[52:55]
	v_mfma_f32_16x16x32_bf16 v[48:51], v[132:135], v[192:195], v[48:51]
	v_mfma_f32_16x16x32_bf16 v[44:47], v[124:127], v[200:203], v[44:47]
	v_mfma_f32_16x16x32_bf16 v[40:43], v[132:135], v[200:203], v[40:43]
	v_mfma_f32_16x16x32_bf16 v[36:39], v[124:127], v[228:231], v[36:39]
	v_mfma_f32_16x16x32_bf16 v[32:35], v[132:135], v[228:231], v[32:35]
	v_mfma_f32_16x16x32_bf16 v[60:63], v[128:131], v[168:171], v[60:63]
	v_mfma_f32_16x16x32_bf16 v[56:59], v[160:163], v[168:171], v[56:59]
	v_mfma_f32_16x16x32_bf16 v[52:55], v[128:131], v[196:199], v[52:55]
	v_mfma_f32_16x16x32_bf16 v[48:51], v[160:163], v[196:199], v[48:51]
	v_mfma_f32_16x16x32_bf16 v[44:47], v[128:131], v[204:207], v[44:47]
	v_mfma_f32_16x16x32_bf16 v[40:43], v[160:163], v[204:207], v[40:43]
	v_mfma_f32_16x16x32_bf16 v[36:39], v[128:131], v[232:235], v[36:39]
	v_mfma_f32_16x16x32_bf16 v[32:35], v[160:163], v[232:235], v[32:35]
	s_setprio 0
	s_barrier
; #define PG8_STAGE(bufoff, gbase, voff) do { _Pragma("unroll") for (int _i = 0; _i < 2; ++_i) \
;         __builtin_amdgcn_global_load_lds((const unsigned*)((const char*)(gbase) + (voff)[_i]), (PG8_LAS unsigned*)(lds + (bufoff) + ldsw + _i * 8192), 16, 0, 0); } while (0)
; #define PG8_LDA(dst, b, h) do { _Pragma("unroll") for (int m = 0; m < 4; ++m) _Pragma("unroll") for (int k = 0; k < 2; ++k) dst[m][k] = *(const PG8_LAS bf16x8*)(lds + PG8_SA(b, h) + aoff + m * 2048 + k * 1024); } while (0)
; #define PG8_MMA(ai, bj, At, Bt) do { __builtin_amdgcn_s_setprio(1); _Pragma("unroll") for (int m = 0; m < 4; ++m) _Pragma("unroll") for (int n = 0; n < 2; ++n) _Pragma("unroll") for (int k = 0; k < 2; ++k) \
;         acc[ai][bj][m][n] = __builtin_amdgcn_mfma_f32_16x16x32_bf16(Bt[n][k], At[m][k], acc[ai][bj][m][n], 0, 0, 0); __builtin_amdgcn_s_setprio(0); } while (0)
; #define PG8_WAIT_V(n) asm volatile("s_waitcnt vmcnt(" #n ")" ::: "memory")
; #define PG8_WAIT_L(n) asm volatile("s_waitcnt lgkmcnt(" #n ")" ::: "memory")
; #define PG8_BAR __builtin_amdgcn_s_barrier()
; #define PG8_SCHED __builtin_amdgcn_sched_barrier(0)
; template <class Epi, class Sched, bool ALIGN_EPI = false, bool SP2 = false>
; __device__ __forceinline__ void gemm_phase(PG8_LAS unsigned char* lds, const Gemm g, const Sched& S, const Epi& E) {
;     ...
;             PG8_LDA(At, 1, 1); PG8_STAGE(PG8_SB(1, 0), b3, voffB); PG8_STAGE(PG8_SB(1, 1), b3 + hstepB, voffB); PG8_STAGE(PG8_SA(1, 0), a3, voffA);
;             PG8_WAIT_V(8); PG8_WAIT_L(0); PG8_BAR; PG8_MMA(1, 0, At, B0); PG8_MMA(1, 1, At, B1); PG8_BAR; PG8_SCHED;
	s_add_i32 s48, s70, s56
	v_lshl_add_u64 v[236:237], v[236:237], 0, s[10:11]
	s_mov_b32 m0, s48
	ds_read_b128 v[164:167], v209 offset:49152
	ds_read_b128 v[168:171], v209 offset:50176
	ds_read_b128 v[192:195], v209 offset:51200
	ds_read_b128 v[196:199], v209 offset:52224
	ds_read_b128 v[200:203], v209 offset:53248
	ds_read_b128 v[204:207], v209 offset:54272
	ds_read_b128 v[228:231], v209 offset:55296
	ds_read_b128 v[232:235], v209 offset:56320
	global_load_lds_dwordx4 v[236:237], off
	s_add_i32 m0, s48, 0x2000
	s_add_u32 s46, s46, 0x40080
	v_lshl_add_u64 v[236:237], v[238:239], 0, s[10:11]
	s_addc_u32 s47, s47, 0
	s_add_i32 s48, s71, s56
	global_load_lds_dwordx4 v[236:237], off
	v_lshl_add_u64 v[236:237], s[46:47], 0, v[174:175]
	s_mov_b32 m0, s48
	s_nop 0
	global_load_lds_dwordx4 v[236:237], off
	v_lshl_add_u64 v[236:237], s[46:47], 0, v[178:179]
	s_add_i32 m0, s48, 0x2000
	s_nop 0
	global_load_lds_dwordx4 v[236:237], off
	v_lshl_add_u64 v[236:237], s[44:45], 0, v[172:173]
	s_mov_b32 m0, s66
	s_nop 0
	global_load_lds_dwordx4 v[236:237], off
	v_lshl_add_u64 v[236:237], s[44:45], 0, v[176:177]
	s_mov_b32 m0, s67
	s_nop 0
	global_load_lds_dwordx4 v[236:237], off
	s_waitcnt vmcnt(8)
	s_waitcnt lgkmcnt(0)
	s_barrier
	s_setprio 1
	s_waitcnt lgkmcnt(0)
	v_mfma_f32_16x16x32_bf16 v[92:95], v[100:103], v[164:167], v[92:95]
	v_mfma_f32_16x16x32_bf16 v[88:91], v[108:111], v[164:167], v[88:91]
	v_mfma_f32_16x16x32_bf16 v[84:87], v[100:103], v[192:195], v[84:87]
	v_mfma_f32_16x16x32_bf16 v[80:83], v[108:111], v[192:195], v[80:83]
	v_mfma_f32_16x16x32_bf16 v[76:79], v[100:103], v[200:203], v[76:79]
	v_mfma_f32_16x16x32_bf16 v[72:75], v[108:111], v[200:203], v[72:75]
	v_mfma_f32_16x16x32_bf16 v[68:71], v[100:103], v[228:231], v[68:71]
	v_mfma_f32_16x16x32_bf16 v[64:67], v[108:111], v[228:231], v[64:67]
	v_mfma_f32_16x16x32_bf16 v[92:95], v[104:107], v[168:171], v[92:95]
	v_mfma_f32_16x16x32_bf16 v[88:91], v[120:123], v[168:171], v[88:91]
	v_mfma_f32_16x16x32_bf16 v[84:87], v[104:107], v[196:199], v[84:87]
	v_mfma_f32_16x16x32_bf16 v[80:83], v[120:123], v[196:199], v[80:83]
	v_mfma_f32_16x16x32_bf16 v[76:79], v[104:107], v[204:207], v[76:79]
	v_mfma_f32_16x16x32_bf16 v[72:75], v[120:123], v[204:207], v[72:75]
	v_mfma_f32_16x16x32_bf16 v[68:71], v[104:107], v[232:235], v[68:71]
	v_mfma_f32_16x16x32_bf16 v[64:67], v[120:123], v[232:235], v[64:67]
	s_setprio 0
	s_setprio 1
	v_mfma_f32_16x16x32_bf16 v[28:31], v[124:127], v[164:167], v[28:31]
	v_mfma_f32_16x16x32_bf16 v[24:27], v[132:135], v[164:167], v[24:27]
	v_mfma_f32_16x16x32_bf16 v[20:23], v[124:127], v[192:195], v[20:23]
	v_mfma_f32_16x16x32_bf16 v[16:19], v[132:135], v[192:195], v[16:19]
	v_mfma_f32_16x16x32_bf16 v[12:15], v[124:127], v[200:203], v[12:15]
	v_mfma_f32_16x16x32_bf16 v[8:11], v[132:135], v[200:203], v[8:11]
	v_mfma_f32_16x16x32_bf16 v[4:7], v[124:127], v[228:231], v[4:7]
	v_mfma_f32_16x16x32_bf16 v[0:3], v[132:135], v[228:231], v[0:3]
	v_mfma_f32_16x16x32_bf16 v[28:31], v[128:131], v[168:171], v[28:31]
	v_mfma_f32_16x16x32_bf16 v[24:27], v[160:163], v[168:171], v[24:27]
	v_mfma_f32_16x16x32_bf16 v[20:23], v[128:131], v[196:199], v[20:23]
	v_mfma_f32_16x16x32_bf16 v[16:19], v[160:163], v[196:199], v[16:19]
	v_mfma_f32_16x16x32_bf16 v[12:15], v[128:131], v[204:207], v[12:15]
	v_mfma_f32_16x16x32_bf16 v[8:11], v[160:163], v[204:207], v[8:11]
	v_mfma_f32_16x16x32_bf16 v[4:7], v[128:131], v[232:235], v[4:7]
	v_mfma_f32_16x16x32_bf16 v[0:3], v[160:163], v[232:235], v[0:3]
	s_setprio 0
	s_barrier
	s_add_i32 s85, s85, 2
	s_add_u32 s42, s42, 0x100
	s_addc_u32 s43, s43, 0
	s_cmp_gt_u32 s85, 13
	s_cbranch_scc0 .LBB0_612
	s_and_b64 vcc, exec, s[24:25]
	s_cbranch_vccz .LBB0_615
	s_barrier

; #define PG8_STAGE(bufoff, gbase, voff) do { _Pragma("unroll") for (int _i = 0; _i < 2; ++_i) \
;         __builtin_amdgcn_global_load_lds((const unsigned*)((const char*)(gbase) + (voff)[_i]), (PG8_LAS unsigned*)(lds + (bufoff) + ldsw + _i * 8192), 16, 0, 0); } while (0)
; #define PG8_LDA(dst, b, h) do { _Pragma("unroll") for (int m = 0; m < 4; ++m) _Pragma("unroll") for (int k = 0; k < 2; ++k) dst[m][k] = *(const PG8_LAS bf16x8*)(lds + PG8_SA(b, h) + aoff + m * 2048 + k * 1024); } while (0)
; #define PG8_LDB(dst, b, h) do { _Pragma("unroll") for (int n = 0; n < 2; ++n) _Pragma("unroll") for (int k = 0; k < 2; ++k) dst[n][k] = *(const PG8_LAS bf16x8*)(lds + PG8_SB(b, h) + boff + n * 2048 + k * 1024); } while (0)
; #define PG8_MMA(ai, bj, At, Bt) do { __builtin_amdgcn_s_setprio(1); _Pragma("unroll") for (int m = 0; m < 4; ++m) _Pragma("unroll") for (int n = 0; n < 2; ++n) _Pragma("unroll") for (int k = 0; k < 2; ++k) \
;         acc[ai][bj][m][n] = __builtin_amdgcn_mfma_f32_16x16x32_bf16(Bt[n][k], At[m][k], acc[ai][bj][m][n], 0, 0, 0); __builtin_amdgcn_s_setprio(0); } while (0)
; #define PG8_WAIT_V(n) asm volatile("s_waitcnt vmcnt(" #n ")" ::: "memory")
; #define PG8_WAIT_L(n) asm volatile("s_waitcnt lgkmcnt(" #n ")" ::: "memory")
; template <class Epi, class Sched, bool ALIGN_EPI = false, bool SP2 = false>
; __device__ __forceinline__ void gemm_phase(PG8_LAS unsigned char* lds, const Gemm g, const Sched& S, const Epi& E) {
;     ...
;             const bool last = (t == nt - 2);
;             const char* a1 = cA + PG8_AK(t + 1);
;             const char* a2 = last ? nA : cA + PG8_AK(t + 2); const char* b2 = last ? nB : cB + (size_t)(t + 2) * kstep;
;             const char* a3 = last ? nA + PG8_AK(1) : cA + PG8_AK(t + 3); const char* b3 = b2 + kstep;
;             if (last && has_next) S.a_ready(nxt);
;             if constexpr (SP2) {
;             PG8_LDB(B0, 0, 0); PG8_LDB(B1, 0, 1); PG8_SCHED; PG8_LDA(At, 0, 0); PG8_STAGE(PG8_SA(1, 1), a1 + hstepA, voffA);
;             PG8_WAIT_V(8); PG8_WAIT_L(0); PG8_BAR; PG8_MMA(0, 0, At, B0); PG8_MMA(0, 1, At, B1); PG8_BAR; PG8_SCHED;
;             PG8_LDA(At, 0, 1); PG8_STAGE(PG8_SB(0, 0), b2, voffB); PG8_STAGE(PG8_SB(0, 1), b2 + hstepB, voffB); PG8_STAGE(PG8_SA(0, 0), a2, voffA);
;             PG8_WAIT_V(8); PG8_WAIT_L(0); PG8_BAR; PG8_MMA(1, 0, At, B0); PG8_MMA(1, 1, At, B1); PG8_BAR; PG8_SCHED;
.LBB0_782:
	ds_read_b128 v[100:103], v167
	ds_read_b128 v[154:157], v167 offset:1024
	ds_read_b128 v[158:161], v167 offset:2048
	ds_read_b128 v[170:173], v167 offset:3072
	ds_read_b128 v[174:177], v168
	ds_read_b128 v[178:181], v168 offset:1024
	ds_read_b128 v[182:185], v168 offset:2048
	ds_read_b128 v[186:189], v168 offset:3072
	s_add_u32 s36, s6, s34
	s_addc_u32 s37, s7, s35
	s_add_u32 s40, s36, 0x100
	s_addc_u32 s41, s37, 0
	s_add_u32 s38, s62, s34
	s_addc_u32 s39, s63, s35
	s_add_u32 s36, s36, 0x180
	s_addc_u32 s37, s37, 0
	s_cmpk_eq_i32 s34, 0x700
	s_cselect_b32 s37, s61, s37
	s_cselect_b32 s36, s31, s36
	s_cselect_b32 s39, s23, s39
	s_cselect_b32 s38, s25, s38
	s_cselect_b32 s41, s3, s41
	s_cselect_b32 s40, s9, s40
	v_lshl_add_u64 v[162:163], v[98:99], 0, s[34:35]
	s_add_i32 m0, s47, 0xc000
	ds_read_b128 v[190:193], v169
	ds_read_b128 v[194:197], v169 offset:1024
	ds_read_b128 v[198:201], v169 offset:2048
	ds_read_b128 v[202:205], v169 offset:3072
	ds_read_b128 v[206:209], v169 offset:4096
	ds_read_b128 v[210:213], v169 offset:5120
	ds_read_b128 v[214:217], v169 offset:6144
	ds_read_b128 v[218:221], v169 offset:7168
	global_load_lds_dwordx4 v[162:163], off
	v_lshl_add_u64 v[162:163], v[96:97], 0, s[34:35]
	s_add_i32 m0, s47, 0xe000
	s_nop 0
	global_load_lds_dwordx4 v[162:163], off
	s_waitcnt vmcnt(8)
	s_waitcnt lgkmcnt(0)
	s_barrier
	s_setprio 1
	s_waitcnt lgkmcnt(0)
	v_mfma_f32_16x16x32_bf16 v[132:135], v[100:103], v[190:193], v[132:135]
	v_mfma_f32_16x16x32_bf16 v[128:131], v[158:161], v[190:193], v[128:131]
	v_mfma_f32_16x16x32_bf16 v[124:127], v[100:103], v[198:201], v[124:127]
	v_mfma_f32_16x16x32_bf16 v[120:123], v[158:161], v[198:201], v[120:123]
	v_mfma_f32_16x16x32_bf16 v[116:119], v[100:103], v[206:209], v[116:119]
	v_mfma_f32_16x16x32_bf16 v[112:115], v[158:161], v[206:209], v[112:115]
	v_mfma_f32_16x16x32_bf16 v[108:111], v[100:103], v[214:217], v[108:111]
	v_mfma_f32_16x16x32_bf16 v[104:107], v[158:161], v[214:217], v[104:107]
	v_mfma_f32_16x16x32_bf16 v[132:135], v[154:157], v[194:197], v[132:135]
	v_mfma_f32_16x16x32_bf16 v[128:131], v[170:173], v[194:197], v[128:131]
	v_mfma_f32_16x16x32_bf16 v[124:127], v[154:157], v[202:205], v[124:127]
	v_mfma_f32_16x16x32_bf16 v[120:123], v[170:173], v[202:205], v[120:123]
	v_mfma_f32_16x16x32_bf16 v[116:119], v[154:157], v[210:213], v[116:119]
	v_mfma_f32_16x16x32_bf16 v[112:115], v[170:173], v[210:213], v[112:115]
	v_mfma_f32_16x16x32_bf16 v[108:111], v[154:157], v[218:221], v[108:111]
	v_mfma_f32_16x16x32_bf16 v[104:107], v[170:173], v[218:221], v[104:107]
	s_setprio 0
	s_setprio 1
	v_mfma_f32_16x16x32_bf16 v[60:63], v[174:177], v[190:193], v[60:63]
	v_mfma_f32_16x16x32_bf16 v[56:59], v[182:185], v[190:193], v[56:59]
	v_mfma_f32_16x16x32_bf16 v[52:55], v[174:177], v[198:201], v[52:55]
	v_mfma_f32_16x16x32_bf16 v[48:51], v[182:185], v[198:201], v[48:51]
	v_mfma_f32_16x16x32_bf16 v[44:47], v[174:177], v[206:209], v[44:47]
	v_mfma_f32_16x16x32_bf16 v[40:43], v[182:185], v[206:209], v[40:43]
	v_mfma_f32_16x16x32_bf16 v[36:39], v[174:177], v[214:217], v[36:39]
	v_mfma_f32_16x16x32_bf16 v[32:35], v[182:185], v[214:217], v[32:35]
	v_mfma_f32_16x16x32_bf16 v[60:63], v[178:181], v[194:197], v[60:63]
	v_mfma_f32_16x16x32_bf16 v[56:59], v[186:189], v[194:197], v[56:59]
	v_mfma_f32_16x16x32_bf16 v[52:55], v[178:181], v[202:205], v[52:55]
	v_mfma_f32_16x16x32_bf16 v[48:51], v[186:189], v[202:205], v[48:51]
	v_mfma_f32_16x16x32_bf16 v[44:47], v[178:181], v[210:213], v[44:47]
	v_mfma_f32_16x16x32_bf16 v[40:43], v[186:189], v[210:213], v[40:43]
	v_mfma_f32_16x16x32_bf16 v[36:39], v[178:181], v[218:221], v[36:39]
	v_mfma_f32_16x16x32_bf16 v[32:35], v[186:189], v[218:221], v[32:35]
	s_setprio 0
	s_barrier
	s_add_i32 s65, s58, s46
	v_lshl_add_u64 v[162:163], s[38:39], 0, v[138:139]
	s_mov_b32 m0, s65
	ds_read_b128 v[190:193], v169 offset:16384
	ds_read_b128 v[194:197], v169 offset:17408
	ds_read_b128 v[198:201], v169 offset:18432
	ds_read_b128 v[202:205], v169 offset:19456
	ds_read_b128 v[206:209], v169 offset:20480
	ds_read_b128 v[210:213], v169 offset:21504
	ds_read_b128 v[214:217], v169 offset:22528
	ds_read_b128 v[218:221], v169 offset:23552
	global_load_lds_dwordx4 v[162:163], off
	s_add_i32 m0, s65, 0x2000
	s_add_u32 s66, s38, 0x40000
	v_lshl_add_u64 v[222:223], s[38:39], 0, v[142:143]
	s_addc_u32 s67, s39, 0
	s_add_i32 s65, s59, s46
	global_load_lds_dwordx4 v[222:223], off
	v_lshl_add_u64 v[224:225], s[66:67], 0, v[138:139]
	s_mov_b32 m0, s65
	s_nop 0
	global_load_lds_dwordx4 v[224:225], off
	v_lshl_add_u64 v[224:225], s[66:67], 0, v[142:143]
	s_add_i32 m0, s65, 0x2000
	s_nop 0
	global_load_lds_dwordx4 v[224:225], off
	s_waitcnt vmcnt(6)
	s_waitcnt lgkmcnt(0)
	s_barrier
; #define PG8_STAGE(bufoff, gbase, voff) do { _Pragma("unroll") for (int _i = 0; _i < 2; ++_i) \
;         __builtin_amdgcn_global_load_lds((const unsigned*)((const char*)(gbase) + (voff)[_i]), (PG8_LAS unsigned*)(lds + (bufoff) + ldsw + _i * 8192), 16, 0, 0); } while (0)
; #define PG8_LDA(dst, b, h) do { _Pragma("unroll") for (int m = 0; m < 4; ++m) _Pragma("unroll") for (int k = 0; k < 2; ++k) dst[m][k] = *(const PG8_LAS bf16x8*)(lds + PG8_SA(b, h) + aoff + m * 2048 + k * 1024); } while (0)
; #define PG8_LDB(dst, b, h) do { _Pragma("unroll") for (int n = 0; n < 2; ++n) _Pragma("unroll") for (int k = 0; k < 2; ++k) dst[n][k] = *(const PG8_LAS bf16x8*)(lds + PG8_SB(b, h) + boff + n * 2048 + k * 1024); } while (0)
; #define PG8_MMA(ai, bj, At, Bt) do { __builtin_amdgcn_s_setprio(1); _Pragma("unroll") for (int m = 0; m < 4; ++m) _Pragma("unroll") for (int n = 0; n < 2; ++n) _Pragma("unroll") for (int k = 0; k < 2; ++k) \
;         acc[ai][bj][m][n] = __builtin_amdgcn_mfma_f32_16x16x32_bf16(Bt[n][k], At[m][k], acc[ai][bj][m][n], 0, 0, 0); __builtin_amdgcn_s_setprio(0); } while (0)
; #define PG8_WAIT_V(n) asm volatile("s_waitcnt vmcnt(" #n ")" ::: "memory")
; #define PG8_WAIT_L(n) asm volatile("s_waitcnt lgkmcnt(" #n ")" ::: "memory")
; #define PG8_BAR __builtin_amdgcn_s_barrier()
; #define PG8_SCHED __builtin_amdgcn_sched_barrier(0)
; template <class Epi, class Sched, bool ALIGN_EPI = false, bool SP2 = false>
; __device__ __forceinline__ void gemm_phase(PG8_LAS unsigned char* lds, const Gemm g, const Sched& S, const Epi& E) {
;     ...
;             PG8_WAIT_V(8); PG8_WAIT_L(0); PG8_BAR; PG8_MMA(1, 0, At, B0); PG8_MMA(1, 1, At, B1); PG8_BAR; PG8_SCHED;
;             PG8_LDB(B0, 1, 0); PG8_LDB(B1, 1, 1); PG8_SCHED; PG8_LDA(At, 1, 0); PG8_STAGE(PG8_SA(0, 1), a2 + hstepA, voffA);
;             PG8_WAIT_V(8); PG8_WAIT_L(0); PG8_BAR; PG8_MMA(0, 0, At, B0); PG8_MMA(0, 1, At, B1); PG8_BAR; PG8_SCHED;
	s_setprio 1
	s_waitcnt lgkmcnt(0)
	v_mfma_f32_16x16x32_bf16 v[92:95], v[100:103], v[190:193], v[92:95]
	v_mfma_f32_16x16x32_bf16 v[88:91], v[158:161], v[190:193], v[88:91]
	v_mfma_f32_16x16x32_bf16 v[84:87], v[100:103], v[198:201], v[84:87]
	v_mfma_f32_16x16x32_bf16 v[80:83], v[158:161], v[198:201], v[80:83]
	v_mfma_f32_16x16x32_bf16 v[76:79], v[100:103], v[206:209], v[76:79]
	v_mfma_f32_16x16x32_bf16 v[72:75], v[158:161], v[206:209], v[72:75]
	v_mfma_f32_16x16x32_bf16 v[68:71], v[100:103], v[214:217], v[68:71]
	v_mfma_f32_16x16x32_bf16 v[64:67], v[158:161], v[214:217], v[64:67]
	v_mfma_f32_16x16x32_bf16 v[92:95], v[154:157], v[194:197], v[92:95]
	v_mfma_f32_16x16x32_bf16 v[88:91], v[170:173], v[194:197], v[88:91]
	v_mfma_f32_16x16x32_bf16 v[84:87], v[154:157], v[202:205], v[84:87]
	v_mfma_f32_16x16x32_bf16 v[80:83], v[170:173], v[202:205], v[80:83]
	v_mfma_f32_16x16x32_bf16 v[76:79], v[154:157], v[210:213], v[76:79]
	v_mfma_f32_16x16x32_bf16 v[72:75], v[170:173], v[210:213], v[72:75]
	v_mfma_f32_16x16x32_bf16 v[68:71], v[154:157], v[218:221], v[68:71]
	v_mfma_f32_16x16x32_bf16 v[64:67], v[170:173], v[218:221], v[64:67]
	s_setprio 0
	s_setprio 1
	v_mfma_f32_16x16x32_bf16 v[28:31], v[174:177], v[190:193], v[28:31]
	v_mfma_f32_16x16x32_bf16 v[24:27], v[182:185], v[190:193], v[24:27]
	v_mfma_f32_16x16x32_bf16 v[20:23], v[174:177], v[198:201], v[20:23]
	v_mfma_f32_16x16x32_bf16 v[16:19], v[182:185], v[198:201], v[16:19]
	v_mfma_f32_16x16x32_bf16 v[12:15], v[174:177], v[206:209], v[12:15]
	v_mfma_f32_16x16x32_bf16 v[8:11], v[182:185], v[206:209], v[8:11]
	v_mfma_f32_16x16x32_bf16 v[4:7], v[174:177], v[214:217], v[4:7]
	v_mfma_f32_16x16x32_bf16 v[0:3], v[182:185], v[214:217], v[0:3]
	v_mfma_f32_16x16x32_bf16 v[28:31], v[178:181], v[194:197], v[28:31]
	v_mfma_f32_16x16x32_bf16 v[24:27], v[186:189], v[194:197], v[24:27]
	v_mfma_f32_16x16x32_bf16 v[20:23], v[178:181], v[202:205], v[20:23]
	v_mfma_f32_16x16x32_bf16 v[16:19], v[186:189], v[202:205], v[16:19]
	v_mfma_f32_16x16x32_bf16 v[12:15], v[178:181], v[210:213], v[12:15]
	v_mfma_f32_16x16x32_bf16 v[8:11], v[186:189], v[210:213], v[8:11]
	v_mfma_f32_16x16x32_bf16 v[4:7], v[178:181], v[218:221], v[4:7]
	v_mfma_f32_16x16x32_bf16 v[0:3], v[186:189], v[218:221], v[0:3]
	s_setprio 0
	s_barrier
	s_add_i32 s65, 0, 0x18000
	s_add_i32 s66, 0, 0x1c000
	v_add_u32_e32 v170, s65, v165
	v_add_u32_e32 v186, s66, v165
	ds_read_b128 v[100:103], v170
	ds_read_b128 v[154:157], v170 offset:1024
	ds_read_b128 v[158:161], v170 offset:2048
	ds_read_b128 v[170:173], v170 offset:3072
	ds_read_b128 v[174:177], v186
	ds_read_b128 v[178:181], v186 offset:1024
	ds_read_b128 v[182:185], v186 offset:2048
	ds_read_b128 v[186:189], v186 offset:3072
	v_lshl_add_u64 v[224:225], s[40:41], 0, v[136:137]
	s_mov_b32 m0, s47
	s_nop 0
	global_load_lds_dwordx4 v[224:225], off
	v_lshl_add_u64 v[224:225], s[40:41], 0, v[140:141]
	s_mov_b32 m0, s48
	s_nop 0
	global_load_lds_dwordx4 v[224:225], off
	s_add_u32 s40, s40, 0x40000
	s_addc_u32 s41, s41, 0
	s_mov_b32 m0, s49
	v_lshl_add_u64 v[224:225], s[40:41], 0, v[136:137]
	ds_read_b128 v[190:193], v169 offset:32768
	ds_read_b128 v[194:197], v169 offset:33792
	ds_read_b128 v[198:201], v169 offset:34816
	ds_read_b128 v[202:205], v169 offset:35840
	ds_read_b128 v[206:209], v169 offset:36864
	ds_read_b128 v[210:213], v169 offset:37888
	ds_read_b128 v[214:217], v169 offset:38912
	ds_read_b128 v[218:221], v169 offset:39936
	global_load_lds_dwordx4 v[224:225], off
	v_lshl_add_u64 v[224:225], s[40:41], 0, v[140:141]
	s_mov_b32 m0, s50
	s_nop 0
	global_load_lds_dwordx4 v[224:225], off
	s_waitcnt vmcnt(8)
	s_waitcnt lgkmcnt(0)
	s_barrier
	s_setprio 1
	s_waitcnt lgkmcnt(0)
	v_mfma_f32_16x16x32_bf16 v[132:135], v[100:103], v[190:193], v[132:135]
	v_mfma_f32_16x16x32_bf16 v[128:131], v[158:161], v[190:193], v[128:131]
	v_mfma_f32_16x16x32_bf16 v[124:127], v[100:103], v[198:201], v[124:127]
	v_mfma_f32_16x16x32_bf16 v[120:123], v[158:161], v[198:201], v[120:123]
	v_mfma_f32_16x16x32_bf16 v[116:119], v[100:103], v[206:209], v[116:119]
	v_mfma_f32_16x16x32_bf16 v[112:115], v[158:161], v[206:209], v[112:115]
	v_mfma_f32_16x16x32_bf16 v[108:111], v[100:103], v[214:217], v[108:111]
	v_mfma_f32_16x16x32_bf16 v[104:107], v[158:161], v[214:217], v[104:107]
	v_mfma_f32_16x16x32_bf16 v[132:135], v[154:157], v[194:197], v[132:135]
	v_mfma_f32_16x16x32_bf16 v[128:131], v[170:173], v[194:197], v[128:131]
	v_mfma_f32_16x16x32_bf16 v[124:127], v[154:157], v[202:205], v[124:127]
	v_mfma_f32_16x16x32_bf16 v[120:123], v[170:173], v[202:205], v[120:123]
	v_mfma_f32_16x16x32_bf16 v[116:119], v[154:157], v[210:213], v[116:119]
	v_mfma_f32_16x16x32_bf16 v[112:115], v[170:173], v[210:213], v[112:115]
	v_mfma_f32_16x16x32_bf16 v[108:111], v[154:157], v[218:221], v[108:111]
	v_mfma_f32_16x16x32_bf16 v[104:107], v[170:173], v[218:221], v[104:107]
	s_setprio 0
	s_setprio 1
	v_mfma_f32_16x16x32_bf16 v[60:63], v[174:177], v[190:193], v[60:63]
	v_mfma_f32_16x16x32_bf16 v[56:59], v[182:185], v[190:193], v[56:59]
	v_mfma_f32_16x16x32_bf16 v[52:55], v[174:177], v[198:201], v[52:55]
	v_mfma_f32_16x16x32_bf16 v[48:51], v[182:185], v[198:201], v[48:51]
	v_mfma_f32_16x16x32_bf16 v[44:47], v[174:177], v[206:209], v[44:47]
	v_mfma_f32_16x16x32_bf16 v[40:43], v[182:185], v[206:209], v[40:43]
	v_mfma_f32_16x16x32_bf16 v[36:39], v[174:177], v[214:217], v[36:39]
	v_mfma_f32_16x16x32_bf16 v[32:35], v[182:185], v[214:217], v[32:35]
	v_mfma_f32_16x16x32_bf16 v[60:63], v[178:181], v[194:197], v[60:63]
	v_mfma_f32_16x16x32_bf16 v[56:59], v[186:189], v[194:197], v[56:59]
	v_mfma_f32_16x16x32_bf16 v[52:55], v[178:181], v[202:205], v[52:55]
	v_mfma_f32_16x16x32_bf16 v[48:51], v[186:189], v[202:205], v[48:51]
	v_mfma_f32_16x16x32_bf16 v[44:47], v[178:181], v[210:213], v[44:47]
	v_mfma_f32_16x16x32_bf16 v[40:43], v[186:189], v[210:213], v[40:43]
	v_mfma_f32_16x16x32_bf16 v[36:39], v[178:181], v[218:221], v[36:39]
	v_mfma_f32_16x16x32_bf16 v[32:35], v[186:189], v[218:221], v[32:35]
	s_setprio 0
	s_barrier
; #define PG8_STAGE(bufoff, gbase, voff) do { _Pragma("unroll") for (int _i = 0; _i < 2; ++_i) \
;         __builtin_amdgcn_global_load_lds((const unsigned*)((const char*)(gbase) + (voff)[_i]), (PG8_LAS unsigned*)(lds + (bufoff) + ldsw + _i * 8192), 16, 0, 0); } while (0)
; #define PG8_LDA(dst, b, h) do { _Pragma("unroll") for (int m = 0; m < 4; ++m) _Pragma("unroll") for (int k = 0; k < 2; ++k) dst[m][k] = *(const PG8_LAS bf16x8*)(lds + PG8_SA(b, h) + aoff + m * 2048 + k * 1024); } while (0)
; #define PG8_MMA(ai, bj, At, Bt) do { __builtin_amdgcn_s_setprio(1); _Pragma("unroll") for (int m = 0; m < 4; ++m) _Pragma("unroll") for (int n = 0; n < 2; ++n) _Pragma("unroll") for (int k = 0; k < 2; ++k) \
;         acc[ai][bj][m][n] = __builtin_amdgcn_mfma_f32_16x16x32_bf16(Bt[n][k], At[m][k], acc[ai][bj][m][n], 0, 0, 0); __builtin_amdgcn_s_setprio(0); } while (0)
; #define PG8_WAIT_V(n) asm volatile("s_waitcnt vmcnt(" #n ")" ::: "memory")
; #define PG8_WAIT_L(n) asm volatile("s_waitcnt lgkmcnt(" #n ")" ::: "memory")
; #define PG8_BAR __builtin_amdgcn_s_barrier()
; #define PG8_SCHED __builtin_amdgcn_sched_barrier(0)
; template <class Epi, class Sched, bool ALIGN_EPI = false, bool SP2 = false>
; __device__ __forceinline__ void gemm_phase(PG8_LAS unsigned char* lds, const Gemm g, const Sched& S, const Epi& E) {
;     ...
;             PG8_LDA(At, 1, 1); PG8_STAGE(PG8_SB(1, 0), b3, voffB); PG8_STAGE(PG8_SB(1, 1), b3 + hstepB, voffB); PG8_STAGE(PG8_SA(1, 0), a3, voffA);
;             PG8_WAIT_V(8); PG8_WAIT_L(0); PG8_BAR; PG8_MMA(1, 0, At, B0); PG8_MMA(1, 1, At, B1); PG8_BAR; PG8_SCHED;
	s_add_i32 s40, s65, s46
	v_lshl_add_u64 v[162:163], v[162:163], 0, s[18:19]
	s_mov_b32 m0, s40
	ds_read_b128 v[190:193], v169 offset:49152
	ds_read_b128 v[194:197], v169 offset:50176
	ds_read_b128 v[198:201], v169 offset:51200
	ds_read_b128 v[202:205], v169 offset:52224
	ds_read_b128 v[206:209], v169 offset:53248
	ds_read_b128 v[210:213], v169 offset:54272
	ds_read_b128 v[214:217], v169 offset:55296
	ds_read_b128 v[218:221], v169 offset:56320
	global_load_lds_dwordx4 v[162:163], off
	s_add_i32 m0, s40, 0x2000
	s_add_u32 s38, s38, 0x40080
	v_lshl_add_u64 v[162:163], v[222:223], 0, s[18:19]
	s_addc_u32 s39, s39, 0
	s_add_i32 s40, s66, s46
	global_load_lds_dwordx4 v[162:163], off
	v_lshl_add_u64 v[162:163], s[38:39], 0, v[138:139]
	s_mov_b32 m0, s40
	s_nop 0
	global_load_lds_dwordx4 v[162:163], off
	v_lshl_add_u64 v[162:163], s[38:39], 0, v[142:143]
	s_add_i32 m0, s40, 0x2000
	s_nop 0
	global_load_lds_dwordx4 v[162:163], off
	v_lshl_add_u64 v[162:163], s[36:37], 0, v[136:137]
	s_mov_b32 m0, s53
	s_nop 0
	global_load_lds_dwordx4 v[162:163], off
	v_lshl_add_u64 v[162:163], s[36:37], 0, v[140:141]
	s_mov_b32 m0, s54
	s_nop 0
	global_load_lds_dwordx4 v[162:163], off
	s_waitcnt vmcnt(8)
	s_waitcnt lgkmcnt(0)
	s_barrier
	s_setprio 1
	s_waitcnt lgkmcnt(0)
	v_mfma_f32_16x16x32_bf16 v[92:95], v[100:103], v[190:193], v[92:95]
	v_mfma_f32_16x16x32_bf16 v[88:91], v[158:161], v[190:193], v[88:91]
	v_mfma_f32_16x16x32_bf16 v[84:87], v[100:103], v[198:201], v[84:87]
	v_mfma_f32_16x16x32_bf16 v[80:83], v[158:161], v[198:201], v[80:83]
	v_mfma_f32_16x16x32_bf16 v[76:79], v[100:103], v[206:209], v[76:79]
	v_mfma_f32_16x16x32_bf16 v[72:75], v[158:161], v[206:209], v[72:75]
	v_mfma_f32_16x16x32_bf16 v[68:71], v[100:103], v[214:217], v[68:71]
	v_mfma_f32_16x16x32_bf16 v[64:67], v[158:161], v[214:217], v[64:67]
	v_mfma_f32_16x16x32_bf16 v[92:95], v[154:157], v[194:197], v[92:95]
	v_mfma_f32_16x16x32_bf16 v[88:91], v[170:173], v[194:197], v[88:91]
	v_mfma_f32_16x16x32_bf16 v[84:87], v[154:157], v[202:205], v[84:87]
	v_mfma_f32_16x16x32_bf16 v[80:83], v[170:173], v[202:205], v[80:83]
	v_mfma_f32_16x16x32_bf16 v[76:79], v[154:157], v[210:213], v[76:79]
	v_mfma_f32_16x16x32_bf16 v[72:75], v[170:173], v[210:213], v[72:75]
	v_mfma_f32_16x16x32_bf16 v[68:71], v[154:157], v[218:221], v[68:71]
	v_mfma_f32_16x16x32_bf16 v[64:67], v[170:173], v[218:221], v[64:67]
	s_setprio 0
	s_setprio 1
	v_mfma_f32_16x16x32_bf16 v[28:31], v[174:177], v[190:193], v[28:31]
	v_mfma_f32_16x16x32_bf16 v[24:27], v[182:185], v[190:193], v[24:27]
	v_mfma_f32_16x16x32_bf16 v[20:23], v[174:177], v[198:201], v[20:23]
	v_mfma_f32_16x16x32_bf16 v[16:19], v[182:185], v[198:201], v[16:19]
	v_mfma_f32_16x16x32_bf16 v[12:15], v[174:177], v[206:209], v[12:15]
	v_mfma_f32_16x16x32_bf16 v[8:11], v[182:185], v[206:209], v[8:11]
	v_mfma_f32_16x16x32_bf16 v[4:7], v[174:177], v[214:217], v[4:7]
	v_mfma_f32_16x16x32_bf16 v[0:3], v[182:185], v[214:217], v[0:3]
	v_mfma_f32_16x16x32_bf16 v[28:31], v[178:181], v[194:197], v[28:31]
	v_mfma_f32_16x16x32_bf16 v[24:27], v[186:189], v[194:197], v[24:27]
	v_mfma_f32_16x16x32_bf16 v[20:23], v[178:181], v[202:205], v[20:23]
	v_mfma_f32_16x16x32_bf16 v[16:19], v[186:189], v[202:205], v[16:19]
	v_mfma_f32_16x16x32_bf16 v[12:15], v[178:181], v[210:213], v[12:15]
	v_mfma_f32_16x16x32_bf16 v[8:11], v[186:189], v[210:213], v[8:11]
	v_mfma_f32_16x16x32_bf16 v[4:7], v[178:181], v[218:221], v[4:7]
	v_mfma_f32_16x16x32_bf16 v[0:3], v[186:189], v[218:221], v[0:3]
	s_setprio 0
	s_barrier
	s_add_i32 s64, s64, 2
	s_add_u32 s34, s34, 0x100
	s_addc_u32 s35, s35, 0
	s_cmp_gt_u32 s64, 13
	s_cbranch_scc0 .LBB0_782
	s_and_b64 vcc, exec, s[20:21]
	s_cbranch_vccz .LBB0_785
	s_barrier

; #define PG8_STAGE(bufoff, gbase, voff) do { _Pragma("unroll") for (int _i = 0; _i < 2; ++_i) \
;         __builtin_amdgcn_global_load_lds((const unsigned*)((const char*)(gbase) + (voff)[_i]), (PG8_LAS unsigned*)(lds + (bufoff) + ldsw + _i * 8192), 16, 0, 0); } while (0)
; #define PG8_LDA(dst, b, h) do { _Pragma("unroll") for (int m = 0; m < 4; ++m) _Pragma("unroll") for (int k = 0; k < 2; ++k) dst[m][k] = *(const PG8_LAS bf16x8*)(lds + PG8_SA(b, h) + aoff + m * 2048 + k * 1024); } while (0)
; #define PG8_LDB(dst, b, h) do { _Pragma("unroll") for (int n = 0; n < 2; ++n) _Pragma("unroll") for (int k = 0; k < 2; ++k) dst[n][k] = *(const PG8_LAS bf16x8*)(lds + PG8_SB(b, h) + boff + n * 2048 + k * 1024); } while (0)
; #define PG8_MMA(ai, bj, At, Bt) do { __builtin_amdgcn_s_setprio(1); _Pragma("unroll") for (int m = 0; m < 4; ++m) _Pragma("unroll") for (int n = 0; n < 2; ++n) _Pragma("unroll") for (int k = 0; k < 2; ++k) \
;         acc[ai][bj][m][n] = __builtin_amdgcn_mfma_f32_16x16x32_bf16(Bt[n][k], At[m][k], acc[ai][bj][m][n], 0, 0, 0); __builtin_amdgcn_s_setprio(0); } while (0)
; #define PG8_WAIT_V(n) asm volatile("s_waitcnt vmcnt(" #n ")" ::: "memory")
; #define PG8_WAIT_L(n) asm volatile("s_waitcnt lgkmcnt(" #n ")" ::: "memory")
; template <class Epi, class Sched, bool ALIGN_EPI = false, bool SP2 = false>
; __device__ __forceinline__ void gemm_phase(PG8_LAS unsigned char* lds, const Gemm g, const Sched& S, const Epi& E) {
;     ...
;             const bool last = (t == nt - 2);
;             const char* a1 = cA + PG8_AK(t + 1);
;             const char* a2 = last ? nA : cA + PG8_AK(t + 2); const char* b2 = last ? nB : cB + (size_t)(t + 2) * kstep;
;             const char* a3 = last ? nA + PG8_AK(1) : cA + PG8_AK(t + 3); const char* b3 = b2 + kstep;
;             if (last && has_next) S.a_ready(nxt);
;             if constexpr (SP2) {
;             PG8_LDB(B0, 0, 0); PG8_LDB(B1, 0, 1); PG8_SCHED; PG8_LDA(At, 0, 0); PG8_STAGE(PG8_SA(1, 1), a1 + hstepA, voffA);
;             PG8_WAIT_V(8); PG8_WAIT_L(0); PG8_BAR; PG8_MMA(0, 0, At, B0); PG8_MMA(0, 1, At, B1); PG8_BAR; PG8_SCHED;
;             PG8_LDA(At, 0, 1); PG8_STAGE(PG8_SB(0, 0), b2, voffB); PG8_STAGE(PG8_SB(0, 1), b2 + hstepB, voffB); PG8_STAGE(PG8_SA(0, 0), a2, voffA);
;             PG8_WAIT_V(8); PG8_WAIT_L(0); PG8_BAR; PG8_MMA(1, 0, At, B0); PG8_MMA(1, 1, At, B1); PG8_BAR; PG8_SCHED;
.LBB0_1191:
	ds_read_b128 v[128:131], v191
	ds_read_b128 v[132:135], v191 offset:1024
	ds_read_b128 v[136:139], v191 offset:2048
	ds_read_b128 v[140:143], v191 offset:3072
	ds_read_b128 v[162:165], v192
	ds_read_b128 v[166:169], v192 offset:1024
	ds_read_b128 v[194:197], v192 offset:2048
	ds_read_b128 v[198:201], v192 offset:3072
	s_add_u32 s38, s36, 0x800000
	s_addc_u32 s39, s37, 0
	s_cmp_eq_u32 s67, 12
	s_cselect_b32 s43, s3, s39
	s_cselect_b32 s42, s27, s38
	s_cselect_b32 s41, s25, s66
	s_cselect_b32 s40, s35, s65
	v_lshl_add_u64 v[170:171], s[36:37], 0, v[156:157]
	s_add_i32 m0, s50, 0xc000
	ds_read_b128 v[202:205], v174
	ds_read_b128 v[206:209], v174 offset:1024
	ds_read_b128 v[210:213], v174 offset:2048
	ds_read_b128 v[214:217], v174 offset:3072
	ds_read_b128 v[218:221], v174 offset:4096
	ds_read_b128 v[222:225], v174 offset:5120
	ds_read_b128 v[226:229], v174 offset:6144
	ds_read_b128 v[230:233], v174 offset:7168
	global_load_lds_dwordx4 v[170:171], off
	v_lshl_add_u64 v[170:171], s[36:37], 0, v[154:155]
	s_add_i32 m0, s50, 0xe000
	s_nop 0
	global_load_lds_dwordx4 v[170:171], off
	s_waitcnt vmcnt(8)
	s_waitcnt lgkmcnt(0)
	s_barrier
	s_setprio 1
	s_waitcnt lgkmcnt(0)
	v_mfma_f32_16x16x32_bf16 v[124:127], v[128:131], v[202:205], v[124:127]
	v_mfma_f32_16x16x32_bf16 v[120:123], v[136:139], v[202:205], v[120:123]
	v_mfma_f32_16x16x32_bf16 v[116:119], v[128:131], v[210:213], v[116:119]
	v_mfma_f32_16x16x32_bf16 v[112:115], v[136:139], v[210:213], v[112:115]
	v_mfma_f32_16x16x32_bf16 v[108:111], v[128:131], v[218:221], v[108:111]
	v_mfma_f32_16x16x32_bf16 v[104:107], v[136:139], v[218:221], v[104:107]
	v_mfma_f32_16x16x32_bf16 v[100:103], v[128:131], v[226:229], v[100:103]
	v_mfma_f32_16x16x32_bf16 v[96:99], v[136:139], v[226:229], v[96:99]
	v_mfma_f32_16x16x32_bf16 v[124:127], v[132:135], v[206:209], v[124:127]
	v_mfma_f32_16x16x32_bf16 v[120:123], v[140:143], v[206:209], v[120:123]
	v_mfma_f32_16x16x32_bf16 v[116:119], v[132:135], v[214:217], v[116:119]
	v_mfma_f32_16x16x32_bf16 v[112:115], v[140:143], v[214:217], v[112:115]
	v_mfma_f32_16x16x32_bf16 v[108:111], v[132:135], v[222:225], v[108:111]
	v_mfma_f32_16x16x32_bf16 v[104:107], v[140:143], v[222:225], v[104:107]
	v_mfma_f32_16x16x32_bf16 v[100:103], v[132:135], v[230:233], v[100:103]
	v_mfma_f32_16x16x32_bf16 v[96:99], v[140:143], v[230:233], v[96:99]
	s_setprio 0
	s_setprio 1
	v_mfma_f32_16x16x32_bf16 v[60:63], v[162:165], v[202:205], v[60:63]
	v_mfma_f32_16x16x32_bf16 v[56:59], v[194:197], v[202:205], v[56:59]
	v_mfma_f32_16x16x32_bf16 v[52:55], v[162:165], v[210:213], v[52:55]
	v_mfma_f32_16x16x32_bf16 v[48:51], v[194:197], v[210:213], v[48:51]
	v_mfma_f32_16x16x32_bf16 v[44:47], v[162:165], v[218:221], v[44:47]
	v_mfma_f32_16x16x32_bf16 v[40:43], v[194:197], v[218:221], v[40:43]
	v_mfma_f32_16x16x32_bf16 v[36:39], v[162:165], v[226:229], v[36:39]
	v_mfma_f32_16x16x32_bf16 v[32:35], v[194:197], v[226:229], v[32:35]
	v_mfma_f32_16x16x32_bf16 v[60:63], v[166:169], v[206:209], v[60:63]
	v_mfma_f32_16x16x32_bf16 v[56:59], v[198:201], v[206:209], v[56:59]
	v_mfma_f32_16x16x32_bf16 v[52:55], v[166:169], v[214:217], v[52:55]
	v_mfma_f32_16x16x32_bf16 v[48:51], v[198:201], v[214:217], v[48:51]
	v_mfma_f32_16x16x32_bf16 v[44:47], v[166:169], v[222:225], v[44:47]
	v_mfma_f32_16x16x32_bf16 v[40:43], v[198:201], v[222:225], v[40:43]
	v_mfma_f32_16x16x32_bf16 v[36:39], v[166:169], v[230:233], v[36:39]
	v_mfma_f32_16x16x32_bf16 v[32:35], v[198:201], v[230:233], v[32:35]
	s_setprio 0
	s_barrier
	s_add_i32 s36, s62, s49
	v_lshl_add_u64 v[170:171], s[40:41], 0, v[146:147]
	s_mov_b32 m0, s36
	ds_read_b128 v[202:205], v174 offset:16384
	ds_read_b128 v[206:209], v174 offset:17408
	ds_read_b128 v[210:213], v174 offset:18432
	ds_read_b128 v[214:217], v174 offset:19456
	ds_read_b128 v[218:221], v174 offset:20480
	ds_read_b128 v[222:225], v174 offset:21504
	ds_read_b128 v[226:229], v174 offset:22528
	ds_read_b128 v[230:233], v174 offset:23552
	global_load_lds_dwordx4 v[170:171], off
	s_add_i32 m0, s36, 0x2000
	s_add_u32 s36, s40, 0x40000
	v_lshl_add_u64 v[234:235], s[40:41], 0, v[150:151]
	s_addc_u32 s37, s41, 0
	s_add_i32 s68, s63, s49
	global_load_lds_dwordx4 v[234:235], off
	v_lshl_add_u64 v[236:237], s[36:37], 0, v[146:147]
	s_mov_b32 m0, s68
	v_lshl_add_u64 v[238:239], s[42:43], 0, v[148:149]
	global_load_lds_dwordx4 v[236:237], off
	v_lshl_add_u64 v[236:237], s[36:37], 0, v[150:151]
	s_add_i32 m0, s68, 0x2000
	s_nop 0
	global_load_lds_dwordx4 v[236:237], off
	s_waitcnt vmcnt(6)
	s_waitcnt lgkmcnt(0)
	s_barrier
; #define PG8_STAGE(bufoff, gbase, voff) do { _Pragma("unroll") for (int _i = 0; _i < 2; ++_i) \
;         __builtin_amdgcn_global_load_lds((const unsigned*)((const char*)(gbase) + (voff)[_i]), (PG8_LAS unsigned*)(lds + (bufoff) + ldsw + _i * 8192), 16, 0, 0); } while (0)
; #define PG8_LDA(dst, b, h) do { _Pragma("unroll") for (int m = 0; m < 4; ++m) _Pragma("unroll") for (int k = 0; k < 2; ++k) dst[m][k] = *(const PG8_LAS bf16x8*)(lds + PG8_SA(b, h) + aoff + m * 2048 + k * 1024); } while (0)
; #define PG8_LDB(dst, b, h) do { _Pragma("unroll") for (int n = 0; n < 2; ++n) _Pragma("unroll") for (int k = 0; k < 2; ++k) dst[n][k] = *(const PG8_LAS bf16x8*)(lds + PG8_SB(b, h) + boff + n * 2048 + k * 1024); } while (0)
; #define PG8_MMA(ai, bj, At, Bt) do { __builtin_amdgcn_s_setprio(1); _Pragma("unroll") for (int m = 0; m < 4; ++m) _Pragma("unroll") for (int n = 0; n < 2; ++n) _Pragma("unroll") for (int k = 0; k < 2; ++k) \
;         acc[ai][bj][m][n] = __builtin_amdgcn_mfma_f32_16x16x32_bf16(Bt[n][k], At[m][k], acc[ai][bj][m][n], 0, 0, 0); __builtin_amdgcn_s_setprio(0); } while (0)
; #define PG8_WAIT_V(n) asm volatile("s_waitcnt vmcnt(" #n ")" ::: "memory")
; #define PG8_WAIT_L(n) asm volatile("s_waitcnt lgkmcnt(" #n ")" ::: "memory")
; #define PG8_BAR __builtin_amdgcn_s_barrier()
; #define PG8_SCHED __builtin_amdgcn_sched_barrier(0)
; template <class Epi, class Sched, bool ALIGN_EPI = false, bool SP2 = false>
; __device__ __forceinline__ void gemm_phase(PG8_LAS unsigned char* lds, const Gemm g, const Sched& S, const Epi& E) {
;     ...
;             PG8_WAIT_V(8); PG8_WAIT_L(0); PG8_BAR; PG8_MMA(1, 0, At, B0); PG8_MMA(1, 1, At, B1); PG8_BAR; PG8_SCHED;
;             PG8_LDB(B0, 1, 0); PG8_LDB(B1, 1, 1); PG8_SCHED; PG8_LDA(At, 1, 0); PG8_STAGE(PG8_SA(0, 1), a2 + hstepA, voffA);
;             PG8_WAIT_V(8); PG8_WAIT_L(0); PG8_BAR; PG8_MMA(0, 0, At, B0); PG8_MMA(0, 1, At, B1); PG8_BAR; PG8_SCHED;
	s_setprio 1
	s_waitcnt lgkmcnt(0)
	v_mfma_f32_16x16x32_bf16 v[92:95], v[128:131], v[202:205], v[92:95]
	v_mfma_f32_16x16x32_bf16 v[88:91], v[136:139], v[202:205], v[88:91]
	v_mfma_f32_16x16x32_bf16 v[84:87], v[128:131], v[210:213], v[84:87]
	v_mfma_f32_16x16x32_bf16 v[80:83], v[136:139], v[210:213], v[80:83]
	v_mfma_f32_16x16x32_bf16 v[76:79], v[128:131], v[218:221], v[76:79]
	v_mfma_f32_16x16x32_bf16 v[72:75], v[136:139], v[218:221], v[72:75]
	v_mfma_f32_16x16x32_bf16 v[68:71], v[128:131], v[226:229], v[68:71]
	v_mfma_f32_16x16x32_bf16 v[64:67], v[136:139], v[226:229], v[64:67]
	v_mfma_f32_16x16x32_bf16 v[92:95], v[132:135], v[206:209], v[92:95]
	v_mfma_f32_16x16x32_bf16 v[88:91], v[140:143], v[206:209], v[88:91]
	v_mfma_f32_16x16x32_bf16 v[84:87], v[132:135], v[214:217], v[84:87]
	v_mfma_f32_16x16x32_bf16 v[80:83], v[140:143], v[214:217], v[80:83]
	v_mfma_f32_16x16x32_bf16 v[76:79], v[132:135], v[222:225], v[76:79]
	v_mfma_f32_16x16x32_bf16 v[72:75], v[140:143], v[222:225], v[72:75]
	v_mfma_f32_16x16x32_bf16 v[68:71], v[132:135], v[230:233], v[68:71]
	v_mfma_f32_16x16x32_bf16 v[64:67], v[140:143], v[230:233], v[64:67]
	s_setprio 0
	s_setprio 1
	v_mfma_f32_16x16x32_bf16 v[28:31], v[162:165], v[202:205], v[28:31]
	v_mfma_f32_16x16x32_bf16 v[24:27], v[194:197], v[202:205], v[24:27]
	v_mfma_f32_16x16x32_bf16 v[20:23], v[162:165], v[210:213], v[20:23]
	v_mfma_f32_16x16x32_bf16 v[16:19], v[194:197], v[210:213], v[16:19]
	v_mfma_f32_16x16x32_bf16 v[12:15], v[162:165], v[218:221], v[12:15]
	v_mfma_f32_16x16x32_bf16 v[8:11], v[194:197], v[218:221], v[8:11]
	v_mfma_f32_16x16x32_bf16 v[4:7], v[162:165], v[226:229], v[4:7]
	v_mfma_f32_16x16x32_bf16 v[0:3], v[194:197], v[226:229], v[0:3]
	v_mfma_f32_16x16x32_bf16 v[28:31], v[166:169], v[206:209], v[28:31]
	v_mfma_f32_16x16x32_bf16 v[24:27], v[198:201], v[206:209], v[24:27]
	v_mfma_f32_16x16x32_bf16 v[20:23], v[166:169], v[214:217], v[20:23]
	v_mfma_f32_16x16x32_bf16 v[16:19], v[198:201], v[214:217], v[16:19]
	v_mfma_f32_16x16x32_bf16 v[12:15], v[166:169], v[222:225], v[12:15]
	v_mfma_f32_16x16x32_bf16 v[8:11], v[198:201], v[222:225], v[8:11]
	v_mfma_f32_16x16x32_bf16 v[4:7], v[166:169], v[230:233], v[4:7]
	v_mfma_f32_16x16x32_bf16 v[0:3], v[198:201], v[230:233], v[0:3]
	s_setprio 0
	s_barrier
	s_add_i32 s68, 0, 0x18000
	s_add_i32 s69, 0, 0x1c000
	v_add_u32_e32 v140, s68, v173
	v_add_u32_e32 v153, s69, v173
	ds_read_b128 v[128:131], v140
	ds_read_b128 v[132:135], v140 offset:1024
	ds_read_b128 v[136:139], v140 offset:2048
	ds_read_b128 v[140:143], v140 offset:3072
	ds_read_b128 v[162:165], v153
	ds_read_b128 v[166:169], v153 offset:1024
	ds_read_b128 v[194:197], v153 offset:2048
	ds_read_b128 v[198:201], v153 offset:3072
	s_add_u32 s36, s42, 0x8000
	s_addc_u32 s37, s43, 0
	v_lshl_add_u64 v[236:237], s[42:43], 0, v[144:145]
	s_mov_b32 m0, s50
	s_nop 0
	global_load_lds_dwordx4 v[236:237], off
	s_mov_b32 m0, s51
	s_nop 0
	global_load_lds_dwordx4 v[238:239], off
	s_mov_b32 m0, s52
	v_lshl_add_u64 v[240:241], s[36:37], 0, v[144:145]
	ds_read_b128 v[202:205], v174 offset:32768
	ds_read_b128 v[206:209], v174 offset:33792
	ds_read_b128 v[210:213], v174 offset:34816
	ds_read_b128 v[214:217], v174 offset:35840
	ds_read_b128 v[218:221], v174 offset:36864
	ds_read_b128 v[222:225], v174 offset:37888
	ds_read_b128 v[226:229], v174 offset:38912
	ds_read_b128 v[230:233], v174 offset:39936
	global_load_lds_dwordx4 v[240:241], off
	v_lshl_add_u64 v[240:241], s[36:37], 0, v[148:149]
	s_mov_b32 m0, s53
	s_nop 0
	global_load_lds_dwordx4 v[240:241], off
	s_waitcnt vmcnt(8)
	s_waitcnt lgkmcnt(0)
	s_barrier
	s_setprio 1
	s_waitcnt lgkmcnt(0)
	v_mfma_f32_16x16x32_bf16 v[124:127], v[128:131], v[202:205], v[124:127]
	v_mfma_f32_16x16x32_bf16 v[120:123], v[136:139], v[202:205], v[120:123]
	v_mfma_f32_16x16x32_bf16 v[116:119], v[128:131], v[210:213], v[116:119]
	v_mfma_f32_16x16x32_bf16 v[112:115], v[136:139], v[210:213], v[112:115]
	v_mfma_f32_16x16x32_bf16 v[108:111], v[128:131], v[218:221], v[108:111]
	v_mfma_f32_16x16x32_bf16 v[104:107], v[136:139], v[218:221], v[104:107]
	v_mfma_f32_16x16x32_bf16 v[100:103], v[128:131], v[226:229], v[100:103]
	v_mfma_f32_16x16x32_bf16 v[96:99], v[136:139], v[226:229], v[96:99]
	v_mfma_f32_16x16x32_bf16 v[124:127], v[132:135], v[206:209], v[124:127]
	v_mfma_f32_16x16x32_bf16 v[120:123], v[140:143], v[206:209], v[120:123]
	v_mfma_f32_16x16x32_bf16 v[116:119], v[132:135], v[214:217], v[116:119]
	v_mfma_f32_16x16x32_bf16 v[112:115], v[140:143], v[214:217], v[112:115]
	v_mfma_f32_16x16x32_bf16 v[108:111], v[132:135], v[222:225], v[108:111]
	v_mfma_f32_16x16x32_bf16 v[104:107], v[140:143], v[222:225], v[104:107]
	v_mfma_f32_16x16x32_bf16 v[100:103], v[132:135], v[230:233], v[100:103]
	v_mfma_f32_16x16x32_bf16 v[96:99], v[140:143], v[230:233], v[96:99]
	s_setprio 0
	s_setprio 1
	v_mfma_f32_16x16x32_bf16 v[60:63], v[162:165], v[202:205], v[60:63]
	v_mfma_f32_16x16x32_bf16 v[56:59], v[194:197], v[202:205], v[56:59]
	v_mfma_f32_16x16x32_bf16 v[52:55], v[162:165], v[210:213], v[52:55]
	v_mfma_f32_16x16x32_bf16 v[48:51], v[194:197], v[210:213], v[48:51]
	v_mfma_f32_16x16x32_bf16 v[44:47], v[162:165], v[218:221], v[44:47]
	v_mfma_f32_16x16x32_bf16 v[40:43], v[194:197], v[218:221], v[40:43]
	v_mfma_f32_16x16x32_bf16 v[36:39], v[162:165], v[226:229], v[36:39]
	v_mfma_f32_16x16x32_bf16 v[32:35], v[194:197], v[226:229], v[32:35]
	v_mfma_f32_16x16x32_bf16 v[60:63], v[166:169], v[206:209], v[60:63]
	v_mfma_f32_16x16x32_bf16 v[56:59], v[198:201], v[206:209], v[56:59]
	v_mfma_f32_16x16x32_bf16 v[52:55], v[166:169], v[214:217], v[52:55]
	v_mfma_f32_16x16x32_bf16 v[48:51], v[198:201], v[214:217], v[48:51]
	v_mfma_f32_16x16x32_bf16 v[44:47], v[166:169], v[222:225], v[44:47]
	v_mfma_f32_16x16x32_bf16 v[40:43], v[198:201], v[222:225], v[40:43]
	v_mfma_f32_16x16x32_bf16 v[36:39], v[166:169], v[230:233], v[36:39]
	v_mfma_f32_16x16x32_bf16 v[32:35], v[198:201], v[230:233], v[32:35]
	s_setprio 0
	s_barrier
; #define PG8_STAGE(bufoff, gbase, voff) do { _Pragma("unroll") for (int _i = 0; _i < 2; ++_i) \
;         __builtin_amdgcn_global_load_lds((const unsigned*)((const char*)(gbase) + (voff)[_i]), (PG8_LAS unsigned*)(lds + (bufoff) + ldsw + _i * 8192), 16, 0, 0); } while (0)
; #define PG8_LDA(dst, b, h) do { _Pragma("unroll") for (int m = 0; m < 4; ++m) _Pragma("unroll") for (int k = 0; k < 2; ++k) dst[m][k] = *(const PG8_LAS bf16x8*)(lds + PG8_SA(b, h) + aoff + m * 2048 + k * 1024); } while (0)
; #define PG8_MMA(ai, bj, At, Bt) do { __builtin_amdgcn_s_setprio(1); _Pragma("unroll") for (int m = 0; m < 4; ++m) _Pragma("unroll") for (int n = 0; n < 2; ++n) _Pragma("unroll") for (int k = 0; k < 2; ++k) \
;         acc[ai][bj][m][n] = __builtin_amdgcn_mfma_f32_16x16x32_bf16(Bt[n][k], At[m][k], acc[ai][bj][m][n], 0, 0, 0); __builtin_amdgcn_s_setprio(0); } while (0)
; #define PG8_WAIT_V(n) asm volatile("s_waitcnt vmcnt(" #n ")" ::: "memory")
; #define PG8_WAIT_L(n) asm volatile("s_waitcnt lgkmcnt(" #n ")" ::: "memory")
; #define PG8_BAR __builtin_amdgcn_s_barrier()
; #define PG8_SCHED __builtin_amdgcn_sched_barrier(0)
; template <class Epi, class Sched, bool ALIGN_EPI = false, bool SP2 = false>
; __device__ __forceinline__ void gemm_phase(PG8_LAS unsigned char* lds, const Gemm g, const Sched& S, const Epi& E) {
;     ...
;             PG8_LDA(At, 1, 1); PG8_STAGE(PG8_SB(1, 0), b3, voffB); PG8_STAGE(PG8_SB(1, 1), b3 + hstepB, voffB); PG8_STAGE(PG8_SA(1, 0), a3, voffA);
;             PG8_WAIT_V(8); PG8_WAIT_L(0); PG8_BAR; PG8_MMA(1, 0, At, B0); PG8_MMA(1, 1, At, B1); PG8_BAR; PG8_SCHED;
	s_add_i32 s36, s68, s49
	v_lshl_add_u64 v[170:171], v[170:171], 0, s[18:19]
	s_mov_b32 m0, s36
	ds_read_b128 v[202:205], v174 offset:49152
	ds_read_b128 v[206:209], v174 offset:50176
	ds_read_b128 v[210:213], v174 offset:51200
	ds_read_b128 v[214:217], v174 offset:52224
	ds_read_b128 v[218:221], v174 offset:53248
	ds_read_b128 v[222:225], v174 offset:54272
	ds_read_b128 v[226:229], v174 offset:55296
	ds_read_b128 v[230:233], v174 offset:56320
	global_load_lds_dwordx4 v[170:171], off
	s_add_i32 m0, s36, 0x2000
	s_add_u32 s36, s40, 0x40080
	v_lshl_add_u64 v[170:171], v[234:235], 0, s[18:19]
	s_addc_u32 s37, s41, 0
	s_add_i32 s40, s69, s49
	global_load_lds_dwordx4 v[170:171], off
	v_lshl_add_u64 v[170:171], s[36:37], 0, v[146:147]
	s_mov_b32 m0, s40
	s_nop 0
	global_load_lds_dwordx4 v[170:171], off
	v_lshl_add_u64 v[170:171], s[36:37], 0, v[150:151]
	s_add_i32 m0, s40, 0x2000
	s_nop 0
	global_load_lds_dwordx4 v[170:171], off
	v_lshl_add_u64 v[170:171], v[236:237], 0, s[18:19]
	s_mov_b32 m0, s58
	s_nop 0
	global_load_lds_dwordx4 v[170:171], off
	v_lshl_add_u64 v[170:171], v[238:239], 0, s[18:19]
	s_mov_b32 m0, s59
	s_nop 0
	global_load_lds_dwordx4 v[170:171], off
	s_waitcnt vmcnt(8)
	s_waitcnt lgkmcnt(0)
	s_barrier
	s_setprio 1
	s_waitcnt lgkmcnt(0)
	v_mfma_f32_16x16x32_bf16 v[92:95], v[128:131], v[202:205], v[92:95]
	v_mfma_f32_16x16x32_bf16 v[88:91], v[136:139], v[202:205], v[88:91]
	v_mfma_f32_16x16x32_bf16 v[84:87], v[128:131], v[210:213], v[84:87]
	v_mfma_f32_16x16x32_bf16 v[80:83], v[136:139], v[210:213], v[80:83]
	v_mfma_f32_16x16x32_bf16 v[76:79], v[128:131], v[218:221], v[76:79]
	v_mfma_f32_16x16x32_bf16 v[72:75], v[136:139], v[218:221], v[72:75]
	v_mfma_f32_16x16x32_bf16 v[68:71], v[128:131], v[226:229], v[68:71]
	v_mfma_f32_16x16x32_bf16 v[64:67], v[136:139], v[226:229], v[64:67]
	v_mfma_f32_16x16x32_bf16 v[92:95], v[132:135], v[206:209], v[92:95]
	v_mfma_f32_16x16x32_bf16 v[88:91], v[140:143], v[206:209], v[88:91]
	v_mfma_f32_16x16x32_bf16 v[84:87], v[132:135], v[214:217], v[84:87]
	v_mfma_f32_16x16x32_bf16 v[80:83], v[140:143], v[214:217], v[80:83]
	v_mfma_f32_16x16x32_bf16 v[76:79], v[132:135], v[222:225], v[76:79]
	v_mfma_f32_16x16x32_bf16 v[72:75], v[140:143], v[222:225], v[72:75]
	v_mfma_f32_16x16x32_bf16 v[68:71], v[132:135], v[230:233], v[68:71]
	v_mfma_f32_16x16x32_bf16 v[64:67], v[140:143], v[230:233], v[64:67]
	s_setprio 0
	s_setprio 1
	v_mfma_f32_16x16x32_bf16 v[28:31], v[162:165], v[202:205], v[28:31]
	v_mfma_f32_16x16x32_bf16 v[24:27], v[194:197], v[202:205], v[24:27]
	v_mfma_f32_16x16x32_bf16 v[20:23], v[162:165], v[210:213], v[20:23]
	v_mfma_f32_16x16x32_bf16 v[16:19], v[194:197], v[210:213], v[16:19]
	v_mfma_f32_16x16x32_bf16 v[12:15], v[162:165], v[218:221], v[12:15]
	v_mfma_f32_16x16x32_bf16 v[8:11], v[194:197], v[218:221], v[8:11]
	v_mfma_f32_16x16x32_bf16 v[4:7], v[162:165], v[226:229], v[4:7]
	v_mfma_f32_16x16x32_bf16 v[0:3], v[194:197], v[226:229], v[0:3]
	v_mfma_f32_16x16x32_bf16 v[28:31], v[166:169], v[206:209], v[28:31]
	v_mfma_f32_16x16x32_bf16 v[24:27], v[198:201], v[206:209], v[24:27]
	v_mfma_f32_16x16x32_bf16 v[20:23], v[166:169], v[214:217], v[20:23]
	v_mfma_f32_16x16x32_bf16 v[16:19], v[198:201], v[214:217], v[16:19]
	v_mfma_f32_16x16x32_bf16 v[12:15], v[166:169], v[222:225], v[12:15]
	v_mfma_f32_16x16x32_bf16 v[8:11], v[198:201], v[222:225], v[8:11]
	v_mfma_f32_16x16x32_bf16 v[4:7], v[166:169], v[230:233], v[4:7]
	v_mfma_f32_16x16x32_bf16 v[0:3], v[198:201], v[230:233], v[0:3]
	s_setprio 0
	s_barrier
	s_add_i32 s67, s67, 2
	s_add_u32 s65, s65, 0x100
	s_addc_u32 s66, s66, 0
	s_cmp_gt_u32 s67, 13
	s_mov_b64 s[36:37], s[38:39]
	s_cbranch_scc0 .LBB0_1191
	s_and_b64 vcc, exec, s[20:21]
	s_cbranch_vccz .LBB0_1194
	s_barrier

; #define PG8_STAGE(bufoff, gbase, voff) do { _Pragma("unroll") for (int _i = 0; _i < 2; ++_i) \
;         __builtin_amdgcn_global_load_lds((const unsigned*)((const char*)(gbase) + (voff)[_i]), (PG8_LAS unsigned*)(lds + (bufoff) + ldsw + _i * 8192), 16, 0, 0); } while (0)
; #define PG8_LDA(dst, b, h) do { _Pragma("unroll") for (int m = 0; m < 4; ++m) _Pragma("unroll") for (int k = 0; k < 2; ++k) dst[m][k] = *(const PG8_LAS bf16x8*)(lds + PG8_SA(b, h) + aoff + m * 2048 + k * 1024); } while (0)
; #define PG8_LDB(dst, b, h) do { _Pragma("unroll") for (int n = 0; n < 2; ++n) _Pragma("unroll") for (int k = 0; k < 2; ++k) dst[n][k] = *(const PG8_LAS bf16x8*)(lds + PG8_SB(b, h) + boff + n * 2048 + k * 1024); } while (0)
; #define PG8_MMA(ai, bj, At, Bt) do { __builtin_amdgcn_s_setprio(1); _Pragma("unroll") for (int m = 0; m < 4; ++m) _Pragma("unroll") for (int n = 0; n < 2; ++n) _Pragma("unroll") for (int k = 0; k < 2; ++k) \
;         acc[ai][bj][m][n] = __builtin_amdgcn_mfma_f32_16x16x32_bf16(Bt[n][k], At[m][k], acc[ai][bj][m][n], 0, 0, 0); __builtin_amdgcn_s_setprio(0); } while (0)
; #define PG8_WAIT_V(n) asm volatile("s_waitcnt vmcnt(" #n ")" ::: "memory")
; #define PG8_WAIT_L(n) asm volatile("s_waitcnt lgkmcnt(" #n ")" ::: "memory")
; template <class Epi, class Sched, bool ALIGN_EPI = false, bool SP2 = false>
; __device__ __forceinline__ void gemm_phase(PG8_LAS unsigned char* lds, const Gemm g, const Sched& S, const Epi& E) {
;     ...
;             const bool last = (t == nt - 2);
;             const char* a1 = cA + PG8_AK(t + 1);
;             const char* a2 = last ? nA : cA + PG8_AK(t + 2); const char* b2 = last ? nB : cB + (size_t)(t + 2) * kstep;
;             const char* a3 = last ? nA + PG8_AK(1) : cA + PG8_AK(t + 3); const char* b3 = b2 + kstep;
;             if (last && has_next) S.a_ready(nxt);
;             if constexpr (SP2) {
;             PG8_LDB(B0, 0, 0); PG8_LDB(B1, 0, 1); PG8_SCHED; PG8_LDA(At, 0, 0); PG8_STAGE(PG8_SA(1, 1), a1 + hstepA, voffA);
;             PG8_WAIT_V(8); PG8_WAIT_L(0); PG8_BAR; PG8_MMA(0, 0, At, B0); PG8_MMA(0, 1, At, B1); PG8_BAR; PG8_SCHED;
;             PG8_LDA(At, 0, 1); PG8_STAGE(PG8_SB(0, 0), b2, voffB); PG8_STAGE(PG8_SB(0, 1), b2 + hstepB, voffB); PG8_STAGE(PG8_SA(0, 0), a2, voffA);
;             PG8_WAIT_V(8); PG8_WAIT_L(0); PG8_BAR; PG8_MMA(1, 0, At, B0); PG8_MMA(1, 1, At, B1); PG8_BAR; PG8_SCHED;
.LBB0_1275:
	ds_read_b128 v[132:135], v171
	ds_read_b128 v[136:139], v171 offset:1024
	ds_read_b128 v[140:143], v171 offset:2048
	ds_read_b128 v[178:181], v171 offset:3072
	ds_read_b128 v[182:185], v173
	ds_read_b128 v[186:189], v173 offset:1024
	ds_read_b128 v[190:193], v173 offset:2048
	ds_read_b128 v[194:197], v173 offset:3072
	s_add_u32 s38, s34, s36
	s_addc_u32 s39, s35, s37
	s_add_u32 s42, s38, 0x100
	s_addc_u32 s43, s39, 0
	s_add_u32 s40, s66, s36
	s_addc_u32 s41, s67, s37
	s_add_u32 s38, s38, 0x180
	s_addc_u32 s39, s39, 0
	s_cmpk_eq_i32 s36, 0x700
	s_cselect_b32 s39, s65, s39
	s_cselect_b32 s38, s64, s38
	s_cselect_b32 s41, s23, s41
	s_cselect_b32 s40, s63, s40
	s_cselect_b32 s43, s3, s43
	s_cselect_b32 s42, s25, s42
	v_lshl_add_u64 v[230:231], v[130:131], 0, s[36:37]
	s_add_i32 m0, s31, 0xc000
	ds_read_b128 v[198:201], v175
	ds_read_b128 v[202:205], v175 offset:1024
	ds_read_b128 v[206:209], v175 offset:2048
	ds_read_b128 v[210:213], v175 offset:3072
	ds_read_b128 v[214:217], v175 offset:4096
	ds_read_b128 v[218:221], v175 offset:5120
	ds_read_b128 v[222:225], v175 offset:6144
	ds_read_b128 v[226:229], v175 offset:7168
	global_load_lds_dwordx4 v[230:231], off
	v_lshl_add_u64 v[230:231], v[128:129], 0, s[36:37]
	s_add_i32 m0, s31, 0xe000
	s_nop 0
	global_load_lds_dwordx4 v[230:231], off
	s_waitcnt vmcnt(8)
	s_waitcnt lgkmcnt(0)
	s_barrier
	s_setprio 1
	s_waitcnt lgkmcnt(0)
	v_mfma_f32_16x16x32_bf16 v[124:127], v[132:135], v[198:201], v[124:127]
	v_mfma_f32_16x16x32_bf16 v[120:123], v[140:143], v[198:201], v[120:123]
	v_mfma_f32_16x16x32_bf16 v[116:119], v[132:135], v[206:209], v[116:119]
	v_mfma_f32_16x16x32_bf16 v[112:115], v[140:143], v[206:209], v[112:115]
	v_mfma_f32_16x16x32_bf16 v[108:111], v[132:135], v[214:217], v[108:111]
	v_mfma_f32_16x16x32_bf16 v[104:107], v[140:143], v[214:217], v[104:107]
	v_mfma_f32_16x16x32_bf16 v[100:103], v[132:135], v[222:225], v[100:103]
	v_mfma_f32_16x16x32_bf16 v[96:99], v[140:143], v[222:225], v[96:99]
	v_mfma_f32_16x16x32_bf16 v[124:127], v[136:139], v[202:205], v[124:127]
	v_mfma_f32_16x16x32_bf16 v[120:123], v[178:181], v[202:205], v[120:123]
	v_mfma_f32_16x16x32_bf16 v[116:119], v[136:139], v[210:213], v[116:119]
	v_mfma_f32_16x16x32_bf16 v[112:115], v[178:181], v[210:213], v[112:115]
	v_mfma_f32_16x16x32_bf16 v[108:111], v[136:139], v[218:221], v[108:111]
	v_mfma_f32_16x16x32_bf16 v[104:107], v[178:181], v[218:221], v[104:107]
	v_mfma_f32_16x16x32_bf16 v[100:103], v[136:139], v[226:229], v[100:103]
	v_mfma_f32_16x16x32_bf16 v[96:99], v[178:181], v[226:229], v[96:99]
	s_setprio 0
	s_setprio 1
	v_mfma_f32_16x16x32_bf16 v[64:67], v[182:185], v[198:201], v[64:67]
	v_mfma_f32_16x16x32_bf16 v[56:59], v[190:193], v[198:201], v[56:59]
	v_mfma_f32_16x16x32_bf16 v[52:55], v[182:185], v[206:209], v[52:55]
	v_mfma_f32_16x16x32_bf16 v[48:51], v[190:193], v[206:209], v[48:51]
	v_mfma_f32_16x16x32_bf16 v[44:47], v[182:185], v[214:217], v[44:47]
	v_mfma_f32_16x16x32_bf16 v[40:43], v[190:193], v[214:217], v[40:43]
	v_mfma_f32_16x16x32_bf16 v[36:39], v[182:185], v[222:225], v[36:39]
	v_mfma_f32_16x16x32_bf16 v[32:35], v[190:193], v[222:225], v[32:35]
	v_mfma_f32_16x16x32_bf16 v[64:67], v[186:189], v[202:205], v[64:67]
	v_mfma_f32_16x16x32_bf16 v[56:59], v[194:197], v[202:205], v[56:59]
	v_mfma_f32_16x16x32_bf16 v[52:55], v[186:189], v[210:213], v[52:55]
	v_mfma_f32_16x16x32_bf16 v[48:51], v[194:197], v[210:213], v[48:51]
	v_mfma_f32_16x16x32_bf16 v[44:47], v[186:189], v[218:221], v[44:47]
	v_mfma_f32_16x16x32_bf16 v[40:43], v[194:197], v[218:221], v[40:43]
	v_mfma_f32_16x16x32_bf16 v[36:39], v[186:189], v[226:229], v[36:39]
	v_mfma_f32_16x16x32_bf16 v[32:35], v[194:197], v[226:229], v[32:35]
	s_setprio 0
	s_barrier
	s_add_i32 s69, s59, s49
	v_lshl_add_u64 v[230:231], s[40:41], 0, v[148:149]
	s_mov_b32 m0, s69
	ds_read_b128 v[198:201], v175 offset:16384
	ds_read_b128 v[202:205], v175 offset:17408
	ds_read_b128 v[206:209], v175 offset:18432
	ds_read_b128 v[210:213], v175 offset:19456
	ds_read_b128 v[214:217], v175 offset:20480
	ds_read_b128 v[218:221], v175 offset:21504
	ds_read_b128 v[222:225], v175 offset:22528
	ds_read_b128 v[226:229], v175 offset:23552
	global_load_lds_dwordx4 v[230:231], off
	s_add_i32 m0, s69, 0x2000
	s_add_u32 s70, s40, 0x40000
	v_lshl_add_u64 v[232:233], s[40:41], 0, v[144:145]
	s_addc_u32 s71, s41, 0
	s_add_i32 s69, s60, s49
	global_load_lds_dwordx4 v[232:233], off
	v_lshl_add_u64 v[234:235], s[70:71], 0, v[148:149]
	s_mov_b32 m0, s69
	s_nop 0
	global_load_lds_dwordx4 v[234:235], off
	v_lshl_add_u64 v[234:235], s[70:71], 0, v[144:145]
	s_add_i32 m0, s69, 0x2000
	s_nop 0
	global_load_lds_dwordx4 v[234:235], off
	s_waitcnt vmcnt(6)
	s_waitcnt lgkmcnt(0)
	s_barrier
; #define PG8_STAGE(bufoff, gbase, voff) do { _Pragma("unroll") for (int _i = 0; _i < 2; ++_i) \
;         __builtin_amdgcn_global_load_lds((const unsigned*)((const char*)(gbase) + (voff)[_i]), (PG8_LAS unsigned*)(lds + (bufoff) + ldsw + _i * 8192), 16, 0, 0); } while (0)
; #define PG8_LDA(dst, b, h) do { _Pragma("unroll") for (int m = 0; m < 4; ++m) _Pragma("unroll") for (int k = 0; k < 2; ++k) dst[m][k] = *(const PG8_LAS bf16x8*)(lds + PG8_SA(b, h) + aoff + m * 2048 + k * 1024); } while (0)
; #define PG8_LDB(dst, b, h) do { _Pragma("unroll") for (int n = 0; n < 2; ++n) _Pragma("unroll") for (int k = 0; k < 2; ++k) dst[n][k] = *(const PG8_LAS bf16x8*)(lds + PG8_SB(b, h) + boff + n * 2048 + k * 1024); } while (0)
; #define PG8_MMA(ai, bj, At, Bt) do { __builtin_amdgcn_s_setprio(1); _Pragma("unroll") for (int m = 0; m < 4; ++m) _Pragma("unroll") for (int n = 0; n < 2; ++n) _Pragma("unroll") for (int k = 0; k < 2; ++k) \
;         acc[ai][bj][m][n] = __builtin_amdgcn_mfma_f32_16x16x32_bf16(Bt[n][k], At[m][k], acc[ai][bj][m][n], 0, 0, 0); __builtin_amdgcn_s_setprio(0); } while (0)
; #define PG8_WAIT_V(n) asm volatile("s_waitcnt vmcnt(" #n ")" ::: "memory")
; #define PG8_WAIT_L(n) asm volatile("s_waitcnt lgkmcnt(" #n ")" ::: "memory")
; #define PG8_BAR __builtin_amdgcn_s_barrier()
; #define PG8_SCHED __builtin_amdgcn_sched_barrier(0)
; template <class Epi, class Sched, bool ALIGN_EPI = false, bool SP2 = false>
; __device__ __forceinline__ void gemm_phase(PG8_LAS unsigned char* lds, const Gemm g, const Sched& S, const Epi& E) {
;     ...
;             PG8_WAIT_V(8); PG8_WAIT_L(0); PG8_BAR; PG8_MMA(1, 0, At, B0); PG8_MMA(1, 1, At, B1); PG8_BAR; PG8_SCHED;
;             PG8_LDB(B0, 1, 0); PG8_LDB(B1, 1, 1); PG8_SCHED; PG8_LDA(At, 1, 0); PG8_STAGE(PG8_SA(0, 1), a2 + hstepA, voffA);
;             PG8_WAIT_V(8); PG8_WAIT_L(0); PG8_BAR; PG8_MMA(0, 0, At, B0); PG8_MMA(0, 1, At, B1); PG8_BAR; PG8_SCHED;
	s_setprio 1
	s_waitcnt lgkmcnt(0)
	v_mfma_f32_16x16x32_bf16 v[92:95], v[132:135], v[198:201], v[92:95]
	v_mfma_f32_16x16x32_bf16 v[88:91], v[140:143], v[198:201], v[88:91]
	v_mfma_f32_16x16x32_bf16 v[84:87], v[132:135], v[206:209], v[84:87]
	v_mfma_f32_16x16x32_bf16 v[80:83], v[140:143], v[206:209], v[80:83]
	v_mfma_f32_16x16x32_bf16 v[76:79], v[132:135], v[214:217], v[76:79]
	v_mfma_f32_16x16x32_bf16 v[72:75], v[140:143], v[214:217], v[72:75]
	v_mfma_f32_16x16x32_bf16 v[68:71], v[132:135], v[222:225], v[68:71]
	v_mfma_f32_16x16x32_bf16 v[60:63], v[140:143], v[222:225], v[60:63]
	v_mfma_f32_16x16x32_bf16 v[92:95], v[136:139], v[202:205], v[92:95]
	v_mfma_f32_16x16x32_bf16 v[88:91], v[178:181], v[202:205], v[88:91]
	v_mfma_f32_16x16x32_bf16 v[84:87], v[136:139], v[210:213], v[84:87]
	v_mfma_f32_16x16x32_bf16 v[80:83], v[178:181], v[210:213], v[80:83]
	v_mfma_f32_16x16x32_bf16 v[76:79], v[136:139], v[218:221], v[76:79]
	v_mfma_f32_16x16x32_bf16 v[72:75], v[178:181], v[218:221], v[72:75]
	v_mfma_f32_16x16x32_bf16 v[68:71], v[136:139], v[226:229], v[68:71]
	v_mfma_f32_16x16x32_bf16 v[60:63], v[178:181], v[226:229], v[60:63]
	s_setprio 0
	s_setprio 1
	v_mfma_f32_16x16x32_bf16 v[28:31], v[182:185], v[198:201], v[28:31]
	v_mfma_f32_16x16x32_bf16 v[24:27], v[190:193], v[198:201], v[24:27]
	v_mfma_f32_16x16x32_bf16 v[20:23], v[182:185], v[206:209], v[20:23]
	v_mfma_f32_16x16x32_bf16 v[16:19], v[190:193], v[206:209], v[16:19]
	v_mfma_f32_16x16x32_bf16 v[12:15], v[182:185], v[214:217], v[12:15]
	v_mfma_f32_16x16x32_bf16 v[8:11], v[190:193], v[214:217], v[8:11]
	v_mfma_f32_16x16x32_bf16 v[4:7], v[182:185], v[222:225], v[4:7]
	v_mfma_f32_16x16x32_bf16 v[0:3], v[190:193], v[222:225], v[0:3]
	v_mfma_f32_16x16x32_bf16 v[28:31], v[186:189], v[202:205], v[28:31]
	v_mfma_f32_16x16x32_bf16 v[24:27], v[194:197], v[202:205], v[24:27]
	v_mfma_f32_16x16x32_bf16 v[20:23], v[186:189], v[210:213], v[20:23]
	v_mfma_f32_16x16x32_bf16 v[16:19], v[194:197], v[210:213], v[16:19]
	v_mfma_f32_16x16x32_bf16 v[12:15], v[186:189], v[218:221], v[12:15]
	v_mfma_f32_16x16x32_bf16 v[8:11], v[194:197], v[218:221], v[8:11]
	v_mfma_f32_16x16x32_bf16 v[4:7], v[186:189], v[226:229], v[4:7]
	v_mfma_f32_16x16x32_bf16 v[0:3], v[194:197], v[226:229], v[0:3]
	s_setprio 0
	s_barrier
	s_add_i32 s69, 0, 0x18000
	v_add_u32_e32 v160, s69, v163
	s_add_i32 s70, 0, 0x1c000
	ds_read_b128 v[132:135], v160
	ds_read_b128 v[136:139], v160 offset:1024
	ds_read_b128 v[140:143], v160 offset:2048
	ds_read_b128 v[178:181], v160 offset:3072
	v_add_u32_e32 v160, s70, v163
	ds_read_b128 v[182:185], v160
	ds_read_b128 v[186:189], v160 offset:1024
	ds_read_b128 v[190:193], v160 offset:2048
	ds_read_b128 v[194:197], v160 offset:3072
	v_lshl_add_u64 v[234:235], s[42:43], 0, v[150:151]
	s_mov_b32 m0, s31
	s_nop 0
	global_load_lds_dwordx4 v[234:235], off
	v_lshl_add_u64 v[234:235], s[42:43], 0, v[146:147]
	s_mov_b32 m0, s52
	s_nop 0
	global_load_lds_dwordx4 v[234:235], off
	s_add_u32 s42, s42, 0x40000
	s_addc_u32 s43, s43, 0
	s_mov_b32 m0, s53
	v_lshl_add_u64 v[234:235], s[42:43], 0, v[150:151]
	ds_read_b128 v[198:201], v175 offset:32768
	ds_read_b128 v[202:205], v175 offset:33792
	ds_read_b128 v[206:209], v175 offset:34816
	ds_read_b128 v[210:213], v175 offset:35840
	ds_read_b128 v[214:217], v175 offset:36864
	ds_read_b128 v[218:221], v175 offset:37888
	ds_read_b128 v[222:225], v175 offset:38912
	ds_read_b128 v[226:229], v175 offset:39936
	global_load_lds_dwordx4 v[234:235], off
	v_lshl_add_u64 v[234:235], s[42:43], 0, v[146:147]
	s_mov_b32 m0, s54
	s_nop 0
	global_load_lds_dwordx4 v[234:235], off
	s_waitcnt vmcnt(8)
	s_waitcnt lgkmcnt(0)
	s_barrier
	s_setprio 1
	s_waitcnt lgkmcnt(0)
	v_mfma_f32_16x16x32_bf16 v[124:127], v[132:135], v[198:201], v[124:127]
	v_mfma_f32_16x16x32_bf16 v[120:123], v[140:143], v[198:201], v[120:123]
	v_mfma_f32_16x16x32_bf16 v[116:119], v[132:135], v[206:209], v[116:119]
	v_mfma_f32_16x16x32_bf16 v[112:115], v[140:143], v[206:209], v[112:115]
	v_mfma_f32_16x16x32_bf16 v[108:111], v[132:135], v[214:217], v[108:111]
	v_mfma_f32_16x16x32_bf16 v[104:107], v[140:143], v[214:217], v[104:107]
	v_mfma_f32_16x16x32_bf16 v[100:103], v[132:135], v[222:225], v[100:103]
	v_mfma_f32_16x16x32_bf16 v[96:99], v[140:143], v[222:225], v[96:99]
	v_mfma_f32_16x16x32_bf16 v[124:127], v[136:139], v[202:205], v[124:127]
	v_mfma_f32_16x16x32_bf16 v[120:123], v[178:181], v[202:205], v[120:123]
	v_mfma_f32_16x16x32_bf16 v[116:119], v[136:139], v[210:213], v[116:119]
	v_mfma_f32_16x16x32_bf16 v[112:115], v[178:181], v[210:213], v[112:115]
	v_mfma_f32_16x16x32_bf16 v[108:111], v[136:139], v[218:221], v[108:111]
	v_mfma_f32_16x16x32_bf16 v[104:107], v[178:181], v[218:221], v[104:107]
	v_mfma_f32_16x16x32_bf16 v[100:103], v[136:139], v[226:229], v[100:103]
	v_mfma_f32_16x16x32_bf16 v[96:99], v[178:181], v[226:229], v[96:99]
	s_setprio 0
	s_setprio 1
	v_mfma_f32_16x16x32_bf16 v[64:67], v[182:185], v[198:201], v[64:67]
	v_mfma_f32_16x16x32_bf16 v[56:59], v[190:193], v[198:201], v[56:59]
	v_mfma_f32_16x16x32_bf16 v[52:55], v[182:185], v[206:209], v[52:55]
	v_mfma_f32_16x16x32_bf16 v[48:51], v[190:193], v[206:209], v[48:51]
	v_mfma_f32_16x16x32_bf16 v[44:47], v[182:185], v[214:217], v[44:47]
	v_mfma_f32_16x16x32_bf16 v[40:43], v[190:193], v[214:217], v[40:43]
	v_mfma_f32_16x16x32_bf16 v[36:39], v[182:185], v[222:225], v[36:39]
	v_mfma_f32_16x16x32_bf16 v[32:35], v[190:193], v[222:225], v[32:35]
	v_mfma_f32_16x16x32_bf16 v[64:67], v[186:189], v[202:205], v[64:67]
	v_mfma_f32_16x16x32_bf16 v[56:59], v[194:197], v[202:205], v[56:59]
	v_mfma_f32_16x16x32_bf16 v[52:55], v[186:189], v[210:213], v[52:55]
	v_mfma_f32_16x16x32_bf16 v[48:51], v[194:197], v[210:213], v[48:51]
	v_mfma_f32_16x16x32_bf16 v[44:47], v[186:189], v[218:221], v[44:47]
	v_mfma_f32_16x16x32_bf16 v[40:43], v[194:197], v[218:221], v[40:43]
	v_mfma_f32_16x16x32_bf16 v[36:39], v[186:189], v[226:229], v[36:39]
	v_mfma_f32_16x16x32_bf16 v[32:35], v[194:197], v[226:229], v[32:35]
	s_setprio 0
	s_barrier
; #define PG8_STAGE(bufoff, gbase, voff) do { _Pragma("unroll") for (int _i = 0; _i < 2; ++_i) \
;         __builtin_amdgcn_global_load_lds((const unsigned*)((const char*)(gbase) + (voff)[_i]), (PG8_LAS unsigned*)(lds + (bufoff) + ldsw + _i * 8192), 16, 0, 0); } while (0)
; #define PG8_LDA(dst, b, h) do { _Pragma("unroll") for (int m = 0; m < 4; ++m) _Pragma("unroll") for (int k = 0; k < 2; ++k) dst[m][k] = *(const PG8_LAS bf16x8*)(lds + PG8_SA(b, h) + aoff + m * 2048 + k * 1024); } while (0)
; #define PG8_MMA(ai, bj, At, Bt) do { __builtin_amdgcn_s_setprio(1); _Pragma("unroll") for (int m = 0; m < 4; ++m) _Pragma("unroll") for (int n = 0; n < 2; ++n) _Pragma("unroll") for (int k = 0; k < 2; ++k) \
;         acc[ai][bj][m][n] = __builtin_amdgcn_mfma_f32_16x16x32_bf16(Bt[n][k], At[m][k], acc[ai][bj][m][n], 0, 0, 0); __builtin_amdgcn_s_setprio(0); } while (0)
; #define PG8_WAIT_V(n) asm volatile("s_waitcnt vmcnt(" #n ")" ::: "memory")
; #define PG8_WAIT_L(n) asm volatile("s_waitcnt lgkmcnt(" #n ")" ::: "memory")
; #define PG8_BAR __builtin_amdgcn_s_barrier()
; #define PG8_SCHED __builtin_amdgcn_sched_barrier(0)
; template <class Epi, class Sched, bool ALIGN_EPI = false, bool SP2 = false>
; __device__ __forceinline__ void gemm_phase(PG8_LAS unsigned char* lds, const Gemm g, const Sched& S, const Epi& E) {
;     ...
;             PG8_LDA(At, 1, 1); PG8_STAGE(PG8_SB(1, 0), b3, voffB); PG8_STAGE(PG8_SB(1, 1), b3 + hstepB, voffB); PG8_STAGE(PG8_SA(1, 0), a3, voffA);
;             PG8_WAIT_V(8); PG8_WAIT_L(0); PG8_BAR; PG8_MMA(1, 0, At, B0); PG8_MMA(1, 1, At, B1); PG8_BAR; PG8_SCHED;
	s_add_i32 s42, s69, s49
	v_lshl_add_u64 v[230:231], v[230:231], 0, s[16:17]
	s_mov_b32 m0, s42
	ds_read_b128 v[198:201], v175 offset:49152
	ds_read_b128 v[202:205], v175 offset:50176
	ds_read_b128 v[206:209], v175 offset:51200
	ds_read_b128 v[210:213], v175 offset:52224
	ds_read_b128 v[214:217], v175 offset:53248
	ds_read_b128 v[218:221], v175 offset:54272
	ds_read_b128 v[222:225], v175 offset:55296
	ds_read_b128 v[226:229], v175 offset:56320
	global_load_lds_dwordx4 v[230:231], off
	s_add_i32 m0, s42, 0x2000
	s_add_u32 s40, s40, 0x40080
	v_lshl_add_u64 v[230:231], v[232:233], 0, s[16:17]
	s_addc_u32 s41, s41, 0
	s_add_i32 s42, s70, s49
	global_load_lds_dwordx4 v[230:231], off
	v_lshl_add_u64 v[230:231], s[40:41], 0, v[148:149]
	s_mov_b32 m0, s42
	s_nop 0
	global_load_lds_dwordx4 v[230:231], off
	v_lshl_add_u64 v[230:231], s[40:41], 0, v[144:145]
	s_add_i32 m0, s42, 0x2000
	s_nop 0
	global_load_lds_dwordx4 v[230:231], off
	v_lshl_add_u64 v[230:231], s[38:39], 0, v[150:151]
	s_mov_b32 m0, s56
	s_nop 0
	global_load_lds_dwordx4 v[230:231], off
	v_lshl_add_u64 v[230:231], s[38:39], 0, v[146:147]
	s_mov_b32 m0, s57
	s_nop 0
	global_load_lds_dwordx4 v[230:231], off
	s_waitcnt vmcnt(8)
	s_waitcnt lgkmcnt(0)
	s_barrier
	s_setprio 1
	s_waitcnt lgkmcnt(0)
	v_mfma_f32_16x16x32_bf16 v[92:95], v[132:135], v[198:201], v[92:95]
	v_mfma_f32_16x16x32_bf16 v[88:91], v[140:143], v[198:201], v[88:91]
	v_mfma_f32_16x16x32_bf16 v[84:87], v[132:135], v[206:209], v[84:87]
	v_mfma_f32_16x16x32_bf16 v[80:83], v[140:143], v[206:209], v[80:83]
	v_mfma_f32_16x16x32_bf16 v[76:79], v[132:135], v[214:217], v[76:79]
	v_mfma_f32_16x16x32_bf16 v[72:75], v[140:143], v[214:217], v[72:75]
	v_mfma_f32_16x16x32_bf16 v[68:71], v[132:135], v[222:225], v[68:71]
	v_mfma_f32_16x16x32_bf16 v[60:63], v[140:143], v[222:225], v[60:63]
	v_mfma_f32_16x16x32_bf16 v[92:95], v[136:139], v[202:205], v[92:95]
	v_mfma_f32_16x16x32_bf16 v[88:91], v[178:181], v[202:205], v[88:91]
	v_mfma_f32_16x16x32_bf16 v[84:87], v[136:139], v[210:213], v[84:87]
	v_mfma_f32_16x16x32_bf16 v[80:83], v[178:181], v[210:213], v[80:83]
	v_mfma_f32_16x16x32_bf16 v[76:79], v[136:139], v[218:221], v[76:79]
	v_mfma_f32_16x16x32_bf16 v[72:75], v[178:181], v[218:221], v[72:75]
	v_mfma_f32_16x16x32_bf16 v[68:71], v[136:139], v[226:229], v[68:71]
	v_mfma_f32_16x16x32_bf16 v[60:63], v[178:181], v[226:229], v[60:63]
	s_setprio 0
	s_setprio 1
	v_mfma_f32_16x16x32_bf16 v[28:31], v[182:185], v[198:201], v[28:31]
	v_mfma_f32_16x16x32_bf16 v[24:27], v[190:193], v[198:201], v[24:27]
	v_mfma_f32_16x16x32_bf16 v[20:23], v[182:185], v[206:209], v[20:23]
	v_mfma_f32_16x16x32_bf16 v[16:19], v[190:193], v[206:209], v[16:19]
	v_mfma_f32_16x16x32_bf16 v[12:15], v[182:185], v[214:217], v[12:15]
	v_mfma_f32_16x16x32_bf16 v[8:11], v[190:193], v[214:217], v[8:11]
	v_mfma_f32_16x16x32_bf16 v[4:7], v[182:185], v[222:225], v[4:7]
	v_mfma_f32_16x16x32_bf16 v[0:3], v[190:193], v[222:225], v[0:3]
	v_mfma_f32_16x16x32_bf16 v[28:31], v[186:189], v[202:205], v[28:31]
	v_mfma_f32_16x16x32_bf16 v[24:27], v[194:197], v[202:205], v[24:27]
	v_mfma_f32_16x16x32_bf16 v[20:23], v[186:189], v[210:213], v[20:23]
	v_mfma_f32_16x16x32_bf16 v[16:19], v[194:197], v[210:213], v[16:19]
	v_mfma_f32_16x16x32_bf16 v[12:15], v[186:189], v[218:221], v[12:15]
	v_mfma_f32_16x16x32_bf16 v[8:11], v[194:197], v[218:221], v[8:11]
	v_mfma_f32_16x16x32_bf16 v[4:7], v[186:189], v[226:229], v[4:7]
	v_mfma_f32_16x16x32_bf16 v[0:3], v[194:197], v[226:229], v[0:3]
	s_setprio 0
	s_barrier
	s_add_i32 s68, s68, 2
	s_add_u32 s36, s36, 0x100
	s_addc_u32 s37, s37, 0
	s_cmp_gt_u32 s68, 13
	s_cbranch_scc0 .LBB0_1275
	s_and_b64 vcc, exec, s[18:19]
	s_cbranch_vccz .LBB0_1278
	s_barrier

; #define PG8_STAGE(bufoff, gbase, voff) do { _Pragma("unroll") for (int _i = 0; _i < 2; ++_i) \
;         __builtin_amdgcn_global_load_lds((const unsigned*)((const char*)(gbase) + (voff)[_i]), (PG8_LAS unsigned*)(lds + (bufoff) + ldsw + _i * 8192), 16, 0, 0); } while (0)
; #define PG8_LDA(dst, b, h) do { _Pragma("unroll") for (int m = 0; m < 4; ++m) _Pragma("unroll") for (int k = 0; k < 2; ++k) dst[m][k] = *(const PG8_LAS bf16x8*)(lds + PG8_SA(b, h) + aoff + m * 2048 + k * 1024); } while (0)
; #define PG8_LDB(dst, b, h) do { _Pragma("unroll") for (int n = 0; n < 2; ++n) _Pragma("unroll") for (int k = 0; k < 2; ++k) dst[n][k] = *(const PG8_LAS bf16x8*)(lds + PG8_SB(b, h) + boff + n * 2048 + k * 1024); } while (0)
; #define PG8_MMA(ai, bj, At, Bt) do { __builtin_amdgcn_s_setprio(1); _Pragma("unroll") for (int m = 0; m < 4; ++m) _Pragma("unroll") for (int n = 0; n < 2; ++n) _Pragma("unroll") for (int k = 0; k < 2; ++k) \
;         acc[ai][bj][m][n] = __builtin_amdgcn_mfma_f32_16x16x32_bf16(Bt[n][k], At[m][k], acc[ai][bj][m][n], 0, 0, 0); __builtin_amdgcn_s_setprio(0); } while (0)
; #define PG8_WAIT_V(n) asm volatile("s_waitcnt vmcnt(" #n ")" ::: "memory")
; #define PG8_WAIT_L(n) asm volatile("s_waitcnt lgkmcnt(" #n ")" ::: "memory")
; template <class Epi, class Sched, bool ALIGN_EPI = false, bool SP2 = false>
; __device__ __forceinline__ void gemm_phase(PG8_LAS unsigned char* lds, const Gemm g, const Sched& S, const Epi& E) {
;     ...
;             const bool last = (t == nt - 2);
;             const char* a1 = cA + PG8_AK(t + 1);
;             const char* a2 = last ? nA : cA + PG8_AK(t + 2); const char* b2 = last ? nB : cB + (size_t)(t + 2) * kstep;
;             const char* a3 = last ? nA + PG8_AK(1) : cA + PG8_AK(t + 3); const char* b3 = b2 + kstep;
;             if (last && has_next) S.a_ready(nxt);
;             if constexpr (SP2) {
;             PG8_LDB(B0, 0, 0); PG8_LDB(B1, 0, 1); PG8_SCHED; PG8_LDA(At, 0, 0); PG8_STAGE(PG8_SA(1, 1), a1 + hstepA, voffA);
;             PG8_WAIT_V(8); PG8_WAIT_L(0); PG8_BAR; PG8_MMA(0, 0, At, B0); PG8_MMA(0, 1, At, B1); PG8_BAR; PG8_SCHED;
;             PG8_LDA(At, 0, 1); PG8_STAGE(PG8_SB(0, 0), b2, voffB); PG8_STAGE(PG8_SB(0, 1), b2 + hstepB, voffB); PG8_STAGE(PG8_SA(0, 0), a2, voffA);
;             PG8_WAIT_V(8); PG8_WAIT_L(0); PG8_BAR; PG8_MMA(1, 0, At, B0); PG8_MMA(1, 1, At, B1); PG8_BAR; PG8_SCHED;
.LBB0_1379:
	ds_read_b128 v[124:127], v210
	ds_read_b128 v[128:131], v210 offset:1024
	ds_read_b128 v[132:135], v210 offset:2048
	ds_read_b128 v[144:147], v210 offset:3072
	ds_read_b128 v[148:151], v211
	ds_read_b128 v[170:173], v211 offset:1024
	ds_read_b128 v[174:177], v211 offset:2048
	ds_read_b128 v[178:181], v211 offset:3072
	s_add_u32 s42, s38, s40
	s_addc_u32 s43, s39, s41
	s_add_u32 s46, s42, 0x100
	s_addc_u32 s47, s43, 0
	s_add_u32 s44, s78, s40
	s_addc_u32 s45, s79, s41
	s_add_u32 s42, s42, 0x180
	s_addc_u32 s43, s43, 0
	s_cmpk_eq_i32 s40, 0x1500
	s_cselect_b32 s43, s10, s43
	s_cselect_b32 s42, s3, s42
	s_cselect_b32 s45, s37, s45
	s_cselect_b32 s44, s36, s44
	s_cselect_b32 s47, s9, s47
	s_cselect_b32 s46, s8, s46
	v_lshl_add_u64 v[206:207], v[122:123], 0, s[40:41]
	s_add_i32 m0, s53, 0xc000
	ds_read_b128 v[212:215], v191
	ds_read_b128 v[216:219], v191 offset:1024
	ds_read_b128 v[220:223], v191 offset:2048
	ds_read_b128 v[224:227], v191 offset:3072
	ds_read_b128 v[228:231], v191 offset:4096
	ds_read_b128 v[232:235], v191 offset:5120
	ds_read_b128 v[236:239], v191 offset:6144
	ds_read_b128 v[240:243], v191 offset:7168
	global_load_lds_dwordx4 v[206:207], off
	v_lshl_add_u64 v[206:207], v[120:121], 0, s[40:41]
	s_add_i32 m0, s53, 0xe000
	s_nop 0
	global_load_lds_dwordx4 v[206:207], off
	s_waitcnt vmcnt(8)
	s_waitcnt lgkmcnt(0)
	s_barrier
	s_setprio 1
	s_waitcnt lgkmcnt(0)
	v_mfma_f32_16x16x32_bf16 v[140:143], v[124:127], v[212:215], v[140:143]
	v_mfma_f32_16x16x32_bf16 v[136:139], v[132:135], v[212:215], v[136:139]
	v_mfma_f32_16x16x32_bf16 v[116:119], v[124:127], v[220:223], v[116:119]
	v_mfma_f32_16x16x32_bf16 v[112:115], v[132:135], v[220:223], v[112:115]
	v_mfma_f32_16x16x32_bf16 v[108:111], v[124:127], v[228:231], v[108:111]
	v_mfma_f32_16x16x32_bf16 v[104:107], v[132:135], v[228:231], v[104:107]
	v_mfma_f32_16x16x32_bf16 v[100:103], v[124:127], v[236:239], v[100:103]
	v_mfma_f32_16x16x32_bf16 v[96:99], v[132:135], v[236:239], v[96:99]
	v_mfma_f32_16x16x32_bf16 v[140:143], v[128:131], v[216:219], v[140:143]
	v_mfma_f32_16x16x32_bf16 v[136:139], v[144:147], v[216:219], v[136:139]
	v_mfma_f32_16x16x32_bf16 v[116:119], v[128:131], v[224:227], v[116:119]
	v_mfma_f32_16x16x32_bf16 v[112:115], v[144:147], v[224:227], v[112:115]
	v_mfma_f32_16x16x32_bf16 v[108:111], v[128:131], v[232:235], v[108:111]
	v_mfma_f32_16x16x32_bf16 v[104:107], v[144:147], v[232:235], v[104:107]
	v_mfma_f32_16x16x32_bf16 v[100:103], v[128:131], v[240:243], v[100:103]
	v_mfma_f32_16x16x32_bf16 v[96:99], v[144:147], v[240:243], v[96:99]
	s_setprio 0
	s_setprio 1
	v_mfma_f32_16x16x32_bf16 v[60:63], v[148:151], v[212:215], v[60:63]
	v_mfma_f32_16x16x32_bf16 v[56:59], v[174:177], v[212:215], v[56:59]
	v_mfma_f32_16x16x32_bf16 v[52:55], v[148:151], v[220:223], v[52:55]
	v_mfma_f32_16x16x32_bf16 v[48:51], v[174:177], v[220:223], v[48:51]
	v_mfma_f32_16x16x32_bf16 v[44:47], v[148:151], v[228:231], v[44:47]
	v_mfma_f32_16x16x32_bf16 v[40:43], v[174:177], v[228:231], v[40:43]
	v_mfma_f32_16x16x32_bf16 v[36:39], v[148:151], v[236:239], v[36:39]
	v_mfma_f32_16x16x32_bf16 v[32:35], v[174:177], v[236:239], v[32:35]
	v_mfma_f32_16x16x32_bf16 v[60:63], v[170:173], v[216:219], v[60:63]
	v_mfma_f32_16x16x32_bf16 v[56:59], v[178:181], v[216:219], v[56:59]
	v_mfma_f32_16x16x32_bf16 v[52:55], v[170:173], v[224:227], v[52:55]
	v_mfma_f32_16x16x32_bf16 v[48:51], v[178:181], v[224:227], v[48:51]
	v_mfma_f32_16x16x32_bf16 v[44:47], v[170:173], v[232:235], v[44:47]
	v_mfma_f32_16x16x32_bf16 v[40:43], v[178:181], v[232:235], v[40:43]
	v_mfma_f32_16x16x32_bf16 v[36:39], v[170:173], v[240:243], v[36:39]
	v_mfma_f32_16x16x32_bf16 v[32:35], v[178:181], v[240:243], v[32:35]
	s_setprio 0
	s_barrier
	s_add_i32 s70, s67, s52
	v_lshl_add_u64 v[206:207], s[44:45], 0, v[154:155]
	s_mov_b32 m0, s70
	ds_read_b128 v[212:215], v191 offset:16384
	ds_read_b128 v[216:219], v191 offset:17408
	ds_read_b128 v[220:223], v191 offset:18432
	ds_read_b128 v[224:227], v191 offset:19456
	ds_read_b128 v[228:231], v191 offset:20480
	ds_read_b128 v[232:235], v191 offset:21504
	ds_read_b128 v[236:239], v191 offset:22528
	ds_read_b128 v[240:243], v191 offset:23552
	global_load_lds_dwordx4 v[206:207], off
	s_add_i32 m0, s70, 0x2000
	s_add_u32 s70, s44, 0xb0000
	v_lshl_add_u64 v[244:245], s[44:45], 0, v[158:159]
	s_addc_u32 s71, s45, 0
	s_add_i32 s85, s68, s52
	global_load_lds_dwordx4 v[244:245], off
	v_lshl_add_u64 v[246:247], s[70:71], 0, v[154:155]
	s_mov_b32 m0, s85
	s_nop 0
	global_load_lds_dwordx4 v[246:247], off
	v_lshl_add_u64 v[246:247], s[70:71], 0, v[158:159]
	s_add_i32 m0, s85, 0x2000
	s_nop 0
	global_load_lds_dwordx4 v[246:247], off
	s_waitcnt vmcnt(6)
	s_waitcnt lgkmcnt(0)
	s_barrier
; #define PG8_STAGE(bufoff, gbase, voff) do { _Pragma("unroll") for (int _i = 0; _i < 2; ++_i) \
;         __builtin_amdgcn_global_load_lds((const unsigned*)((const char*)(gbase) + (voff)[_i]), (PG8_LAS unsigned*)(lds + (bufoff) + ldsw + _i * 8192), 16, 0, 0); } while (0)
; #define PG8_LDA(dst, b, h) do { _Pragma("unroll") for (int m = 0; m < 4; ++m) _Pragma("unroll") for (int k = 0; k < 2; ++k) dst[m][k] = *(const PG8_LAS bf16x8*)(lds + PG8_SA(b, h) + aoff + m * 2048 + k * 1024); } while (0)
; #define PG8_LDB(dst, b, h) do { _Pragma("unroll") for (int n = 0; n < 2; ++n) _Pragma("unroll") for (int k = 0; k < 2; ++k) dst[n][k] = *(const PG8_LAS bf16x8*)(lds + PG8_SB(b, h) + boff + n * 2048 + k * 1024); } while (0)
; #define PG8_MMA(ai, bj, At, Bt) do { __builtin_amdgcn_s_setprio(1); _Pragma("unroll") for (int m = 0; m < 4; ++m) _Pragma("unroll") for (int n = 0; n < 2; ++n) _Pragma("unroll") for (int k = 0; k < 2; ++k) \
;         acc[ai][bj][m][n] = __builtin_amdgcn_mfma_f32_16x16x32_bf16(Bt[n][k], At[m][k], acc[ai][bj][m][n], 0, 0, 0); __builtin_amdgcn_s_setprio(0); } while (0)
; #define PG8_WAIT_V(n) asm volatile("s_waitcnt vmcnt(" #n ")" ::: "memory")
; #define PG8_WAIT_L(n) asm volatile("s_waitcnt lgkmcnt(" #n ")" ::: "memory")
; #define PG8_BAR __builtin_amdgcn_s_barrier()
; #define PG8_SCHED __builtin_amdgcn_sched_barrier(0)
; template <class Epi, class Sched, bool ALIGN_EPI = false, bool SP2 = false>
; __device__ __forceinline__ void gemm_phase(PG8_LAS unsigned char* lds, const Gemm g, const Sched& S, const Epi& E) {
;     ...
;             PG8_WAIT_V(8); PG8_WAIT_L(0); PG8_BAR; PG8_MMA(1, 0, At, B0); PG8_MMA(1, 1, At, B1); PG8_BAR; PG8_SCHED;
;             PG8_LDB(B0, 1, 0); PG8_LDB(B1, 1, 1); PG8_SCHED; PG8_LDA(At, 1, 0); PG8_STAGE(PG8_SA(0, 1), a2 + hstepA, voffA);
;             PG8_WAIT_V(8); PG8_WAIT_L(0); PG8_BAR; PG8_MMA(0, 0, At, B0); PG8_MMA(0, 1, At, B1); PG8_BAR; PG8_SCHED;
	s_setprio 1
	s_waitcnt lgkmcnt(0)
	v_mfma_f32_16x16x32_bf16 v[92:95], v[124:127], v[212:215], v[92:95]
	v_mfma_f32_16x16x32_bf16 v[88:91], v[132:135], v[212:215], v[88:91]
	v_mfma_f32_16x16x32_bf16 v[84:87], v[124:127], v[220:223], v[84:87]
	v_mfma_f32_16x16x32_bf16 v[80:83], v[132:135], v[220:223], v[80:83]
	v_mfma_f32_16x16x32_bf16 v[76:79], v[124:127], v[228:231], v[76:79]
	v_mfma_f32_16x16x32_bf16 v[72:75], v[132:135], v[228:231], v[72:75]
	v_mfma_f32_16x16x32_bf16 v[68:71], v[124:127], v[236:239], v[68:71]
	v_mfma_f32_16x16x32_bf16 v[64:67], v[132:135], v[236:239], v[64:67]
	v_mfma_f32_16x16x32_bf16 v[92:95], v[128:131], v[216:219], v[92:95]
	v_mfma_f32_16x16x32_bf16 v[88:91], v[144:147], v[216:219], v[88:91]
	v_mfma_f32_16x16x32_bf16 v[84:87], v[128:131], v[224:227], v[84:87]
	v_mfma_f32_16x16x32_bf16 v[80:83], v[144:147], v[224:227], v[80:83]
	v_mfma_f32_16x16x32_bf16 v[76:79], v[128:131], v[232:235], v[76:79]
	v_mfma_f32_16x16x32_bf16 v[72:75], v[144:147], v[232:235], v[72:75]
	v_mfma_f32_16x16x32_bf16 v[68:71], v[128:131], v[240:243], v[68:71]
	v_mfma_f32_16x16x32_bf16 v[64:67], v[144:147], v[240:243], v[64:67]
	s_setprio 0
	s_setprio 1
	v_mfma_f32_16x16x32_bf16 v[28:31], v[148:151], v[212:215], v[28:31]
	v_mfma_f32_16x16x32_bf16 v[24:27], v[174:177], v[212:215], v[24:27]
	v_mfma_f32_16x16x32_bf16 v[20:23], v[148:151], v[220:223], v[20:23]
	v_mfma_f32_16x16x32_bf16 v[16:19], v[174:177], v[220:223], v[16:19]
	v_mfma_f32_16x16x32_bf16 v[12:15], v[148:151], v[228:231], v[12:15]
	v_mfma_f32_16x16x32_bf16 v[8:11], v[174:177], v[228:231], v[8:11]
	v_mfma_f32_16x16x32_bf16 v[4:7], v[148:151], v[236:239], v[4:7]
	v_mfma_f32_16x16x32_bf16 v[0:3], v[174:177], v[236:239], v[0:3]
	v_mfma_f32_16x16x32_bf16 v[28:31], v[170:173], v[216:219], v[28:31]
	v_mfma_f32_16x16x32_bf16 v[24:27], v[178:181], v[216:219], v[24:27]
	v_mfma_f32_16x16x32_bf16 v[20:23], v[170:173], v[224:227], v[20:23]
	v_mfma_f32_16x16x32_bf16 v[16:19], v[178:181], v[224:227], v[16:19]
	v_mfma_f32_16x16x32_bf16 v[12:15], v[170:173], v[232:235], v[12:15]
	v_mfma_f32_16x16x32_bf16 v[8:11], v[178:181], v[232:235], v[8:11]
	v_mfma_f32_16x16x32_bf16 v[4:7], v[170:173], v[240:243], v[4:7]
	v_mfma_f32_16x16x32_bf16 v[0:3], v[178:181], v[240:243], v[0:3]
	s_setprio 0
	s_barrier
	s_add_i32 s70, 0, 0x18000
	s_add_i32 s71, 0, 0x1c000
	v_add_u32_e32 v144, s70, v185
	v_add_u32_e32 v161, s71, v185
	ds_read_b128 v[124:127], v144
	ds_read_b128 v[128:131], v144 offset:1024
	ds_read_b128 v[132:135], v144 offset:2048
	ds_read_b128 v[144:147], v144 offset:3072
	ds_read_b128 v[148:151], v161
	ds_read_b128 v[170:173], v161 offset:1024
	ds_read_b128 v[174:177], v161 offset:2048
	ds_read_b128 v[178:181], v161 offset:3072
	v_lshl_add_u64 v[246:247], s[46:47], 0, v[152:153]
	s_mov_b32 m0, s53
	s_nop 0
	global_load_lds_dwordx4 v[246:247], off
	v_lshl_add_u64 v[246:247], s[46:47], 0, v[156:157]
	s_mov_b32 m0, s54
	s_nop 0
	global_load_lds_dwordx4 v[246:247], off
	s_add_u32 s46, s46, 0xb0000
	s_addc_u32 s47, s47, 0
	s_mov_b32 m0, s55
	v_lshl_add_u64 v[246:247], s[46:47], 0, v[152:153]
	ds_read_b128 v[212:215], v191 offset:32768
	ds_read_b128 v[216:219], v191 offset:33792
	ds_read_b128 v[220:223], v191 offset:34816
	ds_read_b128 v[224:227], v191 offset:35840
	ds_read_b128 v[228:231], v191 offset:36864
	ds_read_b128 v[232:235], v191 offset:37888
	ds_read_b128 v[236:239], v191 offset:38912
	ds_read_b128 v[240:243], v191 offset:39936
	global_load_lds_dwordx4 v[246:247], off
	v_lshl_add_u64 v[246:247], s[46:47], 0, v[156:157]
	s_mov_b32 m0, s56
	s_nop 0
	global_load_lds_dwordx4 v[246:247], off
	s_waitcnt vmcnt(8)
	s_waitcnt lgkmcnt(0)
	s_barrier
	s_setprio 1
	s_waitcnt lgkmcnt(0)
	v_mfma_f32_16x16x32_bf16 v[140:143], v[124:127], v[212:215], v[140:143]
	v_mfma_f32_16x16x32_bf16 v[136:139], v[132:135], v[212:215], v[136:139]
	v_mfma_f32_16x16x32_bf16 v[116:119], v[124:127], v[220:223], v[116:119]
	v_mfma_f32_16x16x32_bf16 v[112:115], v[132:135], v[220:223], v[112:115]
	v_mfma_f32_16x16x32_bf16 v[108:111], v[124:127], v[228:231], v[108:111]
	v_mfma_f32_16x16x32_bf16 v[104:107], v[132:135], v[228:231], v[104:107]
	v_mfma_f32_16x16x32_bf16 v[100:103], v[124:127], v[236:239], v[100:103]
	v_mfma_f32_16x16x32_bf16 v[96:99], v[132:135], v[236:239], v[96:99]
	v_mfma_f32_16x16x32_bf16 v[140:143], v[128:131], v[216:219], v[140:143]
	v_mfma_f32_16x16x32_bf16 v[136:139], v[144:147], v[216:219], v[136:139]
	v_mfma_f32_16x16x32_bf16 v[116:119], v[128:131], v[224:227], v[116:119]
	v_mfma_f32_16x16x32_bf16 v[112:115], v[144:147], v[224:227], v[112:115]
	v_mfma_f32_16x16x32_bf16 v[108:111], v[128:131], v[232:235], v[108:111]
	v_mfma_f32_16x16x32_bf16 v[104:107], v[144:147], v[232:235], v[104:107]
	v_mfma_f32_16x16x32_bf16 v[100:103], v[128:131], v[240:243], v[100:103]
	v_mfma_f32_16x16x32_bf16 v[96:99], v[144:147], v[240:243], v[96:99]
	s_setprio 0
	s_setprio 1
	v_mfma_f32_16x16x32_bf16 v[60:63], v[148:151], v[212:215], v[60:63]
	v_mfma_f32_16x16x32_bf16 v[56:59], v[174:177], v[212:215], v[56:59]
	v_mfma_f32_16x16x32_bf16 v[52:55], v[148:151], v[220:223], v[52:55]
	v_mfma_f32_16x16x32_bf16 v[48:51], v[174:177], v[220:223], v[48:51]
	v_mfma_f32_16x16x32_bf16 v[44:47], v[148:151], v[228:231], v[44:47]
	v_mfma_f32_16x16x32_bf16 v[40:43], v[174:177], v[228:231], v[40:43]
	v_mfma_f32_16x16x32_bf16 v[36:39], v[148:151], v[236:239], v[36:39]
	v_mfma_f32_16x16x32_bf16 v[32:35], v[174:177], v[236:239], v[32:35]
	v_mfma_f32_16x16x32_bf16 v[60:63], v[170:173], v[216:219], v[60:63]
	v_mfma_f32_16x16x32_bf16 v[56:59], v[178:181], v[216:219], v[56:59]
	v_mfma_f32_16x16x32_bf16 v[52:55], v[170:173], v[224:227], v[52:55]
	v_mfma_f32_16x16x32_bf16 v[48:51], v[178:181], v[224:227], v[48:51]
	v_mfma_f32_16x16x32_bf16 v[44:47], v[170:173], v[232:235], v[44:47]
	v_mfma_f32_16x16x32_bf16 v[40:43], v[178:181], v[232:235], v[40:43]
	v_mfma_f32_16x16x32_bf16 v[36:39], v[170:173], v[240:243], v[36:39]
	v_mfma_f32_16x16x32_bf16 v[32:35], v[178:181], v[240:243], v[32:35]
	s_setprio 0
	s_barrier
; #define PG8_STAGE(bufoff, gbase, voff) do { _Pragma("unroll") for (int _i = 0; _i < 2; ++_i) \
;         __builtin_amdgcn_global_load_lds((const unsigned*)((const char*)(gbase) + (voff)[_i]), (PG8_LAS unsigned*)(lds + (bufoff) + ldsw + _i * 8192), 16, 0, 0); } while (0)
; #define PG8_LDA(dst, b, h) do { _Pragma("unroll") for (int m = 0; m < 4; ++m) _Pragma("unroll") for (int k = 0; k < 2; ++k) dst[m][k] = *(const PG8_LAS bf16x8*)(lds + PG8_SA(b, h) + aoff + m * 2048 + k * 1024); } while (0)
; #define PG8_MMA(ai, bj, At, Bt) do { __builtin_amdgcn_s_setprio(1); _Pragma("unroll") for (int m = 0; m < 4; ++m) _Pragma("unroll") for (int n = 0; n < 2; ++n) _Pragma("unroll") for (int k = 0; k < 2; ++k) \
;         acc[ai][bj][m][n] = __builtin_amdgcn_mfma_f32_16x16x32_bf16(Bt[n][k], At[m][k], acc[ai][bj][m][n], 0, 0, 0); __builtin_amdgcn_s_setprio(0); } while (0)
; #define PG8_WAIT_V(n) asm volatile("s_waitcnt vmcnt(" #n ")" ::: "memory")
; #define PG8_WAIT_L(n) asm volatile("s_waitcnt lgkmcnt(" #n ")" ::: "memory")
; #define PG8_BAR __builtin_amdgcn_s_barrier()
; #define PG8_SCHED __builtin_amdgcn_sched_barrier(0)
; template <class Epi, class Sched, bool ALIGN_EPI = false, bool SP2 = false>
; __device__ __forceinline__ void gemm_phase(PG8_LAS unsigned char* lds, const Gemm g, const Sched& S, const Epi& E) {
;     ...
;             PG8_LDA(At, 1, 1); PG8_STAGE(PG8_SB(1, 0), b3, voffB); PG8_STAGE(PG8_SB(1, 1), b3 + hstepB, voffB); PG8_STAGE(PG8_SA(1, 0), a3, voffA);
;             PG8_WAIT_V(8); PG8_WAIT_L(0); PG8_BAR; PG8_MMA(1, 0, At, B0); PG8_MMA(1, 1, At, B1); PG8_BAR; PG8_SCHED;
;     ...
;         if constexpr (ALIGN_EPI) { if (wr == 0) PG8_BAR; }
	s_add_i32 s46, s70, s52
	v_lshl_add_u64 v[206:207], v[206:207], 0, s[26:27]
	s_mov_b32 m0, s46
	ds_read_b128 v[212:215], v191 offset:49152
	ds_read_b128 v[216:219], v191 offset:50176
	ds_read_b128 v[220:223], v191 offset:51200
	ds_read_b128 v[224:227], v191 offset:52224
	ds_read_b128 v[228:231], v191 offset:53248
	ds_read_b128 v[232:235], v191 offset:54272
	ds_read_b128 v[236:239], v191 offset:55296
	ds_read_b128 v[240:243], v191 offset:56320
	global_load_lds_dwordx4 v[206:207], off
	s_add_i32 m0, s46, 0x2000
	s_add_u32 s44, s44, 0xb0080
	v_lshl_add_u64 v[206:207], v[244:245], 0, s[26:27]
	s_addc_u32 s45, s45, 0
	s_add_i32 s46, s71, s52
	global_load_lds_dwordx4 v[206:207], off
	v_lshl_add_u64 v[206:207], s[44:45], 0, v[154:155]
	s_mov_b32 m0, s46
	s_nop 0
	global_load_lds_dwordx4 v[206:207], off
	v_lshl_add_u64 v[206:207], s[44:45], 0, v[158:159]
	s_add_i32 m0, s46, 0x2000
	s_nop 0
	global_load_lds_dwordx4 v[206:207], off
	v_lshl_add_u64 v[206:207], s[42:43], 0, v[152:153]
	s_mov_b32 m0, s63
	s_nop 0
	global_load_lds_dwordx4 v[206:207], off
	v_lshl_add_u64 v[206:207], s[42:43], 0, v[156:157]
	s_mov_b32 m0, s64
	s_nop 0
	global_load_lds_dwordx4 v[206:207], off
	s_waitcnt vmcnt(8)
	s_waitcnt lgkmcnt(0)
	s_barrier
	s_setprio 1
	s_waitcnt lgkmcnt(0)
	v_mfma_f32_16x16x32_bf16 v[92:95], v[124:127], v[212:215], v[92:95]
	v_mfma_f32_16x16x32_bf16 v[88:91], v[132:135], v[212:215], v[88:91]
	v_mfma_f32_16x16x32_bf16 v[84:87], v[124:127], v[220:223], v[84:87]
	v_mfma_f32_16x16x32_bf16 v[80:83], v[132:135], v[220:223], v[80:83]
	v_mfma_f32_16x16x32_bf16 v[76:79], v[124:127], v[228:231], v[76:79]
	v_mfma_f32_16x16x32_bf16 v[72:75], v[132:135], v[228:231], v[72:75]
	v_mfma_f32_16x16x32_bf16 v[68:71], v[124:127], v[236:239], v[68:71]
	v_mfma_f32_16x16x32_bf16 v[64:67], v[132:135], v[236:239], v[64:67]
	v_mfma_f32_16x16x32_bf16 v[92:95], v[128:131], v[216:219], v[92:95]
	v_mfma_f32_16x16x32_bf16 v[88:91], v[144:147], v[216:219], v[88:91]
	v_mfma_f32_16x16x32_bf16 v[84:87], v[128:131], v[224:227], v[84:87]
	v_mfma_f32_16x16x32_bf16 v[80:83], v[144:147], v[224:227], v[80:83]
	v_mfma_f32_16x16x32_bf16 v[76:79], v[128:131], v[232:235], v[76:79]
	v_mfma_f32_16x16x32_bf16 v[72:75], v[144:147], v[232:235], v[72:75]
	v_mfma_f32_16x16x32_bf16 v[68:71], v[128:131], v[240:243], v[68:71]
	v_mfma_f32_16x16x32_bf16 v[64:67], v[144:147], v[240:243], v[64:67]
	s_setprio 0
	s_setprio 1
	v_mfma_f32_16x16x32_bf16 v[28:31], v[148:151], v[212:215], v[28:31]
	v_mfma_f32_16x16x32_bf16 v[24:27], v[174:177], v[212:215], v[24:27]
	v_mfma_f32_16x16x32_bf16 v[20:23], v[148:151], v[220:223], v[20:23]
	v_mfma_f32_16x16x32_bf16 v[16:19], v[174:177], v[220:223], v[16:19]
	v_mfma_f32_16x16x32_bf16 v[12:15], v[148:151], v[228:231], v[12:15]
	v_mfma_f32_16x16x32_bf16 v[8:11], v[174:177], v[228:231], v[8:11]
	v_mfma_f32_16x16x32_bf16 v[4:7], v[148:151], v[236:239], v[4:7]
	v_mfma_f32_16x16x32_bf16 v[0:3], v[174:177], v[236:239], v[0:3]
	v_mfma_f32_16x16x32_bf16 v[28:31], v[170:173], v[216:219], v[28:31]
	v_mfma_f32_16x16x32_bf16 v[24:27], v[178:181], v[216:219], v[24:27]
	v_mfma_f32_16x16x32_bf16 v[20:23], v[170:173], v[224:227], v[20:23]
	v_mfma_f32_16x16x32_bf16 v[16:19], v[178:181], v[224:227], v[16:19]
	v_mfma_f32_16x16x32_bf16 v[12:15], v[170:173], v[232:235], v[12:15]
	v_mfma_f32_16x16x32_bf16 v[8:11], v[178:181], v[232:235], v[8:11]
	v_mfma_f32_16x16x32_bf16 v[4:7], v[170:173], v[240:243], v[4:7]
	v_mfma_f32_16x16x32_bf16 v[0:3], v[178:181], v[240:243], v[0:3]
	s_setprio 0
	s_barrier
	s_add_i32 s84, s84, 2
	s_add_u32 s40, s40, 0x100
	s_addc_u32 s41, s41, 0
	s_cmp_gt_u32 s84, 41
	s_cbranch_scc0 .LBB0_1379
	s_and_b64 vcc, exec, s[28:29]
	s_cbranch_vccz .LBB0_1382
	s_barrier

; #define PG8_STAGE(bufoff, gbase, voff) do { _Pragma("unroll") for (int _i = 0; _i < 2; ++_i) \
;         __builtin_amdgcn_global_load_lds((const unsigned*)((const char*)(gbase) + (voff)[_i]), (PG8_LAS unsigned*)(lds + (bufoff) + ldsw + _i * 8192), 16, 0, 0); } while (0)
; #define PG8_LDA(dst, b, h) do { _Pragma("unroll") for (int m = 0; m < 4; ++m) _Pragma("unroll") for (int k = 0; k < 2; ++k) dst[m][k] = *(const PG8_LAS bf16x8*)(lds + PG8_SA(b, h) + aoff + m * 2048 + k * 1024); } while (0)
; #define PG8_LDB(dst, b, h) do { _Pragma("unroll") for (int n = 0; n < 2; ++n) _Pragma("unroll") for (int k = 0; k < 2; ++k) dst[n][k] = *(const PG8_LAS bf16x8*)(lds + PG8_SB(b, h) + boff + n * 2048 + k * 1024); } while (0)
; #define PG8_MMA(ai, bj, At, Bt) do { __builtin_amdgcn_s_setprio(1); _Pragma("unroll") for (int m = 0; m < 4; ++m) _Pragma("unroll") for (int n = 0; n < 2; ++n) _Pragma("unroll") for (int k = 0; k < 2; ++k) \
;         acc[ai][bj][m][n] = __builtin_amdgcn_mfma_f32_16x16x32_bf16(Bt[n][k], At[m][k], acc[ai][bj][m][n], 0, 0, 0); __builtin_amdgcn_s_setprio(0); } while (0)
; #define PG8_WAIT_V(n) asm volatile("s_waitcnt vmcnt(" #n ")" ::: "memory")
; #define PG8_WAIT_L(n) asm volatile("s_waitcnt lgkmcnt(" #n ")" ::: "memory")
; template <class Epi, class Sched, bool ALIGN_EPI = false, bool SP2 = false>
; __device__ __forceinline__ void gemm_phase(PG8_LAS unsigned char* lds, const Gemm g, const Sched& S, const Epi& E) {
;     ...
;             const bool last = (t == nt - 2);
;             const char* a1 = cA + PG8_AK(t + 1);
;             const char* a2 = last ? nA : cA + PG8_AK(t + 2); const char* b2 = last ? nB : cB + (size_t)(t + 2) * kstep;
;             const char* a3 = last ? nA + PG8_AK(1) : cA + PG8_AK(t + 3); const char* b3 = b2 + kstep;
;             if (last && has_next) S.a_ready(nxt);
;             if constexpr (SP2) {
;             PG8_LDB(B0, 0, 0); PG8_LDB(B1, 0, 1); PG8_SCHED; PG8_LDA(At, 0, 0); PG8_STAGE(PG8_SA(1, 1), a1 + hstepA, voffA);
;             PG8_WAIT_V(8); PG8_WAIT_L(0); PG8_BAR; PG8_MMA(0, 0, At, B0); PG8_MMA(0, 1, At, B1); PG8_BAR; PG8_SCHED;
;             PG8_LDA(At, 0, 1); PG8_STAGE(PG8_SB(0, 0), b2, voffB); PG8_STAGE(PG8_SB(0, 1), b2 + hstepB, voffB); PG8_STAGE(PG8_SA(0, 0), a2, voffA);
;             PG8_WAIT_V(8); PG8_WAIT_L(0); PG8_BAR; PG8_MMA(1, 0, At, B0); PG8_MMA(1, 1, At, B1); PG8_BAR; PG8_SCHED;
.LBB0_1471:
	ds_read_b128 v[100:103], v222
	ds_read_b128 v[104:107], v222 offset:1024
	ds_read_b128 v[108:111], v222 offset:2048
	ds_read_b128 v[120:123], v222 offset:3072
	ds_read_b128 v[124:127], v223
	ds_read_b128 v[128:131], v223 offset:1024
	ds_read_b128 v[132:135], v223 offset:2048
	ds_read_b128 v[160:163], v223 offset:3072
	s_add_u32 s44, s40, s42
	s_addc_u32 s45, s41, s43
	s_add_u32 s48, s44, 0x100
	s_addc_u32 s49, s45, 0
	s_add_u32 s46, s83, s42
	s_addc_u32 s47, s84, s43
	s_add_u32 s44, s44, 0x180
	s_addc_u32 s45, s45, 0
	s_cmpk_eq_i32 s42, 0x700
	s_cselect_b32 s45, s82, s45
	s_cselect_b32 s44, s79, s44
	s_cselect_b32 s47, s29, s47
	s_cselect_b32 s46, s78, s46
	s_cselect_b32 s49, s3, s49
	s_cselect_b32 s48, s31, s48
	v_lshl_add_u64 v[200:201], v[98:99], 0, s[42:43]
	s_add_i32 m0, s57, 0xc000
	ds_read_b128 v[164:167], v203
	ds_read_b128 v[168:171], v203 offset:1024
	ds_read_b128 v[192:195], v203 offset:2048
	ds_read_b128 v[196:199], v203 offset:3072
	ds_read_b128 v[224:227], v203 offset:4096
	ds_read_b128 v[228:231], v203 offset:5120
	ds_read_b128 v[232:235], v203 offset:6144
	ds_read_b128 v[236:239], v203 offset:7168
	global_load_lds_dwordx4 v[200:201], off
	v_lshl_add_u64 v[200:201], v[96:97], 0, s[42:43]
	s_add_i32 m0, s57, 0xe000
	s_nop 0
	global_load_lds_dwordx4 v[200:201], off
	s_waitcnt vmcnt(8)
	s_waitcnt lgkmcnt(0)
	s_barrier
	s_setprio 1
	s_waitcnt lgkmcnt(0)
	v_mfma_f32_16x16x32_bf16 v[156:159], v[100:103], v[164:167], v[156:159]
	v_mfma_f32_16x16x32_bf16 v[152:155], v[108:111], v[164:167], v[152:155]
	v_mfma_f32_16x16x32_bf16 v[148:151], v[100:103], v[192:195], v[148:151]
	v_mfma_f32_16x16x32_bf16 v[144:147], v[108:111], v[192:195], v[144:147]
	v_mfma_f32_16x16x32_bf16 v[140:143], v[100:103], v[224:227], v[140:143]
	v_mfma_f32_16x16x32_bf16 v[136:139], v[108:111], v[224:227], v[136:139]
	v_mfma_f32_16x16x32_bf16 v[116:119], v[100:103], v[232:235], v[116:119]
	v_mfma_f32_16x16x32_bf16 v[112:115], v[108:111], v[232:235], v[112:115]
	v_mfma_f32_16x16x32_bf16 v[156:159], v[104:107], v[168:171], v[156:159]
	v_mfma_f32_16x16x32_bf16 v[152:155], v[120:123], v[168:171], v[152:155]
	v_mfma_f32_16x16x32_bf16 v[148:151], v[104:107], v[196:199], v[148:151]
	v_mfma_f32_16x16x32_bf16 v[144:147], v[120:123], v[196:199], v[144:147]
	v_mfma_f32_16x16x32_bf16 v[140:143], v[104:107], v[228:231], v[140:143]
	v_mfma_f32_16x16x32_bf16 v[136:139], v[120:123], v[228:231], v[136:139]
	v_mfma_f32_16x16x32_bf16 v[116:119], v[104:107], v[236:239], v[116:119]
	v_mfma_f32_16x16x32_bf16 v[112:115], v[120:123], v[236:239], v[112:115]
	s_setprio 0
	s_setprio 1
	v_mfma_f32_16x16x32_bf16 v[60:63], v[124:127], v[164:167], v[60:63]
	v_mfma_f32_16x16x32_bf16 v[56:59], v[132:135], v[164:167], v[56:59]
	v_mfma_f32_16x16x32_bf16 v[52:55], v[124:127], v[192:195], v[52:55]
	v_mfma_f32_16x16x32_bf16 v[48:51], v[132:135], v[192:195], v[48:51]
	v_mfma_f32_16x16x32_bf16 v[44:47], v[124:127], v[224:227], v[44:47]
	v_mfma_f32_16x16x32_bf16 v[40:43], v[132:135], v[224:227], v[40:43]
	v_mfma_f32_16x16x32_bf16 v[36:39], v[124:127], v[232:235], v[36:39]
	v_mfma_f32_16x16x32_bf16 v[32:35], v[132:135], v[232:235], v[32:35]
	v_mfma_f32_16x16x32_bf16 v[60:63], v[128:131], v[168:171], v[60:63]
	v_mfma_f32_16x16x32_bf16 v[56:59], v[160:163], v[168:171], v[56:59]
	v_mfma_f32_16x16x32_bf16 v[52:55], v[128:131], v[196:199], v[52:55]
	v_mfma_f32_16x16x32_bf16 v[48:51], v[160:163], v[196:199], v[48:51]
	v_mfma_f32_16x16x32_bf16 v[44:47], v[128:131], v[228:231], v[44:47]
	v_mfma_f32_16x16x32_bf16 v[40:43], v[160:163], v[228:231], v[40:43]
	v_mfma_f32_16x16x32_bf16 v[36:39], v[128:131], v[236:239], v[36:39]
	v_mfma_f32_16x16x32_bf16 v[32:35], v[160:163], v[236:239], v[32:35]
	s_setprio 0
	s_barrier
	s_add_i32 s70, s69, s56
	v_lshl_add_u64 v[200:201], s[46:47], 0, v[174:175]
	s_mov_b32 m0, s70
	ds_read_b128 v[164:167], v203 offset:16384
	ds_read_b128 v[168:171], v203 offset:17408
	ds_read_b128 v[192:195], v203 offset:18432
	ds_read_b128 v[196:199], v203 offset:19456
	ds_read_b128 v[224:227], v203 offset:20480
	ds_read_b128 v[228:231], v203 offset:21504
	ds_read_b128 v[232:235], v203 offset:22528
	ds_read_b128 v[236:239], v203 offset:23552
	global_load_lds_dwordx4 v[200:201], off
	s_add_i32 m0, s70, 0x2000
	s_add_u32 s70, s46, 0x40000
	v_lshl_add_u64 v[206:207], s[46:47], 0, v[178:179]
	s_addc_u32 s71, s47, 0
	s_add_i32 s86, s80, s56
	global_load_lds_dwordx4 v[206:207], off
	v_lshl_add_u64 v[240:241], s[70:71], 0, v[174:175]
	s_mov_b32 m0, s86
	s_nop 0
	global_load_lds_dwordx4 v[240:241], off
	v_lshl_add_u64 v[240:241], s[70:71], 0, v[178:179]
	s_add_i32 m0, s86, 0x2000
	s_nop 0
	global_load_lds_dwordx4 v[240:241], off
	s_waitcnt vmcnt(6)
	s_waitcnt lgkmcnt(0)
	s_barrier
; #define PG8_STAGE(bufoff, gbase, voff) do { _Pragma("unroll") for (int _i = 0; _i < 2; ++_i) \
;         __builtin_amdgcn_global_load_lds((const unsigned*)((const char*)(gbase) + (voff)[_i]), (PG8_LAS unsigned*)(lds + (bufoff) + ldsw + _i * 8192), 16, 0, 0); } while (0)
; #define PG8_LDA(dst, b, h) do { _Pragma("unroll") for (int m = 0; m < 4; ++m) _Pragma("unroll") for (int k = 0; k < 2; ++k) dst[m][k] = *(const PG8_LAS bf16x8*)(lds + PG8_SA(b, h) + aoff + m * 2048 + k * 1024); } while (0)
; #define PG8_LDB(dst, b, h) do { _Pragma("unroll") for (int n = 0; n < 2; ++n) _Pragma("unroll") for (int k = 0; k < 2; ++k) dst[n][k] = *(const PG8_LAS bf16x8*)(lds + PG8_SB(b, h) + boff + n * 2048 + k * 1024); } while (0)
; #define PG8_MMA(ai, bj, At, Bt) do { __builtin_amdgcn_s_setprio(1); _Pragma("unroll") for (int m = 0; m < 4; ++m) _Pragma("unroll") for (int n = 0; n < 2; ++n) _Pragma("unroll") for (int k = 0; k < 2; ++k) \
;         acc[ai][bj][m][n] = __builtin_amdgcn_mfma_f32_16x16x32_bf16(Bt[n][k], At[m][k], acc[ai][bj][m][n], 0, 0, 0); __builtin_amdgcn_s_setprio(0); } while (0)
; #define PG8_WAIT_V(n) asm volatile("s_waitcnt vmcnt(" #n ")" ::: "memory")
; #define PG8_WAIT_L(n) asm volatile("s_waitcnt lgkmcnt(" #n ")" ::: "memory")
; #define PG8_BAR __builtin_amdgcn_s_barrier()
; #define PG8_SCHED __builtin_amdgcn_sched_barrier(0)
; template <class Epi, class Sched, bool ALIGN_EPI = false, bool SP2 = false>
; __device__ __forceinline__ void gemm_phase(PG8_LAS unsigned char* lds, const Gemm g, const Sched& S, const Epi& E) {
;     ...
;             PG8_WAIT_V(8); PG8_WAIT_L(0); PG8_BAR; PG8_MMA(1, 0, At, B0); PG8_MMA(1, 1, At, B1); PG8_BAR; PG8_SCHED;
;             PG8_LDB(B0, 1, 0); PG8_LDB(B1, 1, 1); PG8_SCHED; PG8_LDA(At, 1, 0); PG8_STAGE(PG8_SA(0, 1), a2 + hstepA, voffA);
;             PG8_WAIT_V(8); PG8_WAIT_L(0); PG8_BAR; PG8_MMA(0, 0, At, B0); PG8_MMA(0, 1, At, B1); PG8_BAR; PG8_SCHED;
	s_setprio 1
	s_waitcnt lgkmcnt(0)
	v_mfma_f32_16x16x32_bf16 v[92:95], v[100:103], v[164:167], v[92:95]
	v_mfma_f32_16x16x32_bf16 v[88:91], v[108:111], v[164:167], v[88:91]
	v_mfma_f32_16x16x32_bf16 v[84:87], v[100:103], v[192:195], v[84:87]
	v_mfma_f32_16x16x32_bf16 v[80:83], v[108:111], v[192:195], v[80:83]
	v_mfma_f32_16x16x32_bf16 v[76:79], v[100:103], v[224:227], v[76:79]
	v_mfma_f32_16x16x32_bf16 v[72:75], v[108:111], v[224:227], v[72:75]
	v_mfma_f32_16x16x32_bf16 v[68:71], v[100:103], v[232:235], v[68:71]
	v_mfma_f32_16x16x32_bf16 v[64:67], v[108:111], v[232:235], v[64:67]
	v_mfma_f32_16x16x32_bf16 v[92:95], v[104:107], v[168:171], v[92:95]
	v_mfma_f32_16x16x32_bf16 v[88:91], v[120:123], v[168:171], v[88:91]
	v_mfma_f32_16x16x32_bf16 v[84:87], v[104:107], v[196:199], v[84:87]
	v_mfma_f32_16x16x32_bf16 v[80:83], v[120:123], v[196:199], v[80:83]
	v_mfma_f32_16x16x32_bf16 v[76:79], v[104:107], v[228:231], v[76:79]
	v_mfma_f32_16x16x32_bf16 v[72:75], v[120:123], v[228:231], v[72:75]
	v_mfma_f32_16x16x32_bf16 v[68:71], v[104:107], v[236:239], v[68:71]
	v_mfma_f32_16x16x32_bf16 v[64:67], v[120:123], v[236:239], v[64:67]
	s_setprio 0
	s_setprio 1
	v_mfma_f32_16x16x32_bf16 v[28:31], v[124:127], v[164:167], v[28:31]
	v_mfma_f32_16x16x32_bf16 v[24:27], v[132:135], v[164:167], v[24:27]
	v_mfma_f32_16x16x32_bf16 v[20:23], v[124:127], v[192:195], v[20:23]
	v_mfma_f32_16x16x32_bf16 v[16:19], v[132:135], v[192:195], v[16:19]
	v_mfma_f32_16x16x32_bf16 v[12:15], v[124:127], v[224:227], v[12:15]
	v_mfma_f32_16x16x32_bf16 v[8:11], v[132:135], v[224:227], v[8:11]
	v_mfma_f32_16x16x32_bf16 v[4:7], v[124:127], v[232:235], v[4:7]
	v_mfma_f32_16x16x32_bf16 v[0:3], v[132:135], v[232:235], v[0:3]
	v_mfma_f32_16x16x32_bf16 v[28:31], v[128:131], v[168:171], v[28:31]
	v_mfma_f32_16x16x32_bf16 v[24:27], v[160:163], v[168:171], v[24:27]
	v_mfma_f32_16x16x32_bf16 v[20:23], v[128:131], v[196:199], v[20:23]
	v_mfma_f32_16x16x32_bf16 v[16:19], v[160:163], v[196:199], v[16:19]
	v_mfma_f32_16x16x32_bf16 v[12:15], v[128:131], v[228:231], v[12:15]
	v_mfma_f32_16x16x32_bf16 v[8:11], v[160:163], v[228:231], v[8:11]
	v_mfma_f32_16x16x32_bf16 v[4:7], v[128:131], v[236:239], v[4:7]
	v_mfma_f32_16x16x32_bf16 v[0:3], v[160:163], v[236:239], v[0:3]
	s_setprio 0
	s_barrier
	s_add_i32 s70, 0, 0x18000
	s_add_i32 s71, 0, 0x1c000
	v_add_u32_e32 v120, s70, v189
	v_add_u32_e32 v160, s71, v189
	ds_read_b128 v[100:103], v120
	ds_read_b128 v[104:107], v120 offset:1024
	ds_read_b128 v[108:111], v120 offset:2048
	ds_read_b128 v[120:123], v120 offset:3072
	ds_read_b128 v[124:127], v160
	ds_read_b128 v[128:131], v160 offset:1024
	ds_read_b128 v[132:135], v160 offset:2048
	ds_read_b128 v[160:163], v160 offset:3072
	v_lshl_add_u64 v[240:241], s[48:49], 0, v[172:173]
	s_mov_b32 m0, s57
	s_nop 0
	global_load_lds_dwordx4 v[240:241], off
	v_lshl_add_u64 v[240:241], s[48:49], 0, v[176:177]
	s_mov_b32 m0, s58
	s_nop 0
	global_load_lds_dwordx4 v[240:241], off
	s_add_u32 s48, s48, 0x40000
	s_addc_u32 s49, s49, 0
	s_mov_b32 m0, s59
	v_lshl_add_u64 v[240:241], s[48:49], 0, v[172:173]
	ds_read_b128 v[164:167], v203 offset:32768
	ds_read_b128 v[168:171], v203 offset:33792
	ds_read_b128 v[192:195], v203 offset:34816
	ds_read_b128 v[196:199], v203 offset:35840
	ds_read_b128 v[224:227], v203 offset:36864
	ds_read_b128 v[228:231], v203 offset:37888
	ds_read_b128 v[232:235], v203 offset:38912
	ds_read_b128 v[236:239], v203 offset:39936
	global_load_lds_dwordx4 v[240:241], off
	v_lshl_add_u64 v[240:241], s[48:49], 0, v[176:177]
	s_mov_b32 m0, s60
	s_nop 0
	global_load_lds_dwordx4 v[240:241], off
	s_waitcnt vmcnt(8)
	s_waitcnt lgkmcnt(0)
	s_barrier
	s_setprio 1
	s_waitcnt lgkmcnt(0)
	v_mfma_f32_16x16x32_bf16 v[156:159], v[100:103], v[164:167], v[156:159]
	v_mfma_f32_16x16x32_bf16 v[152:155], v[108:111], v[164:167], v[152:155]
	v_mfma_f32_16x16x32_bf16 v[148:151], v[100:103], v[192:195], v[148:151]
	v_mfma_f32_16x16x32_bf16 v[144:147], v[108:111], v[192:195], v[144:147]
	v_mfma_f32_16x16x32_bf16 v[140:143], v[100:103], v[224:227], v[140:143]
	v_mfma_f32_16x16x32_bf16 v[136:139], v[108:111], v[224:227], v[136:139]
	v_mfma_f32_16x16x32_bf16 v[116:119], v[100:103], v[232:235], v[116:119]
	v_mfma_f32_16x16x32_bf16 v[112:115], v[108:111], v[232:235], v[112:115]
	v_mfma_f32_16x16x32_bf16 v[156:159], v[104:107], v[168:171], v[156:159]
	v_mfma_f32_16x16x32_bf16 v[152:155], v[120:123], v[168:171], v[152:155]
	v_mfma_f32_16x16x32_bf16 v[148:151], v[104:107], v[196:199], v[148:151]
	v_mfma_f32_16x16x32_bf16 v[144:147], v[120:123], v[196:199], v[144:147]
	v_mfma_f32_16x16x32_bf16 v[140:143], v[104:107], v[228:231], v[140:143]
	v_mfma_f32_16x16x32_bf16 v[136:139], v[120:123], v[228:231], v[136:139]
	v_mfma_f32_16x16x32_bf16 v[116:119], v[104:107], v[236:239], v[116:119]
	v_mfma_f32_16x16x32_bf16 v[112:115], v[120:123], v[236:239], v[112:115]
	s_setprio 0
	s_setprio 1
	v_mfma_f32_16x16x32_bf16 v[60:63], v[124:127], v[164:167], v[60:63]
	v_mfma_f32_16x16x32_bf16 v[56:59], v[132:135], v[164:167], v[56:59]
	v_mfma_f32_16x16x32_bf16 v[52:55], v[124:127], v[192:195], v[52:55]
	v_mfma_f32_16x16x32_bf16 v[48:51], v[132:135], v[192:195], v[48:51]
	v_mfma_f32_16x16x32_bf16 v[44:47], v[124:127], v[224:227], v[44:47]
	v_mfma_f32_16x16x32_bf16 v[40:43], v[132:135], v[224:227], v[40:43]
	v_mfma_f32_16x16x32_bf16 v[36:39], v[124:127], v[232:235], v[36:39]
	v_mfma_f32_16x16x32_bf16 v[32:35], v[132:135], v[232:235], v[32:35]
	v_mfma_f32_16x16x32_bf16 v[60:63], v[128:131], v[168:171], v[60:63]
	v_mfma_f32_16x16x32_bf16 v[56:59], v[160:163], v[168:171], v[56:59]
	v_mfma_f32_16x16x32_bf16 v[52:55], v[128:131], v[196:199], v[52:55]
	v_mfma_f32_16x16x32_bf16 v[48:51], v[160:163], v[196:199], v[48:51]
	v_mfma_f32_16x16x32_bf16 v[44:47], v[128:131], v[228:231], v[44:47]
	v_mfma_f32_16x16x32_bf16 v[40:43], v[160:163], v[228:231], v[40:43]
	v_mfma_f32_16x16x32_bf16 v[36:39], v[128:131], v[236:239], v[36:39]
	v_mfma_f32_16x16x32_bf16 v[32:35], v[160:163], v[236:239], v[32:35]
	s_setprio 0
	s_barrier
; #define PG8_STAGE(bufoff, gbase, voff) do { _Pragma("unroll") for (int _i = 0; _i < 2; ++_i) \
;         __builtin_amdgcn_global_load_lds((const unsigned*)((const char*)(gbase) + (voff)[_i]), (PG8_LAS unsigned*)(lds + (bufoff) + ldsw + _i * 8192), 16, 0, 0); } while (0)
; #define PG8_LDA(dst, b, h) do { _Pragma("unroll") for (int m = 0; m < 4; ++m) _Pragma("unroll") for (int k = 0; k < 2; ++k) dst[m][k] = *(const PG8_LAS bf16x8*)(lds + PG8_SA(b, h) + aoff + m * 2048 + k * 1024); } while (0)
; #define PG8_MMA(ai, bj, At, Bt) do { __builtin_amdgcn_s_setprio(1); _Pragma("unroll") for (int m = 0; m < 4; ++m) _Pragma("unroll") for (int n = 0; n < 2; ++n) _Pragma("unroll") for (int k = 0; k < 2; ++k) \
;         acc[ai][bj][m][n] = __builtin_amdgcn_mfma_f32_16x16x32_bf16(Bt[n][k], At[m][k], acc[ai][bj][m][n], 0, 0, 0); __builtin_amdgcn_s_setprio(0); } while (0)
; #define PG8_WAIT_V(n) asm volatile("s_waitcnt vmcnt(" #n ")" ::: "memory")
; #define PG8_WAIT_L(n) asm volatile("s_waitcnt lgkmcnt(" #n ")" ::: "memory")
; #define PG8_BAR __builtin_amdgcn_s_barrier()
; #define PG8_SCHED __builtin_amdgcn_sched_barrier(0)
; template <class Epi, class Sched, bool ALIGN_EPI = false, bool SP2 = false>
; __device__ __forceinline__ void gemm_phase(PG8_LAS unsigned char* lds, const Gemm g, const Sched& S, const Epi& E) {
;     ...
;             PG8_LDA(At, 1, 1); PG8_STAGE(PG8_SB(1, 0), b3, voffB); PG8_STAGE(PG8_SB(1, 1), b3 + hstepB, voffB); PG8_STAGE(PG8_SA(1, 0), a3, voffA);
;             PG8_WAIT_V(8); PG8_WAIT_L(0); PG8_BAR; PG8_MMA(1, 0, At, B0); PG8_MMA(1, 1, At, B1); PG8_BAR; PG8_SCHED;
;     ...
;         if constexpr (ALIGN_EPI) { if (wr == 0) PG8_BAR; }
	s_add_i32 s48, s70, s56
	v_lshl_add_u64 v[200:201], v[200:201], 0, s[10:11]
	s_mov_b32 m0, s48
	ds_read_b128 v[164:167], v203 offset:49152
	ds_read_b128 v[168:171], v203 offset:50176
	ds_read_b128 v[192:195], v203 offset:51200
	ds_read_b128 v[196:199], v203 offset:52224
	ds_read_b128 v[224:227], v203 offset:53248
	ds_read_b128 v[228:231], v203 offset:54272
	ds_read_b128 v[232:235], v203 offset:55296
	ds_read_b128 v[236:239], v203 offset:56320
	global_load_lds_dwordx4 v[200:201], off
	s_add_i32 m0, s48, 0x2000
	s_add_u32 s46, s46, 0x40080
	v_lshl_add_u64 v[200:201], v[206:207], 0, s[10:11]
	s_addc_u32 s47, s47, 0
	s_add_i32 s48, s71, s56
	global_load_lds_dwordx4 v[200:201], off
	v_lshl_add_u64 v[200:201], s[46:47], 0, v[174:175]
	s_mov_b32 m0, s48
	s_nop 0
	global_load_lds_dwordx4 v[200:201], off
	v_lshl_add_u64 v[200:201], s[46:47], 0, v[178:179]
	s_add_i32 m0, s48, 0x2000
	s_nop 0
	global_load_lds_dwordx4 v[200:201], off
	v_lshl_add_u64 v[200:201], s[44:45], 0, v[172:173]
	s_mov_b32 m0, s66
	s_nop 0
	global_load_lds_dwordx4 v[200:201], off
	v_lshl_add_u64 v[200:201], s[44:45], 0, v[176:177]
	s_mov_b32 m0, s67
	s_nop 0
	global_load_lds_dwordx4 v[200:201], off
	s_waitcnt vmcnt(8)
	s_waitcnt lgkmcnt(0)
	s_barrier
	s_setprio 1
	s_waitcnt lgkmcnt(0)
	v_mfma_f32_16x16x32_bf16 v[92:95], v[100:103], v[164:167], v[92:95]
	v_mfma_f32_16x16x32_bf16 v[88:91], v[108:111], v[164:167], v[88:91]
	v_mfma_f32_16x16x32_bf16 v[84:87], v[100:103], v[192:195], v[84:87]
	v_mfma_f32_16x16x32_bf16 v[80:83], v[108:111], v[192:195], v[80:83]
	v_mfma_f32_16x16x32_bf16 v[76:79], v[100:103], v[224:227], v[76:79]
	v_mfma_f32_16x16x32_bf16 v[72:75], v[108:111], v[224:227], v[72:75]
	v_mfma_f32_16x16x32_bf16 v[68:71], v[100:103], v[232:235], v[68:71]
	v_mfma_f32_16x16x32_bf16 v[64:67], v[108:111], v[232:235], v[64:67]
	v_mfma_f32_16x16x32_bf16 v[92:95], v[104:107], v[168:171], v[92:95]
	v_mfma_f32_16x16x32_bf16 v[88:91], v[120:123], v[168:171], v[88:91]
	v_mfma_f32_16x16x32_bf16 v[84:87], v[104:107], v[196:199], v[84:87]
	v_mfma_f32_16x16x32_bf16 v[80:83], v[120:123], v[196:199], v[80:83]
	v_mfma_f32_16x16x32_bf16 v[76:79], v[104:107], v[228:231], v[76:79]
	v_mfma_f32_16x16x32_bf16 v[72:75], v[120:123], v[228:231], v[72:75]
	v_mfma_f32_16x16x32_bf16 v[68:71], v[104:107], v[236:239], v[68:71]
	v_mfma_f32_16x16x32_bf16 v[64:67], v[120:123], v[236:239], v[64:67]
	s_setprio 0
	s_setprio 1
	v_mfma_f32_16x16x32_bf16 v[28:31], v[124:127], v[164:167], v[28:31]
	v_mfma_f32_16x16x32_bf16 v[24:27], v[132:135], v[164:167], v[24:27]
	v_mfma_f32_16x16x32_bf16 v[20:23], v[124:127], v[192:195], v[20:23]
	v_mfma_f32_16x16x32_bf16 v[16:19], v[132:135], v[192:195], v[16:19]
	v_mfma_f32_16x16x32_bf16 v[12:15], v[124:127], v[224:227], v[12:15]
	v_mfma_f32_16x16x32_bf16 v[8:11], v[132:135], v[224:227], v[8:11]
	v_mfma_f32_16x16x32_bf16 v[4:7], v[124:127], v[232:235], v[4:7]
	v_mfma_f32_16x16x32_bf16 v[0:3], v[132:135], v[232:235], v[0:3]
	v_mfma_f32_16x16x32_bf16 v[28:31], v[128:131], v[168:171], v[28:31]
	v_mfma_f32_16x16x32_bf16 v[24:27], v[160:163], v[168:171], v[24:27]
	v_mfma_f32_16x16x32_bf16 v[20:23], v[128:131], v[196:199], v[20:23]
	v_mfma_f32_16x16x32_bf16 v[16:19], v[160:163], v[196:199], v[16:19]
	v_mfma_f32_16x16x32_bf16 v[12:15], v[128:131], v[228:231], v[12:15]
	v_mfma_f32_16x16x32_bf16 v[8:11], v[160:163], v[228:231], v[8:11]
	v_mfma_f32_16x16x32_bf16 v[4:7], v[128:131], v[236:239], v[4:7]
	v_mfma_f32_16x16x32_bf16 v[0:3], v[160:163], v[236:239], v[0:3]
	s_setprio 0
	s_barrier
	s_add_i32 s85, s85, 2
	s_add_u32 s42, s42, 0x100
	s_addc_u32 s43, s43, 0
	s_cmp_gt_u32 s85, 13
	s_cbranch_scc0 .LBB0_1471
	s_and_b64 vcc, exec, s[24:25]
	s_cbranch_vccz .LBB0_1474
	s_barrier

; #define PG8_STAGE(bufoff, gbase, voff) do { _Pragma("unroll") for (int _i = 0; _i < 2; ++_i) \
;         __builtin_amdgcn_global_load_lds((const unsigned*)((const char*)(gbase) + (voff)[_i]), (PG8_LAS unsigned*)(lds + (bufoff) + ldsw + _i * 8192), 16, 0, 0); } while (0)
; #define PG8_LDA(dst, b, h) do { _Pragma("unroll") for (int m = 0; m < 4; ++m) _Pragma("unroll") for (int k = 0; k < 2; ++k) dst[m][k] = *(const PG8_LAS bf16x8*)(lds + PG8_SA(b, h) + aoff + m * 2048 + k * 1024); } while (0)
; #define PG8_LDB(dst, b, h) do { _Pragma("unroll") for (int n = 0; n < 2; ++n) _Pragma("unroll") for (int k = 0; k < 2; ++k) dst[n][k] = *(const PG8_LAS bf16x8*)(lds + PG8_SB(b, h) + boff + n * 2048 + k * 1024); } while (0)
; #define PG8_MMA(ai, bj, At, Bt) do { __builtin_amdgcn_s_setprio(1); _Pragma("unroll") for (int m = 0; m < 4; ++m) _Pragma("unroll") for (int n = 0; n < 2; ++n) _Pragma("unroll") for (int k = 0; k < 2; ++k) \
;         acc[ai][bj][m][n] = __builtin_amdgcn_mfma_f32_16x16x32_bf16(Bt[n][k], At[m][k], acc[ai][bj][m][n], 0, 0, 0); __builtin_amdgcn_s_setprio(0); } while (0)
; #define PG8_WAIT_V(n) asm volatile("s_waitcnt vmcnt(" #n ")" ::: "memory")
; #define PG8_WAIT_L(n) asm volatile("s_waitcnt lgkmcnt(" #n ")" ::: "memory")
; template <class Epi, class Sched, bool ALIGN_EPI = false, bool SP2 = false>
; __device__ __forceinline__ void gemm_phase(PG8_LAS unsigned char* lds, const Gemm g, const Sched& S, const Epi& E) {
;     ...
;             const bool last = (t == nt - 2);
;             const char* a1 = cA + PG8_AK(t + 1);
;             const char* a2 = last ? nA : cA + PG8_AK(t + 2); const char* b2 = last ? nB : cB + (size_t)(t + 2) * kstep;
;             const char* a3 = last ? nA + PG8_AK(1) : cA + PG8_AK(t + 3); const char* b3 = b2 + kstep;
;             if (last && has_next) S.a_ready(nxt);
;             if constexpr (SP2) {
;             PG8_LDB(B0, 0, 0); PG8_LDB(B1, 0, 1); PG8_SCHED; PG8_LDA(At, 0, 0); PG8_STAGE(PG8_SA(1, 1), a1 + hstepA, voffA);
;             PG8_WAIT_V(8); PG8_WAIT_L(0); PG8_BAR; PG8_MMA(0, 0, At, B0); PG8_MMA(0, 1, At, B1); PG8_BAR; PG8_SCHED;
;             PG8_LDA(At, 0, 1); PG8_STAGE(PG8_SB(0, 0), b2, voffB); PG8_STAGE(PG8_SB(0, 1), b2 + hstepB, voffB); PG8_STAGE(PG8_SA(0, 0), a2, voffA);
;             PG8_WAIT_V(8); PG8_WAIT_L(0); PG8_BAR; PG8_MMA(1, 0, At, B0); PG8_MMA(1, 1, At, B1); PG8_BAR; PG8_SCHED;
.LBB0_1638:
	ds_read_b128 v[132:135], v172
	ds_read_b128 v[158:161], v172 offset:1024
	ds_read_b128 v[176:179], v172 offset:2048
	ds_read_b128 v[180:183], v172 offset:3072
	ds_read_b128 v[184:187], v173
	ds_read_b128 v[188:191], v173 offset:1024
	ds_read_b128 v[192:195], v173 offset:2048
	ds_read_b128 v[196:199], v173 offset:3072
	s_add_u32 s38, s28, s34
	s_addc_u32 s39, s29, s35
	s_add_u32 s42, s38, 0x100
	s_addc_u32 s43, s39, 0
	s_add_u32 s40, s62, s34
	s_addc_u32 s41, s63, s35
	s_add_u32 s38, s38, 0x180
	s_addc_u32 s39, s39, 0
	s_cmpk_eq_i32 s34, 0x700
	s_cselect_b32 s39, s37, s39
	s_cselect_b32 s38, s31, s38
	s_cselect_b32 s41, s21, s41
	s_cselect_b32 s40, s23, s40
	s_cselect_b32 s43, s3, s43
	s_cselect_b32 s42, s10, s42
	v_lshl_add_u64 v[232:233], v[130:131], 0, s[34:35]
	s_add_i32 m0, s49, 0xc000
	ds_read_b128 v[200:203], v174
	ds_read_b128 v[204:207], v174 offset:1024
	ds_read_b128 v[208:211], v174 offset:2048
	ds_read_b128 v[212:215], v174 offset:3072
	ds_read_b128 v[216:219], v174 offset:4096
	ds_read_b128 v[220:223], v174 offset:5120
	ds_read_b128 v[224:227], v174 offset:6144
	ds_read_b128 v[228:231], v174 offset:7168
	global_load_lds_dwordx4 v[232:233], off
	v_lshl_add_u64 v[232:233], v[128:129], 0, s[34:35]
	s_add_i32 m0, s49, 0xe000
	s_nop 0
	global_load_lds_dwordx4 v[232:233], off
	s_waitcnt vmcnt(8)
	s_waitcnt lgkmcnt(0)
	s_barrier
	s_setprio 1
	s_waitcnt lgkmcnt(0)
	v_mfma_f32_16x16x32_bf16 v[124:127], v[132:135], v[200:203], v[124:127]
	v_mfma_f32_16x16x32_bf16 v[120:123], v[176:179], v[200:203], v[120:123]
	v_mfma_f32_16x16x32_bf16 v[108:111], v[132:135], v[208:211], v[108:111]
	v_mfma_f32_16x16x32_bf16 v[104:107], v[176:179], v[208:211], v[104:107]
	v_mfma_f32_16x16x32_bf16 v[92:95], v[132:135], v[216:219], v[92:95]
	v_mfma_f32_16x16x32_bf16 v[88:91], v[176:179], v[216:219], v[88:91]
	v_mfma_f32_16x16x32_bf16 v[76:79], v[132:135], v[224:227], v[76:79]
	v_mfma_f32_16x16x32_bf16 v[72:75], v[176:179], v[224:227], v[72:75]
	v_mfma_f32_16x16x32_bf16 v[124:127], v[158:161], v[204:207], v[124:127]
	v_mfma_f32_16x16x32_bf16 v[120:123], v[180:183], v[204:207], v[120:123]
	v_mfma_f32_16x16x32_bf16 v[108:111], v[158:161], v[212:215], v[108:111]
	v_mfma_f32_16x16x32_bf16 v[104:107], v[180:183], v[212:215], v[104:107]
	v_mfma_f32_16x16x32_bf16 v[92:95], v[158:161], v[220:223], v[92:95]
	v_mfma_f32_16x16x32_bf16 v[88:91], v[180:183], v[220:223], v[88:91]
	v_mfma_f32_16x16x32_bf16 v[76:79], v[158:161], v[228:231], v[76:79]
	v_mfma_f32_16x16x32_bf16 v[72:75], v[180:183], v[228:231], v[72:75]
	s_setprio 0
	s_setprio 1
	v_mfma_f32_16x16x32_bf16 v[116:119], v[184:187], v[200:203], v[116:119]
	v_mfma_f32_16x16x32_bf16 v[112:115], v[192:195], v[200:203], v[112:115]
	v_mfma_f32_16x16x32_bf16 v[100:103], v[184:187], v[208:211], v[100:103]
	v_mfma_f32_16x16x32_bf16 v[96:99], v[192:195], v[208:211], v[96:99]
	v_mfma_f32_16x16x32_bf16 v[84:87], v[184:187], v[216:219], v[84:87]
	v_mfma_f32_16x16x32_bf16 v[80:83], v[192:195], v[216:219], v[80:83]
	v_mfma_f32_16x16x32_bf16 v[68:71], v[184:187], v[224:227], v[68:71]
	v_mfma_f32_16x16x32_bf16 v[64:67], v[192:195], v[224:227], v[64:67]
	v_mfma_f32_16x16x32_bf16 v[116:119], v[188:191], v[204:207], v[116:119]
	v_mfma_f32_16x16x32_bf16 v[112:115], v[196:199], v[204:207], v[112:115]
	v_mfma_f32_16x16x32_bf16 v[100:103], v[188:191], v[212:215], v[100:103]
	v_mfma_f32_16x16x32_bf16 v[96:99], v[196:199], v[212:215], v[96:99]
	v_mfma_f32_16x16x32_bf16 v[84:87], v[188:191], v[220:223], v[84:87]
	v_mfma_f32_16x16x32_bf16 v[80:83], v[196:199], v[220:223], v[80:83]
	v_mfma_f32_16x16x32_bf16 v[68:71], v[188:191], v[228:231], v[68:71]
	v_mfma_f32_16x16x32_bf16 v[64:67], v[196:199], v[228:231], v[64:67]
	s_setprio 0
	s_barrier
	s_add_i32 s65, s58, s48
	v_lshl_add_u64 v[232:233], s[40:41], 0, v[138:139]
	s_mov_b32 m0, s65
	ds_read_b128 v[200:203], v174 offset:16384
	ds_read_b128 v[204:207], v174 offset:17408
	ds_read_b128 v[208:211], v174 offset:18432
	ds_read_b128 v[212:215], v174 offset:19456
	ds_read_b128 v[216:219], v174 offset:20480
	ds_read_b128 v[220:223], v174 offset:21504
	ds_read_b128 v[224:227], v174 offset:22528
	ds_read_b128 v[228:231], v174 offset:23552
	global_load_lds_dwordx4 v[232:233], off
	s_add_i32 m0, s65, 0x2000
	s_add_u32 s66, s40, 0x40000
	v_lshl_add_u64 v[234:235], s[40:41], 0, v[142:143]
	s_addc_u32 s67, s41, 0
	s_add_i32 s65, s59, s48
	global_load_lds_dwordx4 v[234:235], off
	v_lshl_add_u64 v[236:237], s[66:67], 0, v[138:139]
	s_mov_b32 m0, s65
	s_nop 0
	global_load_lds_dwordx4 v[236:237], off
	v_lshl_add_u64 v[236:237], s[66:67], 0, v[142:143]
	s_add_i32 m0, s65, 0x2000
	s_nop 0
	global_load_lds_dwordx4 v[236:237], off
	s_waitcnt vmcnt(6)
	s_waitcnt lgkmcnt(0)
	s_barrier
; #define PG8_STAGE(bufoff, gbase, voff) do { _Pragma("unroll") for (int _i = 0; _i < 2; ++_i) \
;         __builtin_amdgcn_global_load_lds((const unsigned*)((const char*)(gbase) + (voff)[_i]), (PG8_LAS unsigned*)(lds + (bufoff) + ldsw + _i * 8192), 16, 0, 0); } while (0)
; #define PG8_LDA(dst, b, h) do { _Pragma("unroll") for (int m = 0; m < 4; ++m) _Pragma("unroll") for (int k = 0; k < 2; ++k) dst[m][k] = *(const PG8_LAS bf16x8*)(lds + PG8_SA(b, h) + aoff + m * 2048 + k * 1024); } while (0)
; #define PG8_LDB(dst, b, h) do { _Pragma("unroll") for (int n = 0; n < 2; ++n) _Pragma("unroll") for (int k = 0; k < 2; ++k) dst[n][k] = *(const PG8_LAS bf16x8*)(lds + PG8_SB(b, h) + boff + n * 2048 + k * 1024); } while (0)
; #define PG8_MMA(ai, bj, At, Bt) do { __builtin_amdgcn_s_setprio(1); _Pragma("unroll") for (int m = 0; m < 4; ++m) _Pragma("unroll") for (int n = 0; n < 2; ++n) _Pragma("unroll") for (int k = 0; k < 2; ++k) \
;         acc[ai][bj][m][n] = __builtin_amdgcn_mfma_f32_16x16x32_bf16(Bt[n][k], At[m][k], acc[ai][bj][m][n], 0, 0, 0); __builtin_amdgcn_s_setprio(0); } while (0)
; #define PG8_WAIT_V(n) asm volatile("s_waitcnt vmcnt(" #n ")" ::: "memory")
; #define PG8_WAIT_L(n) asm volatile("s_waitcnt lgkmcnt(" #n ")" ::: "memory")
; #define PG8_BAR __builtin_amdgcn_s_barrier()
; #define PG8_SCHED __builtin_amdgcn_sched_barrier(0)
; template <class Epi, class Sched, bool ALIGN_EPI = false, bool SP2 = false>
; __device__ __forceinline__ void gemm_phase(PG8_LAS unsigned char* lds, const Gemm g, const Sched& S, const Epi& E) {
;     ...
;             PG8_WAIT_V(8); PG8_WAIT_L(0); PG8_BAR; PG8_MMA(1, 0, At, B0); PG8_MMA(1, 1, At, B1); PG8_BAR; PG8_SCHED;
;             PG8_LDB(B0, 1, 0); PG8_LDB(B1, 1, 1); PG8_SCHED; PG8_LDA(At, 1, 0); PG8_STAGE(PG8_SA(0, 1), a2 + hstepA, voffA);
;             PG8_WAIT_V(8); PG8_WAIT_L(0); PG8_BAR; PG8_MMA(0, 0, At, B0); PG8_MMA(0, 1, At, B1); PG8_BAR; PG8_SCHED;
	s_setprio 1
	s_waitcnt lgkmcnt(0)
	v_mfma_f32_16x16x32_bf16 v[60:63], v[132:135], v[200:203], v[60:63]
	v_mfma_f32_16x16x32_bf16 v[56:59], v[176:179], v[200:203], v[56:59]
	v_mfma_f32_16x16x32_bf16 v[44:47], v[132:135], v[208:211], v[44:47]
	v_mfma_f32_16x16x32_bf16 v[40:43], v[176:179], v[208:211], v[40:43]
	v_mfma_f32_16x16x32_bf16 v[28:31], v[132:135], v[216:219], v[28:31]
	v_mfma_f32_16x16x32_bf16 v[24:27], v[176:179], v[216:219], v[24:27]
	v_mfma_f32_16x16x32_bf16 v[12:15], v[132:135], v[224:227], v[12:15]
	v_mfma_f32_16x16x32_bf16 v[8:11], v[176:179], v[224:227], v[8:11]
	v_mfma_f32_16x16x32_bf16 v[60:63], v[158:161], v[204:207], v[60:63]
	v_mfma_f32_16x16x32_bf16 v[56:59], v[180:183], v[204:207], v[56:59]
	v_mfma_f32_16x16x32_bf16 v[44:47], v[158:161], v[212:215], v[44:47]
	v_mfma_f32_16x16x32_bf16 v[40:43], v[180:183], v[212:215], v[40:43]
	v_mfma_f32_16x16x32_bf16 v[28:31], v[158:161], v[220:223], v[28:31]
	v_mfma_f32_16x16x32_bf16 v[24:27], v[180:183], v[220:223], v[24:27]
	v_mfma_f32_16x16x32_bf16 v[12:15], v[158:161], v[228:231], v[12:15]
	v_mfma_f32_16x16x32_bf16 v[8:11], v[180:183], v[228:231], v[8:11]
	s_setprio 0
	s_setprio 1
	v_mfma_f32_16x16x32_bf16 v[52:55], v[184:187], v[200:203], v[52:55]
	v_mfma_f32_16x16x32_bf16 v[48:51], v[192:195], v[200:203], v[48:51]
	v_mfma_f32_16x16x32_bf16 v[36:39], v[184:187], v[208:211], v[36:39]
	v_mfma_f32_16x16x32_bf16 v[32:35], v[192:195], v[208:211], v[32:35]
	v_mfma_f32_16x16x32_bf16 v[20:23], v[184:187], v[216:219], v[20:23]
	v_mfma_f32_16x16x32_bf16 v[16:19], v[192:195], v[216:219], v[16:19]
	v_mfma_f32_16x16x32_bf16 v[4:7], v[184:187], v[224:227], v[4:7]
	v_mfma_f32_16x16x32_bf16 v[0:3], v[192:195], v[224:227], v[0:3]
	v_mfma_f32_16x16x32_bf16 v[52:55], v[188:191], v[204:207], v[52:55]
	v_mfma_f32_16x16x32_bf16 v[48:51], v[196:199], v[204:207], v[48:51]
	v_mfma_f32_16x16x32_bf16 v[36:39], v[188:191], v[212:215], v[36:39]
	v_mfma_f32_16x16x32_bf16 v[32:35], v[196:199], v[212:215], v[32:35]
	v_mfma_f32_16x16x32_bf16 v[20:23], v[188:191], v[220:223], v[20:23]
	v_mfma_f32_16x16x32_bf16 v[16:19], v[196:199], v[220:223], v[16:19]
	v_mfma_f32_16x16x32_bf16 v[4:7], v[188:191], v[228:231], v[4:7]
	v_mfma_f32_16x16x32_bf16 v[0:3], v[196:199], v[228:231], v[0:3]
	s_setprio 0
	s_barrier
	s_add_i32 s65, 0, 0x18000
	v_add_u32_e32 v144, s65, v163
	s_add_i32 s66, 0, 0x1c000
	ds_read_b128 v[132:135], v144
	ds_read_b128 v[158:161], v144 offset:1024
	ds_read_b128 v[176:179], v144 offset:2048
	ds_read_b128 v[180:183], v144 offset:3072
	v_add_u32_e32 v144, s66, v163
	ds_read_b128 v[184:187], v144
	ds_read_b128 v[188:191], v144 offset:1024
	ds_read_b128 v[192:195], v144 offset:2048
	ds_read_b128 v[196:199], v144 offset:3072
	v_lshl_add_u64 v[236:237], s[42:43], 0, v[136:137]
	s_mov_b32 m0, s49
	s_nop 0
	global_load_lds_dwordx4 v[236:237], off
	v_lshl_add_u64 v[236:237], s[42:43], 0, v[140:141]
	s_mov_b32 m0, s50
	s_nop 0
	global_load_lds_dwordx4 v[236:237], off
	s_add_u32 s42, s42, 0x40000
	s_addc_u32 s43, s43, 0
	s_mov_b32 m0, s51
	v_lshl_add_u64 v[236:237], s[42:43], 0, v[136:137]
	ds_read_b128 v[200:203], v174 offset:32768
	ds_read_b128 v[204:207], v174 offset:33792
	ds_read_b128 v[208:211], v174 offset:34816
	ds_read_b128 v[212:215], v174 offset:35840
	ds_read_b128 v[216:219], v174 offset:36864
	ds_read_b128 v[220:223], v174 offset:37888
	ds_read_b128 v[224:227], v174 offset:38912
	ds_read_b128 v[228:231], v174 offset:39936
	global_load_lds_dwordx4 v[236:237], off
	v_lshl_add_u64 v[236:237], s[42:43], 0, v[140:141]
	s_mov_b32 m0, s52
	s_nop 0
	global_load_lds_dwordx4 v[236:237], off
	s_waitcnt vmcnt(8)
	s_waitcnt lgkmcnt(0)
	s_barrier
	s_setprio 1
	s_waitcnt lgkmcnt(0)
	v_mfma_f32_16x16x32_bf16 v[124:127], v[132:135], v[200:203], v[124:127]
	v_mfma_f32_16x16x32_bf16 v[120:123], v[176:179], v[200:203], v[120:123]
	v_mfma_f32_16x16x32_bf16 v[108:111], v[132:135], v[208:211], v[108:111]
	v_mfma_f32_16x16x32_bf16 v[104:107], v[176:179], v[208:211], v[104:107]
	v_mfma_f32_16x16x32_bf16 v[92:95], v[132:135], v[216:219], v[92:95]
	v_mfma_f32_16x16x32_bf16 v[88:91], v[176:179], v[216:219], v[88:91]
	v_mfma_f32_16x16x32_bf16 v[76:79], v[132:135], v[224:227], v[76:79]
	v_mfma_f32_16x16x32_bf16 v[72:75], v[176:179], v[224:227], v[72:75]
	v_mfma_f32_16x16x32_bf16 v[124:127], v[158:161], v[204:207], v[124:127]
	v_mfma_f32_16x16x32_bf16 v[120:123], v[180:183], v[204:207], v[120:123]
	v_mfma_f32_16x16x32_bf16 v[108:111], v[158:161], v[212:215], v[108:111]
	v_mfma_f32_16x16x32_bf16 v[104:107], v[180:183], v[212:215], v[104:107]
	v_mfma_f32_16x16x32_bf16 v[92:95], v[158:161], v[220:223], v[92:95]
	v_mfma_f32_16x16x32_bf16 v[88:91], v[180:183], v[220:223], v[88:91]
	v_mfma_f32_16x16x32_bf16 v[76:79], v[158:161], v[228:231], v[76:79]
	v_mfma_f32_16x16x32_bf16 v[72:75], v[180:183], v[228:231], v[72:75]
	s_setprio 0
	s_setprio 1
	v_mfma_f32_16x16x32_bf16 v[116:119], v[184:187], v[200:203], v[116:119]
	v_mfma_f32_16x16x32_bf16 v[112:115], v[192:195], v[200:203], v[112:115]
	v_mfma_f32_16x16x32_bf16 v[100:103], v[184:187], v[208:211], v[100:103]
	v_mfma_f32_16x16x32_bf16 v[96:99], v[192:195], v[208:211], v[96:99]
	v_mfma_f32_16x16x32_bf16 v[84:87], v[184:187], v[216:219], v[84:87]
	v_mfma_f32_16x16x32_bf16 v[80:83], v[192:195], v[216:219], v[80:83]
	v_mfma_f32_16x16x32_bf16 v[68:71], v[184:187], v[224:227], v[68:71]
	v_mfma_f32_16x16x32_bf16 v[64:67], v[192:195], v[224:227], v[64:67]
	v_mfma_f32_16x16x32_bf16 v[116:119], v[188:191], v[204:207], v[116:119]
	v_mfma_f32_16x16x32_bf16 v[112:115], v[196:199], v[204:207], v[112:115]
	v_mfma_f32_16x16x32_bf16 v[100:103], v[188:191], v[212:215], v[100:103]
	v_mfma_f32_16x16x32_bf16 v[96:99], v[196:199], v[212:215], v[96:99]
	v_mfma_f32_16x16x32_bf16 v[84:87], v[188:191], v[220:223], v[84:87]
	v_mfma_f32_16x16x32_bf16 v[80:83], v[196:199], v[220:223], v[80:83]
	v_mfma_f32_16x16x32_bf16 v[68:71], v[188:191], v[228:231], v[68:71]
	v_mfma_f32_16x16x32_bf16 v[64:67], v[196:199], v[228:231], v[64:67]
	s_setprio 0
	s_barrier
; #define PG8_STAGE(bufoff, gbase, voff) do { _Pragma("unroll") for (int _i = 0; _i < 2; ++_i) \
;         __builtin_amdgcn_global_load_lds((const unsigned*)((const char*)(gbase) + (voff)[_i]), (PG8_LAS unsigned*)(lds + (bufoff) + ldsw + _i * 8192), 16, 0, 0); } while (0)
; #define PG8_LDA(dst, b, h) do { _Pragma("unroll") for (int m = 0; m < 4; ++m) _Pragma("unroll") for (int k = 0; k < 2; ++k) dst[m][k] = *(const PG8_LAS bf16x8*)(lds + PG8_SA(b, h) + aoff + m * 2048 + k * 1024); } while (0)
; #define PG8_MMA(ai, bj, At, Bt) do { __builtin_amdgcn_s_setprio(1); _Pragma("unroll") for (int m = 0; m < 4; ++m) _Pragma("unroll") for (int n = 0; n < 2; ++n) _Pragma("unroll") for (int k = 0; k < 2; ++k) \
;         acc[ai][bj][m][n] = __builtin_amdgcn_mfma_f32_16x16x32_bf16(Bt[n][k], At[m][k], acc[ai][bj][m][n], 0, 0, 0); __builtin_amdgcn_s_setprio(0); } while (0)
; #define PG8_WAIT_V(n) asm volatile("s_waitcnt vmcnt(" #n ")" ::: "memory")
; #define PG8_WAIT_L(n) asm volatile("s_waitcnt lgkmcnt(" #n ")" ::: "memory")
; #define PG8_BAR __builtin_amdgcn_s_barrier()
; #define PG8_SCHED __builtin_amdgcn_sched_barrier(0)
; template <class Epi, class Sched, bool ALIGN_EPI = false, bool SP2 = false>
; __device__ __forceinline__ void gemm_phase(PG8_LAS unsigned char* lds, const Gemm g, const Sched& S, const Epi& E) {
;     ...
;             PG8_LDA(At, 1, 1); PG8_STAGE(PG8_SB(1, 0), b3, voffB); PG8_STAGE(PG8_SB(1, 1), b3 + hstepB, voffB); PG8_STAGE(PG8_SA(1, 0), a3, voffA);
;             PG8_WAIT_V(8); PG8_WAIT_L(0); PG8_BAR; PG8_MMA(1, 0, At, B0); PG8_MMA(1, 1, At, B1); PG8_BAR; PG8_SCHED;
;     ...
;         if constexpr (ALIGN_EPI) { if (wr == 0) PG8_BAR; }
	s_add_i32 s42, s65, s48
	v_lshl_add_u64 v[232:233], v[232:233], 0, s[14:15]
	s_mov_b32 m0, s42
	ds_read_b128 v[200:203], v174 offset:49152
	ds_read_b128 v[204:207], v174 offset:50176
	ds_read_b128 v[208:211], v174 offset:51200
	ds_read_b128 v[212:215], v174 offset:52224
	ds_read_b128 v[216:219], v174 offset:53248
	ds_read_b128 v[220:223], v174 offset:54272
	ds_read_b128 v[224:227], v174 offset:55296
	ds_read_b128 v[228:231], v174 offset:56320
	global_load_lds_dwordx4 v[232:233], off
	s_add_i32 m0, s42, 0x2000
	s_add_u32 s40, s40, 0x40080
	v_lshl_add_u64 v[232:233], v[234:235], 0, s[14:15]
	s_addc_u32 s41, s41, 0
	s_add_i32 s42, s66, s48
	global_load_lds_dwordx4 v[232:233], off
	v_lshl_add_u64 v[232:233], s[40:41], 0, v[138:139]
	s_mov_b32 m0, s42
	s_nop 0
	global_load_lds_dwordx4 v[232:233], off
	v_lshl_add_u64 v[232:233], s[40:41], 0, v[142:143]
	s_add_i32 m0, s42, 0x2000
	s_nop 0
	global_load_lds_dwordx4 v[232:233], off
	v_lshl_add_u64 v[232:233], s[38:39], 0, v[136:137]
	s_mov_b32 m0, s53
	s_nop 0
	global_load_lds_dwordx4 v[232:233], off
	v_lshl_add_u64 v[232:233], s[38:39], 0, v[140:141]
	s_mov_b32 m0, s54
	s_nop 0
	global_load_lds_dwordx4 v[232:233], off
	s_waitcnt vmcnt(8)
	s_waitcnt lgkmcnt(0)
	s_barrier
	s_setprio 1
	s_waitcnt lgkmcnt(0)
	v_mfma_f32_16x16x32_bf16 v[60:63], v[132:135], v[200:203], v[60:63]
	v_mfma_f32_16x16x32_bf16 v[56:59], v[176:179], v[200:203], v[56:59]
	v_mfma_f32_16x16x32_bf16 v[44:47], v[132:135], v[208:211], v[44:47]
	v_mfma_f32_16x16x32_bf16 v[40:43], v[176:179], v[208:211], v[40:43]
	v_mfma_f32_16x16x32_bf16 v[28:31], v[132:135], v[216:219], v[28:31]
	v_mfma_f32_16x16x32_bf16 v[24:27], v[176:179], v[216:219], v[24:27]
	v_mfma_f32_16x16x32_bf16 v[12:15], v[132:135], v[224:227], v[12:15]
	v_mfma_f32_16x16x32_bf16 v[8:11], v[176:179], v[224:227], v[8:11]
	v_mfma_f32_16x16x32_bf16 v[60:63], v[158:161], v[204:207], v[60:63]
	v_mfma_f32_16x16x32_bf16 v[56:59], v[180:183], v[204:207], v[56:59]
	v_mfma_f32_16x16x32_bf16 v[44:47], v[158:161], v[212:215], v[44:47]
	v_mfma_f32_16x16x32_bf16 v[40:43], v[180:183], v[212:215], v[40:43]
	v_mfma_f32_16x16x32_bf16 v[28:31], v[158:161], v[220:223], v[28:31]
	v_mfma_f32_16x16x32_bf16 v[24:27], v[180:183], v[220:223], v[24:27]
	v_mfma_f32_16x16x32_bf16 v[12:15], v[158:161], v[228:231], v[12:15]
	v_mfma_f32_16x16x32_bf16 v[8:11], v[180:183], v[228:231], v[8:11]
	s_setprio 0
	s_setprio 1
	v_mfma_f32_16x16x32_bf16 v[52:55], v[184:187], v[200:203], v[52:55]
	v_mfma_f32_16x16x32_bf16 v[48:51], v[192:195], v[200:203], v[48:51]
	v_mfma_f32_16x16x32_bf16 v[36:39], v[184:187], v[208:211], v[36:39]
	v_mfma_f32_16x16x32_bf16 v[32:35], v[192:195], v[208:211], v[32:35]
	v_mfma_f32_16x16x32_bf16 v[20:23], v[184:187], v[216:219], v[20:23]
	v_mfma_f32_16x16x32_bf16 v[16:19], v[192:195], v[216:219], v[16:19]
	v_mfma_f32_16x16x32_bf16 v[4:7], v[184:187], v[224:227], v[4:7]
	v_mfma_f32_16x16x32_bf16 v[0:3], v[192:195], v[224:227], v[0:3]
	v_mfma_f32_16x16x32_bf16 v[52:55], v[188:191], v[204:207], v[52:55]
	v_mfma_f32_16x16x32_bf16 v[48:51], v[196:199], v[204:207], v[48:51]
	v_mfma_f32_16x16x32_bf16 v[36:39], v[188:191], v[212:215], v[36:39]
	v_mfma_f32_16x16x32_bf16 v[32:35], v[196:199], v[212:215], v[32:35]
	v_mfma_f32_16x16x32_bf16 v[20:23], v[188:191], v[220:223], v[20:23]
	v_mfma_f32_16x16x32_bf16 v[16:19], v[196:199], v[220:223], v[16:19]
	v_mfma_f32_16x16x32_bf16 v[4:7], v[188:191], v[228:231], v[4:7]
	v_mfma_f32_16x16x32_bf16 v[0:3], v[196:199], v[228:231], v[0:3]
	s_setprio 0
	s_barrier
	s_add_i32 s64, s64, 2
	s_add_u32 s34, s34, 0x100
	s_addc_u32 s35, s35, 0
	s_cmp_gt_u32 s64, 13
	s_cbranch_scc0 .LBB0_1638
	s_and_b64 vcc, exec, s[16:17]
	s_cbranch_vccz .LBB0_1643
	s_barrier
	s_cmp_gt_i32 s30, 3
	s_mov_b64 s[28:29], -1
	s_cbranch_scc1 .LBB0_1644

; #define PG8_STAGE(bufoff, gbase, voff) do { _Pragma("unroll") for (int _i = 0; _i < 2; ++_i) \
;         __builtin_amdgcn_global_load_lds((const unsigned*)((const char*)(gbase) + (voff)[_i]), (PG8_LAS unsigned*)(lds + (bufoff) + ldsw + _i * 8192), 16, 0, 0); } while (0)
; #define PG8_LDA(dst, b, h) do { _Pragma("unroll") for (int m = 0; m < 4; ++m) _Pragma("unroll") for (int k = 0; k < 2; ++k) dst[m][k] = *(const PG8_LAS bf16x8*)(lds + PG8_SA(b, h) + aoff + m * 2048 + k * 1024); } while (0)
; #define PG8_LDB(dst, b, h) do { _Pragma("unroll") for (int n = 0; n < 2; ++n) _Pragma("unroll") for (int k = 0; k < 2; ++k) dst[n][k] = *(const PG8_LAS bf16x8*)(lds + PG8_SB(b, h) + boff + n * 2048 + k * 1024); } while (0)
; #define PG8_MMA(ai, bj, At, Bt) do { __builtin_amdgcn_s_setprio(1); _Pragma("unroll") for (int m = 0; m < 4; ++m) _Pragma("unroll") for (int n = 0; n < 2; ++n) _Pragma("unroll") for (int k = 0; k < 2; ++k) \
;         acc[ai][bj][m][n] = __builtin_amdgcn_mfma_f32_16x16x32_bf16(Bt[n][k], At[m][k], acc[ai][bj][m][n], 0, 0, 0); __builtin_amdgcn_s_setprio(0); } while (0)
; #define PG8_WAIT_V(n) asm volatile("s_waitcnt vmcnt(" #n ")" ::: "memory")
; #define PG8_WAIT_L(n) asm volatile("s_waitcnt lgkmcnt(" #n ")" ::: "memory")
; template <class Epi, class Sched, bool ALIGN_EPI = false, bool SP2 = false>
; __device__ __forceinline__ void gemm_phase(PG8_LAS unsigned char* lds, const Gemm g, const Sched& S, const Epi& E) {
;     ...
;             const bool last = (t == nt - 2);
;             const char* a1 = cA + PG8_AK(t + 1);
;             const char* a2 = last ? nA : cA + PG8_AK(t + 2); const char* b2 = last ? nB : cB + (size_t)(t + 2) * kstep;
;             const char* a3 = last ? nA + PG8_AK(1) : cA + PG8_AK(t + 3); const char* b3 = b2 + kstep;
;             if (last && has_next) S.a_ready(nxt);
;             if constexpr (SP2) {
;             PG8_LDB(B0, 0, 0); PG8_LDB(B1, 0, 1); PG8_SCHED; PG8_LDA(At, 0, 0); PG8_STAGE(PG8_SA(1, 1), a1 + hstepA, voffA);
;             PG8_WAIT_V(8); PG8_WAIT_L(0); PG8_BAR; PG8_MMA(0, 0, At, B0); PG8_MMA(0, 1, At, B1); PG8_BAR; PG8_SCHED;
;             PG8_LDA(At, 0, 1); PG8_STAGE(PG8_SB(0, 0), b2, voffB); PG8_STAGE(PG8_SB(0, 1), b2 + hstepB, voffB); PG8_STAGE(PG8_SA(0, 0), a2, voffA);
;             PG8_WAIT_V(8); PG8_WAIT_L(0); PG8_BAR; PG8_MMA(1, 0, At, B0); PG8_MMA(1, 1, At, B1); PG8_BAR; PG8_SCHED;
.LBB0_1841:
	ds_read_b128 v[132:135], v191
	ds_read_b128 v[136:139], v191 offset:1024
	ds_read_b128 v[140:143], v191 offset:2048
	ds_read_b128 v[162:165], v191 offset:3072
	ds_read_b128 v[166:169], v192
	ds_read_b128 v[194:197], v192 offset:1024
	ds_read_b128 v[198:201], v192 offset:2048
	ds_read_b128 v[202:205], v192 offset:3072
	s_add_u32 s40, s36, s38
	s_addc_u32 s41, s37, s39
	s_add_u32 s42, s40, 0x100
	s_addc_u32 s43, s41, 0
	s_add_u32 s70, s69, s38
	s_addc_u32 s71, s78, s39
	s_add_u32 s40, s40, 0x180
	s_addc_u32 s41, s41, 0
	s_cmpk_eq_i32 s38, 0x700
	s_cselect_b32 s45, s3, s43
	s_cselect_b32 s44, s27, s42
	s_cselect_b32 s43, s25, s71
	s_cselect_b32 s42, s35, s70
	s_cselect_b32 s41, s68, s41
	s_cselect_b32 s40, s67, s40
	v_lshl_add_u64 v[170:171], v[130:131], 0, s[38:39]
	s_add_i32 m0, s52, 0xc000
	ds_read_b128 v[206:209], v174
	ds_read_b128 v[210:213], v174 offset:1024
	ds_read_b128 v[214:217], v174 offset:2048
	ds_read_b128 v[218:221], v174 offset:3072
	ds_read_b128 v[222:225], v174 offset:4096
	ds_read_b128 v[226:229], v174 offset:5120
	ds_read_b128 v[230:233], v174 offset:6144
	ds_read_b128 v[234:237], v174 offset:7168
	global_load_lds_dwordx4 v[170:171], off
	v_lshl_add_u64 v[170:171], v[128:129], 0, s[38:39]
	s_add_i32 m0, s52, 0xe000
	s_nop 0
	global_load_lds_dwordx4 v[170:171], off
	s_waitcnt vmcnt(8)
	s_waitcnt lgkmcnt(0)
	s_barrier
	s_setprio 1
	s_waitcnt lgkmcnt(0)
	v_mfma_f32_16x16x32_bf16 v[124:127], v[132:135], v[206:209], v[124:127]
	v_mfma_f32_16x16x32_bf16 v[120:123], v[140:143], v[206:209], v[120:123]
	v_mfma_f32_16x16x32_bf16 v[116:119], v[132:135], v[214:217], v[116:119]
	v_mfma_f32_16x16x32_bf16 v[112:115], v[140:143], v[214:217], v[112:115]
	v_mfma_f32_16x16x32_bf16 v[108:111], v[132:135], v[222:225], v[108:111]
	v_mfma_f32_16x16x32_bf16 v[104:107], v[140:143], v[222:225], v[104:107]
	v_mfma_f32_16x16x32_bf16 v[100:103], v[132:135], v[230:233], v[100:103]
	v_mfma_f32_16x16x32_bf16 v[96:99], v[140:143], v[230:233], v[96:99]
	v_mfma_f32_16x16x32_bf16 v[124:127], v[136:139], v[210:213], v[124:127]
	v_mfma_f32_16x16x32_bf16 v[120:123], v[162:165], v[210:213], v[120:123]
	v_mfma_f32_16x16x32_bf16 v[116:119], v[136:139], v[218:221], v[116:119]
	v_mfma_f32_16x16x32_bf16 v[112:115], v[162:165], v[218:221], v[112:115]
	v_mfma_f32_16x16x32_bf16 v[108:111], v[136:139], v[226:229], v[108:111]
	v_mfma_f32_16x16x32_bf16 v[104:107], v[162:165], v[226:229], v[104:107]
	v_mfma_f32_16x16x32_bf16 v[100:103], v[136:139], v[234:237], v[100:103]
	v_mfma_f32_16x16x32_bf16 v[96:99], v[162:165], v[234:237], v[96:99]
	s_setprio 0
	s_setprio 1
	v_mfma_f32_16x16x32_bf16 v[60:63], v[166:169], v[206:209], v[60:63]
	v_mfma_f32_16x16x32_bf16 v[56:59], v[198:201], v[206:209], v[56:59]
	v_mfma_f32_16x16x32_bf16 v[52:55], v[166:169], v[214:217], v[52:55]
	v_mfma_f32_16x16x32_bf16 v[48:51], v[198:201], v[214:217], v[48:51]
	v_mfma_f32_16x16x32_bf16 v[44:47], v[166:169], v[222:225], v[44:47]
	v_mfma_f32_16x16x32_bf16 v[40:43], v[198:201], v[222:225], v[40:43]
	v_mfma_f32_16x16x32_bf16 v[36:39], v[166:169], v[230:233], v[36:39]
	v_mfma_f32_16x16x32_bf16 v[32:35], v[198:201], v[230:233], v[32:35]
	v_mfma_f32_16x16x32_bf16 v[60:63], v[194:197], v[210:213], v[60:63]
	v_mfma_f32_16x16x32_bf16 v[56:59], v[202:205], v[210:213], v[56:59]
	v_mfma_f32_16x16x32_bf16 v[52:55], v[194:197], v[218:221], v[52:55]
	v_mfma_f32_16x16x32_bf16 v[48:51], v[202:205], v[218:221], v[48:51]
	v_mfma_f32_16x16x32_bf16 v[44:47], v[194:197], v[226:229], v[44:47]
	v_mfma_f32_16x16x32_bf16 v[40:43], v[202:205], v[226:229], v[40:43]
	v_mfma_f32_16x16x32_bf16 v[36:39], v[194:197], v[234:237], v[36:39]
	v_mfma_f32_16x16x32_bf16 v[32:35], v[202:205], v[234:237], v[32:35]
	s_setprio 0
	s_barrier
	s_add_i32 s70, s64, s51
	v_lshl_add_u64 v[170:171], s[42:43], 0, v[146:147]
	s_mov_b32 m0, s70
	ds_read_b128 v[206:209], v174 offset:16384
	ds_read_b128 v[210:213], v174 offset:17408
	ds_read_b128 v[214:217], v174 offset:18432
	ds_read_b128 v[218:221], v174 offset:19456
	ds_read_b128 v[222:225], v174 offset:20480
	ds_read_b128 v[226:229], v174 offset:21504
	ds_read_b128 v[230:233], v174 offset:22528
	ds_read_b128 v[234:237], v174 offset:23552
	global_load_lds_dwordx4 v[170:171], off
	s_add_i32 m0, s70, 0x2000
	s_add_u32 s70, s42, 0x40000
	v_lshl_add_u64 v[238:239], s[42:43], 0, v[150:151]
	s_addc_u32 s71, s43, 0
	s_add_i32 s80, s65, s51
	global_load_lds_dwordx4 v[238:239], off
	v_lshl_add_u64 v[240:241], s[70:71], 0, v[146:147]
	s_mov_b32 m0, s80
	s_nop 0
	global_load_lds_dwordx4 v[240:241], off
	v_lshl_add_u64 v[240:241], s[70:71], 0, v[150:151]
	s_add_i32 m0, s80, 0x2000
	s_nop 0
	global_load_lds_dwordx4 v[240:241], off
	s_waitcnt vmcnt(6)
	s_waitcnt lgkmcnt(0)
	s_barrier
; #define PG8_STAGE(bufoff, gbase, voff) do { _Pragma("unroll") for (int _i = 0; _i < 2; ++_i) \
;         __builtin_amdgcn_global_load_lds((const unsigned*)((const char*)(gbase) + (voff)[_i]), (PG8_LAS unsigned*)(lds + (bufoff) + ldsw + _i * 8192), 16, 0, 0); } while (0)
; #define PG8_LDA(dst, b, h) do { _Pragma("unroll") for (int m = 0; m < 4; ++m) _Pragma("unroll") for (int k = 0; k < 2; ++k) dst[m][k] = *(const PG8_LAS bf16x8*)(lds + PG8_SA(b, h) + aoff + m * 2048 + k * 1024); } while (0)
; #define PG8_LDB(dst, b, h) do { _Pragma("unroll") for (int n = 0; n < 2; ++n) _Pragma("unroll") for (int k = 0; k < 2; ++k) dst[n][k] = *(const PG8_LAS bf16x8*)(lds + PG8_SB(b, h) + boff + n * 2048 + k * 1024); } while (0)
; #define PG8_MMA(ai, bj, At, Bt) do { __builtin_amdgcn_s_setprio(1); _Pragma("unroll") for (int m = 0; m < 4; ++m) _Pragma("unroll") for (int n = 0; n < 2; ++n) _Pragma("unroll") for (int k = 0; k < 2; ++k) \
;         acc[ai][bj][m][n] = __builtin_amdgcn_mfma_f32_16x16x32_bf16(Bt[n][k], At[m][k], acc[ai][bj][m][n], 0, 0, 0); __builtin_amdgcn_s_setprio(0); } while (0)
; #define PG8_WAIT_V(n) asm volatile("s_waitcnt vmcnt(" #n ")" ::: "memory")
; #define PG8_WAIT_L(n) asm volatile("s_waitcnt lgkmcnt(" #n ")" ::: "memory")
; #define PG8_BAR __builtin_amdgcn_s_barrier()
; #define PG8_SCHED __builtin_amdgcn_sched_barrier(0)
; template <class Epi, class Sched, bool ALIGN_EPI = false, bool SP2 = false>
; __device__ __forceinline__ void gemm_phase(PG8_LAS unsigned char* lds, const Gemm g, const Sched& S, const Epi& E) {
;     ...
;             PG8_WAIT_V(8); PG8_WAIT_L(0); PG8_BAR; PG8_MMA(1, 0, At, B0); PG8_MMA(1, 1, At, B1); PG8_BAR; PG8_SCHED;
;             PG8_LDB(B0, 1, 0); PG8_LDB(B1, 1, 1); PG8_SCHED; PG8_LDA(At, 1, 0); PG8_STAGE(PG8_SA(0, 1), a2 + hstepA, voffA);
;             PG8_WAIT_V(8); PG8_WAIT_L(0); PG8_BAR; PG8_MMA(0, 0, At, B0); PG8_MMA(0, 1, At, B1); PG8_BAR; PG8_SCHED;
	s_setprio 1
	s_waitcnt lgkmcnt(0)
	v_mfma_f32_16x16x32_bf16 v[92:95], v[132:135], v[206:209], v[92:95]
	v_mfma_f32_16x16x32_bf16 v[88:91], v[140:143], v[206:209], v[88:91]
	v_mfma_f32_16x16x32_bf16 v[84:87], v[132:135], v[214:217], v[84:87]
	v_mfma_f32_16x16x32_bf16 v[80:83], v[140:143], v[214:217], v[80:83]
	v_mfma_f32_16x16x32_bf16 v[76:79], v[132:135], v[222:225], v[76:79]
	v_mfma_f32_16x16x32_bf16 v[72:75], v[140:143], v[222:225], v[72:75]
	v_mfma_f32_16x16x32_bf16 v[68:71], v[132:135], v[230:233], v[68:71]
	v_mfma_f32_16x16x32_bf16 v[64:67], v[140:143], v[230:233], v[64:67]
	v_mfma_f32_16x16x32_bf16 v[92:95], v[136:139], v[210:213], v[92:95]
	v_mfma_f32_16x16x32_bf16 v[88:91], v[162:165], v[210:213], v[88:91]
	v_mfma_f32_16x16x32_bf16 v[84:87], v[136:139], v[218:221], v[84:87]
	v_mfma_f32_16x16x32_bf16 v[80:83], v[162:165], v[218:221], v[80:83]
	v_mfma_f32_16x16x32_bf16 v[76:79], v[136:139], v[226:229], v[76:79]
	v_mfma_f32_16x16x32_bf16 v[72:75], v[162:165], v[226:229], v[72:75]
	v_mfma_f32_16x16x32_bf16 v[68:71], v[136:139], v[234:237], v[68:71]
	v_mfma_f32_16x16x32_bf16 v[64:67], v[162:165], v[234:237], v[64:67]
	s_setprio 0
	s_setprio 1
	v_mfma_f32_16x16x32_bf16 v[28:31], v[166:169], v[206:209], v[28:31]
	v_mfma_f32_16x16x32_bf16 v[24:27], v[198:201], v[206:209], v[24:27]
	v_mfma_f32_16x16x32_bf16 v[20:23], v[166:169], v[214:217], v[20:23]
	v_mfma_f32_16x16x32_bf16 v[16:19], v[198:201], v[214:217], v[16:19]
	v_mfma_f32_16x16x32_bf16 v[12:15], v[166:169], v[222:225], v[12:15]
	v_mfma_f32_16x16x32_bf16 v[8:11], v[198:201], v[222:225], v[8:11]
	v_mfma_f32_16x16x32_bf16 v[4:7], v[166:169], v[230:233], v[4:7]
	v_mfma_f32_16x16x32_bf16 v[0:3], v[198:201], v[230:233], v[0:3]
	v_mfma_f32_16x16x32_bf16 v[28:31], v[194:197], v[210:213], v[28:31]
	v_mfma_f32_16x16x32_bf16 v[24:27], v[202:205], v[210:213], v[24:27]
	v_mfma_f32_16x16x32_bf16 v[20:23], v[194:197], v[218:221], v[20:23]
	v_mfma_f32_16x16x32_bf16 v[16:19], v[202:205], v[218:221], v[16:19]
	v_mfma_f32_16x16x32_bf16 v[12:15], v[194:197], v[226:229], v[12:15]
	v_mfma_f32_16x16x32_bf16 v[8:11], v[202:205], v[226:229], v[8:11]
	v_mfma_f32_16x16x32_bf16 v[4:7], v[194:197], v[234:237], v[4:7]
	v_mfma_f32_16x16x32_bf16 v[0:3], v[202:205], v[234:237], v[0:3]
	s_setprio 0
	s_barrier
	s_add_i32 s70, 0, 0x18000
	v_add_u32_e32 v153, s70, v173
	s_add_i32 s71, 0, 0x1c000
	ds_read_b128 v[132:135], v153
	ds_read_b128 v[136:139], v153 offset:1024
	ds_read_b128 v[140:143], v153 offset:2048
	ds_read_b128 v[162:165], v153 offset:3072
	v_add_u32_e32 v153, s71, v173
	ds_read_b128 v[166:169], v153
	ds_read_b128 v[194:197], v153 offset:1024
	ds_read_b128 v[198:201], v153 offset:2048
	ds_read_b128 v[202:205], v153 offset:3072
	v_lshl_add_u64 v[240:241], s[44:45], 0, v[144:145]
	s_mov_b32 m0, s52
	s_nop 0
	global_load_lds_dwordx4 v[240:241], off
	v_lshl_add_u64 v[240:241], s[44:45], 0, v[148:149]
	s_mov_b32 m0, s53
	s_nop 0
	global_load_lds_dwordx4 v[240:241], off
	s_add_u32 s44, s44, 0x40000
	s_addc_u32 s45, s45, 0
	s_mov_b32 m0, s54
	v_lshl_add_u64 v[240:241], s[44:45], 0, v[144:145]
	ds_read_b128 v[206:209], v174 offset:32768
	ds_read_b128 v[210:213], v174 offset:33792
	ds_read_b128 v[214:217], v174 offset:34816
	ds_read_b128 v[218:221], v174 offset:35840
	ds_read_b128 v[222:225], v174 offset:36864
	ds_read_b128 v[226:229], v174 offset:37888
	ds_read_b128 v[230:233], v174 offset:38912
	ds_read_b128 v[234:237], v174 offset:39936
	global_load_lds_dwordx4 v[240:241], off
	v_lshl_add_u64 v[240:241], s[44:45], 0, v[148:149]
	s_mov_b32 m0, s55
	s_nop 0
	global_load_lds_dwordx4 v[240:241], off
	s_waitcnt vmcnt(8)
	s_waitcnt lgkmcnt(0)
	s_barrier
	s_setprio 1
	s_waitcnt lgkmcnt(0)
	v_mfma_f32_16x16x32_bf16 v[124:127], v[132:135], v[206:209], v[124:127]
	v_mfma_f32_16x16x32_bf16 v[120:123], v[140:143], v[206:209], v[120:123]
	v_mfma_f32_16x16x32_bf16 v[116:119], v[132:135], v[214:217], v[116:119]
	v_mfma_f32_16x16x32_bf16 v[112:115], v[140:143], v[214:217], v[112:115]
	v_mfma_f32_16x16x32_bf16 v[108:111], v[132:135], v[222:225], v[108:111]
	v_mfma_f32_16x16x32_bf16 v[104:107], v[140:143], v[222:225], v[104:107]
	v_mfma_f32_16x16x32_bf16 v[100:103], v[132:135], v[230:233], v[100:103]
	v_mfma_f32_16x16x32_bf16 v[96:99], v[140:143], v[230:233], v[96:99]
	v_mfma_f32_16x16x32_bf16 v[124:127], v[136:139], v[210:213], v[124:127]
	v_mfma_f32_16x16x32_bf16 v[120:123], v[162:165], v[210:213], v[120:123]
	v_mfma_f32_16x16x32_bf16 v[116:119], v[136:139], v[218:221], v[116:119]
	v_mfma_f32_16x16x32_bf16 v[112:115], v[162:165], v[218:221], v[112:115]
	v_mfma_f32_16x16x32_bf16 v[108:111], v[136:139], v[226:229], v[108:111]
	v_mfma_f32_16x16x32_bf16 v[104:107], v[162:165], v[226:229], v[104:107]
	v_mfma_f32_16x16x32_bf16 v[100:103], v[136:139], v[234:237], v[100:103]
	v_mfma_f32_16x16x32_bf16 v[96:99], v[162:165], v[234:237], v[96:99]
	s_setprio 0
	s_setprio 1
	v_mfma_f32_16x16x32_bf16 v[60:63], v[166:169], v[206:209], v[60:63]
	v_mfma_f32_16x16x32_bf16 v[56:59], v[198:201], v[206:209], v[56:59]
	v_mfma_f32_16x16x32_bf16 v[52:55], v[166:169], v[214:217], v[52:55]
	v_mfma_f32_16x16x32_bf16 v[48:51], v[198:201], v[214:217], v[48:51]
	v_mfma_f32_16x16x32_bf16 v[44:47], v[166:169], v[222:225], v[44:47]
	v_mfma_f32_16x16x32_bf16 v[40:43], v[198:201], v[222:225], v[40:43]
	v_mfma_f32_16x16x32_bf16 v[36:39], v[166:169], v[230:233], v[36:39]
	v_mfma_f32_16x16x32_bf16 v[32:35], v[198:201], v[230:233], v[32:35]
	v_mfma_f32_16x16x32_bf16 v[60:63], v[194:197], v[210:213], v[60:63]
	v_mfma_f32_16x16x32_bf16 v[56:59], v[202:205], v[210:213], v[56:59]
	v_mfma_f32_16x16x32_bf16 v[52:55], v[194:197], v[218:221], v[52:55]
	v_mfma_f32_16x16x32_bf16 v[48:51], v[202:205], v[218:221], v[48:51]
	v_mfma_f32_16x16x32_bf16 v[44:47], v[194:197], v[226:229], v[44:47]
	v_mfma_f32_16x16x32_bf16 v[40:43], v[202:205], v[226:229], v[40:43]
	v_mfma_f32_16x16x32_bf16 v[36:39], v[194:197], v[234:237], v[36:39]
	v_mfma_f32_16x16x32_bf16 v[32:35], v[202:205], v[234:237], v[32:35]
	s_setprio 0
	s_barrier
; #define PG8_STAGE(bufoff, gbase, voff) do { _Pragma("unroll") for (int _i = 0; _i < 2; ++_i) \
;         __builtin_amdgcn_global_load_lds((const unsigned*)((const char*)(gbase) + (voff)[_i]), (PG8_LAS unsigned*)(lds + (bufoff) + ldsw + _i * 8192), 16, 0, 0); } while (0)
; #define PG8_LDA(dst, b, h) do { _Pragma("unroll") for (int m = 0; m < 4; ++m) _Pragma("unroll") for (int k = 0; k < 2; ++k) dst[m][k] = *(const PG8_LAS bf16x8*)(lds + PG8_SA(b, h) + aoff + m * 2048 + k * 1024); } while (0)
; #define PG8_MMA(ai, bj, At, Bt) do { __builtin_amdgcn_s_setprio(1); _Pragma("unroll") for (int m = 0; m < 4; ++m) _Pragma("unroll") for (int n = 0; n < 2; ++n) _Pragma("unroll") for (int k = 0; k < 2; ++k) \
;         acc[ai][bj][m][n] = __builtin_amdgcn_mfma_f32_16x16x32_bf16(Bt[n][k], At[m][k], acc[ai][bj][m][n], 0, 0, 0); __builtin_amdgcn_s_setprio(0); } while (0)
; #define PG8_WAIT_V(n) asm volatile("s_waitcnt vmcnt(" #n ")" ::: "memory")
; #define PG8_WAIT_L(n) asm volatile("s_waitcnt lgkmcnt(" #n ")" ::: "memory")
; #define PG8_BAR __builtin_amdgcn_s_barrier()
; #define PG8_SCHED __builtin_amdgcn_sched_barrier(0)
; template <class Epi, class Sched, bool ALIGN_EPI = false, bool SP2 = false>
; __device__ __forceinline__ void gemm_phase(PG8_LAS unsigned char* lds, const Gemm g, const Sched& S, const Epi& E) {
;     ...
;             PG8_LDA(At, 1, 1); PG8_STAGE(PG8_SB(1, 0), b3, voffB); PG8_STAGE(PG8_SB(1, 1), b3 + hstepB, voffB); PG8_STAGE(PG8_SA(1, 0), a3, voffA);
;             PG8_WAIT_V(8); PG8_WAIT_L(0); PG8_BAR; PG8_MMA(1, 0, At, B0); PG8_MMA(1, 1, At, B1); PG8_BAR; PG8_SCHED;
;     ...
;         if constexpr (ALIGN_EPI) { if (wr == 0) PG8_BAR; }
	s_add_i32 s44, s70, s51
	v_lshl_add_u64 v[170:171], v[170:171], 0, s[18:19]
	s_mov_b32 m0, s44
	ds_read_b128 v[206:209], v174 offset:49152
	ds_read_b128 v[210:213], v174 offset:50176
	ds_read_b128 v[214:217], v174 offset:51200
	ds_read_b128 v[218:221], v174 offset:52224
	ds_read_b128 v[222:225], v174 offset:53248
	ds_read_b128 v[226:229], v174 offset:54272
	ds_read_b128 v[230:233], v174 offset:55296
	ds_read_b128 v[234:237], v174 offset:56320
	global_load_lds_dwordx4 v[170:171], off
	s_add_i32 m0, s44, 0x2000
	s_add_u32 s42, s42, 0x40080
	v_lshl_add_u64 v[170:171], v[238:239], 0, s[18:19]
	s_addc_u32 s43, s43, 0
	s_add_i32 s44, s71, s51
	global_load_lds_dwordx4 v[170:171], off
	v_lshl_add_u64 v[170:171], s[42:43], 0, v[146:147]
	s_mov_b32 m0, s44
	s_nop 0
	global_load_lds_dwordx4 v[170:171], off
	v_lshl_add_u64 v[170:171], s[42:43], 0, v[150:151]
	s_add_i32 m0, s44, 0x2000
	s_nop 0
	global_load_lds_dwordx4 v[170:171], off
	v_lshl_add_u64 v[170:171], s[40:41], 0, v[144:145]
	s_mov_b32 m0, s60
	s_nop 0
	global_load_lds_dwordx4 v[170:171], off
	v_lshl_add_u64 v[170:171], s[40:41], 0, v[148:149]
	s_mov_b32 m0, s61
	s_nop 0
	global_load_lds_dwordx4 v[170:171], off
	s_waitcnt vmcnt(8)
	s_waitcnt lgkmcnt(0)
	s_barrier
	s_setprio 1
	s_waitcnt lgkmcnt(0)
	v_mfma_f32_16x16x32_bf16 v[92:95], v[132:135], v[206:209], v[92:95]
	v_mfma_f32_16x16x32_bf16 v[88:91], v[140:143], v[206:209], v[88:91]
	v_mfma_f32_16x16x32_bf16 v[84:87], v[132:135], v[214:217], v[84:87]
	v_mfma_f32_16x16x32_bf16 v[80:83], v[140:143], v[214:217], v[80:83]
	v_mfma_f32_16x16x32_bf16 v[76:79], v[132:135], v[222:225], v[76:79]
	v_mfma_f32_16x16x32_bf16 v[72:75], v[140:143], v[222:225], v[72:75]
	v_mfma_f32_16x16x32_bf16 v[68:71], v[132:135], v[230:233], v[68:71]
	v_mfma_f32_16x16x32_bf16 v[64:67], v[140:143], v[230:233], v[64:67]
	v_mfma_f32_16x16x32_bf16 v[92:95], v[136:139], v[210:213], v[92:95]
	v_mfma_f32_16x16x32_bf16 v[88:91], v[162:165], v[210:213], v[88:91]
	v_mfma_f32_16x16x32_bf16 v[84:87], v[136:139], v[218:221], v[84:87]
	v_mfma_f32_16x16x32_bf16 v[80:83], v[162:165], v[218:221], v[80:83]
	v_mfma_f32_16x16x32_bf16 v[76:79], v[136:139], v[226:229], v[76:79]
	v_mfma_f32_16x16x32_bf16 v[72:75], v[162:165], v[226:229], v[72:75]
	v_mfma_f32_16x16x32_bf16 v[68:71], v[136:139], v[234:237], v[68:71]
	v_mfma_f32_16x16x32_bf16 v[64:67], v[162:165], v[234:237], v[64:67]
	s_setprio 0
	s_setprio 1
	v_mfma_f32_16x16x32_bf16 v[28:31], v[166:169], v[206:209], v[28:31]
	v_mfma_f32_16x16x32_bf16 v[24:27], v[198:201], v[206:209], v[24:27]
	v_mfma_f32_16x16x32_bf16 v[20:23], v[166:169], v[214:217], v[20:23]
	v_mfma_f32_16x16x32_bf16 v[16:19], v[198:201], v[214:217], v[16:19]
	v_mfma_f32_16x16x32_bf16 v[12:15], v[166:169], v[222:225], v[12:15]
	v_mfma_f32_16x16x32_bf16 v[8:11], v[198:201], v[222:225], v[8:11]
	v_mfma_f32_16x16x32_bf16 v[4:7], v[166:169], v[230:233], v[4:7]
	v_mfma_f32_16x16x32_bf16 v[0:3], v[198:201], v[230:233], v[0:3]
	v_mfma_f32_16x16x32_bf16 v[28:31], v[194:197], v[210:213], v[28:31]
	v_mfma_f32_16x16x32_bf16 v[24:27], v[202:205], v[210:213], v[24:27]
	v_mfma_f32_16x16x32_bf16 v[20:23], v[194:197], v[218:221], v[20:23]
	v_mfma_f32_16x16x32_bf16 v[16:19], v[202:205], v[218:221], v[16:19]
	v_mfma_f32_16x16x32_bf16 v[12:15], v[194:197], v[226:229], v[12:15]
	v_mfma_f32_16x16x32_bf16 v[8:11], v[202:205], v[226:229], v[8:11]
	v_mfma_f32_16x16x32_bf16 v[4:7], v[194:197], v[234:237], v[4:7]
	v_mfma_f32_16x16x32_bf16 v[0:3], v[202:205], v[234:237], v[0:3]
	s_setprio 0
	s_barrier
	s_add_i32 s79, s79, 2
	s_add_u32 s38, s38, 0x100
	s_addc_u32 s39, s39, 0
	s_cmp_gt_u32 s79, 13
	s_cbranch_scc0 .LBB0_1841
	s_and_b64 vcc, exec, s[20:21]
	s_cbranch_vccz .LBB0_1844
	s_barrier

; #define PG8_STAGE(bufoff, gbase, voff) do { _Pragma("unroll") for (int _i = 0; _i < 2; ++_i) \
;         __builtin_amdgcn_global_load_lds((const unsigned*)((const char*)(gbase) + (voff)[_i]), (PG8_LAS unsigned*)(lds + (bufoff) + ldsw + _i * 8192), 16, 0, 0); } while (0)
; #define PG8_LDA(dst, b, h) do { _Pragma("unroll") for (int m = 0; m < 4; ++m) _Pragma("unroll") for (int k = 0; k < 2; ++k) dst[m][k] = *(const PG8_LAS bf16x8*)(lds + PG8_SA(b, h) + aoff + m * 2048 + k * 1024); } while (0)
; #define PG8_LDB(dst, b, h) do { _Pragma("unroll") for (int n = 0; n < 2; ++n) _Pragma("unroll") for (int k = 0; k < 2; ++k) dst[n][k] = *(const PG8_LAS bf16x8*)(lds + PG8_SB(b, h) + boff + n * 2048 + k * 1024); } while (0)
; #define PG8_MMA(ai, bj, At, Bt) do { __builtin_amdgcn_s_setprio(1); _Pragma("unroll") for (int m = 0; m < 4; ++m) _Pragma("unroll") for (int n = 0; n < 2; ++n) _Pragma("unroll") for (int k = 0; k < 2; ++k) \
;         acc[ai][bj][m][n] = __builtin_amdgcn_mfma_f32_16x16x32_bf16(Bt[n][k], At[m][k], acc[ai][bj][m][n], 0, 0, 0); __builtin_amdgcn_s_setprio(0); } while (0)
; #define PG8_WAIT_V(n) asm volatile("s_waitcnt vmcnt(" #n ")" ::: "memory")
; #define PG8_WAIT_L(n) asm volatile("s_waitcnt lgkmcnt(" #n ")" ::: "memory")
; template <class Epi, class Sched, bool ALIGN_EPI = false, bool SP2 = false>
; __device__ __forceinline__ void gemm_phase(PG8_LAS unsigned char* lds, const Gemm g, const Sched& S, const Epi& E) {
;     ...
;             const bool last = (t == nt - 2);
;             const char* a1 = cA + PG8_AK(t + 1);
;             const char* a2 = last ? nA : cA + PG8_AK(t + 2); const char* b2 = last ? nB : cB + (size_t)(t + 2) * kstep;
;             const char* a3 = last ? nA + PG8_AK(1) : cA + PG8_AK(t + 3); const char* b3 = b2 + kstep;
;             if (last && has_next) S.a_ready(nxt);
;             if constexpr (SP2) {
;             PG8_LDB(B0, 0, 0); PG8_LDB(B1, 0, 1); PG8_SCHED; PG8_LDA(At, 0, 0); PG8_STAGE(PG8_SA(1, 1), a1 + hstepA, voffA);
;             PG8_WAIT_V(8); PG8_WAIT_L(0); PG8_BAR; PG8_MMA(0, 0, At, B0); PG8_MMA(0, 1, At, B1); PG8_BAR; PG8_SCHED;
;             PG8_LDA(At, 0, 1); PG8_STAGE(PG8_SB(0, 0), b2, voffB); PG8_STAGE(PG8_SB(0, 1), b2 + hstepB, voffB); PG8_STAGE(PG8_SA(0, 0), a2, voffA);
;             PG8_WAIT_V(8); PG8_WAIT_L(0); PG8_BAR; PG8_MMA(1, 0, At, B0); PG8_MMA(1, 1, At, B1); PG8_BAR; PG8_SCHED;
.LBB0_2888:
	ds_read_b128 v[124:127], v210
	ds_read_b128 v[128:131], v210 offset:1024
	ds_read_b128 v[132:135], v210 offset:2048
	ds_read_b128 v[144:147], v210 offset:3072
	ds_read_b128 v[148:151], v211
	ds_read_b128 v[170:173], v211 offset:1024
	ds_read_b128 v[174:177], v211 offset:2048
	ds_read_b128 v[178:181], v211 offset:3072
	s_add_u32 s42, s38, s40
	s_addc_u32 s43, s39, s41
	s_add_u32 s46, s42, 0x100
	s_addc_u32 s47, s43, 0
	s_add_u32 s44, s78, s40
	s_addc_u32 s45, s79, s41
	s_add_u32 s42, s42, 0x180
	s_addc_u32 s43, s43, 0
	s_cmpk_eq_i32 s40, 0x1500
	s_cselect_b32 s43, s10, s43
	s_cselect_b32 s42, s3, s42
	s_cselect_b32 s45, s37, s45
	s_cselect_b32 s44, s36, s44
	s_cselect_b32 s47, s9, s47
	s_cselect_b32 s46, s8, s46
	v_lshl_add_u64 v[206:207], v[122:123], 0, s[40:41]
	s_add_i32 m0, s53, 0xc000
	ds_read_b128 v[212:215], v191
	ds_read_b128 v[216:219], v191 offset:1024
	ds_read_b128 v[220:223], v191 offset:2048
	ds_read_b128 v[224:227], v191 offset:3072
	ds_read_b128 v[228:231], v191 offset:4096
	ds_read_b128 v[232:235], v191 offset:5120
	ds_read_b128 v[236:239], v191 offset:6144
	ds_read_b128 v[240:243], v191 offset:7168
	global_load_lds_dwordx4 v[206:207], off
	v_lshl_add_u64 v[206:207], v[120:121], 0, s[40:41]
	s_add_i32 m0, s53, 0xe000
	s_nop 0
	global_load_lds_dwordx4 v[206:207], off
	s_waitcnt vmcnt(8)
	s_waitcnt lgkmcnt(0)
	s_barrier
	s_setprio 1
	s_waitcnt lgkmcnt(0)
	v_mfma_f32_16x16x32_bf16 v[140:143], v[124:127], v[212:215], v[140:143]
	v_mfma_f32_16x16x32_bf16 v[136:139], v[132:135], v[212:215], v[136:139]
	v_mfma_f32_16x16x32_bf16 v[116:119], v[124:127], v[220:223], v[116:119]
	v_mfma_f32_16x16x32_bf16 v[112:115], v[132:135], v[220:223], v[112:115]
	v_mfma_f32_16x16x32_bf16 v[108:111], v[124:127], v[228:231], v[108:111]
	v_mfma_f32_16x16x32_bf16 v[104:107], v[132:135], v[228:231], v[104:107]
	v_mfma_f32_16x16x32_bf16 v[100:103], v[124:127], v[236:239], v[100:103]
	v_mfma_f32_16x16x32_bf16 v[96:99], v[132:135], v[236:239], v[96:99]
	v_mfma_f32_16x16x32_bf16 v[140:143], v[128:131], v[216:219], v[140:143]
	v_mfma_f32_16x16x32_bf16 v[136:139], v[144:147], v[216:219], v[136:139]
	v_mfma_f32_16x16x32_bf16 v[116:119], v[128:131], v[224:227], v[116:119]
	v_mfma_f32_16x16x32_bf16 v[112:115], v[144:147], v[224:227], v[112:115]
	v_mfma_f32_16x16x32_bf16 v[108:111], v[128:131], v[232:235], v[108:111]
	v_mfma_f32_16x16x32_bf16 v[104:107], v[144:147], v[232:235], v[104:107]
	v_mfma_f32_16x16x32_bf16 v[100:103], v[128:131], v[240:243], v[100:103]
	v_mfma_f32_16x16x32_bf16 v[96:99], v[144:147], v[240:243], v[96:99]
	s_setprio 0
	s_setprio 1
	v_mfma_f32_16x16x32_bf16 v[60:63], v[148:151], v[212:215], v[60:63]
	v_mfma_f32_16x16x32_bf16 v[56:59], v[174:177], v[212:215], v[56:59]
	v_mfma_f32_16x16x32_bf16 v[52:55], v[148:151], v[220:223], v[52:55]
	v_mfma_f32_16x16x32_bf16 v[48:51], v[174:177], v[220:223], v[48:51]
	v_mfma_f32_16x16x32_bf16 v[44:47], v[148:151], v[228:231], v[44:47]
	v_mfma_f32_16x16x32_bf16 v[40:43], v[174:177], v[228:231], v[40:43]
	v_mfma_f32_16x16x32_bf16 v[36:39], v[148:151], v[236:239], v[36:39]
	v_mfma_f32_16x16x32_bf16 v[32:35], v[174:177], v[236:239], v[32:35]
	v_mfma_f32_16x16x32_bf16 v[60:63], v[170:173], v[216:219], v[60:63]
	v_mfma_f32_16x16x32_bf16 v[56:59], v[178:181], v[216:219], v[56:59]
	v_mfma_f32_16x16x32_bf16 v[52:55], v[170:173], v[224:227], v[52:55]
	v_mfma_f32_16x16x32_bf16 v[48:51], v[178:181], v[224:227], v[48:51]
	v_mfma_f32_16x16x32_bf16 v[44:47], v[170:173], v[232:235], v[44:47]
	v_mfma_f32_16x16x32_bf16 v[40:43], v[178:181], v[232:235], v[40:43]
	v_mfma_f32_16x16x32_bf16 v[36:39], v[170:173], v[240:243], v[36:39]
	v_mfma_f32_16x16x32_bf16 v[32:35], v[178:181], v[240:243], v[32:35]
	s_setprio 0
	s_barrier
	s_add_i32 s70, s69, s52
	v_lshl_add_u64 v[206:207], s[44:45], 0, v[154:155]
	s_mov_b32 m0, s70
	ds_read_b128 v[212:215], v191 offset:16384
	ds_read_b128 v[216:219], v191 offset:17408
	ds_read_b128 v[220:223], v191 offset:18432
	ds_read_b128 v[224:227], v191 offset:19456
	ds_read_b128 v[228:231], v191 offset:20480
	ds_read_b128 v[232:235], v191 offset:21504
	ds_read_b128 v[236:239], v191 offset:22528
	ds_read_b128 v[240:243], v191 offset:23552
	global_load_lds_dwordx4 v[206:207], off
	s_add_i32 m0, s70, 0x2000
	s_add_u32 s70, s44, 0xb0000
	v_lshl_add_u64 v[244:245], s[44:45], 0, v[158:159]
	s_addc_u32 s71, s45, 0
	s_add_i32 s87, s80, s52
	global_load_lds_dwordx4 v[244:245], off
	v_lshl_add_u64 v[246:247], s[70:71], 0, v[154:155]
	s_mov_b32 m0, s87
	s_nop 0
	global_load_lds_dwordx4 v[246:247], off
	v_lshl_add_u64 v[246:247], s[70:71], 0, v[158:159]
	s_add_i32 m0, s87, 0x2000
	s_nop 0
	global_load_lds_dwordx4 v[246:247], off
	s_waitcnt vmcnt(6)
	s_waitcnt lgkmcnt(0)
	s_barrier
; #define PG8_STAGE(bufoff, gbase, voff) do { _Pragma("unroll") for (int _i = 0; _i < 2; ++_i) \
;         __builtin_amdgcn_global_load_lds((const unsigned*)((const char*)(gbase) + (voff)[_i]), (PG8_LAS unsigned*)(lds + (bufoff) + ldsw + _i * 8192), 16, 0, 0); } while (0)
; #define PG8_LDA(dst, b, h) do { _Pragma("unroll") for (int m = 0; m < 4; ++m) _Pragma("unroll") for (int k = 0; k < 2; ++k) dst[m][k] = *(const PG8_LAS bf16x8*)(lds + PG8_SA(b, h) + aoff + m * 2048 + k * 1024); } while (0)
; #define PG8_LDB(dst, b, h) do { _Pragma("unroll") for (int n = 0; n < 2; ++n) _Pragma("unroll") for (int k = 0; k < 2; ++k) dst[n][k] = *(const PG8_LAS bf16x8*)(lds + PG8_SB(b, h) + boff + n * 2048 + k * 1024); } while (0)
; #define PG8_MMA(ai, bj, At, Bt) do { __builtin_amdgcn_s_setprio(1); _Pragma("unroll") for (int m = 0; m < 4; ++m) _Pragma("unroll") for (int n = 0; n < 2; ++n) _Pragma("unroll") for (int k = 0; k < 2; ++k) \
;         acc[ai][bj][m][n] = __builtin_amdgcn_mfma_f32_16x16x32_bf16(Bt[n][k], At[m][k], acc[ai][bj][m][n], 0, 0, 0); __builtin_amdgcn_s_setprio(0); } while (0)
; #define PG8_WAIT_V(n) asm volatile("s_waitcnt vmcnt(" #n ")" ::: "memory")
; #define PG8_WAIT_L(n) asm volatile("s_waitcnt lgkmcnt(" #n ")" ::: "memory")
; #define PG8_BAR __builtin_amdgcn_s_barrier()
; #define PG8_SCHED __builtin_amdgcn_sched_barrier(0)
; template <class Epi, class Sched, bool ALIGN_EPI = false, bool SP2 = false>
; __device__ __forceinline__ void gemm_phase(PG8_LAS unsigned char* lds, const Gemm g, const Sched& S, const Epi& E) {
;     ...
;             PG8_WAIT_V(8); PG8_WAIT_L(0); PG8_BAR; PG8_MMA(1, 0, At, B0); PG8_MMA(1, 1, At, B1); PG8_BAR; PG8_SCHED;
;             PG8_LDB(B0, 1, 0); PG8_LDB(B1, 1, 1); PG8_SCHED; PG8_LDA(At, 1, 0); PG8_STAGE(PG8_SA(0, 1), a2 + hstepA, voffA);
;             PG8_WAIT_V(8); PG8_WAIT_L(0); PG8_BAR; PG8_MMA(0, 0, At, B0); PG8_MMA(0, 1, At, B1); PG8_BAR; PG8_SCHED;
	s_setprio 1
	s_waitcnt lgkmcnt(0)
	v_mfma_f32_16x16x32_bf16 v[92:95], v[124:127], v[212:215], v[92:95]
	v_mfma_f32_16x16x32_bf16 v[88:91], v[132:135], v[212:215], v[88:91]
	v_mfma_f32_16x16x32_bf16 v[84:87], v[124:127], v[220:223], v[84:87]
	v_mfma_f32_16x16x32_bf16 v[80:83], v[132:135], v[220:223], v[80:83]
	v_mfma_f32_16x16x32_bf16 v[76:79], v[124:127], v[228:231], v[76:79]
	v_mfma_f32_16x16x32_bf16 v[72:75], v[132:135], v[228:231], v[72:75]
	v_mfma_f32_16x16x32_bf16 v[68:71], v[124:127], v[236:239], v[68:71]
	v_mfma_f32_16x16x32_bf16 v[64:67], v[132:135], v[236:239], v[64:67]
	v_mfma_f32_16x16x32_bf16 v[92:95], v[128:131], v[216:219], v[92:95]
	v_mfma_f32_16x16x32_bf16 v[88:91], v[144:147], v[216:219], v[88:91]
	v_mfma_f32_16x16x32_bf16 v[84:87], v[128:131], v[224:227], v[84:87]
	v_mfma_f32_16x16x32_bf16 v[80:83], v[144:147], v[224:227], v[80:83]
	v_mfma_f32_16x16x32_bf16 v[76:79], v[128:131], v[232:235], v[76:79]
	v_mfma_f32_16x16x32_bf16 v[72:75], v[144:147], v[232:235], v[72:75]
	v_mfma_f32_16x16x32_bf16 v[68:71], v[128:131], v[240:243], v[68:71]
	v_mfma_f32_16x16x32_bf16 v[64:67], v[144:147], v[240:243], v[64:67]
	s_setprio 0
	s_setprio 1
	v_mfma_f32_16x16x32_bf16 v[28:31], v[148:151], v[212:215], v[28:31]
	v_mfma_f32_16x16x32_bf16 v[24:27], v[174:177], v[212:215], v[24:27]
	v_mfma_f32_16x16x32_bf16 v[20:23], v[148:151], v[220:223], v[20:23]
	v_mfma_f32_16x16x32_bf16 v[16:19], v[174:177], v[220:223], v[16:19]
	v_mfma_f32_16x16x32_bf16 v[12:15], v[148:151], v[228:231], v[12:15]
	v_mfma_f32_16x16x32_bf16 v[8:11], v[174:177], v[228:231], v[8:11]
	v_mfma_f32_16x16x32_bf16 v[4:7], v[148:151], v[236:239], v[4:7]
	v_mfma_f32_16x16x32_bf16 v[0:3], v[174:177], v[236:239], v[0:3]
	v_mfma_f32_16x16x32_bf16 v[28:31], v[170:173], v[216:219], v[28:31]
	v_mfma_f32_16x16x32_bf16 v[24:27], v[178:181], v[216:219], v[24:27]
	v_mfma_f32_16x16x32_bf16 v[20:23], v[170:173], v[224:227], v[20:23]
	v_mfma_f32_16x16x32_bf16 v[16:19], v[178:181], v[224:227], v[16:19]
	v_mfma_f32_16x16x32_bf16 v[12:15], v[170:173], v[232:235], v[12:15]
	v_mfma_f32_16x16x32_bf16 v[8:11], v[178:181], v[232:235], v[8:11]
	v_mfma_f32_16x16x32_bf16 v[4:7], v[170:173], v[240:243], v[4:7]
	v_mfma_f32_16x16x32_bf16 v[0:3], v[178:181], v[240:243], v[0:3]
	s_setprio 0
	s_barrier
	s_add_i32 s70, 0, 0x18000
	s_add_i32 s71, 0, 0x1c000
	v_add_u32_e32 v144, s70, v185
	v_add_u32_e32 v161, s71, v185
	ds_read_b128 v[124:127], v144
	ds_read_b128 v[128:131], v144 offset:1024
	ds_read_b128 v[132:135], v144 offset:2048
	ds_read_b128 v[144:147], v144 offset:3072
	ds_read_b128 v[148:151], v161
	ds_read_b128 v[170:173], v161 offset:1024
	ds_read_b128 v[174:177], v161 offset:2048
	ds_read_b128 v[178:181], v161 offset:3072
	v_lshl_add_u64 v[246:247], s[46:47], 0, v[152:153]
	s_mov_b32 m0, s53
	s_nop 0
	global_load_lds_dwordx4 v[246:247], off
	v_lshl_add_u64 v[246:247], s[46:47], 0, v[156:157]
	s_mov_b32 m0, s54
	s_nop 0
	global_load_lds_dwordx4 v[246:247], off
	s_add_u32 s46, s46, 0xb0000
	s_addc_u32 s47, s47, 0
	s_mov_b32 m0, s55
	v_lshl_add_u64 v[246:247], s[46:47], 0, v[152:153]
	ds_read_b128 v[212:215], v191 offset:32768
	ds_read_b128 v[216:219], v191 offset:33792
	ds_read_b128 v[220:223], v191 offset:34816
	ds_read_b128 v[224:227], v191 offset:35840
	ds_read_b128 v[228:231], v191 offset:36864
	ds_read_b128 v[232:235], v191 offset:37888
	ds_read_b128 v[236:239], v191 offset:38912
	ds_read_b128 v[240:243], v191 offset:39936
	global_load_lds_dwordx4 v[246:247], off
	v_lshl_add_u64 v[246:247], s[46:47], 0, v[156:157]
	s_mov_b32 m0, s56
	s_nop 0
	global_load_lds_dwordx4 v[246:247], off
	s_waitcnt vmcnt(8)
	s_waitcnt lgkmcnt(0)
	s_barrier
	s_setprio 1
	s_waitcnt lgkmcnt(0)
	v_mfma_f32_16x16x32_bf16 v[140:143], v[124:127], v[212:215], v[140:143]
	v_mfma_f32_16x16x32_bf16 v[136:139], v[132:135], v[212:215], v[136:139]
	v_mfma_f32_16x16x32_bf16 v[116:119], v[124:127], v[220:223], v[116:119]
	v_mfma_f32_16x16x32_bf16 v[112:115], v[132:135], v[220:223], v[112:115]
	v_mfma_f32_16x16x32_bf16 v[108:111], v[124:127], v[228:231], v[108:111]
	v_mfma_f32_16x16x32_bf16 v[104:107], v[132:135], v[228:231], v[104:107]
	v_mfma_f32_16x16x32_bf16 v[100:103], v[124:127], v[236:239], v[100:103]
	v_mfma_f32_16x16x32_bf16 v[96:99], v[132:135], v[236:239], v[96:99]
	v_mfma_f32_16x16x32_bf16 v[140:143], v[128:131], v[216:219], v[140:143]
	v_mfma_f32_16x16x32_bf16 v[136:139], v[144:147], v[216:219], v[136:139]
	v_mfma_f32_16x16x32_bf16 v[116:119], v[128:131], v[224:227], v[116:119]
	v_mfma_f32_16x16x32_bf16 v[112:115], v[144:147], v[224:227], v[112:115]
	v_mfma_f32_16x16x32_bf16 v[108:111], v[128:131], v[232:235], v[108:111]
	v_mfma_f32_16x16x32_bf16 v[104:107], v[144:147], v[232:235], v[104:107]
	v_mfma_f32_16x16x32_bf16 v[100:103], v[128:131], v[240:243], v[100:103]
	v_mfma_f32_16x16x32_bf16 v[96:99], v[144:147], v[240:243], v[96:99]
	s_setprio 0
	s_setprio 1
	v_mfma_f32_16x16x32_bf16 v[60:63], v[148:151], v[212:215], v[60:63]
	v_mfma_f32_16x16x32_bf16 v[56:59], v[174:177], v[212:215], v[56:59]
	v_mfma_f32_16x16x32_bf16 v[52:55], v[148:151], v[220:223], v[52:55]
	v_mfma_f32_16x16x32_bf16 v[48:51], v[174:177], v[220:223], v[48:51]
	v_mfma_f32_16x16x32_bf16 v[44:47], v[148:151], v[228:231], v[44:47]
	v_mfma_f32_16x16x32_bf16 v[40:43], v[174:177], v[228:231], v[40:43]
	v_mfma_f32_16x16x32_bf16 v[36:39], v[148:151], v[236:239], v[36:39]
	v_mfma_f32_16x16x32_bf16 v[32:35], v[174:177], v[236:239], v[32:35]
	v_mfma_f32_16x16x32_bf16 v[60:63], v[170:173], v[216:219], v[60:63]
	v_mfma_f32_16x16x32_bf16 v[56:59], v[178:181], v[216:219], v[56:59]
	v_mfma_f32_16x16x32_bf16 v[52:55], v[170:173], v[224:227], v[52:55]
	v_mfma_f32_16x16x32_bf16 v[48:51], v[178:181], v[224:227], v[48:51]
	v_mfma_f32_16x16x32_bf16 v[44:47], v[170:173], v[232:235], v[44:47]
	v_mfma_f32_16x16x32_bf16 v[40:43], v[178:181], v[232:235], v[40:43]
	v_mfma_f32_16x16x32_bf16 v[36:39], v[170:173], v[240:243], v[36:39]
	v_mfma_f32_16x16x32_bf16 v[32:35], v[178:181], v[240:243], v[32:35]
	s_setprio 0
	s_barrier
; #define PG8_STAGE(bufoff, gbase, voff) do { _Pragma("unroll") for (int _i = 0; _i < 2; ++_i) \
;         __builtin_amdgcn_global_load_lds((const unsigned*)((const char*)(gbase) + (voff)[_i]), (PG8_LAS unsigned*)(lds + (bufoff) + ldsw + _i * 8192), 16, 0, 0); } while (0)
; #define PG8_LDA(dst, b, h) do { _Pragma("unroll") for (int m = 0; m < 4; ++m) _Pragma("unroll") for (int k = 0; k < 2; ++k) dst[m][k] = *(const PG8_LAS bf16x8*)(lds + PG8_SA(b, h) + aoff + m * 2048 + k * 1024); } while (0)
; #define PG8_MMA(ai, bj, At, Bt) do { __builtin_amdgcn_s_setprio(1); _Pragma("unroll") for (int m = 0; m < 4; ++m) _Pragma("unroll") for (int n = 0; n < 2; ++n) _Pragma("unroll") for (int k = 0; k < 2; ++k) \
;         acc[ai][bj][m][n] = __builtin_amdgcn_mfma_f32_16x16x32_bf16(Bt[n][k], At[m][k], acc[ai][bj][m][n], 0, 0, 0); __builtin_amdgcn_s_setprio(0); } while (0)
; #define PG8_WAIT_V(n) asm volatile("s_waitcnt vmcnt(" #n ")" ::: "memory")
; #define PG8_WAIT_L(n) asm volatile("s_waitcnt lgkmcnt(" #n ")" ::: "memory")
; #define PG8_BAR __builtin_amdgcn_s_barrier()
; #define PG8_SCHED __builtin_amdgcn_sched_barrier(0)
; template <class Epi, class Sched, bool ALIGN_EPI = false, bool SP2 = false>
; __device__ __forceinline__ void gemm_phase(PG8_LAS unsigned char* lds, const Gemm g, const Sched& S, const Epi& E) {
;     ...
;             PG8_LDA(At, 1, 1); PG8_STAGE(PG8_SB(1, 0), b3, voffB); PG8_STAGE(PG8_SB(1, 1), b3 + hstepB, voffB); PG8_STAGE(PG8_SA(1, 0), a3, voffA);
;             PG8_WAIT_V(8); PG8_WAIT_L(0); PG8_BAR; PG8_MMA(1, 0, At, B0); PG8_MMA(1, 1, At, B1); PG8_BAR; PG8_SCHED;
;     ...
;         if constexpr (ALIGN_EPI) { if (wr == 0) PG8_BAR; }
	s_add_i32 s46, s70, s52
	v_lshl_add_u64 v[206:207], v[206:207], 0, s[26:27]
	s_mov_b32 m0, s46
	ds_read_b128 v[212:215], v191 offset:49152
	ds_read_b128 v[216:219], v191 offset:50176
	ds_read_b128 v[220:223], v191 offset:51200
	ds_read_b128 v[224:227], v191 offset:52224
	ds_read_b128 v[228:231], v191 offset:53248
	ds_read_b128 v[232:235], v191 offset:54272
	ds_read_b128 v[236:239], v191 offset:55296
	ds_read_b128 v[240:243], v191 offset:56320
	global_load_lds_dwordx4 v[206:207], off
	s_add_i32 m0, s46, 0x2000
	s_add_u32 s44, s44, 0xb0080
	v_lshl_add_u64 v[206:207], v[244:245], 0, s[26:27]
	s_addc_u32 s45, s45, 0
	s_add_i32 s46, s71, s52
	global_load_lds_dwordx4 v[206:207], off
	v_lshl_add_u64 v[206:207], s[44:45], 0, v[154:155]
	s_mov_b32 m0, s46
	s_nop 0
	global_load_lds_dwordx4 v[206:207], off
	v_lshl_add_u64 v[206:207], s[44:45], 0, v[158:159]
	s_add_i32 m0, s46, 0x2000
	s_nop 0
	global_load_lds_dwordx4 v[206:207], off
	v_lshl_add_u64 v[206:207], s[42:43], 0, v[152:153]
	s_mov_b32 m0, s65
	s_nop 0
	global_load_lds_dwordx4 v[206:207], off
	v_lshl_add_u64 v[206:207], s[42:43], 0, v[156:157]
	s_mov_b32 m0, s66
	s_nop 0
	global_load_lds_dwordx4 v[206:207], off
	s_waitcnt vmcnt(8)
	s_waitcnt lgkmcnt(0)
	s_barrier
	s_setprio 1
	s_waitcnt lgkmcnt(0)
	v_mfma_f32_16x16x32_bf16 v[92:95], v[124:127], v[212:215], v[92:95]
	v_mfma_f32_16x16x32_bf16 v[88:91], v[132:135], v[212:215], v[88:91]
	v_mfma_f32_16x16x32_bf16 v[84:87], v[124:127], v[220:223], v[84:87]
	v_mfma_f32_16x16x32_bf16 v[80:83], v[132:135], v[220:223], v[80:83]
	v_mfma_f32_16x16x32_bf16 v[76:79], v[124:127], v[228:231], v[76:79]
	v_mfma_f32_16x16x32_bf16 v[72:75], v[132:135], v[228:231], v[72:75]
	v_mfma_f32_16x16x32_bf16 v[68:71], v[124:127], v[236:239], v[68:71]
	v_mfma_f32_16x16x32_bf16 v[64:67], v[132:135], v[236:239], v[64:67]
	v_mfma_f32_16x16x32_bf16 v[92:95], v[128:131], v[216:219], v[92:95]
	v_mfma_f32_16x16x32_bf16 v[88:91], v[144:147], v[216:219], v[88:91]
	v_mfma_f32_16x16x32_bf16 v[84:87], v[128:131], v[224:227], v[84:87]
	v_mfma_f32_16x16x32_bf16 v[80:83], v[144:147], v[224:227], v[80:83]
	v_mfma_f32_16x16x32_bf16 v[76:79], v[128:131], v[232:235], v[76:79]
	v_mfma_f32_16x16x32_bf16 v[72:75], v[144:147], v[232:235], v[72:75]
	v_mfma_f32_16x16x32_bf16 v[68:71], v[128:131], v[240:243], v[68:71]
	v_mfma_f32_16x16x32_bf16 v[64:67], v[144:147], v[240:243], v[64:67]
	s_setprio 0
	s_setprio 1
	v_mfma_f32_16x16x32_bf16 v[28:31], v[148:151], v[212:215], v[28:31]
	v_mfma_f32_16x16x32_bf16 v[24:27], v[174:177], v[212:215], v[24:27]
	v_mfma_f32_16x16x32_bf16 v[20:23], v[148:151], v[220:223], v[20:23]
	v_mfma_f32_16x16x32_bf16 v[16:19], v[174:177], v[220:223], v[16:19]
	v_mfma_f32_16x16x32_bf16 v[12:15], v[148:151], v[228:231], v[12:15]
	v_mfma_f32_16x16x32_bf16 v[8:11], v[174:177], v[228:231], v[8:11]
	v_mfma_f32_16x16x32_bf16 v[4:7], v[148:151], v[236:239], v[4:7]
	v_mfma_f32_16x16x32_bf16 v[0:3], v[174:177], v[236:239], v[0:3]
	v_mfma_f32_16x16x32_bf16 v[28:31], v[170:173], v[216:219], v[28:31]
	v_mfma_f32_16x16x32_bf16 v[24:27], v[178:181], v[216:219], v[24:27]
	v_mfma_f32_16x16x32_bf16 v[20:23], v[170:173], v[224:227], v[20:23]
	v_mfma_f32_16x16x32_bf16 v[16:19], v[178:181], v[224:227], v[16:19]
	v_mfma_f32_16x16x32_bf16 v[12:15], v[170:173], v[232:235], v[12:15]
	v_mfma_f32_16x16x32_bf16 v[8:11], v[178:181], v[232:235], v[8:11]
	v_mfma_f32_16x16x32_bf16 v[4:7], v[170:173], v[240:243], v[4:7]
	v_mfma_f32_16x16x32_bf16 v[0:3], v[178:181], v[240:243], v[0:3]
	s_setprio 0
	s_barrier
	s_add_i32 s86, s86, 2
	s_add_u32 s40, s40, 0x100
	s_addc_u32 s41, s41, 0
	s_cmp_gt_u32 s86, 41
	s_cbranch_scc0 .LBB0_2888
	s_and_b64 vcc, exec, s[28:29]
	s_cbranch_vccz .LBB0_2891
	s_barrier

; #define PG8_STAGE(bufoff, gbase, voff) do { _Pragma("unroll") for (int _i = 0; _i < 2; ++_i) \
;         __builtin_amdgcn_global_load_lds((const unsigned*)((const char*)(gbase) + (voff)[_i]), (PG8_LAS unsigned*)(lds + (bufoff) + ldsw + _i * 8192), 16, 0, 0); } while (0)
; #define PG8_LDA(dst, b, h) do { _Pragma("unroll") for (int m = 0; m < 4; ++m) _Pragma("unroll") for (int k = 0; k < 2; ++k) dst[m][k] = *(const PG8_LAS bf16x8*)(lds + PG8_SA(b, h) + aoff + m * 2048 + k * 1024); } while (0)
; #define PG8_LDB(dst, b, h) do { _Pragma("unroll") for (int n = 0; n < 2; ++n) _Pragma("unroll") for (int k = 0; k < 2; ++k) dst[n][k] = *(const PG8_LAS bf16x8*)(lds + PG8_SB(b, h) + boff + n * 2048 + k * 1024); } while (0)
; #define PG8_MMA(ai, bj, At, Bt) do { __builtin_amdgcn_s_setprio(1); _Pragma("unroll") for (int m = 0; m < 4; ++m) _Pragma("unroll") for (int n = 0; n < 2; ++n) _Pragma("unroll") for (int k = 0; k < 2; ++k) \
;         acc[ai][bj][m][n] = __builtin_amdgcn_mfma_f32_16x16x32_bf16(Bt[n][k], At[m][k], acc[ai][bj][m][n], 0, 0, 0); __builtin_amdgcn_s_setprio(0); } while (0)
; #define PG8_WAIT_V(n) asm volatile("s_waitcnt vmcnt(" #n ")" ::: "memory")
; #define PG8_WAIT_L(n) asm volatile("s_waitcnt lgkmcnt(" #n ")" ::: "memory")
; template <class Epi, class Sched, bool ALIGN_EPI = false, bool SP2 = false>
; __device__ __forceinline__ void gemm_phase(PG8_LAS unsigned char* lds, const Gemm g, const Sched& S, const Epi& E) {
;     ...
;             const bool last = (t == nt - 2);
;             const char* a1 = cA + PG8_AK(t + 1);
;             const char* a2 = last ? nA : cA + PG8_AK(t + 2); const char* b2 = last ? nB : cB + (size_t)(t + 2) * kstep;
;             const char* a3 = last ? nA + PG8_AK(1) : cA + PG8_AK(t + 3); const char* b3 = b2 + kstep;
;             if (last && has_next) S.a_ready(nxt);
;             if constexpr (SP2) {
;             PG8_LDB(B0, 0, 0); PG8_LDB(B1, 0, 1); PG8_SCHED; PG8_LDA(At, 0, 0); PG8_STAGE(PG8_SA(1, 1), a1 + hstepA, voffA);
;             PG8_WAIT_V(8); PG8_WAIT_L(0); PG8_BAR; PG8_MMA(0, 0, At, B0); PG8_MMA(0, 1, At, B1); PG8_BAR; PG8_SCHED;
;             PG8_LDA(At, 0, 1); PG8_STAGE(PG8_SB(0, 0), b2, voffB); PG8_STAGE(PG8_SB(0, 1), b2 + hstepB, voffB); PG8_STAGE(PG8_SA(0, 0), a2, voffA);
;             PG8_WAIT_V(8); PG8_WAIT_L(0); PG8_BAR; PG8_MMA(1, 0, At, B0); PG8_MMA(1, 1, At, B1); PG8_BAR; PG8_SCHED;
.LBB0_2980:
	ds_read_b128 v[108:111], v191
	ds_read_b128 v[112:115], v191 offset:1024
	ds_read_b128 v[116:119], v191 offset:2048
	ds_read_b128 v[120:123], v191 offset:3072
	ds_read_b128 v[124:127], v193
	ds_read_b128 v[128:131], v193 offset:1024
	ds_read_b128 v[132:135], v193 offset:2048
	ds_read_b128 v[160:163], v193 offset:3072
	s_add_u32 s42, s38, s40
	s_addc_u32 s43, s39, s41
	s_add_u32 s46, s42, 0x100
	s_addc_u32 s47, s43, 0
	s_add_u32 s44, s80, s40
	s_addc_u32 s45, s81, s41
	s_add_u32 s42, s42, 0x180
	s_addc_u32 s43, s43, 0
	s_cmpk_eq_i32 s40, 0x700
	s_cselect_b32 s43, s79, s43
	s_cselect_b32 s42, s78, s42
	s_cselect_b32 s45, s27, s45
	s_cselect_b32 s44, s69, s44
	s_cselect_b32 s47, s3, s47
	s_cselect_b32 s46, s29, s46
	v_lshl_add_u64 v[242:243], v[106:107], 0, s[40:41]
	s_add_i32 m0, s54, 0xc000
	ds_read_b128 v[164:167], v187
	ds_read_b128 v[168:171], v187 offset:1024
	ds_read_b128 v[218:221], v187 offset:2048
	ds_read_b128 v[222:225], v187 offset:3072
	ds_read_b128 v[226:229], v187 offset:4096
	ds_read_b128 v[230:233], v187 offset:5120
	ds_read_b128 v[234:237], v187 offset:6144
	ds_read_b128 v[238:241], v187 offset:7168
	global_load_lds_dwordx4 v[242:243], off
	v_lshl_add_u64 v[242:243], v[104:105], 0, s[40:41]
	s_add_i32 m0, s54, 0xe000
	s_nop 0
	global_load_lds_dwordx4 v[242:243], off
	s_waitcnt vmcnt(8)
	s_waitcnt lgkmcnt(0)
	s_barrier
	s_setprio 1
	s_waitcnt lgkmcnt(0)
	v_mfma_f32_16x16x32_bf16 v[156:159], v[108:111], v[164:167], v[156:159]
	v_mfma_f32_16x16x32_bf16 v[152:155], v[116:119], v[164:167], v[152:155]
	v_mfma_f32_16x16x32_bf16 v[148:151], v[108:111], v[218:221], v[148:151]
	v_mfma_f32_16x16x32_bf16 v[144:147], v[116:119], v[218:221], v[144:147]
	v_mfma_f32_16x16x32_bf16 v[140:143], v[108:111], v[226:229], v[140:143]
	v_mfma_f32_16x16x32_bf16 v[136:139], v[116:119], v[226:229], v[136:139]
	v_mfma_f32_16x16x32_bf16 v[100:103], v[108:111], v[234:237], v[100:103]
	v_mfma_f32_16x16x32_bf16 v[96:99], v[116:119], v[234:237], v[96:99]
	v_mfma_f32_16x16x32_bf16 v[156:159], v[112:115], v[168:171], v[156:159]
	v_mfma_f32_16x16x32_bf16 v[152:155], v[120:123], v[168:171], v[152:155]
	v_mfma_f32_16x16x32_bf16 v[148:151], v[112:115], v[222:225], v[148:151]
	v_mfma_f32_16x16x32_bf16 v[144:147], v[120:123], v[222:225], v[144:147]
	v_mfma_f32_16x16x32_bf16 v[140:143], v[112:115], v[230:233], v[140:143]
	v_mfma_f32_16x16x32_bf16 v[136:139], v[120:123], v[230:233], v[136:139]
	v_mfma_f32_16x16x32_bf16 v[100:103], v[112:115], v[238:241], v[100:103]
	v_mfma_f32_16x16x32_bf16 v[96:99], v[120:123], v[238:241], v[96:99]
	s_setprio 0
	s_setprio 1
	v_mfma_f32_16x16x32_bf16 v[60:63], v[124:127], v[164:167], v[60:63]
	v_mfma_f32_16x16x32_bf16 v[56:59], v[132:135], v[164:167], v[56:59]
	v_mfma_f32_16x16x32_bf16 v[52:55], v[124:127], v[218:221], v[52:55]
	v_mfma_f32_16x16x32_bf16 v[48:51], v[132:135], v[218:221], v[48:51]
	v_mfma_f32_16x16x32_bf16 v[44:47], v[124:127], v[226:229], v[44:47]
	v_mfma_f32_16x16x32_bf16 v[40:43], v[132:135], v[226:229], v[40:43]
	v_mfma_f32_16x16x32_bf16 v[36:39], v[124:127], v[234:237], v[36:39]
	v_mfma_f32_16x16x32_bf16 v[32:35], v[132:135], v[234:237], v[32:35]
	v_mfma_f32_16x16x32_bf16 v[60:63], v[128:131], v[168:171], v[60:63]
	v_mfma_f32_16x16x32_bf16 v[56:59], v[160:163], v[168:171], v[56:59]
	v_mfma_f32_16x16x32_bf16 v[52:55], v[128:131], v[222:225], v[52:55]
	v_mfma_f32_16x16x32_bf16 v[48:51], v[160:163], v[222:225], v[48:51]
	v_mfma_f32_16x16x32_bf16 v[44:47], v[128:131], v[230:233], v[44:47]
	v_mfma_f32_16x16x32_bf16 v[40:43], v[160:163], v[230:233], v[40:43]
	v_mfma_f32_16x16x32_bf16 v[36:39], v[128:131], v[238:241], v[36:39]
	v_mfma_f32_16x16x32_bf16 v[32:35], v[160:163], v[238:241], v[32:35]
	s_setprio 0
	s_barrier
	s_add_i32 s70, s66, s53
	v_lshl_add_u64 v[242:243], s[44:45], 0, v[174:175]
	s_mov_b32 m0, s70
	ds_read_b128 v[164:167], v187 offset:16384
	ds_read_b128 v[168:171], v187 offset:17408
	ds_read_b128 v[218:221], v187 offset:18432
	ds_read_b128 v[222:225], v187 offset:19456
	ds_read_b128 v[226:229], v187 offset:20480
	ds_read_b128 v[230:233], v187 offset:21504
	ds_read_b128 v[234:237], v187 offset:22528
	ds_read_b128 v[238:241], v187 offset:23552
	global_load_lds_dwordx4 v[242:243], off
	s_add_i32 m0, s70, 0x2000
	s_add_u32 s70, s44, 0x40000
	v_lshl_add_u64 v[244:245], s[44:45], 0, v[178:179]
	s_addc_u32 s71, s45, 0
	s_add_i32 s83, s67, s53
	global_load_lds_dwordx4 v[244:245], off
	v_lshl_add_u64 v[246:247], s[70:71], 0, v[174:175]
	s_mov_b32 m0, s83
	s_nop 0
	global_load_lds_dwordx4 v[246:247], off
	v_lshl_add_u64 v[246:247], s[70:71], 0, v[178:179]
	s_add_i32 m0, s83, 0x2000
	s_nop 0
	global_load_lds_dwordx4 v[246:247], off
	s_waitcnt vmcnt(6)
	s_waitcnt lgkmcnt(0)
	s_barrier
; #define PG8_STAGE(bufoff, gbase, voff) do { _Pragma("unroll") for (int _i = 0; _i < 2; ++_i) \
;         __builtin_amdgcn_global_load_lds((const unsigned*)((const char*)(gbase) + (voff)[_i]), (PG8_LAS unsigned*)(lds + (bufoff) + ldsw + _i * 8192), 16, 0, 0); } while (0)
; #define PG8_LDA(dst, b, h) do { _Pragma("unroll") for (int m = 0; m < 4; ++m) _Pragma("unroll") for (int k = 0; k < 2; ++k) dst[m][k] = *(const PG8_LAS bf16x8*)(lds + PG8_SA(b, h) + aoff + m * 2048 + k * 1024); } while (0)
; #define PG8_LDB(dst, b, h) do { _Pragma("unroll") for (int n = 0; n < 2; ++n) _Pragma("unroll") for (int k = 0; k < 2; ++k) dst[n][k] = *(const PG8_LAS bf16x8*)(lds + PG8_SB(b, h) + boff + n * 2048 + k * 1024); } while (0)
; #define PG8_MMA(ai, bj, At, Bt) do { __builtin_amdgcn_s_setprio(1); _Pragma("unroll") for (int m = 0; m < 4; ++m) _Pragma("unroll") for (int n = 0; n < 2; ++n) _Pragma("unroll") for (int k = 0; k < 2; ++k) \
;         acc[ai][bj][m][n] = __builtin_amdgcn_mfma_f32_16x16x32_bf16(Bt[n][k], At[m][k], acc[ai][bj][m][n], 0, 0, 0); __builtin_amdgcn_s_setprio(0); } while (0)
; #define PG8_WAIT_V(n) asm volatile("s_waitcnt vmcnt(" #n ")" ::: "memory")
; #define PG8_WAIT_L(n) asm volatile("s_waitcnt lgkmcnt(" #n ")" ::: "memory")
; #define PG8_BAR __builtin_amdgcn_s_barrier()
; #define PG8_SCHED __builtin_amdgcn_sched_barrier(0)
; template <class Epi, class Sched, bool ALIGN_EPI = false, bool SP2 = false>
; __device__ __forceinline__ void gemm_phase(PG8_LAS unsigned char* lds, const Gemm g, const Sched& S, const Epi& E) {
;     ...
;             PG8_WAIT_V(8); PG8_WAIT_L(0); PG8_BAR; PG8_MMA(1, 0, At, B0); PG8_MMA(1, 1, At, B1); PG8_BAR; PG8_SCHED;
;             PG8_LDB(B0, 1, 0); PG8_LDB(B1, 1, 1); PG8_SCHED; PG8_LDA(At, 1, 0); PG8_STAGE(PG8_SA(0, 1), a2 + hstepA, voffA);
;             PG8_WAIT_V(8); PG8_WAIT_L(0); PG8_BAR; PG8_MMA(0, 0, At, B0); PG8_MMA(0, 1, At, B1); PG8_BAR; PG8_SCHED;
	s_setprio 1
	s_waitcnt lgkmcnt(0)
	v_mfma_f32_16x16x32_bf16 v[92:95], v[108:111], v[164:167], v[92:95]
	v_mfma_f32_16x16x32_bf16 v[88:91], v[116:119], v[164:167], v[88:91]
	v_mfma_f32_16x16x32_bf16 v[84:87], v[108:111], v[218:221], v[84:87]
	v_mfma_f32_16x16x32_bf16 v[80:83], v[116:119], v[218:221], v[80:83]
	v_mfma_f32_16x16x32_bf16 v[76:79], v[108:111], v[226:229], v[76:79]
	v_mfma_f32_16x16x32_bf16 v[72:75], v[116:119], v[226:229], v[72:75]
	v_mfma_f32_16x16x32_bf16 v[68:71], v[108:111], v[234:237], v[68:71]
	v_mfma_f32_16x16x32_bf16 v[64:67], v[116:119], v[234:237], v[64:67]
	v_mfma_f32_16x16x32_bf16 v[92:95], v[112:115], v[168:171], v[92:95]
	v_mfma_f32_16x16x32_bf16 v[88:91], v[120:123], v[168:171], v[88:91]
	v_mfma_f32_16x16x32_bf16 v[84:87], v[112:115], v[222:225], v[84:87]
	v_mfma_f32_16x16x32_bf16 v[80:83], v[120:123], v[222:225], v[80:83]
	v_mfma_f32_16x16x32_bf16 v[76:79], v[112:115], v[230:233], v[76:79]
	v_mfma_f32_16x16x32_bf16 v[72:75], v[120:123], v[230:233], v[72:75]
	v_mfma_f32_16x16x32_bf16 v[68:71], v[112:115], v[238:241], v[68:71]
	v_mfma_f32_16x16x32_bf16 v[64:67], v[120:123], v[238:241], v[64:67]
	s_setprio 0
	s_setprio 1
	v_mfma_f32_16x16x32_bf16 v[28:31], v[124:127], v[164:167], v[28:31]
	v_mfma_f32_16x16x32_bf16 v[24:27], v[132:135], v[164:167], v[24:27]
	v_mfma_f32_16x16x32_bf16 v[20:23], v[124:127], v[218:221], v[20:23]
	v_mfma_f32_16x16x32_bf16 v[16:19], v[132:135], v[218:221], v[16:19]
	v_mfma_f32_16x16x32_bf16 v[12:15], v[124:127], v[226:229], v[12:15]
	v_mfma_f32_16x16x32_bf16 v[8:11], v[132:135], v[226:229], v[8:11]
	v_mfma_f32_16x16x32_bf16 v[4:7], v[124:127], v[234:237], v[4:7]
	v_mfma_f32_16x16x32_bf16 v[0:3], v[132:135], v[234:237], v[0:3]
	v_mfma_f32_16x16x32_bf16 v[28:31], v[128:131], v[168:171], v[28:31]
	v_mfma_f32_16x16x32_bf16 v[24:27], v[160:163], v[168:171], v[24:27]
	v_mfma_f32_16x16x32_bf16 v[20:23], v[128:131], v[222:225], v[20:23]
	v_mfma_f32_16x16x32_bf16 v[16:19], v[160:163], v[222:225], v[16:19]
	v_mfma_f32_16x16x32_bf16 v[12:15], v[128:131], v[230:233], v[12:15]
	v_mfma_f32_16x16x32_bf16 v[8:11], v[160:163], v[230:233], v[8:11]
	v_mfma_f32_16x16x32_bf16 v[4:7], v[128:131], v[238:241], v[4:7]
	v_mfma_f32_16x16x32_bf16 v[0:3], v[160:163], v[238:241], v[0:3]
	s_setprio 0
	s_barrier
	s_add_i32 s70, 0, 0x18000
	s_add_i32 s71, 0, 0x1c000
	v_add_u32_e32 v120, s70, v181
	v_add_u32_e32 v160, s71, v181
	ds_read_b128 v[108:111], v120
	ds_read_b128 v[112:115], v120 offset:1024
	ds_read_b128 v[116:119], v120 offset:2048
	ds_read_b128 v[120:123], v120 offset:3072
	ds_read_b128 v[124:127], v160
	ds_read_b128 v[128:131], v160 offset:1024
	ds_read_b128 v[132:135], v160 offset:2048
	ds_read_b128 v[160:163], v160 offset:3072
	v_lshl_add_u64 v[246:247], s[46:47], 0, v[172:173]
	s_mov_b32 m0, s54
	s_nop 0
	global_load_lds_dwordx4 v[246:247], off
	v_lshl_add_u64 v[246:247], s[46:47], 0, v[176:177]
	s_mov_b32 m0, s55
	s_nop 0
	global_load_lds_dwordx4 v[246:247], off
	s_add_u32 s46, s46, 0x40000
	s_addc_u32 s47, s47, 0
	s_mov_b32 m0, s56
	v_lshl_add_u64 v[246:247], s[46:47], 0, v[172:173]
	ds_read_b128 v[164:167], v187 offset:32768
	ds_read_b128 v[168:171], v187 offset:33792
	ds_read_b128 v[218:221], v187 offset:34816
	ds_read_b128 v[222:225], v187 offset:35840
	ds_read_b128 v[226:229], v187 offset:36864
	ds_read_b128 v[230:233], v187 offset:37888
	ds_read_b128 v[234:237], v187 offset:38912
	ds_read_b128 v[238:241], v187 offset:39936
	global_load_lds_dwordx4 v[246:247], off
	v_lshl_add_u64 v[246:247], s[46:47], 0, v[176:177]
	s_mov_b32 m0, s57
	s_nop 0
	global_load_lds_dwordx4 v[246:247], off
	s_waitcnt vmcnt(8)
	s_waitcnt lgkmcnt(0)
	s_barrier
	s_setprio 1
	s_waitcnt lgkmcnt(0)
	v_mfma_f32_16x16x32_bf16 v[156:159], v[108:111], v[164:167], v[156:159]
	v_mfma_f32_16x16x32_bf16 v[152:155], v[116:119], v[164:167], v[152:155]
	v_mfma_f32_16x16x32_bf16 v[148:151], v[108:111], v[218:221], v[148:151]
	v_mfma_f32_16x16x32_bf16 v[144:147], v[116:119], v[218:221], v[144:147]
	v_mfma_f32_16x16x32_bf16 v[140:143], v[108:111], v[226:229], v[140:143]
	v_mfma_f32_16x16x32_bf16 v[136:139], v[116:119], v[226:229], v[136:139]
	v_mfma_f32_16x16x32_bf16 v[100:103], v[108:111], v[234:237], v[100:103]
	v_mfma_f32_16x16x32_bf16 v[96:99], v[116:119], v[234:237], v[96:99]
	v_mfma_f32_16x16x32_bf16 v[156:159], v[112:115], v[168:171], v[156:159]
	v_mfma_f32_16x16x32_bf16 v[152:155], v[120:123], v[168:171], v[152:155]
	v_mfma_f32_16x16x32_bf16 v[148:151], v[112:115], v[222:225], v[148:151]
	v_mfma_f32_16x16x32_bf16 v[144:147], v[120:123], v[222:225], v[144:147]
	v_mfma_f32_16x16x32_bf16 v[140:143], v[112:115], v[230:233], v[140:143]
	v_mfma_f32_16x16x32_bf16 v[136:139], v[120:123], v[230:233], v[136:139]
	v_mfma_f32_16x16x32_bf16 v[100:103], v[112:115], v[238:241], v[100:103]
	v_mfma_f32_16x16x32_bf16 v[96:99], v[120:123], v[238:241], v[96:99]
	s_setprio 0
	s_setprio 1
	v_mfma_f32_16x16x32_bf16 v[60:63], v[124:127], v[164:167], v[60:63]
	v_mfma_f32_16x16x32_bf16 v[56:59], v[132:135], v[164:167], v[56:59]
	v_mfma_f32_16x16x32_bf16 v[52:55], v[124:127], v[218:221], v[52:55]
	v_mfma_f32_16x16x32_bf16 v[48:51], v[132:135], v[218:221], v[48:51]
	v_mfma_f32_16x16x32_bf16 v[44:47], v[124:127], v[226:229], v[44:47]
	v_mfma_f32_16x16x32_bf16 v[40:43], v[132:135], v[226:229], v[40:43]
	v_mfma_f32_16x16x32_bf16 v[36:39], v[124:127], v[234:237], v[36:39]
	v_mfma_f32_16x16x32_bf16 v[32:35], v[132:135], v[234:237], v[32:35]
	v_mfma_f32_16x16x32_bf16 v[60:63], v[128:131], v[168:171], v[60:63]
	v_mfma_f32_16x16x32_bf16 v[56:59], v[160:163], v[168:171], v[56:59]
	v_mfma_f32_16x16x32_bf16 v[52:55], v[128:131], v[222:225], v[52:55]
	v_mfma_f32_16x16x32_bf16 v[48:51], v[160:163], v[222:225], v[48:51]
	v_mfma_f32_16x16x32_bf16 v[44:47], v[128:131], v[230:233], v[44:47]
	v_mfma_f32_16x16x32_bf16 v[40:43], v[160:163], v[230:233], v[40:43]
	v_mfma_f32_16x16x32_bf16 v[36:39], v[128:131], v[238:241], v[36:39]
	v_mfma_f32_16x16x32_bf16 v[32:35], v[160:163], v[238:241], v[32:35]
	s_setprio 0
	s_barrier
; #define PG8_STAGE(bufoff, gbase, voff) do { _Pragma("unroll") for (int _i = 0; _i < 2; ++_i) \
;         __builtin_amdgcn_global_load_lds((const unsigned*)((const char*)(gbase) + (voff)[_i]), (PG8_LAS unsigned*)(lds + (bufoff) + ldsw + _i * 8192), 16, 0, 0); } while (0)
; #define PG8_LDA(dst, b, h) do { _Pragma("unroll") for (int m = 0; m < 4; ++m) _Pragma("unroll") for (int k = 0; k < 2; ++k) dst[m][k] = *(const PG8_LAS bf16x8*)(lds + PG8_SA(b, h) + aoff + m * 2048 + k * 1024); } while (0)
; #define PG8_MMA(ai, bj, At, Bt) do { __builtin_amdgcn_s_setprio(1); _Pragma("unroll") for (int m = 0; m < 4; ++m) _Pragma("unroll") for (int n = 0; n < 2; ++n) _Pragma("unroll") for (int k = 0; k < 2; ++k) \
;         acc[ai][bj][m][n] = __builtin_amdgcn_mfma_f32_16x16x32_bf16(Bt[n][k], At[m][k], acc[ai][bj][m][n], 0, 0, 0); __builtin_amdgcn_s_setprio(0); } while (0)
; #define PG8_WAIT_V(n) asm volatile("s_waitcnt vmcnt(" #n ")" ::: "memory")
; #define PG8_WAIT_L(n) asm volatile("s_waitcnt lgkmcnt(" #n ")" ::: "memory")
; #define PG8_BAR __builtin_amdgcn_s_barrier()
; #define PG8_SCHED __builtin_amdgcn_sched_barrier(0)
; template <class Epi, class Sched, bool ALIGN_EPI = false, bool SP2 = false>
; __device__ __forceinline__ void gemm_phase(PG8_LAS unsigned char* lds, const Gemm g, const Sched& S, const Epi& E) {
;     ...
;             PG8_LDA(At, 1, 1); PG8_STAGE(PG8_SB(1, 0), b3, voffB); PG8_STAGE(PG8_SB(1, 1), b3 + hstepB, voffB); PG8_STAGE(PG8_SA(1, 0), a3, voffA);
;             PG8_WAIT_V(8); PG8_WAIT_L(0); PG8_BAR; PG8_MMA(1, 0, At, B0); PG8_MMA(1, 1, At, B1); PG8_BAR; PG8_SCHED;
;     ...
;         if constexpr (ALIGN_EPI) { if (wr == 0) PG8_BAR; }
	s_add_i32 s46, s70, s53
	v_lshl_add_u64 v[242:243], v[242:243], 0, s[6:7]
	s_mov_b32 m0, s46
	ds_read_b128 v[164:167], v187 offset:49152
	ds_read_b128 v[168:171], v187 offset:50176
	ds_read_b128 v[218:221], v187 offset:51200
	ds_read_b128 v[222:225], v187 offset:52224
	ds_read_b128 v[226:229], v187 offset:53248
	ds_read_b128 v[230:233], v187 offset:54272
	ds_read_b128 v[234:237], v187 offset:55296
	ds_read_b128 v[238:241], v187 offset:56320
	global_load_lds_dwordx4 v[242:243], off
	s_add_i32 m0, s46, 0x2000
	s_add_u32 s44, s44, 0x40080
	v_lshl_add_u64 v[242:243], v[244:245], 0, s[6:7]
	s_addc_u32 s45, s45, 0
	s_add_i32 s46, s71, s53
	global_load_lds_dwordx4 v[242:243], off
	v_lshl_add_u64 v[242:243], s[44:45], 0, v[174:175]
	s_mov_b32 m0, s46
	s_nop 0
	global_load_lds_dwordx4 v[242:243], off
	v_lshl_add_u64 v[242:243], s[44:45], 0, v[178:179]
	s_add_i32 m0, s46, 0x2000
	s_nop 0
	global_load_lds_dwordx4 v[242:243], off
	v_lshl_add_u64 v[242:243], s[42:43], 0, v[172:173]
	s_mov_b32 m0, s63
	s_nop 0
	global_load_lds_dwordx4 v[242:243], off
	v_lshl_add_u64 v[242:243], s[42:43], 0, v[176:177]
	s_mov_b32 m0, s64
	s_nop 0
	global_load_lds_dwordx4 v[242:243], off
	s_waitcnt vmcnt(8)
	s_waitcnt lgkmcnt(0)
	s_barrier
	s_setprio 1
	s_waitcnt lgkmcnt(0)
	v_mfma_f32_16x16x32_bf16 v[92:95], v[108:111], v[164:167], v[92:95]
	v_mfma_f32_16x16x32_bf16 v[88:91], v[116:119], v[164:167], v[88:91]
	v_mfma_f32_16x16x32_bf16 v[84:87], v[108:111], v[218:221], v[84:87]
	v_mfma_f32_16x16x32_bf16 v[80:83], v[116:119], v[218:221], v[80:83]
	v_mfma_f32_16x16x32_bf16 v[76:79], v[108:111], v[226:229], v[76:79]
	v_mfma_f32_16x16x32_bf16 v[72:75], v[116:119], v[226:229], v[72:75]
	v_mfma_f32_16x16x32_bf16 v[68:71], v[108:111], v[234:237], v[68:71]
	v_mfma_f32_16x16x32_bf16 v[64:67], v[116:119], v[234:237], v[64:67]
	v_mfma_f32_16x16x32_bf16 v[92:95], v[112:115], v[168:171], v[92:95]
	v_mfma_f32_16x16x32_bf16 v[88:91], v[120:123], v[168:171], v[88:91]
	v_mfma_f32_16x16x32_bf16 v[84:87], v[112:115], v[222:225], v[84:87]
	v_mfma_f32_16x16x32_bf16 v[80:83], v[120:123], v[222:225], v[80:83]
	v_mfma_f32_16x16x32_bf16 v[76:79], v[112:115], v[230:233], v[76:79]
	v_mfma_f32_16x16x32_bf16 v[72:75], v[120:123], v[230:233], v[72:75]
	v_mfma_f32_16x16x32_bf16 v[68:71], v[112:115], v[238:241], v[68:71]
	v_mfma_f32_16x16x32_bf16 v[64:67], v[120:123], v[238:241], v[64:67]
	s_setprio 0
	s_setprio 1
	v_mfma_f32_16x16x32_bf16 v[28:31], v[124:127], v[164:167], v[28:31]
	v_mfma_f32_16x16x32_bf16 v[24:27], v[132:135], v[164:167], v[24:27]
	v_mfma_f32_16x16x32_bf16 v[20:23], v[124:127], v[218:221], v[20:23]
	v_mfma_f32_16x16x32_bf16 v[16:19], v[132:135], v[218:221], v[16:19]
	v_mfma_f32_16x16x32_bf16 v[12:15], v[124:127], v[226:229], v[12:15]
	v_mfma_f32_16x16x32_bf16 v[8:11], v[132:135], v[226:229], v[8:11]
	v_mfma_f32_16x16x32_bf16 v[4:7], v[124:127], v[234:237], v[4:7]
	v_mfma_f32_16x16x32_bf16 v[0:3], v[132:135], v[234:237], v[0:3]
	v_mfma_f32_16x16x32_bf16 v[28:31], v[128:131], v[168:171], v[28:31]
	v_mfma_f32_16x16x32_bf16 v[24:27], v[160:163], v[168:171], v[24:27]
	v_mfma_f32_16x16x32_bf16 v[20:23], v[128:131], v[222:225], v[20:23]
	v_mfma_f32_16x16x32_bf16 v[16:19], v[160:163], v[222:225], v[16:19]
	v_mfma_f32_16x16x32_bf16 v[12:15], v[128:131], v[230:233], v[12:15]
	v_mfma_f32_16x16x32_bf16 v[8:11], v[160:163], v[230:233], v[8:11]
	v_mfma_f32_16x16x32_bf16 v[4:7], v[128:131], v[238:241], v[4:7]
	v_mfma_f32_16x16x32_bf16 v[0:3], v[160:163], v[238:241], v[0:3]
	s_setprio 0
	s_barrier
	s_add_i32 s82, s82, 2
	s_add_u32 s40, s40, 0x100
	s_addc_u32 s41, s41, 0
	s_cmp_gt_u32 s82, 13
	s_cbranch_scc0 .LBB0_2980
	s_and_b64 vcc, exec, s[22:23]
	s_cbranch_vccz .LBB0_2983
	s_barrier
